# adds ret R-update LDS read-ahead and software-pipelined K-loops for FFN-out, xo, xq, DA-qkv, RET-qkvg, mem-kv GEMMs
# speedup vs baseline: 1.0347x; 1.0065x over previous
; DI f32x16 zero16() { f32x16 z; for (int i = 0; i < 16; ++i) z[i] = 0.f; return z; }
; DI int launder(int x) { asm volatile("" : "+v"(x)); return x; }
; template <int BK> DI int swz(int row) { constexpr int CPR = BK / 8; return (row / (16 / CPR)) % CPR; }
; DI void wait_vm0() { asm volatile("s_waitcnt vmcnt(0)" ::: "memory"); }
;   DI void pre(int grow0, int gcol0, int lane, int w, char* lds) { xpass(0, grow0, gcol0, lane, w, lds); }
;     ...
;   const int tid = launder(threadIdx.x), lane = tid & 63, w = tid >> 6, wm = w % WM, wn = w / WM;
;   const int l31 = lane & 31, hh = lane >> 5;
;   f32x16 acc[2][NTW];
; #pragma unroll
;   for (int a = 0; a < 2; ++a)
; #pragma unroll
;     for (int b = 0; b < NTW; ++b) acc[a][b] = zero16();
;   const bf16_t* Ag = A + (size_t)row0 * lda; const bf16_t* Bg = Bt + (size_t)col0 * ldb;
;   const int wv = __builtin_amdgcn_readfirstlane(tid >> 6);
;   __syncthreads();
;   if (!pre) { stage_tile<BM, BK>(Ag, lda, lds, tid); stage_tile<BN, BK>(Bg, ldb, lds + ABYTES, tid); }
;   wait_vm0();
;   __syncthreads();
;     ...
;     for (int mt = 0; mt < 2; ++mt) { int row = wm * 64 + mt * 32 + l31; fa[0][mt] = *(const bf16x8*)(cur + row * (BK * 2) + ((hh ^ swz<BK>(row)) << 4)); }
; #pragma unroll
;     for (int nt = 0; nt < NTW; ++nt) { int row = wn * (32 * NTW) + nt * 32 + l31; fb[0][nt] = *(const bf16x8*)(cur + ABYTES + row * (BK * 2) + ((hh ^ swz<BK>(row)) << 4)); }
; #pragma unroll
;     for (int kk = 0; kk < NKK; ++kk) {
;       if (kk + 1 < NKK) {
;         const int ch = (kk + 1) * 2 + hh;
; #pragma unroll
;         for (int mt = 0; mt < 2; ++mt) { int row = wm * 64 + mt * 32 + l31; fa[(kk + 1) & 1][mt] = *(const bf16x8*)(cur + row * (BK * 2) + ((ch ^ swz<BK>(row)) << 4)); }
; #pragma unroll
;         for (int nt = 0; nt < NTW; ++nt) { int row = wn * (32 * NTW) + nt * 32 + l31; fb[(kk + 1) & 1][nt] = *(const bf16x8*)(cur + ABYTES + row * (BK * 2) + ((ch ^ swz<BK>(row)) << 4)); }
.LBB0_168:
	s_mov_b64 s[30:31], -1
	s_waitcnt lgkmcnt(0)
	s_mov_b64 s[42:43], 0
	s_cmp_lt_i32 s70, 2
	s_mov_b64 s[6:7], 0
	v_writelane_b32 v255, s71, 50
	s_cbranch_scc1 .LBB0_243
	s_cmp_eq_u32 s70, 2
	s_mov_b64 s[6:7], -1
	s_cbranch_scc0 .LBB0_288
	s_cmp_lt_i32 s71, 1
	s_cbranch_scc1 .LBB0_277
	s_cmp_lg_u32 s71, 1
	s_cbranch_scc0 .LBB0_259
	v_readlane_b32 s2, v254, 61
	v_readlane_b32 s3, v254, 62
	v_mov_b32_e32 v8, v216
	s_load_dwordx2 s[2:3], s[2:3], 0x1f8
	v_readlane_b32 s6, v253, 13
	v_ashrrev_i32_e32 v2, 31, v8
	v_lshrrev_b32_e32 v3, 29, v2
	v_lshrrev_b32_e32 v2, 28, v2
	v_add_u32_e32 v2, v8, v2
	v_ashrrev_i32_e32 v2, 4, v2
	v_lshrrev_b32_e32 v5, 29, v2
	v_add_u32_e32 v3, v8, v3
	v_add_u32_e32 v5, v2, v5
	v_readlane_b32 s7, v253, 14
	s_waitcnt lgkmcnt(0)
	s_add_u32 s2, s2, s6
	v_and_b32_e32 v4, 0xffffff8, v3
	v_and_b32_e32 v5, 0xffffff8, v5
	s_addc_u32 s3, s3, s7
	v_sub_u32_e32 v4, v8, v4
	v_sub_u32_e32 v2, v2, v5
	v_lshlrev_b32_e32 v3, 8, v3
	v_readfirstlane_b32 s7, v8
	v_xor_b32_e32 v2, v2, v4
	v_and_b32_e32 v3, 0xfffff800, v3
	v_readlane_b32 s30, v253, 11
	s_lshl_b32 s7, s7, 4
	v_lshl_add_u32 v2, v2, 4, v3
	v_mov_b32_e32 v3, v1
	v_readlane_b32 s31, v253, 12
	s_and_b32 s7, s7, 0xfffffc00
	s_mov_b32 m0, s7
	v_lshl_add_u64 v[4:5], s[30:31], 0, v[2:3]
	s_barrier
	s_nop 0
	global_load_lds_dwordx4 v2, s[30:31]
	v_lshl_add_u64 v[6:7], v[4:5], 0, s[58:59]
	s_add_i32 m0, s7, 0x2000
	s_waitcnt vmcnt(0)
	v_lshl_add_u64 v[130:131], s[2:3], 0, v[2:3]
	global_load_lds_dwordx4 v[6:7], off
	v_lshl_add_u64 v[6:7], v[4:5], 0, s[48:49]
	s_add_i32 m0, s7, 0x4000
	v_lshl_add_u64 v[4:5], v[4:5], 0, s[50:51]
	global_load_lds_dwordx4 v[6:7], off
	s_add_i32 m0, s7, 0x6000
	v_ashrrev_i32_e32 v134, 6, v8
	global_load_lds_dwordx4 v[4:5], off
	s_add_i32 m0, s7, 0x8000
	v_lshl_add_u64 v[4:5], v[130:131], 0, s[58:59]
	global_load_lds_dwordx4 v2, s[2:3]
	s_add_i32 m0, s7, 0xa000
	v_and_b32_e32 v6, 31, v8
	global_load_lds_dwordx4 v[4:5], off
	v_lshl_add_u64 v[4:5], v[130:131], 0, s[48:49]
	s_add_i32 m0, s7, 0xc000
	v_and_b32_e32 v0, 63, v8
	global_load_lds_dwordx4 v[4:5], off
	v_lshl_add_u64 v[4:5], v[130:131], 0, s[50:51]
	s_add_i32 m0, s7, 0xe000
	v_bfe_u32 v135, v8, 5, 1
	global_load_lds_dwordx4 v[4:5], off
	v_lshrrev_b32_e32 v4, 30, v134
	v_add_u32_e32 v4, v134, v4
	v_ashrrev_i32_e32 v5, 2, v4
	v_mul_i32_i24_e32 v7, 4, v5
	v_sub_u32_e32 v7, v134, v7
	v_lshlrev_b32_e32 v169, 6, v7
	v_lshlrev_b32_e32 v164, 7, v5
	v_or_b32_e32 v5, v169, v6
	v_bfe_u32 v7, v7, 25, 1
	v_lshlrev_b32_e32 v136, 7, v5
	v_add_u32_e32 v8, v5, v7
	v_or_b32_e32 v5, 32, v5
	v_lshlrev_b32_e32 v144, 7, v5
	v_add_u32_e32 v5, v5, v7
	v_ashrrev_i32_e32 v7, 1, v5
	v_ashrrev_i32_e32 v5, 31, v5
	v_ashrrev_i32_e32 v9, 1, v8
	v_ashrrev_i32_e32 v8, 31, v8
	v_lshrrev_b32_e32 v5, 29, v5
	v_lshrrev_b32_e32 v8, 29, v8
	v_add_u32_e32 v5, v7, v5
	v_add_u32_e32 v8, v9, v8
	v_and_b32_e32 v5, -8, v5
	v_and_b32_e32 v8, -8, v8
	v_sub_u32_e32 v5, v7, v5
	v_or_b32_e32 v6, v164, v6
	v_sub_u32_e32 v8, v9, v8
	v_xor_b32_e32 v7, v5, v135
	v_lshrrev_b32_e32 v4, 31, v4
	v_xor_b32_e32 v9, v8, v135
	v_lshlrev_b32_e32 v146, 4, v7
	v_add_u32_e32 v7, v6, v4
	v_lshlrev_b32_e32 v143, 4, v9
	v_ashrrev_i32_e32 v9, 1, v7
	v_ashrrev_i32_e32 v7, 31, v7
	v_lshrrev_b32_e32 v7, 29, v7
	v_add_u32_e32 v7, v9, v7
	v_and_b32_e32 v7, -8, v7
	v_sub_u32_e32 v7, v9, v7
	v_xor_b32_e32 v9, v7, v135
	v_lshlrev_b32_e32 v151, 4, v9
	v_or_b32_e32 v9, 32, v6
	v_lshlrev_b32_e32 v152, 7, v9
	v_add_u32_e32 v9, v9, v4
	v_ashrrev_i32_e32 v10, 1, v9
	v_ashrrev_i32_e32 v9, 31, v9
	v_lshrrev_b32_e32 v9, 29, v9
	v_add_u32_e32 v9, v10, v9
	v_and_b32_e32 v9, -8, v9
	v_sub_u32_e32 v9, v10, v9
	v_xor_b32_e32 v10, v9, v135
	v_lshlrev_b32_e32 v145, 7, v6
	v_lshlrev_b32_e32 v156, 4, v10
	v_or_b32_e32 v10, 64, v6
	v_or_b32_e32 v6, 0x60, v6
	v_lshlrev_b32_e32 v155, 7, v10
	v_add_u32_e32 v10, v10, v4
	v_add_u32_e32 v4, v6, v4
	v_lshlrev_b32_e32 v158, 7, v6
	v_ashrrev_i32_e32 v6, 1, v4
	v_ashrrev_i32_e32 v4, 31, v4
	v_lshrrev_b32_e32 v4, 29, v4
	v_add_u32_e32 v4, v6, v4
	v_and_b32_e32 v4, -8, v4
	v_sub_u32_e32 v4, v6, v4
	v_ashrrev_i32_e32 v11, 1, v10
	v_ashrrev_i32_e32 v10, 31, v10
	v_xor_b32_e32 v6, v4, v135
	v_lshrrev_b32_e32 v10, 29, v10
	v_lshlrev_b32_e32 v168, 4, v6
	v_bitop3_b32 v6, v8, v135, 2 bitop3:0x1e
	v_add_u32_e32 v10, v11, v10
	v_lshlrev_b32_e32 v166, 4, v6
	v_bitop3_b32 v6, v5, v135, 2 bitop3:0x1e
	v_and_b32_e32 v10, -8, v10
	v_lshlrev_b32_e32 v167, 4, v6
	v_bitop3_b32 v6, v7, v135, 2 bitop3:0x1e
	v_sub_u32_e32 v10, v11, v10
	v_lshlrev_b32_e32 v161, 4, v6
	v_bitop3_b32 v6, v9, v135, 2 bitop3:0x1e
	v_lshlrev_b32_e32 v163, 4, v6
	v_bitop3_b32 v6, v10, v135, 2 bitop3:0x1e
	v_lshlrev_b32_e32 v159, 4, v6
	v_bitop3_b32 v6, v4, v135, 2 bitop3:0x1e
	v_lshlrev_b32_e32 v160, 4, v6
	v_bitop3_b32 v6, v8, v135, 4 bitop3:0x1e
	v_lshlrev_b32_e32 v153, 4, v6
	v_bitop3_b32 v6, v5, v135, 4 bitop3:0x1e
	v_lshlrev_b32_e32 v154, 4, v6
	v_bitop3_b32 v6, v7, v135, 4 bitop3:0x1e
	v_readfirstlane_b32 s6, v134
	v_lshlrev_b32_e32 v149, 4, v6
	v_bitop3_b32 v6, v9, v135, 4 bitop3:0x1e
	v_bitop3_b32 v5, v5, v135, 6 bitop3:0x1e
	s_lshl_b32 s2, s6, 10
	v_lshlrev_b32_e32 v150, 4, v6
	v_bitop3_b32 v6, v10, v135, 4 bitop3:0x1e
	v_lshlrev_b32_e32 v142, 4, v5
	v_bitop3_b32 v5, v7, v135, 6 bitop3:0x1e
	v_readlane_b32 s6, v254, 28
	s_waitcnt vmcnt(0)
; DI f32x16 zero16() { f32x16 z; for (int i = 0; i < 16; ++i) z[i] = 0.f; return z; }
; template <int BK> DI int swz(int row) { constexpr int CPR = BK / 8; return (row / (16 / CPR)) % CPR; }
;   DI void pre(int grow0, int gcol0, int lane, int w, char* lds) { xpass(0, grow0, gcol0, lane, w, lds); }
;     ...
;   f32x16 acc[2][NTW];
; #pragma unroll
;   for (int a = 0; a < 2; ++a)
; #pragma unroll
;     for (int b = 0; b < NTW; ++b) acc[a][b] = zero16();
;     ...
;   for (int kt = 0; kt < nk; ++kt) {
;     char* cur = lds + (kt & 1) * STG; char* nxt = lds + ((kt + 1) & 1) * STG;
;     const bool more = kt + 1 < nk;
;     const bf16_t* An = Ag + (kt + 1) * BK; const bf16_t* Bn = Bg + (kt + 1) * BK;
;     if (!more) epi.pre(row0 + wm * 64, col0 + wn * (32 * NTW), lane, w, lds);
;     bf16x8 fa[2][2], fb[2][NTW];
; #pragma unroll
;     for (int mt = 0; mt < 2; ++mt) { int row = wm * 64 + mt * 32 + l31; fa[0][mt] = *(const bf16x8*)(cur + row * (BK * 2) + ((hh ^ swz<BK>(row)) << 4)); }
; #pragma unroll
;     for (int nt = 0; nt < NTW; ++nt) { int row = wn * (32 * NTW) + nt * 32 + l31; fb[0][nt] = *(const bf16x8*)(cur + ABYTES + row * (BK * 2) + ((hh ^ swz<BK>(row)) << 4)); }
; #pragma unroll
;     for (int kk = 0; kk < NKK; ++kk) {
;       if (kk + 1 < NKK) {
;         const int ch = (kk + 1) * 2 + hh;
; #pragma unroll
;         for (int mt = 0; mt < 2; ++mt) { int row = wm * 64 + mt * 32 + l31; fa[(kk + 1) & 1][mt] = *(const bf16x8*)(cur + row * (BK * 2) + ((ch ^ swz<BK>(row)) << 4)); }
; #pragma unroll
;         for (int nt = 0; nt < NTW; ++nt) { int row = wn * (32 * NTW) + nt * 32 + l31; fb[(kk + 1) & 1][nt] = *(const bf16x8*)(cur + ABYTES + row * (BK * 2) + ((ch ^ swz<BK>(row)) << 4)); }
	v_lshlrev_b32_e32 v147, 4, v6
	v_bitop3_b32 v6, v4, v135, 4 bitop3:0x1e
	v_lshlrev_b32_e32 v139, 4, v5
	v_bitop3_b32 v5, v9, v135, 6 bitop3:0x1e
	v_readlane_b32 s7, v254, 29
	v_xor_b32_e32 v11, v10, v135
	v_lshlrev_b32_e32 v148, 4, v6
	v_bitop3_b32 v6, v8, v135, 6 bitop3:0x1e
	v_lshlrev_b32_e32 v140, 4, v5
	v_bitop3_b32 v5, v10, v135, 6 bitop3:0x1e
	v_bitop3_b32 v4, v4, v135, 6 bitop3:0x1e
	v_lshl_add_u64 v[132:133], s[6:7], 0, v[2:3]
	v_mov_b32_e32 v2, 0
	v_lshlrev_b32_e32 v157, 4, v11
	v_lshlrev_b32_e32 v141, 4, v6
	v_lshlrev_b32_e32 v137, 4, v5
	v_lshlrev_b32_e32 v138, 4, v4
	s_mov_b64 s[6:7], 0
	s_mov_b32 s3, 0x10000
	v_mov_b32_e32 v3, v2
	v_mov_b32_e32 v4, v2
	v_mov_b32_e32 v5, v2
	v_mov_b32_e32 v6, v2
	v_mov_b32_e32 v7, v2
	v_mov_b32_e32 v8, v2
	v_mov_b32_e32 v9, v2
	v_mov_b32_e32 v10, v2
	v_mov_b32_e32 v11, v2
	v_mov_b32_e32 v12, v2
	v_mov_b32_e32 v13, v2
	v_mov_b32_e32 v14, v2
	v_mov_b32_e32 v15, v2
	v_mov_b32_e32 v16, v2
	v_mov_b32_e32 v17, v2
	v_mov_b32_e32 v18, v2
	v_mov_b32_e32 v19, v2
	v_mov_b32_e32 v20, v2
	v_mov_b32_e32 v21, v2
	v_mov_b32_e32 v22, v2
	v_mov_b32_e32 v23, v2
	v_mov_b32_e32 v24, v2
	v_mov_b32_e32 v25, v2
	v_mov_b32_e32 v26, v2
	v_mov_b32_e32 v27, v2
	v_mov_b32_e32 v28, v2
	v_mov_b32_e32 v29, v2
	v_mov_b32_e32 v30, v2
	v_mov_b32_e32 v31, v2
	v_mov_b32_e32 v32, v2
	v_mov_b32_e32 v33, v2
	v_mov_b32_e32 v34, v2
	v_mov_b32_e32 v35, v2
	v_mov_b32_e32 v36, v2
	v_mov_b32_e32 v37, v2
	v_mov_b32_e32 v38, v2
	v_mov_b32_e32 v39, v2
	v_mov_b32_e32 v40, v2
	v_mov_b32_e32 v41, v2
	v_mov_b32_e32 v42, v2
	v_mov_b32_e32 v43, v2
	v_mov_b32_e32 v44, v2
	v_mov_b32_e32 v45, v2
	v_mov_b32_e32 v46, v2
	v_mov_b32_e32 v47, v2
	v_mov_b32_e32 v48, v2
	v_mov_b32_e32 v49, v2
	v_mov_b32_e32 v50, v2
	v_mov_b32_e32 v51, v2
	v_mov_b32_e32 v52, v2
	v_mov_b32_e32 v53, v2
	v_mov_b32_e32 v54, v2
	v_mov_b32_e32 v55, v2
	v_mov_b32_e32 v56, v2
	v_mov_b32_e32 v57, v2
	v_mov_b32_e32 v58, v2
	v_mov_b32_e32 v59, v2
	v_mov_b32_e32 v60, v2
	v_mov_b32_e32 v61, v2
	v_mov_b32_e32 v62, v2
	v_mov_b32_e32 v63, v2
	v_mov_b32_e32 v64, v2
	v_mov_b32_e32 v65, v2
	v_mov_b32_e32 v66, v2
	v_mov_b32_e32 v67, v2
	v_mov_b32_e32 v68, v2
	v_mov_b32_e32 v69, v2
	v_mov_b32_e32 v70, v2
	v_mov_b32_e32 v71, v2
	v_mov_b32_e32 v72, v2
	v_mov_b32_e32 v73, v2
	v_mov_b32_e32 v74, v2
	v_mov_b32_e32 v75, v2
	v_mov_b32_e32 v76, v2
	v_mov_b32_e32 v77, v2
	v_mov_b32_e32 v78, v2
	v_mov_b32_e32 v79, v2
	v_mov_b32_e32 v80, v2
	v_mov_b32_e32 v81, v2
	v_mov_b32_e32 v82, v2
	v_mov_b32_e32 v83, v2
	v_mov_b32_e32 v84, v2
	v_mov_b32_e32 v85, v2
	v_mov_b32_e32 v86, v2
	v_mov_b32_e32 v87, v2
	v_mov_b32_e32 v88, v2
	v_mov_b32_e32 v89, v2
	v_mov_b32_e32 v90, v2
	v_mov_b32_e32 v91, v2
	v_mov_b32_e32 v92, v2
	v_mov_b32_e32 v93, v2
	v_mov_b32_e32 v94, v2
	v_mov_b32_e32 v95, v2
	v_mov_b32_e32 v96, v2
	v_mov_b32_e32 v97, v2
	v_mov_b32_e32 v98, v2
	v_mov_b32_e32 v99, v2
	v_mov_b32_e32 v100, v2
	v_mov_b32_e32 v101, v2
	v_mov_b32_e32 v102, v2
	v_mov_b32_e32 v103, v2
	v_mov_b32_e32 v104, v2
	v_mov_b32_e32 v105, v2
	v_mov_b32_e32 v106, v2
	v_mov_b32_e32 v107, v2
	v_mov_b32_e32 v108, v2
	v_mov_b32_e32 v109, v2
	v_mov_b32_e32 v110, v2
	v_mov_b32_e32 v111, v2
	v_mov_b32_e32 v112, v2
	v_mov_b32_e32 v113, v2
	v_mov_b32_e32 v114, v2
	v_mov_b32_e32 v115, v2
	v_mov_b32_e32 v116, v2
	v_mov_b32_e32 v117, v2
	v_mov_b32_e32 v118, v2
	v_mov_b32_e32 v119, v2
	v_mov_b32_e32 v120, v2
	v_mov_b32_e32 v121, v2
	v_mov_b32_e32 v122, v2
	v_mov_b32_e32 v123, v2
	v_mov_b32_e32 v124, v2
	v_mov_b32_e32 v125, v2
	v_mov_b32_e32 v126, v2
	v_mov_b32_e32 v127, v2
	v_mov_b32_e32 v128, v2
	v_mov_b32_e32 v129, v2
	s_waitcnt vmcnt(0) lgkmcnt(0)
	s_barrier
	v_add_u32_e32 v170, v136, v143
	v_add_u32_e32 v174, v144, v146
	ds_read_b128 v[170:173], v170
	v_add_u32_e32 v178, v145, v151
	ds_read_b128 v[174:177], v174
	v_add_u32_e32 v182, v152, v156
	ds_read_b128 v[178:181], v178 offset:32768
	v_add_u32_e32 v186, v155, v157
	ds_read_b128 v[182:185], v182 offset:32768
	v_add_u32_e32 v190, v158, v168
	ds_read_b128 v[186:189], v186 offset:32768
	ds_read_b128 v[190:193], v190 offset:32768
.LBB0_173:
	s_and_b32 s30, s3, 0x10000
	s_xor_b32 s100, s30, 0x10000
	s_add_i32 s31, s30, s2
	v_add3_u32 v194, s100, v136, v166
	v_add3_u32 v198, s100, v144, v167
	ds_read_b128 v[194:197], v194
	v_add3_u32 v202, s100, v145, v161
	ds_read_b128 v[198:201], v198
	v_add3_u32 v206, s100, v152, v163
	ds_read_b128 v[202:205], v202 offset:32768
	v_add3_u32 v210, s100, v155, v159
	ds_read_b128 v[206:209], v206 offset:32768
	v_add3_u32 v226, s100, v158, v160
	ds_read_b128 v[210:213], v210 offset:32768
	ds_read_b128 v[226:229], v226 offset:32768
	v_lshl_add_u64 v[214:215], v[132:133], 0, s[6:7]
	v_lshl_add_u64 v[230:231], v[130:131], 0, s[6:7]
	s_mov_b32 m0, s31
	v_lshl_add_u64 v[232:233], v[214:215], 0, s[28:29]
	s_setprio 1
	s_waitcnt lgkmcnt(6)
; DI f32x16 mfma(bf16x8 a, bf16x8 b, f32x16 c) { return __builtin_amdgcn_mfma_f32_32x32x16_bf16(a, b, c, 0, 0, 0); }
; template <int BK> DI int swz(int row) { constexpr int CPR = BK / 8; return (row / (16 / CPR)) % CPR; }
; DI void wait_vm0() { asm volatile("s_waitcnt vmcnt(0)" ::: "memory"); }
;   DI void pre(int grow0, int gcol0, int lane, int w, char* lds) { xpass(0, grow0, gcol0, lane, w, lds); }
;     ...
;   for (int kt = 0; kt < nk; ++kt) {
;     char* cur = lds + (kt & 1) * STG; char* nxt = lds + ((kt + 1) & 1) * STG;
;     const bool more = kt + 1 < nk;
;     const bf16_t* An = Ag + (kt + 1) * BK; const bf16_t* Bn = Bg + (kt + 1) * BK;
;     if (!more) epi.pre(row0 + wm * 64, col0 + wn * (32 * NTW), lane, w, lds);
;     bf16x8 fa[2][2], fb[2][NTW];
; #pragma unroll
;     for (int mt = 0; mt < 2; ++mt) { int row = wm * 64 + mt * 32 + l31; fa[0][mt] = *(const bf16x8*)(cur + row * (BK * 2) + ((hh ^ swz<BK>(row)) << 4)); }
; #pragma unroll
;     for (int nt = 0; nt < NTW; ++nt) { int row = wn * (32 * NTW) + nt * 32 + l31; fb[0][nt] = *(const bf16x8*)(cur + ABYTES + row * (BK * 2) + ((hh ^ swz<BK>(row)) << 4)); }
; #pragma unroll
;     for (int kk = 0; kk < NKK; ++kk) {
;       if (kk + 1 < NKK) {
;         const int ch = (kk + 1) * 2 + hh;
; #pragma unroll
;         for (int mt = 0; mt < 2; ++mt) { int row = wm * 64 + mt * 32 + l31; fa[(kk + 1) & 1][mt] = *(const bf16x8*)(cur + row * (BK * 2) + ((ch ^ swz<BK>(row)) << 4)); }
; #pragma unroll
;         for (int nt = 0; nt < NTW; ++nt) { int row = wn * (32 * NTW) + nt * 32 + l31; fb[(kk + 1) & 1][nt] = *(const bf16x8*)(cur + ABYTES + row * (BK * 2) + ((ch ^ swz<BK>(row)) << 4)); }
;       }
;       if (more) {
; #pragma unroll
;         for (int q = 0; q < PPK; ++q) {
;           const int pi = kk * PPK + q;
;           if (pi < NPA) stage_piece<BM, BK>(An, lda, nxt, tid, pi, wv);
;           else if (pi < NP) stage_piece<BN, BK>(Bn, ldb, nxt + ABYTES, tid, pi - NPA, wv);
;         }
;       }
;       __builtin_amdgcn_s_setprio(1);
; #pragma unroll
;       for (int mt = 0; mt < 2; ++mt)
; #pragma unroll
;         for (int nt = 0; nt < NTW; ++nt) acc[mt][nt] = mfma(fa[kk & 1][mt], fb[kk & 1][nt], acc[mt][nt]);
;       __builtin_amdgcn_s_setprio(0);
;       __builtin_amdgcn_sched_barrier(0);
;     }
;     wait_vm0();
;     __syncthreads();
;   }
	v_mfma_f32_32x32x16_bf16 v[114:129], v[170:173], v[178:181], v[114:129]
	global_load_lds_dwordx4 v[232:233], off
	v_lshl_add_u64 v[232:233], v[214:215], 0, s[24:25]
	s_add_i32 m0, s31, 0x2000
	v_mfma_f32_32x32x16_bf16 v[98:113], v[170:173], v[182:185], v[98:113]
	global_load_lds_dwordx4 v[232:233], off
	v_lshl_add_u64 v[232:233], v[214:215], 0, s[26:27]
	s_add_i32 m0, s31, 0x4000
	v_mfma_f32_32x32x16_bf16 v[82:97], v[170:173], v[186:189], v[82:97]
	global_load_lds_dwordx4 v[232:233], off
	v_lshl_add_u64 v[232:233], v[214:215], 0, s[38:39]
	s_add_i32 m0, s31, 0x6000
	v_mfma_f32_32x32x16_bf16 v[66:81], v[170:173], v[190:193], v[66:81]
	global_load_lds_dwordx4 v[232:233], off
	v_lshl_add_u64 v[232:233], v[230:231], 0, s[28:29]
	s_add_i32 m0, s31, 0x8000
	v_mfma_f32_32x32x16_bf16 v[50:65], v[174:177], v[178:181], v[50:65]
	global_load_lds_dwordx4 v[232:233], off
	v_lshl_add_u64 v[232:233], v[230:231], 0, s[24:25]
	s_add_i32 m0, s31, 0xa000
	v_mfma_f32_32x32x16_bf16 v[34:49], v[174:177], v[182:185], v[34:49]
	global_load_lds_dwordx4 v[232:233], off
	v_lshl_add_u64 v[232:233], v[230:231], 0, s[26:27]
	s_add_i32 m0, s31, 0xc000
	v_mfma_f32_32x32x16_bf16 v[18:33], v[174:177], v[186:189], v[18:33]
	global_load_lds_dwordx4 v[232:233], off
	v_lshl_add_u64 v[232:233], v[230:231], 0, s[38:39]
	s_add_i32 m0, s31, 0xe000
	v_mfma_f32_32x32x16_bf16 v[2:17], v[174:177], v[190:193], v[2:17]
	global_load_lds_dwordx4 v[232:233], off
	s_setprio 0
	v_add3_u32 v170, s100, v136, v153
	v_add3_u32 v174, s100, v144, v154
	ds_read_b128 v[170:173], v170
	v_add3_u32 v178, s100, v145, v149
	ds_read_b128 v[174:177], v174
	v_add3_u32 v182, s100, v152, v150
	ds_read_b128 v[178:181], v178 offset:32768
	v_add3_u32 v186, s100, v155, v147
	ds_read_b128 v[182:185], v182 offset:32768
	v_add3_u32 v190, s100, v158, v148
	ds_read_b128 v[186:189], v186 offset:32768
	ds_read_b128 v[190:193], v190 offset:32768
	s_setprio 1
	s_waitcnt lgkmcnt(6)
	v_mfma_f32_32x32x16_bf16 v[114:129], v[194:197], v[202:205], v[114:129]
	v_mfma_f32_32x32x16_bf16 v[98:113], v[194:197], v[206:209], v[98:113]
	v_mfma_f32_32x32x16_bf16 v[82:97], v[194:197], v[210:213], v[82:97]
	v_mfma_f32_32x32x16_bf16 v[66:81], v[194:197], v[226:229], v[66:81]
	v_mfma_f32_32x32x16_bf16 v[50:65], v[198:201], v[202:205], v[50:65]
	v_mfma_f32_32x32x16_bf16 v[34:49], v[198:201], v[206:209], v[34:49]
	v_mfma_f32_32x32x16_bf16 v[18:33], v[198:201], v[210:213], v[18:33]
	v_mfma_f32_32x32x16_bf16 v[2:17], v[198:201], v[226:229], v[2:17]
	s_setprio 0
	v_add3_u32 v194, s100, v136, v141
	v_add3_u32 v198, s100, v144, v142
	ds_read_b128 v[194:197], v194
	v_add3_u32 v202, s100, v145, v139
	ds_read_b128 v[198:201], v198
	v_add3_u32 v206, s100, v152, v140
	ds_read_b128 v[202:205], v202 offset:32768
	v_add3_u32 v210, s100, v155, v137
	ds_read_b128 v[206:209], v206 offset:32768
	v_add3_u32 v226, s100, v158, v138
	ds_read_b128 v[210:213], v210 offset:32768
	ds_read_b128 v[226:229], v226 offset:32768
	s_setprio 1
	s_waitcnt lgkmcnt(6)
	v_mfma_f32_32x32x16_bf16 v[114:129], v[170:173], v[178:181], v[114:129]
	v_mfma_f32_32x32x16_bf16 v[98:113], v[170:173], v[182:185], v[98:113]
	v_mfma_f32_32x32x16_bf16 v[82:97], v[170:173], v[186:189], v[82:97]
	v_mfma_f32_32x32x16_bf16 v[66:81], v[170:173], v[190:193], v[66:81]
	v_mfma_f32_32x32x16_bf16 v[50:65], v[174:177], v[178:181], v[50:65]
	v_mfma_f32_32x32x16_bf16 v[34:49], v[174:177], v[182:185], v[34:49]
	v_mfma_f32_32x32x16_bf16 v[18:33], v[174:177], v[186:189], v[18:33]
	v_mfma_f32_32x32x16_bf16 v[2:17], v[174:177], v[190:193], v[2:17]
	s_setprio 0
	s_add_u32 s6, s6, 0x80
	s_addc_u32 s7, s7, 0
	s_add_i32 s3, s3, 0x10000
	s_waitcnt vmcnt(0) lgkmcnt(0)
	s_barrier
	v_add3_u32 v170, s30, v136, v143
	v_add3_u32 v174, s30, v144, v146
	ds_read_b128 v[170:173], v170
	v_add3_u32 v178, s30, v145, v151
	ds_read_b128 v[174:177], v174
	v_add3_u32 v182, s30, v152, v156
	ds_read_b128 v[178:181], v178 offset:32768
	v_add3_u32 v186, s30, v155, v157
	ds_read_b128 v[182:185], v182 offset:32768
	v_add3_u32 v190, s30, v158, v168
	ds_read_b128 v[186:189], v186 offset:32768
	ds_read_b128 v[190:193], v190 offset:32768
	s_setprio 1
	v_mfma_f32_32x32x16_bf16 v[114:129], v[194:197], v[202:205], v[114:129]
	v_mfma_f32_32x32x16_bf16 v[98:113], v[194:197], v[206:209], v[98:113]
	v_mfma_f32_32x32x16_bf16 v[82:97], v[194:197], v[210:213], v[82:97]
	v_mfma_f32_32x32x16_bf16 v[66:81], v[194:197], v[226:229], v[66:81]
	v_mfma_f32_32x32x16_bf16 v[50:65], v[198:201], v[202:205], v[50:65]
	v_mfma_f32_32x32x16_bf16 v[34:49], v[198:201], v[206:209], v[34:49]
	v_mfma_f32_32x32x16_bf16 v[18:33], v[198:201], v[210:213], v[18:33]
	v_mfma_f32_32x32x16_bf16 v[2:17], v[198:201], v[226:229], v[2:17]
	s_setprio 0
	s_cmpk_lg_i32 s6, 0x780
	s_cbranch_scc1 .LBB0_173
; DI f32x16 mfma(bf16x8 a, bf16x8 b, f32x16 c) { return __builtin_amdgcn_mfma_f32_32x32x16_bf16(a, b, c, 0, 0, 0); }
;     ...
;     if (!more) epi.pre(row0 + wm * 64, col0 + wn * (32 * NTW), lane, w, lds);
;     bf16x8 fa[2][2], fb[2][NTW];
; #pragma unroll
;     for (int mt = 0; mt < 2; ++mt) { int row = wm * 64 + mt * 32 + l31; fa[0][mt] = *(const bf16x8*)(cur + row * (BK * 2) + ((hh ^ swz<BK>(row)) << 4)); }
; #pragma unroll
;     for (int nt = 0; nt < NTW; ++nt) { int row = wn * (32 * NTW) + nt * 32 + l31; fb[0][nt] = *(const bf16x8*)(cur + ABYTES + row * (BK * 2) + ((hh ^ swz<BK>(row)) << 4)); }
; #pragma unroll
;     for (int kk = 0; kk < NKK; ++kk) {
;       if (kk + 1 < NKK) {
;         const int ch = (kk + 1) * 2 + hh;
; #pragma unroll
;         for (int mt = 0; mt < 2; ++mt) { int row = wm * 64 + mt * 32 + l31; fa[(kk + 1) & 1][mt] = *(const bf16x8*)(cur + row * (BK * 2) + ((ch ^ swz<BK>(row)) << 4)); }
; #pragma unroll
;         for (int nt = 0; nt < NTW; ++nt) { int row = wn * (32 * NTW) + nt * 32 + l31; fb[(kk + 1) & 1][nt] = *(const bf16x8*)(cur + ABYTES + row * (BK * 2) + ((ch ^ swz<BK>(row)) << 4)); }
;       }
;       if (more) {
; #pragma unroll
;         for (int q = 0; q < PPK; ++q) {
;           const int pi = kk * PPK + q;
;           if (pi < NPA) stage_piece<BM, BK>(An, lda, nxt, tid, pi, wv);
;           else if (pi < NP) stage_piece<BN, BK>(Bn, ldb, nxt + ABYTES, tid, pi - NPA, wv);
;         }
;       }
;       __builtin_amdgcn_s_setprio(1);
; #pragma unroll
;       for (int mt = 0; mt < 2; ++mt)
; #pragma unroll
;         for (int nt = 0; nt < NTW; ++nt) acc[mt][nt] = mfma(fa[kk & 1][mt], fb[kk & 1][nt], acc[mt][nt]);
;       __builtin_amdgcn_s_setprio(0);
;       __builtin_amdgcn_sched_barrier(0);
;     }
;   DI void xpass(int ps, int grow0, int gcol0, int lane, int w, char* lds) const {
;     char* xs = lds + (ps & 1) * 65536 + __builtin_amdgcn_readfirstlane(w) * 8192;
;     const float* xsrc = Xin + (size_t)(grow0 + (ps >> 1) * 32 + (ps & 1) * 16 + (lane >> 5)) * D_ + gcol0 + (lane & 31) * 4;
; #pragma unroll
;     for (int pc = 0; pc < 8; ++pc)
;       __builtin_amdgcn_global_load_lds((const unsigned*)(xsrc + (size_t)(2 * pc) * D_), (__attribute__((address_space(3))) unsigned*)(xs + pc * 1024), 16, 0, 0);
;   }
;   DI void pre(int grow0, int gcol0, int lane, int w, char* lds) { xpass(0, grow0, gcol0, lane, w, lds); }
	s_waitcnt lgkmcnt(0)
	v_readlane_b32 s3, v253, 9
	v_readlane_b32 s6, v253, 27
	v_readfirstlane_b32 s2, v134
	v_or_b32_e32 v130, s3, v135
	v_add_u32_e32 v130, v130, v169
	v_ashrrev_i32_e32 v131, 31, v130
	v_lshlrev_b64 v[130:131], 12, v[130:131]
	v_add_u32_e32 v132, s6, v164
	v_ashrrev_i32_e32 v133, 31, v132
	v_lshl_add_u64 v[130:131], s[10:11], 0, v[130:131]
	v_lshlrev_b32_e32 v0, 4, v0
	s_lshl_b32 s2, s2, 13
	v_lshl_add_u64 v[130:131], v[132:133], 2, v[130:131]
	v_and_b32_e32 v132, 0x1f0, v0
	v_mov_b32_e32 v133, v1
	v_lshl_add_u64 v[130:131], v[130:131], 0, v[132:133]
	s_mov_b32 m0, s2
	s_mov_b64 s[34:35], 0x2000
	global_load_lds_dwordx4 v[130:131], off
	v_lshl_add_u64 v[132:133], v[130:131], 0, s[34:35]
	s_or_b32 m0, s2, 0x400
	s_mov_b64 s[36:37], 0x4000
	global_load_lds_dwordx4 v[132:133], off
	v_lshl_add_u64 v[132:133], v[130:131], 0, s[36:37]
	s_or_b32 m0, s2, 0x800
	s_mov_b64 s[40:41], 0x6000
	global_load_lds_dwordx4 v[132:133], off
	v_lshl_add_u64 v[132:133], v[130:131], 0, s[40:41]
	s_or_b32 m0, s2, 0xc00
	s_mov_b64 s[44:45], 0x8000
	global_load_lds_dwordx4 v[132:133], off
	v_lshl_add_u64 v[132:133], v[130:131], 0, s[44:45]
	s_or_b32 m0, s2, 0x1000
	s_mov_b64 s[46:47], 0xa000
	global_load_lds_dwordx4 v[132:133], off
	v_lshl_add_u64 v[132:133], v[130:131], 0, s[46:47]
	s_or_b32 m0, s2, 0x1400
	s_mov_b64 s[52:53], 0xc000
	global_load_lds_dwordx4 v[132:133], off
	v_lshl_add_u64 v[132:133], v[130:131], 0, s[52:53]
	s_or_b32 m0, s2, 0x1800
	s_mov_b64 s[54:55], 0xe000
	global_load_lds_dwordx4 v[132:133], off
	v_lshl_add_u64 v[130:131], v[130:131], 0, s[54:55]
	s_or_b32 m0, s2, 0x1c00
	v_add_u32_e32 v0, s30, v136
	global_load_lds_dwordx4 v[130:131], off
	v_add_u32_e32 v134, s30, v144
	v_add_u32_e32 v130, v0, v143
	v_add_u32_e32 v135, v134, v146
	s_waitcnt vmcnt(0)
	ds_read_b128 v[130:133], v130
	ds_read_b128 v[170:173], v135
	v_add_u32_e32 v135, s30, v145
	v_add_u32_e32 v136, v135, v151
	v_add_u32_e32 v143, s30, v152
	v_add_u32_e32 v144, v143, v156
	ds_read_b128 v[174:177], v136 offset:32768
	ds_read_b128 v[178:181], v144 offset:32768
	v_add_u32_e32 v136, s30, v155
	v_add_u32_e32 v144, v136, v157
	v_add_u32_e32 v164, s30, v158
	v_add_u32_e32 v145, v164, v168
	ds_read_b128 v[182:185], v144 offset:32768
	ds_read_b128 v[186:189], v145 offset:32768
	v_add_u32_e32 v144, v0, v166
	v_add_u32_e32 v145, v134, v167
	ds_read_b128 v[166:169], v144
	ds_read_b128 v[190:193], v145
	v_add_u32_e32 v144, v135, v161
	v_add_u32_e32 v145, v143, v163
	ds_read_b128 v[194:197], v144 offset:32768
	ds_read_b128 v[198:201], v145 offset:32768
	v_add_u32_e32 v144, v136, v159
	v_add_u32_e32 v145, v164, v160
	ds_read_b128 v[156:159], v144 offset:32768
	ds_read_b128 v[202:205], v145 offset:32768
	v_readlane_b32 s7, v253, 28
	s_setprio 1
	s_waitcnt lgkmcnt(0)
	v_mfma_f32_32x32x16_bf16 v[114:129], v[130:133], v[174:177], v[114:129]
	v_mfma_f32_32x32x16_bf16 v[98:113], v[130:133], v[178:181], v[98:113]
	v_mfma_f32_32x32x16_bf16 v[82:97], v[130:133], v[182:185], v[82:97]
	v_mfma_f32_32x32x16_bf16 v[66:81], v[130:133], v[186:189], v[66:81]
	v_mfma_f32_32x32x16_bf16 v[50:65], v[170:173], v[174:177], v[50:65]
	v_mfma_f32_32x32x16_bf16 v[34:49], v[170:173], v[178:181], v[34:49]
	v_mfma_f32_32x32x16_bf16 v[18:33], v[170:173], v[182:185], v[18:33]
	v_mfma_f32_32x32x16_bf16 v[2:17], v[170:173], v[186:189], v[2:17]
	s_setprio 0
	v_add_u32_e32 v130, v0, v153
	v_add_u32_e32 v144, v134, v154
	ds_read_b128 v[130:133], v130
	ds_read_b128 v[152:155], v144
	v_add_u32_e32 v144, v135, v149
	v_add_u32_e32 v145, v143, v150
	ds_read_b128 v[170:173], v144 offset:32768
	ds_read_b128 v[174:177], v145 offset:32768
	v_add_u32_e32 v144, v136, v147
	v_add_u32_e32 v148, v164, v148
	ds_read_b128 v[144:147], v144 offset:32768
	ds_read_b128 v[148:151], v148 offset:32768
	s_setprio 1
	v_mfma_f32_32x32x16_bf16 v[114:129], v[166:169], v[194:197], v[114:129]
	v_mfma_f32_32x32x16_bf16 v[98:113], v[166:169], v[198:201], v[98:113]
	v_mfma_f32_32x32x16_bf16 v[82:97], v[166:169], v[156:159], v[82:97]
	v_mfma_f32_32x32x16_bf16 v[66:81], v[166:169], v[202:205], v[66:81]
	v_mfma_f32_32x32x16_bf16 v[50:65], v[190:193], v[194:197], v[50:65]
	v_mfma_f32_32x32x16_bf16 v[34:49], v[190:193], v[198:201], v[34:49]
	v_mfma_f32_32x32x16_bf16 v[18:33], v[190:193], v[156:159], v[18:33]
	v_mfma_f32_32x32x16_bf16 v[2:17], v[190:193], v[202:205], v[2:17]
	s_setprio 0
	v_add_u32_e32 v0, v0, v141
	v_add_u32_e32 v134, v134, v142
	ds_read_b128 v[156:159], v0
	ds_read_b128 v[166:169], v134
	v_add_u32_e32 v0, v135, v139
	v_add_u32_e32 v134, v143, v140
	ds_read_b128 v[140:143], v0 offset:32768
	ds_read_b128 v[178:181], v134 offset:32768
	v_add_u32_e32 v0, v136, v137
	v_add_u32_e32 v138, v164, v138
	ds_read_b128 v[134:137], v0 offset:32768
	ds_read_b128 v[182:185], v138 offset:32768
	s_setprio 1
	s_waitcnt lgkmcnt(9)
	v_mfma_f32_32x32x16_bf16 v[114:129], v[130:133], v[170:173], v[114:129]
	s_waitcnt lgkmcnt(8)
	v_mfma_f32_32x32x16_bf16 v[98:113], v[130:133], v[174:177], v[98:113]
	s_waitcnt lgkmcnt(7)
	v_mfma_f32_32x32x16_bf16 v[82:97], v[130:133], v[144:147], v[82:97]
	s_waitcnt lgkmcnt(6)
	v_mfma_f32_32x32x16_bf16 v[66:81], v[130:133], v[148:151], v[66:81]
	v_mfma_f32_32x32x16_bf16 v[50:65], v[152:155], v[170:173], v[50:65]
	v_mfma_f32_32x32x16_bf16 v[34:49], v[152:155], v[174:177], v[34:49]
	v_mfma_f32_32x32x16_bf16 v[18:33], v[152:155], v[144:147], v[18:33]
	v_mfma_f32_32x32x16_bf16 v[2:17], v[152:155], v[148:151], v[2:17]
	s_setprio 0
	s_setprio 1
	s_waitcnt lgkmcnt(3)
	v_mfma_f32_32x32x16_bf16 v[114:129], v[156:159], v[140:143], v[114:129]
	s_waitcnt lgkmcnt(2)
	v_mfma_f32_32x32x16_bf16 v[98:113], v[156:159], v[178:181], v[98:113]
	s_waitcnt lgkmcnt(1)
	v_mfma_f32_32x32x16_bf16 v[82:97], v[156:159], v[134:137], v[82:97]
	s_waitcnt lgkmcnt(0)
	v_mfma_f32_32x32x16_bf16 v[66:81], v[156:159], v[182:185], v[66:81]
	v_mfma_f32_32x32x16_bf16 v[50:65], v[166:169], v[140:143], v[50:65]
	v_mfma_f32_32x32x16_bf16 v[34:49], v[166:169], v[178:181], v[34:49]
	v_mfma_f32_32x32x16_bf16 v[18:33], v[166:169], v[134:137], v[18:33]
	v_mfma_f32_32x32x16_bf16 v[2:17], v[166:169], v[182:185], v[2:17]
	s_setprio 0
	v_mov_b32_e32 v164, v216
	s_waitcnt vmcnt(0)
	s_barrier
; template <int CTRL> DI float dpp_f(float v) { return __int_as_float(__builtin_amdgcn_update_dpp(0, __float_as_int(v), CTRL, 0xF, 0xF, true)); }
; DI float row16_sum(float v) {
;   v += dpp_f<0xB1>(v);
;   v += dpp_f<0x4E>(v);
;   v += dpp_f<0x141>(v);
;   v += dpp_f<0x140>(v);
;   return v;
; }
;   DI void xpass(int ps, int grow0, int gcol0, int lane, int w, char* lds) const {
;     char* xs = lds + (ps & 1) * 65536 + __builtin_amdgcn_readfirstlane(w) * 8192;
;     const float* xsrc = Xin + (size_t)(grow0 + (ps >> 1) * 32 + (ps & 1) * 16 + (lane >> 5)) * D_ + gcol0 + (lane & 31) * 4;
; #pragma unroll
;     for (int pc = 0; pc < 8; ++pc)
;       __builtin_amdgcn_global_load_lds((const unsigned*)(xsrc + (size_t)(2 * pc) * D_), (__attribute__((address_space(3))) unsigned*)(xs + pc * 1024), 16, 0, 0);
;   }
;   DI void operator()(f32x16 (&acc)[2][4], int grow0, int gcol0, int lane, int w, char* lds) {
;     ...
;     for (int ps = 0; ps < 4; ++ps) {
;       const int mt = ps >> 1;
;       if (ps + 1 < 4) {
;         if (ps >= 1) asm volatile("s_waitcnt lgkmcnt(0)" ::: "memory");
;         xpass(ps + 1, grow0, gcol0, lane, w, lds);
;         if (ps >= 1) asm volatile("s_waitcnt vmcnt(8)" ::: "memory");
;       } else asm volatile("s_waitcnt vmcnt(0)" ::: "memory");
;       const char* xs = lds + (ps & 1) * 65536 + w * 8192;
; #pragma unroll
;       for (int qq = 0; qq < 2; ++qq)
; #pragma unroll
;         for (int e = 0; e < 4; ++e) {
;           const int i = 4 * (2 * (ps & 1) + qq) + e;
;           const float* xr = (const float*)(xs + (8 * qq + 4 * hh + e) * 512) + l31;
;           float s1 = 0.f, s2 = 0.f;
; #pragma unroll
;           for (int nt = 0; nt < 4; ++nt) {
;             float v = (acc[mt][nt][i] + bia[nt]) * csc[nt];
;             float z = ALPHA * xr[nt * 32] + hs * v;
;             acc[mt][nt][i] = z; s1 += z; s2 += z * z;
;           }
;           s1 = row16_sum(s1); s2 = row16_sum(s2);
;           if ((lane & 15) == 0) { f32x2 sv = {s1, s2}; *(f32x2*)(redw + (mt * 32 + (i & 3) + 8 * (i >> 2)) * 2) = sv; }
	v_mov_b32_e32 v133, v1
	v_ashrrev_i32_e32 v158, 6, v164
	v_lshrrev_b32_e32 v0, 30, v158
	v_add_u32_e32 v0, v158, v0
	v_ashrrev_i32_e32 v134, 2, v0
	v_mul_i32_i24_e32 v0, 4, v134
	v_sub_u32_e32 v0, v158, v0
	v_lshlrev_b32_e32 v135, 6, v0
	v_add_u32_e32 v163, s3, v135
	v_bfe_u32 v0, v164, 5, 1
	v_or_b32_e32 v159, v163, v0
	v_or_b32_e32 v130, 16, v159
	v_lshlrev_b32_e32 v200, 2, v164
	v_ashrrev_i32_e32 v131, 31, v130
	v_lshl_add_u32 v184, v134, 7, s6
	v_and_b32_e32 v0, 0x7c, v200
	v_lshlrev_b64 v[130:131], 12, v[130:131]
	v_ashrrev_i32_e32 v185, 31, v184
	v_readfirstlane_b32 s2, v158
	v_lshl_add_u64 v[130:131], s[10:11], 0, v[130:131]
	v_lshlrev_b32_e32 v0, 2, v0
	s_lshl_b32 s2, s2, 13
	v_lshl_add_u64 v[130:131], v[184:185], 2, v[130:131]
	v_mov_b32_e32 v132, v0
	s_add_i32 m0, s2, 0x10000
	v_lshl_add_u64 v[130:131], v[130:131], 0, v[132:133]
	global_load_lds_dwordx4 v[130:131], off
	v_lshl_add_u64 v[132:133], v[130:131], 0, s[34:35]
	s_add_i32 m0, s2, 0x10400
	v_and_b32_e32 v210, 0xc0, v135
	global_load_lds_dwordx4 v[132:133], off
	v_lshl_add_u64 v[132:133], v[130:131], 0, s[36:37]
	s_add_i32 m0, s2, 0x10800
	v_mov_b32_e32 v136, v114
	global_load_lds_dwordx4 v[132:133], off
	v_lshl_add_u64 v[132:133], v[130:131], 0, s[40:41]
	s_add_i32 m0, s2, 0x10c00
	v_mov_b32_e32 v137, v82
	global_load_lds_dwordx4 v[132:133], off
	v_lshl_add_u64 v[132:133], v[130:131], 0, s[44:45]
	s_add_i32 m0, s2, 0x11000
	v_mov_b32_e32 v140, v98
	global_load_lds_dwordx4 v[132:133], off
	v_lshl_add_u64 v[132:133], v[130:131], 0, s[46:47]
	s_add_i32 m0, s2, 0x11400
	v_mov_b32_e32 v141, v82
	global_load_lds_dwordx4 v[132:133], off
	v_lshl_add_u64 v[132:133], v[130:131], 0, s[52:53]
	s_add_i32 m0, s2, 0x11800
	v_lshl_add_u64 v[130:131], v[130:131], 0, s[54:55]
	global_load_lds_dwordx4 v[132:133], off
	s_add_i32 m0, s2, 0x11c00
	v_bfe_u32 v132, v164, 4, 1
	global_load_lds_dwordx4 v[130:131], off
	v_and_b32_e32 v130, 31, v164
	v_lshlrev_b32_e32 v131, 1, v134
	v_bfe_u32 v134, v164, 3, 3
	v_and_or_b32 v131, v131, 2, v132
	v_and_b32_e32 v132, 4, v134
	v_lshlrev_b32_e32 v130, 2, v130
	v_lshl_or_b32 v138, v158, 13, v130
	v_lshlrev_b32_e32 v154, 9, v132
	v_or_b32_e32 v133, v210, v132
	v_and_b32_e32 v130, 15, v164
	v_or_b32_e32 v132, v138, v154
	v_lshlrev_b32_e32 v135, 3, v133
	v_lshl_or_b32 v139, v131, 11, v221
	v_cmp_eq_u32_e32 vcc, 0, v130
	s_waitcnt vmcnt(8)
	ds_read2_b32 v[130:131], v132 offset1:32
	ds_read2_b32 v[132:133], v132 offset0:64 offset1:96
	v_pk_add_f32 v[136:137], v[136:137], 0 op_sel_hi:[1,0]
	v_pk_add_f32 v[140:141], v[140:141], 0 op_sel_hi:[1,0]
	s_mov_b32 s2, s67
	s_waitcnt lgkmcnt(0)
	v_mov_b32_e32 v142, v130
	v_mov_b32_e32 v143, v132
	v_mov_b32_e32 v130, v131
	v_mov_b32_e32 v131, v132
	v_pk_fma_f32 v[186:187], v[142:143], s[2:3], v[136:137] op_sel_hi:[1,0,1]
	v_pk_fma_f32 v[188:189], v[130:131], s[2:3], v[140:141] op_sel_hi:[1,0,1]
	v_pk_mul_f32 v[144:145], v[142:143], s[2:3] op_sel_hi:[1,0]
	v_pk_mul_f32 v[142:143], v[186:187], v[186:187]
	v_pk_mul_f32 v[130:131], v[188:189], v[188:189]
	v_pk_mov_b32 v[136:137], v[136:137], v[142:143] op_sel:[1,0]
	v_pk_mov_b32 v[130:131], v[144:145], v[130:131] op_sel:[1,0]
	v_add_f32_e32 v180, 0, v66
	v_pk_add_f32 v[130:131], v[136:137], v[130:131]
	v_pk_add_f32 v[136:137], v[186:187], v[188:189]
	v_pk_mul_f32 v[140:141], v[186:187], v[188:189]
	v_fmac_f32_e32 v180, 0x3fd744fd, v133
	v_mov_b32_e32 v137, v141
	v_pk_add_f32 v[130:131], v[136:137], v[130:131]
	v_mul_f32_e32 v181, v180, v180
	v_pk_add_f32 v[130:131], v[130:131], v[180:181]
	v_add_u32_e32 v181, v139, v135
	s_nop 0
	v_mov_b32_dpp v132, v130 quad_perm:[1,0,3,2] row_mask:0xf bank_mask:0xf bound_ctrl:1
	v_mov_b32_dpp v133, v131 quad_perm:[1,0,3,2] row_mask:0xf bank_mask:0xf bound_ctrl:1
	v_pk_add_f32 v[130:131], v[130:131], v[132:133]
	s_nop 1
	v_mov_b32_dpp v132, v130 quad_perm:[2,3,0,1] row_mask:0xf bank_mask:0xf bound_ctrl:1
	v_mov_b32_dpp v133, v131 quad_perm:[2,3,0,1] row_mask:0xf bank_mask:0xf bound_ctrl:1
	v_pk_add_f32 v[130:131], v[130:131], v[132:133]
	s_nop 1
	v_mov_b32_dpp v132, v130 row_half_mirror row_mask:0xf bank_mask:0xf bound_ctrl:1
	v_mov_b32_dpp v133, v131 row_half_mirror row_mask:0xf bank_mask:0xf bound_ctrl:1
	v_pk_add_f32 v[130:131], v[130:131], v[132:133]
	s_nop 1
	v_mov_b32_dpp v132, v130 row_mirror row_mask:0xf bank_mask:0xf bound_ctrl:1
	v_mov_b32_dpp v133, v131 row_mirror row_mask:0xf bank_mask:0xf bound_ctrl:1
	s_and_saveexec_b64 s[6:7], vcc
	v_pk_add_f32 v[130:131], v[130:131], v[132:133]
	ds_write_b64 v181, v[130:131]
	s_or_b64 exec, exec, s[6:7]
	v_add_u32_e32 v168, v138, v154
	ds_read2_b32 v[130:131], v168 offset0:128 offset1:160
	ds_read2_b32 v[132:133], v168 offset0:192 offset1:224
	v_mov_b32_e32 v82, v115
	v_add_f32_e32 v152, 0, v67
	v_pk_add_f32 v[66:67], v[82:83], 0 op_sel_hi:[1,0]
	v_mov_b32_e32 v82, v99
	v_pk_add_f32 v[82:83], v[82:83], 0 op_sel_hi:[1,0]
	s_waitcnt lgkmcnt(1)
	v_mov_b32_e32 v98, v130
	s_waitcnt lgkmcnt(0)
; template <int CTRL> DI float dpp_f(float v) { return __int_as_float(__builtin_amdgcn_update_dpp(0, __float_as_int(v), CTRL, 0xF, 0xF, true)); }
; DI float row16_sum(float v) {
;   v += dpp_f<0xB1>(v);
;   v += dpp_f<0x4E>(v);
;   v += dpp_f<0x141>(v);
;   v += dpp_f<0x140>(v);
;   return v;
; }
;   DI void operator()(f32x16 (&acc)[2][4], int grow0, int gcol0, int lane, int w, char* lds) {
;     ...
; #pragma unroll
;       for (int qq = 0; qq < 2; ++qq)
; #pragma unroll
;         for (int e = 0; e < 4; ++e) {
;           const int i = 4 * (2 * (ps & 1) + qq) + e;
;           const float* xr = (const float*)(xs + (8 * qq + 4 * hh + e) * 512) + l31;
;           float s1 = 0.f, s2 = 0.f;
; #pragma unroll
;           for (int nt = 0; nt < 4; ++nt) {
;             float v = (acc[mt][nt][i] + bia[nt]) * csc[nt];
;             float z = ALPHA * xr[nt * 32] + hs * v;
;             acc[mt][nt][i] = z; s1 += z; s2 += z * z;
;           }
;           s1 = row16_sum(s1); s2 = row16_sum(s2);
;           if ((lane & 15) == 0) { f32x2 sv = {s1, s2}; *(f32x2*)(redw + (mt * 32 + (i & 3) + 8 * (i >> 2)) * 2) = sv; }
;         }
	v_mov_b32_e32 v99, v132
	s_mov_b32 s2, s67
	v_mov_b32_e32 v130, v131
	v_mov_b32_e32 v131, v132
	v_pk_fma_f32 v[166:167], v[98:99], s[2:3], v[66:67] op_sel_hi:[1,0,1]
	v_pk_fma_f32 v[172:173], v[130:131], s[2:3], v[82:83] op_sel_hi:[1,0,1]
	v_pk_mul_f32 v[114:115], v[98:99], s[2:3] op_sel_hi:[1,0]
	v_pk_mul_f32 v[98:99], v[166:167], v[166:167]
	v_pk_mul_f32 v[82:83], v[172:173], v[172:173]
	v_pk_mov_b32 v[66:67], v[66:67], v[98:99] op_sel:[1,0]
	v_pk_mov_b32 v[82:83], v[114:115], v[82:83] op_sel:[1,0]
	v_pk_mul_f32 v[98:99], v[166:167], v[172:173]
	v_pk_add_f32 v[66:67], v[66:67], v[82:83]
	v_pk_add_f32 v[82:83], v[166:167], v[172:173]
	v_fmac_f32_e32 v152, 0x3fd744fd, v133
	v_mov_b32_e32 v83, v99
	v_pk_add_f32 v[66:67], v[82:83], v[66:67]
	v_mul_f32_e32 v153, v152, v152
	v_pk_add_f32 v[66:67], v[66:67], v[152:153]
	s_nop 1
	v_mov_b32_dpp v82, v66 quad_perm:[1,0,3,2] row_mask:0xf bank_mask:0xf bound_ctrl:1
	v_mov_b32_dpp v83, v67 quad_perm:[1,0,3,2] row_mask:0xf bank_mask:0xf bound_ctrl:1
	v_pk_add_f32 v[66:67], v[66:67], v[82:83]
	s_nop 1
	v_mov_b32_dpp v82, v66 quad_perm:[2,3,0,1] row_mask:0xf bank_mask:0xf bound_ctrl:1
	v_mov_b32_dpp v83, v67 quad_perm:[2,3,0,1] row_mask:0xf bank_mask:0xf bound_ctrl:1
	v_pk_add_f32 v[66:67], v[66:67], v[82:83]
	s_nop 1
	v_mov_b32_dpp v82, v66 row_half_mirror row_mask:0xf bank_mask:0xf bound_ctrl:1
	v_mov_b32_dpp v83, v67 row_half_mirror row_mask:0xf bank_mask:0xf bound_ctrl:1
	v_pk_add_f32 v[66:67], v[66:67], v[82:83]
	s_nop 1
	v_mov_b32_dpp v82, v66 row_mirror row_mask:0xf bank_mask:0xf bound_ctrl:1
	v_mov_b32_dpp v83, v67 row_mirror row_mask:0xf bank_mask:0xf bound_ctrl:1
	s_and_saveexec_b64 s[6:7], vcc
	v_pk_add_f32 v[66:67], v[66:67], v[82:83]
	ds_write_b64 v181, v[66:67] offset:8
	s_or_b64 exec, exec, s[6:7]
	v_add_u32_e32 v153, 0x400, v168
	ds_read2_b32 v[82:83], v153 offset1:32
	ds_read2_b32 v[98:99], v153 offset0:64 offset1:96
	v_mov_b32_e32 v114, v116
	v_mov_b32_e32 v115, v84
	v_mov_b32_e32 v130, v100
	v_mov_b32_e32 v131, v84
	v_pk_add_f32 v[114:115], v[114:115], 0 op_sel_hi:[1,0]
	v_pk_add_f32 v[130:131], v[130:131], 0 op_sel_hi:[1,0]
	s_waitcnt lgkmcnt(1)
	v_mov_b32_e32 v132, v82
	s_waitcnt lgkmcnt(0)
	v_mov_b32_e32 v133, v98
	s_mov_b32 s2, s67
	v_mov_b32_e32 v140, v83
	v_mov_b32_e32 v141, v98
	v_pk_fma_f32 v[82:83], v[132:133], s[2:3], v[114:115] op_sel_hi:[1,0,1]
	v_pk_fma_f32 v[150:151], v[140:141], s[2:3], v[130:131] op_sel_hi:[1,0,1]
	v_pk_mul_f32 v[136:137], v[132:133], s[2:3] op_sel_hi:[1,0]
	v_pk_mul_f32 v[132:133], v[82:83], v[82:83]
	v_pk_mul_f32 v[130:131], v[150:151], v[150:151]
	v_pk_mov_b32 v[114:115], v[114:115], v[132:133] op_sel:[1,0]
	v_pk_mov_b32 v[130:131], v[136:137], v[130:131] op_sel:[1,0]
	v_add_f32_e32 v66, 0, v68
	v_pk_add_f32 v[114:115], v[114:115], v[130:131]
	v_pk_add_f32 v[130:131], v[82:83], v[150:151]
	v_pk_mul_f32 v[132:133], v[82:83], v[150:151]
	v_fmac_f32_e32 v66, 0x3fd744fd, v99
	v_mov_b32_e32 v131, v133
	v_pk_add_f32 v[114:115], v[130:131], v[114:115]
	v_mul_f32_e32 v67, v66, v66
	v_pk_add_f32 v[98:99], v[114:115], v[66:67]
	s_nop 1
	v_mov_b32_dpp v114, v98 quad_perm:[1,0,3,2] row_mask:0xf bank_mask:0xf bound_ctrl:1
	v_mov_b32_dpp v115, v99 quad_perm:[1,0,3,2] row_mask:0xf bank_mask:0xf bound_ctrl:1
	v_pk_add_f32 v[98:99], v[98:99], v[114:115]
	s_nop 1
	v_mov_b32_dpp v114, v98 quad_perm:[2,3,0,1] row_mask:0xf bank_mask:0xf bound_ctrl:1
	v_mov_b32_dpp v115, v99 quad_perm:[2,3,0,1] row_mask:0xf bank_mask:0xf bound_ctrl:1
	v_pk_add_f32 v[98:99], v[98:99], v[114:115]
	s_nop 1
	v_mov_b32_dpp v114, v98 row_half_mirror row_mask:0xf bank_mask:0xf bound_ctrl:1
	v_mov_b32_dpp v115, v99 row_half_mirror row_mask:0xf bank_mask:0xf bound_ctrl:1
	v_pk_add_f32 v[98:99], v[98:99], v[114:115]
	s_nop 1
	v_mov_b32_dpp v114, v98 row_mirror row_mask:0xf bank_mask:0xf bound_ctrl:1
	v_mov_b32_dpp v115, v99 row_mirror row_mask:0xf bank_mask:0xf bound_ctrl:1
	s_and_saveexec_b64 s[6:7], vcc
	v_pk_add_f32 v[98:99], v[98:99], v[114:115]
	ds_write_b64 v181, v[98:99] offset:16
	s_or_b64 exec, exec, s[6:7]
	v_lshlrev_b32_e32 v139, 9, v134
	v_or_b32_e32 v146, 0x600, v139
	v_add_u32_e32 v151, v138, v146
	ds_read2_b32 v[98:99], v151 offset1:32
	ds_read2_b32 v[114:115], v151 offset0:64 offset1:96
	v_mov_b32_e32 v84, v117
	v_pk_add_f32 v[116:117], v[84:85], 0 op_sel_hi:[1,0]
	v_mov_b32_e32 v84, v101
	v_pk_add_f32 v[84:85], v[84:85], 0 op_sel_hi:[1,0]
	s_waitcnt lgkmcnt(1)
	v_mov_b32_e32 v100, v98
	s_waitcnt lgkmcnt(0)
	v_mov_b32_e32 v101, v114
	s_mov_b32 s2, s67
	v_mov_b32_e32 v132, v99
	v_mov_b32_e32 v133, v114
	v_pk_mul_f32 v[130:131], v[100:101], s[2:3] op_sel_hi:[1,0]
	v_pk_fma_f32 v[98:99], v[100:101], s[2:3], v[116:117] op_sel_hi:[1,0,1]
	v_pk_fma_f32 v[100:101], v[132:133], s[2:3], v[84:85] op_sel_hi:[1,0,1]
	v_pk_mul_f32 v[134:135], v[98:99], v[98:99]
	v_pk_mul_f32 v[84:85], v[100:101], v[100:101]
	v_pk_mov_b32 v[116:117], v[116:117], v[134:135] op_sel:[1,0]
	v_pk_mov_b32 v[84:85], v[130:131], v[84:85] op_sel:[1,0]
	v_add_f32_e32 v68, 0, v69
	v_pk_add_f32 v[84:85], v[116:117], v[84:85]
	v_pk_add_f32 v[116:117], v[98:99], v[100:101]
	v_pk_mul_f32 v[130:131], v[98:99], v[100:101]
	v_fmac_f32_e32 v68, 0x3fd744fd, v115
	v_mov_b32_e32 v117, v131
	v_pk_add_f32 v[84:85], v[116:117], v[84:85]
	v_mul_f32_e32 v69, v68, v68
	v_pk_add_f32 v[84:85], v[84:85], v[68:69]
	s_nop 1
	v_mov_b32_dpp v114, v84 quad_perm:[1,0,3,2] row_mask:0xf bank_mask:0xf bound_ctrl:1
	v_mov_b32_dpp v115, v85 quad_perm:[1,0,3,2] row_mask:0xf bank_mask:0xf bound_ctrl:1
	v_pk_add_f32 v[84:85], v[84:85], v[114:115]
	s_nop 1
	v_mov_b32_dpp v114, v84 quad_perm:[2,3,0,1] row_mask:0xf bank_mask:0xf bound_ctrl:1
	v_mov_b32_dpp v115, v85 quad_perm:[2,3,0,1] row_mask:0xf bank_mask:0xf bound_ctrl:1
	v_pk_add_f32 v[84:85], v[84:85], v[114:115]
	s_nop 1
	v_mov_b32_dpp v114, v84 row_half_mirror row_mask:0xf bank_mask:0xf bound_ctrl:1
	v_mov_b32_dpp v115, v85 row_half_mirror row_mask:0xf bank_mask:0xf bound_ctrl:1
	v_pk_add_f32 v[84:85], v[84:85], v[114:115]
	s_nop 1
	v_mov_b32_dpp v114, v84 row_mirror row_mask:0xf bank_mask:0xf bound_ctrl:1
	v_mov_b32_dpp v115, v85 row_mirror row_mask:0xf bank_mask:0xf bound_ctrl:1
	s_and_saveexec_b64 s[6:7], vcc
	v_pk_add_f32 v[84:85], v[84:85], v[114:115]
	ds_write_b64 v181, v[84:85] offset:24
	s_or_b64 exec, exec, s[6:7]
	v_add_u32_e32 v67, 0x1000, v168
	ds_read2_b32 v[114:115], v67 offset1:32
	ds_read2_b32 v[130:131], v67 offset0:64 offset1:96
	v_mov_b32_e32 v116, v118
	v_mov_b32_e32 v117, v86
	v_pk_add_f32 v[132:133], v[116:117], 0 op_sel_hi:[1,0]
	v_mov_b32_e32 v116, v102
	v_pk_add_f32 v[116:117], v[116:117], 0 op_sel_hi:[1,0]
	s_waitcnt lgkmcnt(1)
; template <int CTRL> DI float dpp_f(float v) { return __int_as_float(__builtin_amdgcn_update_dpp(0, __float_as_int(v), CTRL, 0xF, 0xF, true)); }
; DI float row16_sum(float v) {
;   v += dpp_f<0xB1>(v);
;   v += dpp_f<0x4E>(v);
;   v += dpp_f<0x141>(v);
;   v += dpp_f<0x140>(v);
;   return v;
; }
;   DI void operator()(f32x16 (&acc)[2][4], int grow0, int gcol0, int lane, int w, char* lds) {
;     ...
; #pragma unroll
;       for (int qq = 0; qq < 2; ++qq)
; #pragma unroll
;         for (int e = 0; e < 4; ++e) {
;           const int i = 4 * (2 * (ps & 1) + qq) + e;
;           const float* xr = (const float*)(xs + (8 * qq + 4 * hh + e) * 512) + l31;
;           float s1 = 0.f, s2 = 0.f;
; #pragma unroll
;           for (int nt = 0; nt < 4; ++nt) {
;             float v = (acc[mt][nt][i] + bia[nt]) * csc[nt];
;             float z = ALPHA * xr[nt * 32] + hs * v;
;             acc[mt][nt][i] = z; s1 += z; s2 += z * z;
;           }
;           s1 = row16_sum(s1); s2 = row16_sum(s2);
;           if ((lane & 15) == 0) { f32x2 sv = {s1, s2}; *(f32x2*)(redw + (mt * 32 + (i & 3) + 8 * (i >> 2)) * 2) = sv; }
;         }
	v_mov_b32_e32 v134, v114
	s_waitcnt lgkmcnt(0)
	v_mov_b32_e32 v135, v130
	s_mov_b32 s2, s67
	v_mov_b32_e32 v140, v115
	v_mov_b32_e32 v141, v130
	v_pk_fma_f32 v[114:115], v[134:135], s[2:3], v[132:133] op_sel_hi:[1,0,1]
	v_pk_fma_f32 v[116:117], v[140:141], s[2:3], v[116:117] op_sel_hi:[1,0,1]
	v_pk_mul_f32 v[136:137], v[134:135], s[2:3] op_sel_hi:[1,0]
	v_pk_mul_f32 v[134:135], v[114:115], v[114:115]
	v_pk_mul_f32 v[140:141], v[116:117], v[116:117]
	v_pk_mov_b32 v[132:133], v[132:133], v[134:135] op_sel:[1,0]
	v_pk_mov_b32 v[134:135], v[136:137], v[140:141] op_sel:[1,0]
	v_add_f32_e32 v84, 0, v70
	v_pk_add_f32 v[132:133], v[132:133], v[134:135]
	v_pk_add_f32 v[134:135], v[114:115], v[116:117]
	v_pk_mul_f32 v[136:137], v[114:115], v[116:117]
	v_fmac_f32_e32 v84, 0x3fd744fd, v131
	v_mov_b32_e32 v135, v137
	v_pk_add_f32 v[132:133], v[134:135], v[132:133]
	v_mul_f32_e32 v85, v84, v84
	v_pk_add_f32 v[130:131], v[132:133], v[84:85]
	s_nop 1
	v_mov_b32_dpp v132, v130 quad_perm:[1,0,3,2] row_mask:0xf bank_mask:0xf bound_ctrl:1
	v_mov_b32_dpp v133, v131 quad_perm:[1,0,3,2] row_mask:0xf bank_mask:0xf bound_ctrl:1
	v_pk_add_f32 v[130:131], v[130:131], v[132:133]
	s_nop 1
	v_mov_b32_dpp v132, v130 quad_perm:[2,3,0,1] row_mask:0xf bank_mask:0xf bound_ctrl:1
	v_mov_b32_dpp v133, v131 quad_perm:[2,3,0,1] row_mask:0xf bank_mask:0xf bound_ctrl:1
	v_pk_add_f32 v[130:131], v[130:131], v[132:133]
	s_nop 1
	v_mov_b32_dpp v132, v130 row_half_mirror row_mask:0xf bank_mask:0xf bound_ctrl:1
	v_mov_b32_dpp v133, v131 row_half_mirror row_mask:0xf bank_mask:0xf bound_ctrl:1
	v_pk_add_f32 v[130:131], v[130:131], v[132:133]
	s_nop 1
	v_mov_b32_dpp v132, v130 row_mirror row_mask:0xf bank_mask:0xf bound_ctrl:1
	v_mov_b32_dpp v133, v131 row_mirror row_mask:0xf bank_mask:0xf bound_ctrl:1
	s_and_saveexec_b64 s[6:7], vcc
	v_pk_add_f32 v[130:131], v[130:131], v[132:133]
	ds_write_b64 v181, v[130:131] offset:64
	s_or_b64 exec, exec, s[6:7]
	ds_read2_b32 v[130:131], v67 offset0:128 offset1:160
	ds_read2_b32 v[132:133], v67 offset0:192 offset1:224
	v_mov_b32_e32 v86, v119
	v_pk_add_f32 v[134:135], v[86:87], 0 op_sel_hi:[1,0]
	v_mov_b32_e32 v86, v103
	v_pk_add_f32 v[86:87], v[86:87], 0 op_sel_hi:[1,0]
	s_waitcnt lgkmcnt(1)
	v_mov_b32_e32 v102, v130
	s_waitcnt lgkmcnt(0)
	v_mov_b32_e32 v103, v132
	s_mov_b32 s2, s67
	v_mov_b32_e32 v118, v131
	v_mov_b32_e32 v119, v132
	v_pk_mul_f32 v[136:137], v[102:103], s[2:3] op_sel_hi:[1,0]
	v_pk_fma_f32 v[102:103], v[102:103], s[2:3], v[134:135] op_sel_hi:[1,0,1]
	v_pk_fma_f32 v[118:119], v[118:119], s[2:3], v[86:87] op_sel_hi:[1,0,1]
	v_pk_mul_f32 v[130:131], v[102:103], v[102:103]
	v_pk_mul_f32 v[86:87], v[118:119], v[118:119]
	v_pk_mov_b32 v[130:131], v[134:135], v[130:131] op_sel:[1,0]
	v_pk_mov_b32 v[86:87], v[136:137], v[86:87] op_sel:[1,0]
	v_add_f32_e32 v70, 0, v71
	v_pk_add_f32 v[86:87], v[130:131], v[86:87]
	v_pk_add_f32 v[130:131], v[102:103], v[118:119]
	v_pk_mul_f32 v[134:135], v[102:103], v[118:119]
	v_fmac_f32_e32 v70, 0x3fd744fd, v133
	v_mov_b32_e32 v131, v135
	v_pk_add_f32 v[86:87], v[130:131], v[86:87]
	v_mul_f32_e32 v71, v70, v70
	v_pk_add_f32 v[86:87], v[86:87], v[70:71]
	s_nop 1
	v_mov_b32_dpp v130, v86 quad_perm:[1,0,3,2] row_mask:0xf bank_mask:0xf bound_ctrl:1
	v_mov_b32_dpp v131, v87 quad_perm:[1,0,3,2] row_mask:0xf bank_mask:0xf bound_ctrl:1
	v_pk_add_f32 v[86:87], v[86:87], v[130:131]
	s_nop 1
	v_mov_b32_dpp v130, v86 quad_perm:[2,3,0,1] row_mask:0xf bank_mask:0xf bound_ctrl:1
	v_mov_b32_dpp v131, v87 quad_perm:[2,3,0,1] row_mask:0xf bank_mask:0xf bound_ctrl:1
	v_pk_add_f32 v[86:87], v[86:87], v[130:131]
	s_nop 1
	v_mov_b32_dpp v130, v86 row_half_mirror row_mask:0xf bank_mask:0xf bound_ctrl:1
	v_mov_b32_dpp v131, v87 row_half_mirror row_mask:0xf bank_mask:0xf bound_ctrl:1
	v_pk_add_f32 v[86:87], v[86:87], v[130:131]
	s_nop 1
	v_mov_b32_dpp v130, v86 row_mirror row_mask:0xf bank_mask:0xf bound_ctrl:1
	v_mov_b32_dpp v131, v87 row_mirror row_mask:0xf bank_mask:0xf bound_ctrl:1
	s_and_saveexec_b64 s[6:7], vcc
	v_pk_add_f32 v[86:87], v[86:87], v[130:131]
	ds_write_b64 v181, v[86:87] offset:72
	s_or_b64 exec, exec, s[6:7]
	v_add_u32_e32 v69, 0x1400, v168
	ds_read2_b32 v[130:131], v69 offset1:32
	ds_read2_b32 v[134:135], v69 offset0:64 offset1:96
	v_mov_b32_e32 v132, v120
	v_mov_b32_e32 v133, v88
	v_pk_add_f32 v[136:137], v[132:133], 0 op_sel_hi:[1,0]
	v_mov_b32_e32 v132, v104
	v_pk_add_f32 v[132:133], v[132:133], 0 op_sel_hi:[1,0]
	s_waitcnt lgkmcnt(1)
	v_mov_b32_e32 v140, v130
	s_waitcnt lgkmcnt(0)
	v_mov_b32_e32 v141, v134
	s_mov_b32 s2, s67
	v_mov_b32_e32 v144, v131
	v_mov_b32_e32 v145, v134
	v_pk_fma_f32 v[130:131], v[140:141], s[2:3], v[136:137] op_sel_hi:[1,0,1]
	v_pk_fma_f32 v[132:133], v[144:145], s[2:3], v[132:133] op_sel_hi:[1,0,1]
	v_pk_mul_f32 v[142:143], v[140:141], s[2:3] op_sel_hi:[1,0]
	v_pk_mul_f32 v[140:141], v[130:131], v[130:131]
	v_pk_mul_f32 v[144:145], v[132:133], v[132:133]
	v_pk_mov_b32 v[136:137], v[136:137], v[140:141] op_sel:[1,0]
	v_pk_mov_b32 v[140:141], v[142:143], v[144:145] op_sel:[1,0]
	v_add_f32_e32 v86, 0, v72
	v_pk_add_f32 v[136:137], v[136:137], v[140:141]
	v_pk_add_f32 v[140:141], v[130:131], v[132:133]
	v_pk_mul_f32 v[142:143], v[130:131], v[132:133]
	v_fmac_f32_e32 v86, 0x3fd744fd, v135
	v_mov_b32_e32 v141, v143
	v_pk_add_f32 v[136:137], v[140:141], v[136:137]
	v_mul_f32_e32 v87, v86, v86
	v_pk_add_f32 v[134:135], v[136:137], v[86:87]
	s_nop 1
	v_mov_b32_dpp v136, v134 quad_perm:[1,0,3,2] row_mask:0xf bank_mask:0xf bound_ctrl:1
	v_mov_b32_dpp v137, v135 quad_perm:[1,0,3,2] row_mask:0xf bank_mask:0xf bound_ctrl:1
	v_pk_add_f32 v[134:135], v[134:135], v[136:137]
	s_nop 1
	v_mov_b32_dpp v136, v134 quad_perm:[2,3,0,1] row_mask:0xf bank_mask:0xf bound_ctrl:1
	v_mov_b32_dpp v137, v135 quad_perm:[2,3,0,1] row_mask:0xf bank_mask:0xf bound_ctrl:1
	v_pk_add_f32 v[134:135], v[134:135], v[136:137]
	s_nop 1
	v_mov_b32_dpp v136, v134 row_half_mirror row_mask:0xf bank_mask:0xf bound_ctrl:1
	v_mov_b32_dpp v137, v135 row_half_mirror row_mask:0xf bank_mask:0xf bound_ctrl:1
	v_pk_add_f32 v[134:135], v[134:135], v[136:137]
	s_nop 1
	v_mov_b32_dpp v136, v134 row_mirror row_mask:0xf bank_mask:0xf bound_ctrl:1
	v_mov_b32_dpp v137, v135 row_mirror row_mask:0xf bank_mask:0xf bound_ctrl:1
	s_and_saveexec_b64 s[6:7], vcc
	v_pk_add_f32 v[134:135], v[134:135], v[136:137]
	ds_write_b64 v181, v[134:135] offset:80
	s_or_b64 exec, exec, s[6:7]
	v_or_b32_e32 v101, 0x1600, v139
	v_add_u32_e32 v71, v138, v101
	ds_read2_b32 v[134:135], v71 offset1:32
	ds_read2_b32 v[136:137], v71 offset0:64 offset1:96
	v_mov_b32_e32 v88, v121
	v_pk_add_f32 v[120:121], v[88:89], 0 op_sel_hi:[1,0]
	v_mov_b32_e32 v88, v105
	v_pk_add_f32 v[104:105], v[88:89], 0 op_sel_hi:[1,0]
	s_waitcnt lgkmcnt(1)
;   DI void xpass(int ps, int grow0, int gcol0, int lane, int w, char* lds) const {
;     char* xs = lds + (ps & 1) * 65536 + __builtin_amdgcn_readfirstlane(w) * 8192;
;     const float* xsrc = Xin + (size_t)(grow0 + (ps >> 1) * 32 + (ps & 1) * 16 + (lane >> 5)) * D_ + gcol0 + (lane & 31) * 4;
; #pragma unroll
;     for (int pc = 0; pc < 8; ++pc)
;       __builtin_amdgcn_global_load_lds((const unsigned*)(xsrc + (size_t)(2 * pc) * D_), (__attribute__((address_space(3))) unsigned*)(xs + pc * 1024), 16, 0, 0);
;   }
;   DI void operator()(f32x16 (&acc)[2][4], int grow0, int gcol0, int lane, int w, char* lds) {
;     ...
;     for (int ps = 0; ps < 4; ++ps) {
;       const int mt = ps >> 1;
;       if (ps + 1 < 4) {
;         if (ps >= 1) asm volatile("s_waitcnt lgkmcnt(0)" ::: "memory");
;         xpass(ps + 1, grow0, gcol0, lane, w, lds);
;         if (ps >= 1) asm volatile("s_waitcnt vmcnt(8)" ::: "memory");
;       } else asm volatile("s_waitcnt vmcnt(0)" ::: "memory");
;       const char* xs = lds + (ps & 1) * 65536 + w * 8192;
; #pragma unroll
;       for (int qq = 0; qq < 2; ++qq)
; #pragma unroll
;         for (int e = 0; e < 4; ++e) {
;           const int i = 4 * (2 * (ps & 1) + qq) + e;
;           const float* xr = (const float*)(xs + (8 * qq + 4 * hh + e) * 512) + l31;
;           float s1 = 0.f, s2 = 0.f;
; #pragma unroll
;           for (int nt = 0; nt < 4; ++nt) {
;             float v = (acc[mt][nt][i] + bia[nt]) * csc[nt];
;             float z = ALPHA * xr[nt * 32] + hs * v;
;             acc[mt][nt][i] = z; s1 += z; s2 += z * z;
;           }
;           s1 = row16_sum(s1); s2 = row16_sum(s2);
;           if ((lane & 15) == 0) { f32x2 sv = {s1, s2}; *(f32x2*)(redw + (mt * 32 + (i & 3) + 8 * (i >> 2)) * 2) = sv; }
;         }
	v_mov_b32_e32 v88, v134
	s_waitcnt lgkmcnt(0)
	v_mov_b32_e32 v89, v136
	s_mov_b32 s2, s67
	v_mov_b32_e32 v134, v135
	v_mov_b32_e32 v135, v136
	v_pk_mul_f32 v[140:141], v[88:89], s[2:3] op_sel_hi:[1,0]
	v_pk_fma_f32 v[88:89], v[88:89], s[2:3], v[120:121] op_sel_hi:[1,0,1]
	v_pk_fma_f32 v[104:105], v[134:135], s[2:3], v[104:105] op_sel_hi:[1,0,1]
	v_pk_mul_f32 v[142:143], v[88:89], v[88:89]
	v_pk_mul_f32 v[134:135], v[104:105], v[104:105]
	v_pk_mov_b32 v[120:121], v[120:121], v[142:143] op_sel:[1,0]
	v_pk_mov_b32 v[134:135], v[140:141], v[134:135] op_sel:[1,0]
	v_add_f32_e32 v72, 0, v73
	v_pk_add_f32 v[120:121], v[120:121], v[134:135]
	v_pk_add_f32 v[134:135], v[88:89], v[104:105]
	v_pk_mul_f32 v[140:141], v[88:89], v[104:105]
	v_fmac_f32_e32 v72, 0x3fd744fd, v137
	v_mov_b32_e32 v135, v141
	v_pk_add_f32 v[120:121], v[134:135], v[120:121]
	v_mul_f32_e32 v73, v72, v72
	v_pk_add_f32 v[120:121], v[120:121], v[72:73]
	s_nop 1
	v_mov_b32_dpp v134, v120 quad_perm:[1,0,3,2] row_mask:0xf bank_mask:0xf bound_ctrl:1
	v_mov_b32_dpp v135, v121 quad_perm:[1,0,3,2] row_mask:0xf bank_mask:0xf bound_ctrl:1
	v_pk_add_f32 v[120:121], v[120:121], v[134:135]
	s_nop 1
	v_mov_b32_dpp v134, v120 quad_perm:[2,3,0,1] row_mask:0xf bank_mask:0xf bound_ctrl:1
	v_mov_b32_dpp v135, v121 quad_perm:[2,3,0,1] row_mask:0xf bank_mask:0xf bound_ctrl:1
	v_pk_add_f32 v[120:121], v[120:121], v[134:135]
	s_nop 1
	v_mov_b32_dpp v134, v120 row_half_mirror row_mask:0xf bank_mask:0xf bound_ctrl:1
	v_mov_b32_dpp v135, v121 row_half_mirror row_mask:0xf bank_mask:0xf bound_ctrl:1
	v_pk_add_f32 v[120:121], v[120:121], v[134:135]
	s_nop 1
	v_mov_b32_dpp v134, v120 row_mirror row_mask:0xf bank_mask:0xf bound_ctrl:1
	v_mov_b32_dpp v135, v121 row_mirror row_mask:0xf bank_mask:0xf bound_ctrl:1
	s_and_saveexec_b64 s[6:7], vcc
	v_pk_add_f32 v[120:121], v[120:121], v[134:135]
	ds_write_b64 v181, v[120:121] offset:88
	s_or_b64 exec, exec, s[6:7]
	v_or_b32_e32 v120, 32, v159
	v_ashrrev_i32_e32 v121, 31, v120
	v_lshlrev_b64 v[120:121], 12, v[120:121]
	v_readfirstlane_b32 s2, v158
	v_lshl_add_u64 v[120:121], s[10:11], 0, v[120:121]
	s_lshl_b32 s2, s2, 13
	v_lshl_add_u64 v[120:121], v[184:185], 2, v[120:121]
	s_waitcnt lgkmcnt(0)
	v_lshl_add_u64 v[120:121], v[120:121], 0, v[0:1]
	s_mov_b32 m0, s2
	s_mov_b64 s[6:7], 0x2000
	global_load_lds_dwordx4 v[120:121], off
	v_lshl_add_u64 v[134:135], v[120:121], 0, s[6:7]
	s_or_b32 m0, s2, 0x400
	s_mov_b64 s[6:7], 0x4000
	global_load_lds_dwordx4 v[134:135], off
	v_lshl_add_u64 v[134:135], v[120:121], 0, s[6:7]
	s_or_b32 m0, s2, 0x800
	s_mov_b64 s[6:7], 0x6000
	global_load_lds_dwordx4 v[134:135], off
	v_lshl_add_u64 v[134:135], v[120:121], 0, s[6:7]
	s_or_b32 m0, s2, 0xc00
	s_mov_b64 s[6:7], 0x8000
	global_load_lds_dwordx4 v[134:135], off
	v_lshl_add_u64 v[134:135], v[120:121], 0, s[6:7]
	s_or_b32 m0, s2, 0x1000
	s_mov_b64 s[6:7], 0xa000
	global_load_lds_dwordx4 v[134:135], off
	v_lshl_add_u64 v[134:135], v[120:121], 0, s[6:7]
	s_or_b32 m0, s2, 0x1400
	s_mov_b64 s[6:7], 0xc000
	global_load_lds_dwordx4 v[134:135], off
	v_lshl_add_u64 v[134:135], v[120:121], 0, s[6:7]
	s_or_b32 m0, s2, 0x1800
	s_mov_b64 s[6:7], 0xe000
	global_load_lds_dwordx4 v[134:135], off
	v_lshl_add_u64 v[120:121], v[120:121], 0, s[6:7]
	s_or_b32 m0, s2, 0x1c00
	v_add_u32_e32 v105, 0x10000, v138
	global_load_lds_dwordx4 v[120:121], off
	s_waitcnt vmcnt(8)
	v_add_u32_e32 v73, v105, v154
	ds_read2_b32 v[134:135], v73 offset1:32
	ds_read2_b32 v[138:139], v73 offset0:64 offset1:96
	v_mov_b32_e32 v136, v122
	v_mov_b32_e32 v137, v90
	v_pk_add_f32 v[140:141], v[136:137], 0 op_sel_hi:[1,0]
	v_mov_b32_e32 v136, v106
	v_pk_add_f32 v[136:137], v[136:137], 0 op_sel_hi:[1,0]
	s_waitcnt lgkmcnt(0)
	v_mov_b32_e32 v142, v134
	v_mov_b32_e32 v143, v138
	s_mov_b32 s2, s67
	v_mov_b32_e32 v148, v135
	v_mov_b32_e32 v149, v138
	v_pk_fma_f32 v[134:135], v[142:143], s[2:3], v[140:141] op_sel_hi:[1,0,1]
	v_pk_fma_f32 v[136:137], v[148:149], s[2:3], v[136:137] op_sel_hi:[1,0,1]
	v_pk_mul_f32 v[144:145], v[142:143], s[2:3] op_sel_hi:[1,0]
	v_pk_mul_f32 v[142:143], v[134:135], v[134:135]
	v_pk_mul_f32 v[148:149], v[136:137], v[136:137]
	v_pk_mov_b32 v[140:141], v[140:141], v[142:143] op_sel:[1,0]
	v_pk_mov_b32 v[142:143], v[144:145], v[148:149] op_sel:[1,0]
	v_add_f32_e32 v120, 0, v74
	v_pk_add_f32 v[140:141], v[140:141], v[142:143]
	v_pk_add_f32 v[142:143], v[134:135], v[136:137]
	v_pk_mul_f32 v[144:145], v[134:135], v[136:137]
	v_fmac_f32_e32 v120, 0x3fd744fd, v139
	v_mov_b32_e32 v143, v145
	v_pk_add_f32 v[140:141], v[142:143], v[140:141]
	v_mul_f32_e32 v121, v120, v120
	v_pk_add_f32 v[138:139], v[140:141], v[120:121]
	s_nop 1
	v_mov_b32_dpp v140, v138 quad_perm:[1,0,3,2] row_mask:0xf bank_mask:0xf bound_ctrl:1
	v_mov_b32_dpp v141, v139 quad_perm:[1,0,3,2] row_mask:0xf bank_mask:0xf bound_ctrl:1
	v_pk_add_f32 v[138:139], v[138:139], v[140:141]
	s_nop 1
	v_mov_b32_dpp v140, v138 quad_perm:[2,3,0,1] row_mask:0xf bank_mask:0xf bound_ctrl:1
	v_mov_b32_dpp v141, v139 quad_perm:[2,3,0,1] row_mask:0xf bank_mask:0xf bound_ctrl:1
	v_pk_add_f32 v[138:139], v[138:139], v[140:141]
	s_nop 1
	v_mov_b32_dpp v140, v138 row_half_mirror row_mask:0xf bank_mask:0xf bound_ctrl:1
	v_mov_b32_dpp v141, v139 row_half_mirror row_mask:0xf bank_mask:0xf bound_ctrl:1
	v_pk_add_f32 v[138:139], v[138:139], v[140:141]
	s_nop 1
	v_mov_b32_dpp v140, v138 row_mirror row_mask:0xf bank_mask:0xf bound_ctrl:1
	v_mov_b32_dpp v141, v139 row_mirror row_mask:0xf bank_mask:0xf bound_ctrl:1
	s_and_saveexec_b64 s[6:7], vcc
	v_pk_add_f32 v[138:139], v[138:139], v[140:141]
	ds_write_b64 v181, v[138:139] offset:128
	s_or_b64 exec, exec, s[6:7]
	v_or_b32_e32 v74, 0x200, v154
	v_add_u32_e32 v85, v105, v74
	ds_read2_b32 v[138:139], v85 offset1:32
	ds_read2_b32 v[140:141], v85 offset0:64 offset1:96
	v_mov_b32_e32 v90, v123
	v_pk_add_f32 v[142:143], v[90:91], 0 op_sel_hi:[1,0]
	v_mov_b32_e32 v90, v107
	v_pk_add_f32 v[90:91], v[90:91], 0 op_sel_hi:[1,0]
	s_waitcnt lgkmcnt(1)
;   DI void operator()(f32x16 (&acc)[2][4], int grow0, int gcol0, int lane, int w, char* lds) {
;     ...
; #pragma unroll
;       for (int qq = 0; qq < 2; ++qq)
; #pragma unroll
;         for (int e = 0; e < 4; ++e) {
;           const int i = 4 * (2 * (ps & 1) + qq) + e;
;           const float* xr = (const float*)(xs + (8 * qq + 4 * hh + e) * 512) + l31;
;           float s1 = 0.f, s2 = 0.f;
; #pragma unroll
;           for (int nt = 0; nt < 4; ++nt) {
;             float v = (acc[mt][nt][i] + bia[nt]) * csc[nt];
;             float z = ALPHA * xr[nt * 32] + hs * v;
;             acc[mt][nt][i] = z; s1 += z; s2 += z * z;
;           }
;           s1 = row16_sum(s1); s2 = row16_sum(s2);
;           if ((lane & 15) == 0) { f32x2 sv = {s1, s2}; *(f32x2*)(redw + (mt * 32 + (i & 3) + 8 * (i >> 2)) * 2) = sv; }
;         }
	v_mov_b32_e32 v106, v138
	s_waitcnt lgkmcnt(0)
	v_mov_b32_e32 v107, v140
	s_mov_b32 s2, s67
	v_mov_b32_e32 v122, v139
	v_mov_b32_e32 v123, v140
	v_pk_mul_f32 v[144:145], v[106:107], s[2:3] op_sel_hi:[1,0]
	v_pk_fma_f32 v[106:107], v[106:107], s[2:3], v[142:143] op_sel_hi:[1,0,1]
	v_pk_fma_f32 v[122:123], v[122:123], s[2:3], v[90:91] op_sel_hi:[1,0,1]
	v_pk_mul_f32 v[138:139], v[106:107], v[106:107]
	v_pk_mul_f32 v[90:91], v[122:123], v[122:123]
	v_pk_mov_b32 v[138:139], v[142:143], v[138:139] op_sel:[1,0]
	v_pk_mov_b32 v[90:91], v[144:145], v[90:91] op_sel:[1,0]
	v_add_f32_e32 v74, 0, v75
	v_pk_add_f32 v[90:91], v[138:139], v[90:91]
	v_pk_add_f32 v[138:139], v[106:107], v[122:123]
	v_pk_mul_f32 v[142:143], v[106:107], v[122:123]
	v_fmac_f32_e32 v74, 0x3fd744fd, v141
	v_mov_b32_e32 v139, v143
	v_pk_add_f32 v[90:91], v[138:139], v[90:91]
	v_mul_f32_e32 v75, v74, v74
	v_pk_add_f32 v[90:91], v[90:91], v[74:75]
	s_nop 1
	v_mov_b32_dpp v138, v90 quad_perm:[1,0,3,2] row_mask:0xf bank_mask:0xf bound_ctrl:1
	v_mov_b32_dpp v139, v91 quad_perm:[1,0,3,2] row_mask:0xf bank_mask:0xf bound_ctrl:1
	v_pk_add_f32 v[90:91], v[90:91], v[138:139]
	s_nop 1
	v_mov_b32_dpp v138, v90 quad_perm:[2,3,0,1] row_mask:0xf bank_mask:0xf bound_ctrl:1
	v_mov_b32_dpp v139, v91 quad_perm:[2,3,0,1] row_mask:0xf bank_mask:0xf bound_ctrl:1
	v_pk_add_f32 v[90:91], v[90:91], v[138:139]
	s_nop 1
	v_mov_b32_dpp v138, v90 row_half_mirror row_mask:0xf bank_mask:0xf bound_ctrl:1
	v_mov_b32_dpp v139, v91 row_half_mirror row_mask:0xf bank_mask:0xf bound_ctrl:1
	v_pk_add_f32 v[90:91], v[90:91], v[138:139]
	s_nop 1
	v_mov_b32_dpp v138, v90 row_mirror row_mask:0xf bank_mask:0xf bound_ctrl:1
	v_mov_b32_dpp v139, v91 row_mirror row_mask:0xf bank_mask:0xf bound_ctrl:1
	s_and_saveexec_b64 s[6:7], vcc
	v_pk_add_f32 v[90:91], v[90:91], v[138:139]
	ds_write_b64 v181, v[90:91] offset:136
	s_or_b64 exec, exec, s[6:7]
	v_or_b32_e32 v75, 0x400, v154
	v_add_u32_e32 v75, v105, v75
	ds_read2_b32 v[138:139], v75 offset1:32
	ds_read2_b32 v[142:143], v75 offset0:64 offset1:96
	v_mov_b32_e32 v140, v124
	v_mov_b32_e32 v141, v92
	v_pk_add_f32 v[144:145], v[140:141], 0 op_sel_hi:[1,0]
	v_mov_b32_e32 v140, v108
	v_pk_add_f32 v[140:141], v[140:141], 0 op_sel_hi:[1,0]
	s_waitcnt lgkmcnt(1)
	v_mov_b32_e32 v148, v138
	s_waitcnt lgkmcnt(0)
	v_mov_b32_e32 v149, v142
	s_mov_b32 s2, s67
	v_mov_b32_e32 v160, v139
	v_mov_b32_e32 v161, v142
	v_pk_fma_f32 v[138:139], v[148:149], s[2:3], v[144:145] op_sel_hi:[1,0,1]
	v_pk_fma_f32 v[140:141], v[160:161], s[2:3], v[140:141] op_sel_hi:[1,0,1]
	v_pk_mul_f32 v[156:157], v[148:149], s[2:3] op_sel_hi:[1,0]
	v_pk_mul_f32 v[148:149], v[138:139], v[138:139]
	v_pk_mul_f32 v[160:161], v[140:141], v[140:141]
	v_pk_mov_b32 v[144:145], v[144:145], v[148:149] op_sel:[1,0]
	v_pk_mov_b32 v[148:149], v[156:157], v[160:161] op_sel:[1,0]
	v_add_f32_e32 v90, 0, v76
	v_pk_add_f32 v[144:145], v[144:145], v[148:149]
	v_pk_add_f32 v[148:149], v[138:139], v[140:141]
	v_pk_mul_f32 v[156:157], v[138:139], v[140:141]
	v_fmac_f32_e32 v90, 0x3fd744fd, v143
	v_mov_b32_e32 v149, v157
	v_pk_add_f32 v[144:145], v[148:149], v[144:145]
	v_mul_f32_e32 v91, v90, v90
	v_pk_add_f32 v[142:143], v[144:145], v[90:91]
	s_nop 1
	v_mov_b32_dpp v144, v142 quad_perm:[1,0,3,2] row_mask:0xf bank_mask:0xf bound_ctrl:1
	v_mov_b32_dpp v145, v143 quad_perm:[1,0,3,2] row_mask:0xf bank_mask:0xf bound_ctrl:1
	v_pk_add_f32 v[142:143], v[142:143], v[144:145]
	s_nop 1
	v_mov_b32_dpp v144, v142 quad_perm:[2,3,0,1] row_mask:0xf bank_mask:0xf bound_ctrl:1
	v_mov_b32_dpp v145, v143 quad_perm:[2,3,0,1] row_mask:0xf bank_mask:0xf bound_ctrl:1
	v_pk_add_f32 v[142:143], v[142:143], v[144:145]
	s_nop 1
	v_mov_b32_dpp v144, v142 row_half_mirror row_mask:0xf bank_mask:0xf bound_ctrl:1
	v_mov_b32_dpp v145, v143 row_half_mirror row_mask:0xf bank_mask:0xf bound_ctrl:1
	v_pk_add_f32 v[142:143], v[142:143], v[144:145]
	s_nop 1
	v_mov_b32_dpp v144, v142 row_mirror row_mask:0xf bank_mask:0xf bound_ctrl:1
	v_mov_b32_dpp v145, v143 row_mirror row_mask:0xf bank_mask:0xf bound_ctrl:1
	s_and_saveexec_b64 s[6:7], vcc
	v_pk_add_f32 v[142:143], v[142:143], v[144:145]
	ds_write_b64 v181, v[142:143] offset:144
	s_or_b64 exec, exec, s[6:7]
	v_add_u32_e32 v87, v105, v146
	ds_read2_b32 v[142:143], v87 offset1:32
	ds_read2_b32 v[144:145], v87 offset0:64 offset1:96
	v_mov_b32_e32 v92, v125
	v_pk_add_f32 v[146:147], v[92:93], 0 op_sel_hi:[1,0]
	v_mov_b32_e32 v92, v109
	v_pk_add_f32 v[92:93], v[92:93], 0 op_sel_hi:[1,0]
	s_waitcnt lgkmcnt(1)
	v_mov_b32_e32 v108, v142
	s_waitcnt lgkmcnt(0)
;   DI void operator()(f32x16 (&acc)[2][4], int grow0, int gcol0, int lane, int w, char* lds) {
;     ...
; #pragma unroll
;       for (int qq = 0; qq < 2; ++qq)
; #pragma unroll
;         for (int e = 0; e < 4; ++e) {
;           const int i = 4 * (2 * (ps & 1) + qq) + e;
;           const float* xr = (const float*)(xs + (8 * qq + 4 * hh + e) * 512) + l31;
;           float s1 = 0.f, s2 = 0.f;
; #pragma unroll
;           for (int nt = 0; nt < 4; ++nt) {
;             float v = (acc[mt][nt][i] + bia[nt]) * csc[nt];
;             float z = ALPHA * xr[nt * 32] + hs * v;
;             acc[mt][nt][i] = z; s1 += z; s2 += z * z;
;           }
;           s1 = row16_sum(s1); s2 = row16_sum(s2);
;           if ((lane & 15) == 0) { f32x2 sv = {s1, s2}; *(f32x2*)(redw + (mt * 32 + (i & 3) + 8 * (i >> 2)) * 2) = sv; }
;         }
	v_mov_b32_e32 v109, v144
	s_mov_b32 s2, s67
	v_mov_b32_e32 v124, v143
	v_mov_b32_e32 v125, v144
	v_pk_mul_f32 v[148:149], v[108:109], s[2:3] op_sel_hi:[1,0]
	v_pk_fma_f32 v[108:109], v[108:109], s[2:3], v[146:147] op_sel_hi:[1,0,1]
	v_pk_fma_f32 v[124:125], v[124:125], s[2:3], v[92:93] op_sel_hi:[1,0,1]
	v_pk_mul_f32 v[142:143], v[108:109], v[108:109]
	v_pk_mul_f32 v[92:93], v[124:125], v[124:125]
	v_pk_mov_b32 v[142:143], v[146:147], v[142:143] op_sel:[1,0]
	v_pk_mov_b32 v[92:93], v[148:149], v[92:93] op_sel:[1,0]
	v_add_f32_e32 v76, 0, v77
	v_pk_add_f32 v[92:93], v[142:143], v[92:93]
	v_pk_add_f32 v[142:143], v[108:109], v[124:125]
	v_pk_mul_f32 v[146:147], v[108:109], v[124:125]
	v_fmac_f32_e32 v76, 0x3fd744fd, v145
	v_mov_b32_e32 v143, v147
	v_pk_add_f32 v[92:93], v[142:143], v[92:93]
	v_mul_f32_e32 v77, v76, v76
	v_pk_add_f32 v[92:93], v[92:93], v[76:77]
	s_nop 1
	v_mov_b32_dpp v142, v92 quad_perm:[1,0,3,2] row_mask:0xf bank_mask:0xf bound_ctrl:1
	v_mov_b32_dpp v143, v93 quad_perm:[1,0,3,2] row_mask:0xf bank_mask:0xf bound_ctrl:1
	v_pk_add_f32 v[92:93], v[92:93], v[142:143]
	s_nop 1
	v_mov_b32_dpp v142, v92 quad_perm:[2,3,0,1] row_mask:0xf bank_mask:0xf bound_ctrl:1
	v_mov_b32_dpp v143, v93 quad_perm:[2,3,0,1] row_mask:0xf bank_mask:0xf bound_ctrl:1
	v_pk_add_f32 v[92:93], v[92:93], v[142:143]
	s_nop 1
	v_mov_b32_dpp v142, v92 row_half_mirror row_mask:0xf bank_mask:0xf bound_ctrl:1
	v_mov_b32_dpp v143, v93 row_half_mirror row_mask:0xf bank_mask:0xf bound_ctrl:1
	v_pk_add_f32 v[92:93], v[92:93], v[142:143]
	s_nop 1
	v_mov_b32_dpp v142, v92 row_mirror row_mask:0xf bank_mask:0xf bound_ctrl:1
	v_mov_b32_dpp v143, v93 row_mirror row_mask:0xf bank_mask:0xf bound_ctrl:1
	s_and_saveexec_b64 s[6:7], vcc
	v_pk_add_f32 v[92:93], v[92:93], v[142:143]
	ds_write_b64 v181, v[92:93] offset:152
	s_or_b64 exec, exec, s[6:7]
	v_or_b32_e32 v77, 0x1000, v154
	v_add_u32_e32 v77, v105, v77
	ds_read2_b32 v[142:143], v77 offset1:32
	ds_read2_b32 v[146:147], v77 offset0:64 offset1:96
	v_mov_b32_e32 v144, v126
	v_mov_b32_e32 v145, v94
	v_pk_add_f32 v[148:149], v[144:145], 0 op_sel_hi:[1,0]
	v_mov_b32_e32 v144, v110
	v_pk_add_f32 v[144:145], v[144:145], 0 op_sel_hi:[1,0]
	s_waitcnt lgkmcnt(1)
	v_mov_b32_e32 v156, v142
	s_waitcnt lgkmcnt(0)
	v_mov_b32_e32 v157, v146
	s_mov_b32 s2, s67
	v_mov_b32_e32 v170, v143
	v_mov_b32_e32 v171, v146
	v_pk_fma_f32 v[142:143], v[156:157], s[2:3], v[148:149] op_sel_hi:[1,0,1]
	v_pk_fma_f32 v[144:145], v[170:171], s[2:3], v[144:145] op_sel_hi:[1,0,1]
	v_pk_mul_f32 v[160:161], v[156:157], s[2:3] op_sel_hi:[1,0]
	v_pk_mul_f32 v[156:157], v[142:143], v[142:143]
	v_pk_mul_f32 v[170:171], v[144:145], v[144:145]
	v_pk_mov_b32 v[148:149], v[148:149], v[156:157] op_sel:[1,0]
	v_pk_mov_b32 v[156:157], v[160:161], v[170:171] op_sel:[1,0]
	v_add_f32_e32 v92, 0, v78
	v_pk_add_f32 v[148:149], v[148:149], v[156:157]
	v_pk_add_f32 v[156:157], v[142:143], v[144:145]
	v_pk_mul_f32 v[160:161], v[142:143], v[144:145]
	v_fmac_f32_e32 v92, 0x3fd744fd, v147
	v_mov_b32_e32 v157, v161
	v_pk_add_f32 v[148:149], v[156:157], v[148:149]
	v_mul_f32_e32 v93, v92, v92
	v_pk_add_f32 v[146:147], v[148:149], v[92:93]
	s_nop 1
	v_mov_b32_dpp v148, v146 quad_perm:[1,0,3,2] row_mask:0xf bank_mask:0xf bound_ctrl:1
	v_mov_b32_dpp v149, v147 quad_perm:[1,0,3,2] row_mask:0xf bank_mask:0xf bound_ctrl:1
	v_pk_add_f32 v[146:147], v[146:147], v[148:149]
	s_nop 1
	v_mov_b32_dpp v148, v146 quad_perm:[2,3,0,1] row_mask:0xf bank_mask:0xf bound_ctrl:1
	v_mov_b32_dpp v149, v147 quad_perm:[2,3,0,1] row_mask:0xf bank_mask:0xf bound_ctrl:1
	v_pk_add_f32 v[146:147], v[146:147], v[148:149]
	s_nop 1
	v_mov_b32_dpp v148, v146 row_half_mirror row_mask:0xf bank_mask:0xf bound_ctrl:1
	v_mov_b32_dpp v149, v147 row_half_mirror row_mask:0xf bank_mask:0xf bound_ctrl:1
	v_pk_add_f32 v[146:147], v[146:147], v[148:149]
	s_nop 1
	v_mov_b32_dpp v148, v146 row_mirror row_mask:0xf bank_mask:0xf bound_ctrl:1
	v_mov_b32_dpp v149, v147 row_mirror row_mask:0xf bank_mask:0xf bound_ctrl:1
	s_and_saveexec_b64 s[6:7], vcc
	v_pk_add_f32 v[146:147], v[146:147], v[148:149]
	ds_write_b64 v181, v[146:147] offset:192
	s_or_b64 exec, exec, s[6:7]
	v_or_b32_e32 v78, 0x1200, v154
	v_add_u32_e32 v91, v105, v78
	ds_read2_b32 v[146:147], v91 offset1:32
	ds_read2_b32 v[148:149], v91 offset0:64 offset1:96
	v_mov_b32_e32 v94, v127
	v_pk_add_f32 v[156:157], v[94:95], 0 op_sel_hi:[1,0]
	v_mov_b32_e32 v94, v111
	v_pk_add_f32 v[94:95], v[94:95], 0 op_sel_hi:[1,0]
	s_waitcnt lgkmcnt(1)
	v_mov_b32_e32 v110, v146
	s_waitcnt lgkmcnt(0)
	v_mov_b32_e32 v111, v148
	s_mov_b32 s2, s67
	v_mov_b32_e32 v126, v147
	v_mov_b32_e32 v127, v148
	v_pk_mul_f32 v[160:161], v[110:111], s[2:3] op_sel_hi:[1,0]
	v_pk_fma_f32 v[110:111], v[110:111], s[2:3], v[156:157] op_sel_hi:[1,0,1]
	v_pk_fma_f32 v[126:127], v[126:127], s[2:3], v[94:95] op_sel_hi:[1,0,1]
	v_pk_mul_f32 v[146:147], v[110:111], v[110:111]
	v_pk_mul_f32 v[94:95], v[126:127], v[126:127]
	v_pk_mov_b32 v[146:147], v[156:157], v[146:147] op_sel:[1,0]
	v_pk_mov_b32 v[94:95], v[160:161], v[94:95] op_sel:[1,0]
	v_add_f32_e32 v78, 0, v79
	v_pk_add_f32 v[94:95], v[146:147], v[94:95]
	v_pk_add_f32 v[146:147], v[110:111], v[126:127]
	v_pk_mul_f32 v[156:157], v[110:111], v[126:127]
	v_fmac_f32_e32 v78, 0x3fd744fd, v149
	v_mov_b32_e32 v147, v157
	v_pk_add_f32 v[94:95], v[146:147], v[94:95]
	v_mul_f32_e32 v79, v78, v78
	v_pk_add_f32 v[94:95], v[94:95], v[78:79]
	s_nop 1
	v_mov_b32_dpp v146, v94 quad_perm:[1,0,3,2] row_mask:0xf bank_mask:0xf bound_ctrl:1
	v_mov_b32_dpp v147, v95 quad_perm:[1,0,3,2] row_mask:0xf bank_mask:0xf bound_ctrl:1
	v_pk_add_f32 v[94:95], v[94:95], v[146:147]
	s_nop 1
	v_mov_b32_dpp v146, v94 quad_perm:[2,3,0,1] row_mask:0xf bank_mask:0xf bound_ctrl:1
	v_mov_b32_dpp v147, v95 quad_perm:[2,3,0,1] row_mask:0xf bank_mask:0xf bound_ctrl:1
	v_pk_add_f32 v[94:95], v[94:95], v[146:147]
	s_nop 1
	v_mov_b32_dpp v146, v94 row_half_mirror row_mask:0xf bank_mask:0xf bound_ctrl:1
	v_mov_b32_dpp v147, v95 row_half_mirror row_mask:0xf bank_mask:0xf bound_ctrl:1
	v_pk_add_f32 v[94:95], v[94:95], v[146:147]
	s_nop 1
	v_mov_b32_dpp v146, v94 row_mirror row_mask:0xf bank_mask:0xf bound_ctrl:1
	v_mov_b32_dpp v147, v95 row_mirror row_mask:0xf bank_mask:0xf bound_ctrl:1
	s_and_saveexec_b64 s[6:7], vcc
	v_pk_add_f32 v[94:95], v[94:95], v[146:147]
	ds_write_b64 v181, v[94:95] offset:200
	s_or_b64 exec, exec, s[6:7]
	v_or_b32_e32 v79, 0x1400, v154
	v_add_u32_e32 v79, v105, v79
	ds_read2_b32 v[146:147], v79 offset1:32
	ds_read2_b32 v[154:155], v79 offset0:64 offset1:96
	v_mov_b32_e32 v148, v128
	v_mov_b32_e32 v149, v96
	v_pk_add_f32 v[156:157], v[148:149], 0 op_sel_hi:[1,0]
	v_mov_b32_e32 v148, v112
	v_pk_add_f32 v[148:149], v[148:149], 0 op_sel_hi:[1,0]
	s_waitcnt lgkmcnt(1)
;   DI void xpass(int ps, int grow0, int gcol0, int lane, int w, char* lds) const {
;     char* xs = lds + (ps & 1) * 65536 + __builtin_amdgcn_readfirstlane(w) * 8192;
;     const float* xsrc = Xin + (size_t)(grow0 + (ps >> 1) * 32 + (ps & 1) * 16 + (lane >> 5)) * D_ + gcol0 + (lane & 31) * 4;
; #pragma unroll
;     for (int pc = 0; pc < 8; ++pc)
;       __builtin_amdgcn_global_load_lds((const unsigned*)(xsrc + (size_t)(2 * pc) * D_), (__attribute__((address_space(3))) unsigned*)(xs + pc * 1024), 16, 0, 0);
;   }
;   DI void operator()(f32x16 (&acc)[2][4], int grow0, int gcol0, int lane, int w, char* lds) {
;     ...
;     for (int ps = 0; ps < 4; ++ps) {
;       const int mt = ps >> 1;
;       if (ps + 1 < 4) {
;         if (ps >= 1) asm volatile("s_waitcnt lgkmcnt(0)" ::: "memory");
;         xpass(ps + 1, grow0, gcol0, lane, w, lds);
;         if (ps >= 1) asm volatile("s_waitcnt vmcnt(8)" ::: "memory");
;       } else asm volatile("s_waitcnt vmcnt(0)" ::: "memory");
;       const char* xs = lds + (ps & 1) * 65536 + w * 8192;
; #pragma unroll
;       for (int qq = 0; qq < 2; ++qq)
; #pragma unroll
;         for (int e = 0; e < 4; ++e) {
;           const int i = 4 * (2 * (ps & 1) + qq) + e;
;           const float* xr = (const float*)(xs + (8 * qq + 4 * hh + e) * 512) + l31;
;           float s1 = 0.f, s2 = 0.f;
; #pragma unroll
;           for (int nt = 0; nt < 4; ++nt) {
;             float v = (acc[mt][nt][i] + bia[nt]) * csc[nt];
;             float z = ALPHA * xr[nt * 32] + hs * v;
;             acc[mt][nt][i] = z; s1 += z; s2 += z * z;
;           }
;           s1 = row16_sum(s1); s2 = row16_sum(s2);
;           if ((lane & 15) == 0) { f32x2 sv = {s1, s2}; *(f32x2*)(redw + (mt * 32 + (i & 3) + 8 * (i >> 2)) * 2) = sv; }
;         }
	v_mov_b32_e32 v160, v146
	s_waitcnt lgkmcnt(0)
	v_mov_b32_e32 v161, v154
	s_mov_b32 s2, s67
	v_mov_b32_e32 v174, v147
	v_mov_b32_e32 v175, v154
	v_pk_fma_f32 v[146:147], v[160:161], s[2:3], v[156:157] op_sel_hi:[1,0,1]
	v_pk_fma_f32 v[148:149], v[174:175], s[2:3], v[148:149] op_sel_hi:[1,0,1]
	v_pk_mul_f32 v[170:171], v[160:161], s[2:3] op_sel_hi:[1,0]
	v_pk_mul_f32 v[160:161], v[146:147], v[146:147]
	v_pk_mul_f32 v[174:175], v[148:149], v[148:149]
	v_pk_mov_b32 v[156:157], v[156:157], v[160:161] op_sel:[1,0]
	v_pk_mov_b32 v[160:161], v[170:171], v[174:175] op_sel:[1,0]
	v_add_f32_e32 v94, 0, v80
	v_pk_add_f32 v[156:157], v[156:157], v[160:161]
	v_pk_add_f32 v[160:161], v[146:147], v[148:149]
	v_pk_mul_f32 v[170:171], v[146:147], v[148:149]
	v_fmac_f32_e32 v94, 0x3fd744fd, v155
	v_mov_b32_e32 v161, v171
	v_pk_add_f32 v[156:157], v[160:161], v[156:157]
	v_mul_f32_e32 v95, v94, v94
	v_pk_add_f32 v[154:155], v[156:157], v[94:95]
	s_nop 1
	v_mov_b32_dpp v156, v154 quad_perm:[1,0,3,2] row_mask:0xf bank_mask:0xf bound_ctrl:1
	v_mov_b32_dpp v157, v155 quad_perm:[1,0,3,2] row_mask:0xf bank_mask:0xf bound_ctrl:1
	v_pk_add_f32 v[154:155], v[154:155], v[156:157]
	s_nop 1
	v_mov_b32_dpp v156, v154 quad_perm:[2,3,0,1] row_mask:0xf bank_mask:0xf bound_ctrl:1
	v_mov_b32_dpp v157, v155 quad_perm:[2,3,0,1] row_mask:0xf bank_mask:0xf bound_ctrl:1
	v_pk_add_f32 v[154:155], v[154:155], v[156:157]
	s_nop 1
	v_mov_b32_dpp v156, v154 row_half_mirror row_mask:0xf bank_mask:0xf bound_ctrl:1
	v_mov_b32_dpp v157, v155 row_half_mirror row_mask:0xf bank_mask:0xf bound_ctrl:1
	v_pk_add_f32 v[154:155], v[154:155], v[156:157]
	s_nop 1
	v_mov_b32_dpp v156, v154 row_mirror row_mask:0xf bank_mask:0xf bound_ctrl:1
	v_mov_b32_dpp v157, v155 row_mirror row_mask:0xf bank_mask:0xf bound_ctrl:1
	s_and_saveexec_b64 s[6:7], vcc
	v_pk_add_f32 v[154:155], v[154:155], v[156:157]
	ds_write_b64 v181, v[154:155] offset:208
	s_or_b64 exec, exec, s[6:7]
	v_add_u32_e32 v93, v105, v101
	ds_read2_b32 v[154:155], v93 offset1:32
	ds_read2_b32 v[156:157], v93 offset0:64 offset1:96
	v_mov_b32_e32 v96, v129
	v_pk_add_f32 v[128:129], v[96:97], 0 op_sel_hi:[1,0]
	v_mov_b32_e32 v96, v113
	v_pk_add_f32 v[112:113], v[96:97], 0 op_sel_hi:[1,0]
	s_waitcnt lgkmcnt(1)
	v_mov_b32_e32 v96, v154
	s_waitcnt lgkmcnt(0)
	v_mov_b32_e32 v97, v156
	s_mov_b32 s2, s67
	v_mov_b32_e32 v154, v155
	v_mov_b32_e32 v155, v156
	v_pk_mul_f32 v[160:161], v[96:97], s[2:3] op_sel_hi:[1,0]
	v_pk_fma_f32 v[96:97], v[96:97], s[2:3], v[128:129] op_sel_hi:[1,0,1]
	v_pk_fma_f32 v[112:113], v[154:155], s[2:3], v[112:113] op_sel_hi:[1,0,1]
	v_pk_mul_f32 v[170:171], v[96:97], v[96:97]
	v_pk_mul_f32 v[154:155], v[112:113], v[112:113]
	v_pk_mov_b32 v[128:129], v[128:129], v[170:171] op_sel:[1,0]
	v_pk_mov_b32 v[154:155], v[160:161], v[154:155] op_sel:[1,0]
	v_add_f32_e32 v80, 0, v81
	v_pk_add_f32 v[128:129], v[128:129], v[154:155]
	v_pk_add_f32 v[154:155], v[96:97], v[112:113]
	v_pk_mul_f32 v[160:161], v[96:97], v[112:113]
	v_fmac_f32_e32 v80, 0x3fd744fd, v157
	v_mov_b32_e32 v155, v161
	v_pk_add_f32 v[128:129], v[154:155], v[128:129]
	v_mul_f32_e32 v81, v80, v80
	v_pk_add_f32 v[128:129], v[128:129], v[80:81]
	s_nop 1
	v_mov_b32_dpp v154, v128 quad_perm:[1,0,3,2] row_mask:0xf bank_mask:0xf bound_ctrl:1
	v_mov_b32_dpp v155, v129 quad_perm:[1,0,3,2] row_mask:0xf bank_mask:0xf bound_ctrl:1
	v_pk_add_f32 v[128:129], v[128:129], v[154:155]
	s_nop 1
	v_mov_b32_dpp v154, v128 quad_perm:[2,3,0,1] row_mask:0xf bank_mask:0xf bound_ctrl:1
	v_mov_b32_dpp v155, v129 quad_perm:[2,3,0,1] row_mask:0xf bank_mask:0xf bound_ctrl:1
	v_pk_add_f32 v[128:129], v[128:129], v[154:155]
	s_nop 1
	v_mov_b32_dpp v154, v128 row_half_mirror row_mask:0xf bank_mask:0xf bound_ctrl:1
	v_mov_b32_dpp v155, v129 row_half_mirror row_mask:0xf bank_mask:0xf bound_ctrl:1
	v_pk_add_f32 v[128:129], v[128:129], v[154:155]
	s_nop 1
	v_mov_b32_dpp v154, v128 row_mirror row_mask:0xf bank_mask:0xf bound_ctrl:1
	v_mov_b32_dpp v155, v129 row_mirror row_mask:0xf bank_mask:0xf bound_ctrl:1
	s_and_saveexec_b64 s[6:7], vcc
	v_pk_add_f32 v[128:129], v[128:129], v[154:155]
	ds_write_b64 v181, v[128:129] offset:216
	s_or_b64 exec, exec, s[6:7]
	v_or_b32_e32 v128, 48, v159
	v_ashrrev_i32_e32 v129, 31, v128
	v_lshlrev_b64 v[128:129], 12, v[128:129]
	v_readfirstlane_b32 s2, v158
	v_lshl_add_u64 v[128:129], s[10:11], 0, v[128:129]
	s_lshl_b32 s2, s2, 13
	v_lshl_add_u64 v[128:129], v[184:185], 2, v[128:129]
	s_waitcnt lgkmcnt(0)
	s_add_i32 m0, s2, 0x10000
	v_lshl_add_u64 v[128:129], v[128:129], 0, v[0:1]
	s_mov_b64 s[6:7], 0x2000
	global_load_lds_dwordx4 v[128:129], off
	v_lshl_add_u64 v[154:155], v[128:129], 0, s[6:7]
	s_add_i32 m0, s2, 0x10400
	s_mov_b64 s[6:7], 0x4000
	global_load_lds_dwordx4 v[154:155], off
	v_lshl_add_u64 v[154:155], v[128:129], 0, s[6:7]
	s_add_i32 m0, s2, 0x10800
	s_mov_b64 s[6:7], 0x6000
	global_load_lds_dwordx4 v[154:155], off
	v_lshl_add_u64 v[154:155], v[128:129], 0, s[6:7]
	s_add_i32 m0, s2, 0x10c00
	s_mov_b64 s[6:7], 0x8000
	global_load_lds_dwordx4 v[154:155], off
	v_lshl_add_u64 v[154:155], v[128:129], 0, s[6:7]
	s_add_i32 m0, s2, 0x11000
	s_mov_b64 s[6:7], 0xa000
	global_load_lds_dwordx4 v[154:155], off
	v_lshl_add_u64 v[154:155], v[128:129], 0, s[6:7]
	s_add_i32 m0, s2, 0x11400
	s_mov_b64 s[6:7], 0xc000
	global_load_lds_dwordx4 v[154:155], off
	v_lshl_add_u64 v[154:155], v[128:129], 0, s[6:7]
	s_add_i32 m0, s2, 0x11800
	s_mov_b64 s[6:7], 0xe000
	global_load_lds_dwordx4 v[154:155], off
	v_lshl_add_u64 v[128:129], v[128:129], 0, s[6:7]
	s_add_i32 m0, s2, 0x11c00
	v_mov_b32_e32 v156, v50
	global_load_lds_dwordx4 v[128:129], off
	s_waitcnt vmcnt(8)
;   DI void operator()(f32x16 (&acc)[2][4], int grow0, int gcol0, int lane, int w, char* lds) {
;     ...
; #pragma unroll
;       for (int qq = 0; qq < 2; ++qq)
; #pragma unroll
;         for (int e = 0; e < 4; ++e) {
;           const int i = 4 * (2 * (ps & 1) + qq) + e;
;           const float* xr = (const float*)(xs + (8 * qq + 4 * hh + e) * 512) + l31;
;           float s1 = 0.f, s2 = 0.f;
; #pragma unroll
;           for (int nt = 0; nt < 4; ++nt) {
;             float v = (acc[mt][nt][i] + bia[nt]) * csc[nt];
;             float z = ALPHA * xr[nt * 32] + hs * v;
;             acc[mt][nt][i] = z; s1 += z; s2 += z * z;
;           }
;           s1 = row16_sum(s1); s2 = row16_sum(s2);
;           if ((lane & 15) == 0) { f32x2 sv = {s1, s2}; *(f32x2*)(redw + (mt * 32 + (i & 3) + 8 * (i >> 2)) * 2) = sv; }
;         }
	ds_read2_b32 v[154:155], v168 offset1:32
	ds_read2_b32 v[158:159], v168 offset0:64 offset1:96
	v_mov_b32_e32 v157, v18
	v_pk_add_f32 v[160:161], v[156:157], 0 op_sel_hi:[1,0]
	v_mov_b32_e32 v156, v34
	v_pk_add_f32 v[156:157], v[156:157], 0 op_sel_hi:[1,0]
	s_waitcnt lgkmcnt(0)
	v_mov_b32_e32 v170, v154
	v_mov_b32_e32 v171, v158
	s_mov_b32 s2, s67
	v_mov_b32_e32 v176, v155
	v_mov_b32_e32 v177, v158
	v_pk_fma_f32 v[154:155], v[170:171], s[2:3], v[160:161] op_sel_hi:[1,0,1]
	v_pk_fma_f32 v[156:157], v[176:177], s[2:3], v[156:157] op_sel_hi:[1,0,1]
	v_pk_mul_f32 v[174:175], v[170:171], s[2:3] op_sel_hi:[1,0]
	v_pk_mul_f32 v[170:171], v[154:155], v[154:155]
	v_pk_mul_f32 v[176:177], v[156:157], v[156:157]
	v_pk_mov_b32 v[160:161], v[160:161], v[170:171] op_sel:[1,0]
	v_pk_mov_b32 v[170:171], v[174:175], v[176:177] op_sel:[1,0]
	v_add_f32_e32 v128, 0, v2
	v_pk_add_f32 v[160:161], v[160:161], v[170:171]
	v_pk_add_f32 v[170:171], v[154:155], v[156:157]
	v_pk_mul_f32 v[174:175], v[154:155], v[156:157]
	v_fmac_f32_e32 v128, 0x3fd744fd, v159
	v_mov_b32_e32 v171, v175
	v_pk_add_f32 v[160:161], v[170:171], v[160:161]
	v_mul_f32_e32 v129, v128, v128
	v_pk_add_f32 v[158:159], v[160:161], v[128:129]
	s_nop 1
	v_mov_b32_dpp v160, v158 quad_perm:[1,0,3,2] row_mask:0xf bank_mask:0xf bound_ctrl:1
	v_mov_b32_dpp v161, v159 quad_perm:[1,0,3,2] row_mask:0xf bank_mask:0xf bound_ctrl:1
	v_pk_add_f32 v[158:159], v[158:159], v[160:161]
	s_nop 1
	v_mov_b32_dpp v160, v158 quad_perm:[2,3,0,1] row_mask:0xf bank_mask:0xf bound_ctrl:1
	v_mov_b32_dpp v161, v159 quad_perm:[2,3,0,1] row_mask:0xf bank_mask:0xf bound_ctrl:1
	v_pk_add_f32 v[158:159], v[158:159], v[160:161]
	s_nop 1
	v_mov_b32_dpp v160, v158 row_half_mirror row_mask:0xf bank_mask:0xf bound_ctrl:1
	v_mov_b32_dpp v161, v159 row_half_mirror row_mask:0xf bank_mask:0xf bound_ctrl:1
	v_pk_add_f32 v[158:159], v[158:159], v[160:161]
	s_nop 1
	v_mov_b32_dpp v160, v158 row_mirror row_mask:0xf bank_mask:0xf bound_ctrl:1
	v_mov_b32_dpp v161, v159 row_mirror row_mask:0xf bank_mask:0xf bound_ctrl:1
	s_and_saveexec_b64 s[6:7], vcc
	v_pk_add_f32 v[158:159], v[158:159], v[160:161]
	ds_write_b64 v181, v[158:159] offset:256
	s_or_b64 exec, exec, s[6:7]
	ds_read2_b32 v[158:159], v168 offset0:128 offset1:160
	ds_read2_b32 v[160:161], v168 offset0:192 offset1:224
	v_mov_b32_e32 v18, v51
	v_pk_add_f32 v[168:169], v[18:19], 0 op_sel_hi:[1,0]
	v_mov_b32_e32 v18, v35
	v_pk_add_f32 v[18:19], v[18:19], 0 op_sel_hi:[1,0]
	s_waitcnt lgkmcnt(1)
	v_mov_b32_e32 v34, v158
	s_waitcnt lgkmcnt(0)
	v_mov_b32_e32 v35, v160
	s_mov_b32 s2, s67
	v_mov_b32_e32 v50, v159
	v_mov_b32_e32 v51, v160
	v_pk_mul_f32 v[170:171], v[34:35], s[2:3] op_sel_hi:[1,0]
	v_pk_fma_f32 v[34:35], v[34:35], s[2:3], v[168:169] op_sel_hi:[1,0,1]
	v_pk_fma_f32 v[50:51], v[50:51], s[2:3], v[18:19] op_sel_hi:[1,0,1]
	v_pk_mul_f32 v[158:159], v[34:35], v[34:35]
	v_pk_mul_f32 v[18:19], v[50:51], v[50:51]
	v_pk_mov_b32 v[158:159], v[168:169], v[158:159] op_sel:[1,0]
	v_pk_mov_b32 v[18:19], v[170:171], v[18:19] op_sel:[1,0]
	v_add_f32_e32 v2, 0, v3
	v_pk_add_f32 v[18:19], v[158:159], v[18:19]
	v_pk_add_f32 v[158:159], v[34:35], v[50:51]
	v_pk_mul_f32 v[168:169], v[34:35], v[50:51]
	v_fmac_f32_e32 v2, 0x3fd744fd, v161
	v_mov_b32_e32 v159, v169
	v_pk_add_f32 v[18:19], v[158:159], v[18:19]
	v_mul_f32_e32 v3, v2, v2
	v_pk_add_f32 v[18:19], v[18:19], v[2:3]
	s_nop 1
	v_mov_b32_dpp v158, v18 quad_perm:[1,0,3,2] row_mask:0xf bank_mask:0xf bound_ctrl:1
	v_mov_b32_dpp v159, v19 quad_perm:[1,0,3,2] row_mask:0xf bank_mask:0xf bound_ctrl:1
	v_pk_add_f32 v[18:19], v[18:19], v[158:159]
	s_nop 1
	v_mov_b32_dpp v158, v18 quad_perm:[2,3,0,1] row_mask:0xf bank_mask:0xf bound_ctrl:1
	v_mov_b32_dpp v159, v19 quad_perm:[2,3,0,1] row_mask:0xf bank_mask:0xf bound_ctrl:1
	v_pk_add_f32 v[18:19], v[18:19], v[158:159]
	s_nop 1
	v_mov_b32_dpp v158, v18 row_half_mirror row_mask:0xf bank_mask:0xf bound_ctrl:1
	v_mov_b32_dpp v159, v19 row_half_mirror row_mask:0xf bank_mask:0xf bound_ctrl:1
	v_pk_add_f32 v[18:19], v[18:19], v[158:159]
	s_nop 1
	v_mov_b32_dpp v158, v18 row_mirror row_mask:0xf bank_mask:0xf bound_ctrl:1
	v_mov_b32_dpp v159, v19 row_mirror row_mask:0xf bank_mask:0xf bound_ctrl:1
	s_and_saveexec_b64 s[6:7], vcc
	v_pk_add_f32 v[18:19], v[18:19], v[158:159]
	ds_write_b64 v181, v[18:19] offset:264
	s_or_b64 exec, exec, s[6:7]
	ds_read2_b32 v[158:159], v153 offset1:32
	ds_read2_b32 v[168:169], v153 offset0:64 offset1:96
	v_mov_b32_e32 v160, v52
	v_mov_b32_e32 v161, v20
	v_pk_add_f32 v[170:171], v[160:161], 0 op_sel_hi:[1,0]
	v_mov_b32_e32 v160, v36
	v_pk_add_f32 v[160:161], v[160:161], 0 op_sel_hi:[1,0]
	s_waitcnt lgkmcnt(1)
	v_mov_b32_e32 v174, v158
	s_waitcnt lgkmcnt(0)
;   DI void operator()(f32x16 (&acc)[2][4], int grow0, int gcol0, int lane, int w, char* lds) {
;     ...
; #pragma unroll
;       for (int qq = 0; qq < 2; ++qq)
; #pragma unroll
;         for (int e = 0; e < 4; ++e) {
;           const int i = 4 * (2 * (ps & 1) + qq) + e;
;           const float* xr = (const float*)(xs + (8 * qq + 4 * hh + e) * 512) + l31;
;           float s1 = 0.f, s2 = 0.f;
; #pragma unroll
;           for (int nt = 0; nt < 4; ++nt) {
;             float v = (acc[mt][nt][i] + bia[nt]) * csc[nt];
;             float z = ALPHA * xr[nt * 32] + hs * v;
;             acc[mt][nt][i] = z; s1 += z; s2 += z * z;
;           }
;           s1 = row16_sum(s1); s2 = row16_sum(s2);
;           if ((lane & 15) == 0) { f32x2 sv = {s1, s2}; *(f32x2*)(redw + (mt * 32 + (i & 3) + 8 * (i >> 2)) * 2) = sv; }
;         }
	v_mov_b32_e32 v175, v168
	s_mov_b32 s2, s67
	v_mov_b32_e32 v178, v159
	v_mov_b32_e32 v179, v168
	v_pk_fma_f32 v[158:159], v[174:175], s[2:3], v[170:171] op_sel_hi:[1,0,1]
	v_pk_fma_f32 v[160:161], v[178:179], s[2:3], v[160:161] op_sel_hi:[1,0,1]
	v_pk_mul_f32 v[176:177], v[174:175], s[2:3] op_sel_hi:[1,0]
	v_pk_mul_f32 v[174:175], v[158:159], v[158:159]
	v_pk_mul_f32 v[178:179], v[160:161], v[160:161]
	v_pk_mov_b32 v[170:171], v[170:171], v[174:175] op_sel:[1,0]
	v_pk_mov_b32 v[174:175], v[176:177], v[178:179] op_sel:[1,0]
	v_add_f32_e32 v18, 0, v4
	v_pk_add_f32 v[170:171], v[170:171], v[174:175]
	v_pk_add_f32 v[174:175], v[158:159], v[160:161]
	v_pk_mul_f32 v[176:177], v[158:159], v[160:161]
	v_fmac_f32_e32 v18, 0x3fd744fd, v169
	v_mov_b32_e32 v175, v177
	v_pk_add_f32 v[170:171], v[174:175], v[170:171]
	v_mul_f32_e32 v19, v18, v18
	v_pk_add_f32 v[168:169], v[170:171], v[18:19]
	s_nop 1
	v_mov_b32_dpp v170, v168 quad_perm:[1,0,3,2] row_mask:0xf bank_mask:0xf bound_ctrl:1
	v_mov_b32_dpp v171, v169 quad_perm:[1,0,3,2] row_mask:0xf bank_mask:0xf bound_ctrl:1
	v_pk_add_f32 v[168:169], v[168:169], v[170:171]
	s_nop 1
	v_mov_b32_dpp v170, v168 quad_perm:[2,3,0,1] row_mask:0xf bank_mask:0xf bound_ctrl:1
	v_mov_b32_dpp v171, v169 quad_perm:[2,3,0,1] row_mask:0xf bank_mask:0xf bound_ctrl:1
	v_pk_add_f32 v[168:169], v[168:169], v[170:171]
	s_nop 1
	v_mov_b32_dpp v170, v168 row_half_mirror row_mask:0xf bank_mask:0xf bound_ctrl:1
	v_mov_b32_dpp v171, v169 row_half_mirror row_mask:0xf bank_mask:0xf bound_ctrl:1
	v_pk_add_f32 v[168:169], v[168:169], v[170:171]
	s_nop 1
	v_mov_b32_dpp v170, v168 row_mirror row_mask:0xf bank_mask:0xf bound_ctrl:1
	v_mov_b32_dpp v171, v169 row_mirror row_mask:0xf bank_mask:0xf bound_ctrl:1
	s_and_saveexec_b64 s[6:7], vcc
	v_pk_add_f32 v[168:169], v[168:169], v[170:171]
	ds_write_b64 v181, v[168:169] offset:272
	s_or_b64 exec, exec, s[6:7]
	ds_read2_b32 v[168:169], v151 offset1:32
	ds_read2_b32 v[170:171], v151 offset0:64 offset1:96
	v_mov_b32_e32 v20, v53
	v_pk_add_f32 v[174:175], v[20:21], 0 op_sel_hi:[1,0]
	v_mov_b32_e32 v20, v37
	v_pk_add_f32 v[20:21], v[20:21], 0 op_sel_hi:[1,0]
	s_waitcnt lgkmcnt(1)
	v_mov_b32_e32 v36, v168
	s_waitcnt lgkmcnt(0)
	v_mov_b32_e32 v37, v170
	s_mov_b32 s2, s67
	v_mov_b32_e32 v52, v169
	v_mov_b32_e32 v53, v170
	v_pk_mul_f32 v[176:177], v[36:37], s[2:3] op_sel_hi:[1,0]
	v_pk_fma_f32 v[36:37], v[36:37], s[2:3], v[174:175] op_sel_hi:[1,0,1]
	v_pk_fma_f32 v[52:53], v[52:53], s[2:3], v[20:21] op_sel_hi:[1,0,1]
	v_pk_mul_f32 v[168:169], v[36:37], v[36:37]
	v_pk_mul_f32 v[20:21], v[52:53], v[52:53]
	v_pk_mov_b32 v[168:169], v[174:175], v[168:169] op_sel:[1,0]
	v_pk_mov_b32 v[20:21], v[176:177], v[20:21] op_sel:[1,0]
	v_add_f32_e32 v4, 0, v5
	v_pk_add_f32 v[20:21], v[168:169], v[20:21]
	v_pk_add_f32 v[168:169], v[36:37], v[52:53]
	v_pk_mul_f32 v[174:175], v[36:37], v[52:53]
	v_fmac_f32_e32 v4, 0x3fd744fd, v171
	v_mov_b32_e32 v169, v175
	v_pk_add_f32 v[20:21], v[168:169], v[20:21]
	v_mul_f32_e32 v5, v4, v4
	v_pk_add_f32 v[20:21], v[20:21], v[4:5]
	s_nop 1
	v_mov_b32_dpp v168, v20 quad_perm:[1,0,3,2] row_mask:0xf bank_mask:0xf bound_ctrl:1
	v_mov_b32_dpp v169, v21 quad_perm:[1,0,3,2] row_mask:0xf bank_mask:0xf bound_ctrl:1
	v_pk_add_f32 v[20:21], v[20:21], v[168:169]
	s_nop 1
	v_mov_b32_dpp v168, v20 quad_perm:[2,3,0,1] row_mask:0xf bank_mask:0xf bound_ctrl:1
	v_mov_b32_dpp v169, v21 quad_perm:[2,3,0,1] row_mask:0xf bank_mask:0xf bound_ctrl:1
	v_pk_add_f32 v[20:21], v[20:21], v[168:169]
	s_nop 1
	v_mov_b32_dpp v168, v20 row_half_mirror row_mask:0xf bank_mask:0xf bound_ctrl:1
	v_mov_b32_dpp v169, v21 row_half_mirror row_mask:0xf bank_mask:0xf bound_ctrl:1
	v_pk_add_f32 v[20:21], v[20:21], v[168:169]
	s_nop 1
	v_mov_b32_dpp v168, v20 row_mirror row_mask:0xf bank_mask:0xf bound_ctrl:1
	v_mov_b32_dpp v169, v21 row_mirror row_mask:0xf bank_mask:0xf bound_ctrl:1
	s_and_saveexec_b64 s[6:7], vcc
	v_pk_add_f32 v[20:21], v[20:21], v[168:169]
	ds_write_b64 v181, v[20:21] offset:280
	s_or_b64 exec, exec, s[6:7]
	ds_read2_b32 v[168:169], v67 offset1:32
	ds_read2_b32 v[174:175], v67 offset0:64 offset1:96
	v_mov_b32_e32 v170, v54
	v_mov_b32_e32 v171, v22
	v_pk_add_f32 v[176:177], v[170:171], 0 op_sel_hi:[1,0]
	v_mov_b32_e32 v170, v38
	v_pk_add_f32 v[170:171], v[170:171], 0 op_sel_hi:[1,0]
	s_waitcnt lgkmcnt(1)
	v_mov_b32_e32 v178, v168
	s_waitcnt lgkmcnt(0)
	v_mov_b32_e32 v179, v174
	s_mov_b32 s2, s67
	v_mov_b32_e32 v190, v169
	v_mov_b32_e32 v191, v174
	v_pk_fma_f32 v[168:169], v[178:179], s[2:3], v[176:177] op_sel_hi:[1,0,1]
	v_pk_fma_f32 v[170:171], v[190:191], s[2:3], v[170:171] op_sel_hi:[1,0,1]
	v_pk_mul_f32 v[182:183], v[178:179], s[2:3] op_sel_hi:[1,0]
	v_pk_mul_f32 v[178:179], v[168:169], v[168:169]
	v_pk_mul_f32 v[190:191], v[170:171], v[170:171]
	v_pk_mov_b32 v[176:177], v[176:177], v[178:179] op_sel:[1,0]
	v_pk_mov_b32 v[178:179], v[182:183], v[190:191] op_sel:[1,0]
	v_add_f32_e32 v20, 0, v6
	v_pk_add_f32 v[176:177], v[176:177], v[178:179]
	v_pk_add_f32 v[178:179], v[168:169], v[170:171]
	v_pk_mul_f32 v[182:183], v[168:169], v[170:171]
	v_fmac_f32_e32 v20, 0x3fd744fd, v175
	v_mov_b32_e32 v179, v183
	v_pk_add_f32 v[176:177], v[178:179], v[176:177]
	v_mul_f32_e32 v21, v20, v20
	v_pk_add_f32 v[174:175], v[176:177], v[20:21]
	s_nop 1
	v_mov_b32_dpp v176, v174 quad_perm:[1,0,3,2] row_mask:0xf bank_mask:0xf bound_ctrl:1
	v_mov_b32_dpp v177, v175 quad_perm:[1,0,3,2] row_mask:0xf bank_mask:0xf bound_ctrl:1
	v_pk_add_f32 v[174:175], v[174:175], v[176:177]
	s_nop 1
	v_mov_b32_dpp v176, v174 quad_perm:[2,3,0,1] row_mask:0xf bank_mask:0xf bound_ctrl:1
	v_mov_b32_dpp v177, v175 quad_perm:[2,3,0,1] row_mask:0xf bank_mask:0xf bound_ctrl:1
	v_pk_add_f32 v[174:175], v[174:175], v[176:177]
	s_nop 1
	v_mov_b32_dpp v176, v174 row_half_mirror row_mask:0xf bank_mask:0xf bound_ctrl:1
	v_mov_b32_dpp v177, v175 row_half_mirror row_mask:0xf bank_mask:0xf bound_ctrl:1
	v_pk_add_f32 v[174:175], v[174:175], v[176:177]
	s_nop 1
	v_mov_b32_dpp v176, v174 row_mirror row_mask:0xf bank_mask:0xf bound_ctrl:1
	v_mov_b32_dpp v177, v175 row_mirror row_mask:0xf bank_mask:0xf bound_ctrl:1
	s_and_saveexec_b64 s[6:7], vcc
	v_pk_add_f32 v[174:175], v[174:175], v[176:177]
	ds_write_b64 v181, v[174:175] offset:320
	s_or_b64 exec, exec, s[6:7]
	ds_read2_b32 v[174:175], v67 offset0:128 offset1:160
	ds_read2_b32 v[176:177], v67 offset0:192 offset1:224
	v_mov_b32_e32 v22, v55
	v_pk_add_f32 v[178:179], v[22:23], 0 op_sel_hi:[1,0]
	v_mov_b32_e32 v22, v39
	v_pk_add_f32 v[22:23], v[22:23], 0 op_sel_hi:[1,0]
	s_waitcnt lgkmcnt(1)
;   DI void operator()(f32x16 (&acc)[2][4], int grow0, int gcol0, int lane, int w, char* lds) {
;     ...
; #pragma unroll
;       for (int qq = 0; qq < 2; ++qq)
; #pragma unroll
;         for (int e = 0; e < 4; ++e) {
;           const int i = 4 * (2 * (ps & 1) + qq) + e;
;           const float* xr = (const float*)(xs + (8 * qq + 4 * hh + e) * 512) + l31;
;           float s1 = 0.f, s2 = 0.f;
; #pragma unroll
;           for (int nt = 0; nt < 4; ++nt) {
;             float v = (acc[mt][nt][i] + bia[nt]) * csc[nt];
;             float z = ALPHA * xr[nt * 32] + hs * v;
;             acc[mt][nt][i] = z; s1 += z; s2 += z * z;
;           }
;           s1 = row16_sum(s1); s2 = row16_sum(s2);
;           if ((lane & 15) == 0) { f32x2 sv = {s1, s2}; *(f32x2*)(redw + (mt * 32 + (i & 3) + 8 * (i >> 2)) * 2) = sv; }
;         }
	v_mov_b32_e32 v38, v174
	s_waitcnt lgkmcnt(0)
	v_mov_b32_e32 v39, v176
	s_mov_b32 s2, s67
	v_mov_b32_e32 v54, v175
	v_mov_b32_e32 v55, v176
	v_pk_mul_f32 v[182:183], v[38:39], s[2:3] op_sel_hi:[1,0]
	v_pk_fma_f32 v[38:39], v[38:39], s[2:3], v[178:179] op_sel_hi:[1,0,1]
	v_pk_fma_f32 v[54:55], v[54:55], s[2:3], v[22:23] op_sel_hi:[1,0,1]
	v_pk_mul_f32 v[174:175], v[38:39], v[38:39]
	v_pk_mul_f32 v[22:23], v[54:55], v[54:55]
	v_pk_mov_b32 v[174:175], v[178:179], v[174:175] op_sel:[1,0]
	v_pk_mov_b32 v[22:23], v[182:183], v[22:23] op_sel:[1,0]
	v_add_f32_e32 v6, 0, v7
	v_pk_add_f32 v[22:23], v[174:175], v[22:23]
	v_pk_add_f32 v[174:175], v[38:39], v[54:55]
	v_pk_mul_f32 v[178:179], v[38:39], v[54:55]
	v_fmac_f32_e32 v6, 0x3fd744fd, v177
	v_mov_b32_e32 v175, v179
	v_pk_add_f32 v[22:23], v[174:175], v[22:23]
	v_mul_f32_e32 v7, v6, v6
	v_pk_add_f32 v[22:23], v[22:23], v[6:7]
	s_nop 1
	v_mov_b32_dpp v174, v22 quad_perm:[1,0,3,2] row_mask:0xf bank_mask:0xf bound_ctrl:1
	v_mov_b32_dpp v175, v23 quad_perm:[1,0,3,2] row_mask:0xf bank_mask:0xf bound_ctrl:1
	v_pk_add_f32 v[22:23], v[22:23], v[174:175]
	s_nop 1
	v_mov_b32_dpp v174, v22 quad_perm:[2,3,0,1] row_mask:0xf bank_mask:0xf bound_ctrl:1
	v_mov_b32_dpp v175, v23 quad_perm:[2,3,0,1] row_mask:0xf bank_mask:0xf bound_ctrl:1
	v_pk_add_f32 v[22:23], v[22:23], v[174:175]
	s_nop 1
	v_mov_b32_dpp v174, v22 row_half_mirror row_mask:0xf bank_mask:0xf bound_ctrl:1
	v_mov_b32_dpp v175, v23 row_half_mirror row_mask:0xf bank_mask:0xf bound_ctrl:1
	v_pk_add_f32 v[22:23], v[22:23], v[174:175]
	s_nop 1
	v_mov_b32_dpp v174, v22 row_mirror row_mask:0xf bank_mask:0xf bound_ctrl:1
	v_mov_b32_dpp v175, v23 row_mirror row_mask:0xf bank_mask:0xf bound_ctrl:1
	s_and_saveexec_b64 s[6:7], vcc
	v_pk_add_f32 v[22:23], v[22:23], v[174:175]
	ds_write_b64 v181, v[22:23] offset:328
	s_or_b64 exec, exec, s[6:7]
	ds_read2_b32 v[174:175], v69 offset1:32
	ds_read2_b32 v[178:179], v69 offset0:64 offset1:96
	v_mov_b32_e32 v176, v56
	v_mov_b32_e32 v177, v24
	v_pk_add_f32 v[182:183], v[176:177], 0 op_sel_hi:[1,0]
	v_mov_b32_e32 v176, v40
	v_pk_add_f32 v[176:177], v[176:177], 0 op_sel_hi:[1,0]
	s_waitcnt lgkmcnt(1)
	v_mov_b32_e32 v190, v174
	s_waitcnt lgkmcnt(0)
	v_mov_b32_e32 v191, v178
	s_mov_b32 s2, s67
	v_mov_b32_e32 v194, v175
	v_mov_b32_e32 v195, v178
	v_pk_fma_f32 v[174:175], v[190:191], s[2:3], v[182:183] op_sel_hi:[1,0,1]
	v_pk_fma_f32 v[176:177], v[194:195], s[2:3], v[176:177] op_sel_hi:[1,0,1]
	v_pk_mul_f32 v[192:193], v[190:191], s[2:3] op_sel_hi:[1,0]
	v_pk_mul_f32 v[190:191], v[174:175], v[174:175]
	v_pk_mul_f32 v[194:195], v[176:177], v[176:177]
	v_pk_mov_b32 v[182:183], v[182:183], v[190:191] op_sel:[1,0]
	v_pk_mov_b32 v[190:191], v[192:193], v[194:195] op_sel:[1,0]
	v_add_f32_e32 v22, 0, v8
	v_pk_add_f32 v[182:183], v[182:183], v[190:191]
	v_pk_add_f32 v[190:191], v[174:175], v[176:177]
	v_pk_mul_f32 v[192:193], v[174:175], v[176:177]
	v_fmac_f32_e32 v22, 0x3fd744fd, v179
	v_mov_b32_e32 v191, v193
	v_pk_add_f32 v[182:183], v[190:191], v[182:183]
	v_mul_f32_e32 v23, v22, v22
	v_pk_add_f32 v[178:179], v[182:183], v[22:23]
	s_nop 1
	v_mov_b32_dpp v182, v178 quad_perm:[1,0,3,2] row_mask:0xf bank_mask:0xf bound_ctrl:1
	v_mov_b32_dpp v183, v179 quad_perm:[1,0,3,2] row_mask:0xf bank_mask:0xf bound_ctrl:1
	v_pk_add_f32 v[178:179], v[178:179], v[182:183]
	s_nop 1
	v_mov_b32_dpp v182, v178 quad_perm:[2,3,0,1] row_mask:0xf bank_mask:0xf bound_ctrl:1
	v_mov_b32_dpp v183, v179 quad_perm:[2,3,0,1] row_mask:0xf bank_mask:0xf bound_ctrl:1
	v_pk_add_f32 v[178:179], v[178:179], v[182:183]
	s_nop 1
	v_mov_b32_dpp v182, v178 row_half_mirror row_mask:0xf bank_mask:0xf bound_ctrl:1
	v_mov_b32_dpp v183, v179 row_half_mirror row_mask:0xf bank_mask:0xf bound_ctrl:1
	v_pk_add_f32 v[178:179], v[178:179], v[182:183]
	s_nop 1
	v_mov_b32_dpp v182, v178 row_mirror row_mask:0xf bank_mask:0xf bound_ctrl:1
	v_mov_b32_dpp v183, v179 row_mirror row_mask:0xf bank_mask:0xf bound_ctrl:1
	s_and_saveexec_b64 s[6:7], vcc
	v_pk_add_f32 v[178:179], v[178:179], v[182:183]
	ds_write_b64 v181, v[178:179] offset:336
	s_or_b64 exec, exec, s[6:7]
	ds_read2_b32 v[178:179], v71 offset1:32
	ds_read2_b32 v[182:183], v71 offset0:64 offset1:96
	v_mov_b32_e32 v24, v57
	v_pk_add_f32 v[190:191], v[24:25], 0 op_sel_hi:[1,0]
	v_mov_b32_e32 v24, v41
	v_pk_add_f32 v[24:25], v[24:25], 0 op_sel_hi:[1,0]
	s_waitcnt lgkmcnt(1)
	v_mov_b32_e32 v40, v178
	s_waitcnt lgkmcnt(0)
	v_mov_b32_e32 v41, v182
	s_mov_b32 s2, s67
	v_mov_b32_e32 v56, v179
	v_mov_b32_e32 v57, v182
	v_pk_mul_f32 v[192:193], v[40:41], s[2:3] op_sel_hi:[1,0]
	v_pk_fma_f32 v[40:41], v[40:41], s[2:3], v[190:191] op_sel_hi:[1,0,1]
	v_pk_fma_f32 v[56:57], v[56:57], s[2:3], v[24:25] op_sel_hi:[1,0,1]
	v_pk_mul_f32 v[178:179], v[40:41], v[40:41]
	v_pk_mul_f32 v[24:25], v[56:57], v[56:57]
	v_pk_mov_b32 v[178:179], v[190:191], v[178:179] op_sel:[1,0]
	v_pk_mov_b32 v[24:25], v[192:193], v[24:25] op_sel:[1,0]
	v_add_f32_e32 v8, 0, v9
	v_pk_add_f32 v[24:25], v[178:179], v[24:25]
	v_pk_add_f32 v[178:179], v[40:41], v[56:57]
	v_pk_mul_f32 v[190:191], v[40:41], v[56:57]
	v_fmac_f32_e32 v8, 0x3fd744fd, v183
	v_mov_b32_e32 v179, v191
	v_pk_add_f32 v[24:25], v[178:179], v[24:25]
	v_mul_f32_e32 v9, v8, v8
	v_pk_add_f32 v[24:25], v[24:25], v[8:9]
	s_nop 1
	v_mov_b32_dpp v178, v24 quad_perm:[1,0,3,2] row_mask:0xf bank_mask:0xf bound_ctrl:1
	v_mov_b32_dpp v179, v25 quad_perm:[1,0,3,2] row_mask:0xf bank_mask:0xf bound_ctrl:1
	v_pk_add_f32 v[24:25], v[24:25], v[178:179]
	s_nop 1
	v_mov_b32_dpp v178, v24 quad_perm:[2,3,0,1] row_mask:0xf bank_mask:0xf bound_ctrl:1
	v_mov_b32_dpp v179, v25 quad_perm:[2,3,0,1] row_mask:0xf bank_mask:0xf bound_ctrl:1
	v_pk_add_f32 v[24:25], v[24:25], v[178:179]
	s_nop 1
	v_mov_b32_dpp v178, v24 row_half_mirror row_mask:0xf bank_mask:0xf bound_ctrl:1
	v_mov_b32_dpp v179, v25 row_half_mirror row_mask:0xf bank_mask:0xf bound_ctrl:1
	v_pk_add_f32 v[24:25], v[24:25], v[178:179]
	s_nop 1
	v_mov_b32_dpp v178, v24 row_mirror row_mask:0xf bank_mask:0xf bound_ctrl:1
	v_mov_b32_dpp v179, v25 row_mirror row_mask:0xf bank_mask:0xf bound_ctrl:1
	s_and_saveexec_b64 s[6:7], vcc
	v_pk_add_f32 v[24:25], v[24:25], v[178:179]
	ds_write_b64 v181, v[24:25] offset:344
	s_or_b64 exec, exec, s[6:7]
	s_waitcnt vmcnt(0)
;   DI void operator()(f32x16 (&acc)[2][4], int grow0, int gcol0, int lane, int w, char* lds) {
;     ...
;         for (int e = 0; e < 4; ++e) {
;           const int i = 4 * (2 * (ps & 1) + qq) + e;
;           const float* xr = (const float*)(xs + (8 * qq + 4 * hh + e) * 512) + l31;
;           float s1 = 0.f, s2 = 0.f;
; #pragma unroll
;           for (int nt = 0; nt < 4; ++nt) {
;             float v = (acc[mt][nt][i] + bia[nt]) * csc[nt];
;             float z = ALPHA * xr[nt * 32] + hs * v;
;             acc[mt][nt][i] = z; s1 += z; s2 += z * z;
;           }
;           s1 = row16_sum(s1); s2 = row16_sum(s2);
;           if ((lane & 15) == 0) { f32x2 sv = {s1, s2}; *(f32x2*)(redw + (mt * 32 + (i & 3) + 8 * (i >> 2)) * 2) = sv; }
	ds_read2_b32 v[182:183], v73 offset1:32
	ds_read2_b32 v[192:193], v73 offset0:64 offset1:96
	v_add_f32_e32 v179, 0, v42
	v_mov_b32_e32 v190, v58
	v_mov_b32_e32 v191, v26
	s_waitcnt lgkmcnt(1)
	v_fmac_f32_e32 v179, 0x3fd744fd, v183
	v_pk_add_f32 v[194:195], v[190:191], 0 op_sel_hi:[1,0]
	s_waitcnt lgkmcnt(0)
	v_mov_b32_e32 v183, v192
	s_mov_b32 s2, s67
	v_pk_fma_f32 v[190:191], v[182:183], s[2:3], v[194:195] op_sel_hi:[1,0,1]
	v_mov_b32_e32 v178, v192
	v_pk_mul_f32 v[182:183], v[190:191], v[190:191]
	v_mov_b32_e32 v196, v165
	v_mov_b32_e32 v197, v179
	v_pk_mov_b32 v[182:183], v[194:195], v[182:183] op_sel:[1,0]
	v_add_f32_e32 v24, 0, v10
	v_pk_fma_f32 v[182:183], v[178:179], v[196:197], v[182:183]
	v_fmac_f32_e32 v24, 0x3fd744fd, v193
	v_pk_mov_b32 v[194:195], v[178:179], v[182:183] op_sel:[1,0]
	v_mul_f32_e32 v25, v24, v24
	v_pk_add_f32 v[196:197], v[190:191], v[194:195]
	v_pk_mul_f32 v[194:195], v[190:191], v[194:195]
	s_nop 0
	v_mov_b32_e32 v197, v195
	v_pk_add_f32 v[194:195], v[182:183], v[196:197]
	s_nop 0
	v_pk_add_f32 v[192:193], v[194:195], v[24:25]
	s_nop 1
	v_mov_b32_dpp v194, v192 quad_perm:[1,0,3,2] row_mask:0xf bank_mask:0xf bound_ctrl:1
	v_mov_b32_dpp v195, v193 quad_perm:[1,0,3,2] row_mask:0xf bank_mask:0xf bound_ctrl:1
	v_pk_add_f32 v[192:193], v[192:193], v[194:195]
	s_nop 1
	v_mov_b32_dpp v194, v192 quad_perm:[2,3,0,1] row_mask:0xf bank_mask:0xf bound_ctrl:1
	v_mov_b32_dpp v195, v193 quad_perm:[2,3,0,1] row_mask:0xf bank_mask:0xf bound_ctrl:1
	v_pk_add_f32 v[192:193], v[192:193], v[194:195]
	s_nop 1
	v_mov_b32_dpp v194, v192 row_half_mirror row_mask:0xf bank_mask:0xf bound_ctrl:1
	v_mov_b32_dpp v195, v193 row_half_mirror row_mask:0xf bank_mask:0xf bound_ctrl:1
	v_pk_add_f32 v[192:193], v[192:193], v[194:195]
	s_nop 1
	v_mov_b32_dpp v194, v192 row_mirror row_mask:0xf bank_mask:0xf bound_ctrl:1
	v_mov_b32_dpp v195, v193 row_mirror row_mask:0xf bank_mask:0xf bound_ctrl:1
	s_and_saveexec_b64 s[6:7], vcc
	v_pk_add_f32 v[192:193], v[192:193], v[194:195]
	ds_write_b64 v181, v[192:193] offset:384
	s_or_b64 exec, exec, s[6:7]
	ds_read2_b32 v[192:193], v85 offset1:32
	ds_read2_b32 v[194:195], v85 offset0:64 offset1:96
	v_mov_b32_e32 v26, v59
	v_pk_add_f32 v[196:197], v[26:27], 0 op_sel_hi:[1,0]
	v_mov_b32_e32 v26, v43
	v_pk_add_f32 v[26:27], v[26:27], 0 op_sel_hi:[1,0]
	s_waitcnt lgkmcnt(1)
	v_mov_b32_e32 v42, v192
	s_waitcnt lgkmcnt(0)
	v_mov_b32_e32 v43, v194
	s_mov_b32 s2, s67
	v_mov_b32_e32 v58, v193
	v_mov_b32_e32 v59, v194
	v_pk_mul_f32 v[198:199], v[42:43], s[2:3] op_sel_hi:[1,0]
	v_pk_fma_f32 v[42:43], v[42:43], s[2:3], v[196:197] op_sel_hi:[1,0,1]
	v_pk_fma_f32 v[58:59], v[58:59], s[2:3], v[26:27] op_sel_hi:[1,0,1]
	v_pk_mul_f32 v[192:193], v[42:43], v[42:43]
	v_pk_mul_f32 v[26:27], v[58:59], v[58:59]
	v_pk_mov_b32 v[192:193], v[196:197], v[192:193] op_sel:[1,0]
	v_pk_mov_b32 v[26:27], v[198:199], v[26:27] op_sel:[1,0]
	v_add_f32_e32 v10, 0, v11
	v_pk_add_f32 v[26:27], v[192:193], v[26:27]
	v_pk_add_f32 v[192:193], v[42:43], v[58:59]
	v_pk_mul_f32 v[196:197], v[42:43], v[58:59]
	v_fmac_f32_e32 v10, 0x3fd744fd, v195
	v_mov_b32_e32 v193, v197
	v_pk_add_f32 v[26:27], v[192:193], v[26:27]
	v_mul_f32_e32 v11, v10, v10
	v_pk_add_f32 v[26:27], v[26:27], v[10:11]
	s_nop 1
	v_mov_b32_dpp v192, v26 quad_perm:[1,0,3,2] row_mask:0xf bank_mask:0xf bound_ctrl:1
	v_mov_b32_dpp v193, v27 quad_perm:[1,0,3,2] row_mask:0xf bank_mask:0xf bound_ctrl:1
	v_pk_add_f32 v[26:27], v[26:27], v[192:193]
	s_nop 1
	v_mov_b32_dpp v192, v26 quad_perm:[2,3,0,1] row_mask:0xf bank_mask:0xf bound_ctrl:1
	v_mov_b32_dpp v193, v27 quad_perm:[2,3,0,1] row_mask:0xf bank_mask:0xf bound_ctrl:1
	v_pk_add_f32 v[26:27], v[26:27], v[192:193]
	s_nop 1
	v_mov_b32_dpp v192, v26 row_half_mirror row_mask:0xf bank_mask:0xf bound_ctrl:1
	v_mov_b32_dpp v193, v27 row_half_mirror row_mask:0xf bank_mask:0xf bound_ctrl:1
	v_pk_add_f32 v[26:27], v[26:27], v[192:193]
	s_nop 1
	v_mov_b32_dpp v192, v26 row_mirror row_mask:0xf bank_mask:0xf bound_ctrl:1
	v_mov_b32_dpp v193, v27 row_mirror row_mask:0xf bank_mask:0xf bound_ctrl:1
	s_and_saveexec_b64 s[6:7], vcc
	v_pk_add_f32 v[26:27], v[26:27], v[192:193]
	ds_write_b64 v181, v[26:27] offset:392
	s_or_b64 exec, exec, s[6:7]
	ds_read2_b32 v[192:193], v75 offset1:32
	ds_read2_b32 v[196:197], v75 offset0:64 offset1:96
	v_mov_b32_e32 v194, v60
	v_mov_b32_e32 v195, v28
	v_pk_add_f32 v[198:199], v[194:195], 0 op_sel_hi:[1,0]
	v_mov_b32_e32 v194, v44
	v_pk_add_f32 v[194:195], v[194:195], 0 op_sel_hi:[1,0]
	s_waitcnt lgkmcnt(1)
	v_mov_b32_e32 v202, v192
	s_waitcnt lgkmcnt(0)
	v_mov_b32_e32 v203, v196
	s_mov_b32 s2, s67
	v_mov_b32_e32 v206, v193
	v_mov_b32_e32 v207, v196
	v_pk_fma_f32 v[192:193], v[202:203], s[2:3], v[198:199] op_sel_hi:[1,0,1]
	v_pk_fma_f32 v[194:195], v[206:207], s[2:3], v[194:195] op_sel_hi:[1,0,1]
	v_pk_mul_f32 v[204:205], v[202:203], s[2:3] op_sel_hi:[1,0]
	v_pk_mul_f32 v[202:203], v[192:193], v[192:193]
	v_pk_mul_f32 v[206:207], v[194:195], v[194:195]
	v_pk_mov_b32 v[198:199], v[198:199], v[202:203] op_sel:[1,0]
	v_pk_mov_b32 v[202:203], v[204:205], v[206:207] op_sel:[1,0]
	v_add_f32_e32 v26, 0, v12
	v_pk_add_f32 v[198:199], v[198:199], v[202:203]
	v_pk_add_f32 v[202:203], v[192:193], v[194:195]
	v_pk_mul_f32 v[204:205], v[192:193], v[194:195]
	v_fmac_f32_e32 v26, 0x3fd744fd, v197
	v_mov_b32_e32 v203, v205
	v_pk_add_f32 v[198:199], v[202:203], v[198:199]
	v_mul_f32_e32 v27, v26, v26
	v_pk_add_f32 v[196:197], v[198:199], v[26:27]
	s_nop 1
	v_mov_b32_dpp v198, v196 quad_perm:[1,0,3,2] row_mask:0xf bank_mask:0xf bound_ctrl:1
	v_mov_b32_dpp v199, v197 quad_perm:[1,0,3,2] row_mask:0xf bank_mask:0xf bound_ctrl:1
	v_pk_add_f32 v[196:197], v[196:197], v[198:199]
	s_nop 1
	v_mov_b32_dpp v198, v196 quad_perm:[2,3,0,1] row_mask:0xf bank_mask:0xf bound_ctrl:1
	v_mov_b32_dpp v199, v197 quad_perm:[2,3,0,1] row_mask:0xf bank_mask:0xf bound_ctrl:1
	v_pk_add_f32 v[196:197], v[196:197], v[198:199]
	s_nop 1
	v_mov_b32_dpp v198, v196 row_half_mirror row_mask:0xf bank_mask:0xf bound_ctrl:1
	v_mov_b32_dpp v199, v197 row_half_mirror row_mask:0xf bank_mask:0xf bound_ctrl:1
	v_pk_add_f32 v[196:197], v[196:197], v[198:199]
	s_nop 1
	v_mov_b32_dpp v198, v196 row_mirror row_mask:0xf bank_mask:0xf bound_ctrl:1
	v_mov_b32_dpp v199, v197 row_mirror row_mask:0xf bank_mask:0xf bound_ctrl:1
	s_and_saveexec_b64 s[6:7], vcc
	v_pk_add_f32 v[196:197], v[196:197], v[198:199]
	ds_write_b64 v181, v[196:197] offset:400
	s_or_b64 exec, exec, s[6:7]
	ds_read2_b32 v[196:197], v87 offset1:32
	ds_read2_b32 v[198:199], v87 offset0:64 offset1:96
	v_mov_b32_e32 v28, v61
	v_pk_add_f32 v[202:203], v[28:29], 0 op_sel_hi:[1,0]
	v_mov_b32_e32 v28, v45
	v_pk_add_f32 v[28:29], v[28:29], 0 op_sel_hi:[1,0]
	s_waitcnt lgkmcnt(1)
;   DI void operator()(f32x16 (&acc)[2][4], int grow0, int gcol0, int lane, int w, char* lds) {
;     ...
;         for (int e = 0; e < 4; ++e) {
;           const int i = 4 * (2 * (ps & 1) + qq) + e;
;           const float* xr = (const float*)(xs + (8 * qq + 4 * hh + e) * 512) + l31;
;           float s1 = 0.f, s2 = 0.f;
; #pragma unroll
;           for (int nt = 0; nt < 4; ++nt) {
;             float v = (acc[mt][nt][i] + bia[nt]) * csc[nt];
;             float z = ALPHA * xr[nt * 32] + hs * v;
;             acc[mt][nt][i] = z; s1 += z; s2 += z * z;
;           }
;           s1 = row16_sum(s1); s2 = row16_sum(s2);
;           if ((lane & 15) == 0) { f32x2 sv = {s1, s2}; *(f32x2*)(redw + (mt * 32 + (i & 3) + 8 * (i >> 2)) * 2) = sv; }
	v_mov_b32_e32 v44, v196
	s_waitcnt lgkmcnt(0)
	v_mov_b32_e32 v45, v198
	s_mov_b32 s2, s67
	v_mov_b32_e32 v60, v197
	v_mov_b32_e32 v61, v198
	v_pk_mul_f32 v[204:205], v[44:45], s[2:3] op_sel_hi:[1,0]
	v_pk_fma_f32 v[44:45], v[44:45], s[2:3], v[202:203] op_sel_hi:[1,0,1]
	v_pk_fma_f32 v[60:61], v[60:61], s[2:3], v[28:29] op_sel_hi:[1,0,1]
	v_pk_mul_f32 v[196:197], v[44:45], v[44:45]
	v_pk_mul_f32 v[28:29], v[60:61], v[60:61]
	v_pk_mov_b32 v[196:197], v[202:203], v[196:197] op_sel:[1,0]
	v_pk_mov_b32 v[28:29], v[204:205], v[28:29] op_sel:[1,0]
	v_add_f32_e32 v12, 0, v13
	v_pk_add_f32 v[28:29], v[196:197], v[28:29]
	v_pk_add_f32 v[196:197], v[44:45], v[60:61]
	v_pk_mul_f32 v[202:203], v[44:45], v[60:61]
	v_fmac_f32_e32 v12, 0x3fd744fd, v199
	v_mov_b32_e32 v197, v203
	v_pk_add_f32 v[28:29], v[196:197], v[28:29]
	v_mul_f32_e32 v13, v12, v12
	v_pk_add_f32 v[28:29], v[28:29], v[12:13]
	s_nop 1
	v_mov_b32_dpp v196, v28 quad_perm:[1,0,3,2] row_mask:0xf bank_mask:0xf bound_ctrl:1
	v_mov_b32_dpp v197, v29 quad_perm:[1,0,3,2] row_mask:0xf bank_mask:0xf bound_ctrl:1
	v_pk_add_f32 v[28:29], v[28:29], v[196:197]
	s_nop 1
	v_mov_b32_dpp v196, v28 quad_perm:[2,3,0,1] row_mask:0xf bank_mask:0xf bound_ctrl:1
	v_mov_b32_dpp v197, v29 quad_perm:[2,3,0,1] row_mask:0xf bank_mask:0xf bound_ctrl:1
	v_pk_add_f32 v[28:29], v[28:29], v[196:197]
	s_nop 1
	v_mov_b32_dpp v196, v28 row_half_mirror row_mask:0xf bank_mask:0xf bound_ctrl:1
	v_mov_b32_dpp v197, v29 row_half_mirror row_mask:0xf bank_mask:0xf bound_ctrl:1
	v_pk_add_f32 v[28:29], v[28:29], v[196:197]
	s_nop 1
	v_mov_b32_dpp v196, v28 row_mirror row_mask:0xf bank_mask:0xf bound_ctrl:1
	v_mov_b32_dpp v197, v29 row_mirror row_mask:0xf bank_mask:0xf bound_ctrl:1
	s_and_saveexec_b64 s[6:7], vcc
	v_pk_add_f32 v[28:29], v[28:29], v[196:197]
	ds_write_b64 v181, v[28:29] offset:408
	s_or_b64 exec, exec, s[6:7]
	ds_read2_b32 v[196:197], v77 offset1:32
	ds_read2_b32 v[202:203], v77 offset0:64 offset1:96
	v_mov_b32_e32 v198, v62
	v_mov_b32_e32 v199, v30
	v_pk_add_f32 v[204:205], v[198:199], 0 op_sel_hi:[1,0]
	v_mov_b32_e32 v198, v46
	v_pk_add_f32 v[198:199], v[198:199], 0 op_sel_hi:[1,0]
	s_waitcnt lgkmcnt(1)
	v_mov_b32_e32 v206, v196
	s_waitcnt lgkmcnt(0)
	v_mov_b32_e32 v207, v202
	s_mov_b32 s2, s67
	v_mov_b32_e32 v212, v197
	v_mov_b32_e32 v213, v202
	v_pk_fma_f32 v[196:197], v[206:207], s[2:3], v[204:205] op_sel_hi:[1,0,1]
	v_pk_fma_f32 v[198:199], v[212:213], s[2:3], v[198:199] op_sel_hi:[1,0,1]
	v_pk_mul_f32 v[208:209], v[206:207], s[2:3] op_sel_hi:[1,0]
	v_pk_mul_f32 v[206:207], v[196:197], v[196:197]
	v_pk_mul_f32 v[212:213], v[198:199], v[198:199]
	v_pk_mov_b32 v[204:205], v[204:205], v[206:207] op_sel:[1,0]
	v_pk_mov_b32 v[206:207], v[208:209], v[212:213] op_sel:[1,0]
	v_add_f32_e32 v28, 0, v14
	v_pk_add_f32 v[204:205], v[204:205], v[206:207]
	v_pk_add_f32 v[206:207], v[196:197], v[198:199]
	v_pk_mul_f32 v[208:209], v[196:197], v[198:199]
	v_fmac_f32_e32 v28, 0x3fd744fd, v203
	v_mov_b32_e32 v207, v209
	v_pk_add_f32 v[204:205], v[206:207], v[204:205]
	v_mul_f32_e32 v29, v28, v28
	v_pk_add_f32 v[202:203], v[204:205], v[28:29]
	s_nop 1
	v_mov_b32_dpp v204, v202 quad_perm:[1,0,3,2] row_mask:0xf bank_mask:0xf bound_ctrl:1
	v_mov_b32_dpp v205, v203 quad_perm:[1,0,3,2] row_mask:0xf bank_mask:0xf bound_ctrl:1
	v_pk_add_f32 v[202:203], v[202:203], v[204:205]
	s_nop 1
	v_mov_b32_dpp v204, v202 quad_perm:[2,3,0,1] row_mask:0xf bank_mask:0xf bound_ctrl:1
	v_mov_b32_dpp v205, v203 quad_perm:[2,3,0,1] row_mask:0xf bank_mask:0xf bound_ctrl:1
	v_pk_add_f32 v[202:203], v[202:203], v[204:205]
	s_nop 1
	v_mov_b32_dpp v204, v202 row_half_mirror row_mask:0xf bank_mask:0xf bound_ctrl:1
	v_mov_b32_dpp v205, v203 row_half_mirror row_mask:0xf bank_mask:0xf bound_ctrl:1
	v_pk_add_f32 v[202:203], v[202:203], v[204:205]
	s_nop 1
	v_mov_b32_dpp v204, v202 row_mirror row_mask:0xf bank_mask:0xf bound_ctrl:1
	v_mov_b32_dpp v205, v203 row_mirror row_mask:0xf bank_mask:0xf bound_ctrl:1
	s_and_saveexec_b64 s[6:7], vcc
	v_pk_add_f32 v[202:203], v[202:203], v[204:205]
	ds_write_b64 v181, v[202:203] offset:448
	s_or_b64 exec, exec, s[6:7]
	ds_read2_b32 v[202:203], v91 offset1:32
	ds_read2_b32 v[204:205], v91 offset0:64 offset1:96
	v_mov_b32_e32 v30, v63
	v_pk_add_f32 v[206:207], v[30:31], 0 op_sel_hi:[1,0]
	v_mov_b32_e32 v30, v47
	v_pk_add_f32 v[30:31], v[30:31], 0 op_sel_hi:[1,0]
	s_waitcnt lgkmcnt(1)
	v_mov_b32_e32 v46, v202
	s_waitcnt lgkmcnt(0)
	v_mov_b32_e32 v47, v204
	s_mov_b32 s2, s67
	v_mov_b32_e32 v62, v203
	v_mov_b32_e32 v63, v204
	v_pk_mul_f32 v[208:209], v[46:47], s[2:3] op_sel_hi:[1,0]
	v_pk_fma_f32 v[46:47], v[46:47], s[2:3], v[206:207] op_sel_hi:[1,0,1]
	v_pk_fma_f32 v[62:63], v[62:63], s[2:3], v[30:31] op_sel_hi:[1,0,1]
	v_pk_mul_f32 v[202:203], v[46:47], v[46:47]
	v_pk_mul_f32 v[30:31], v[62:63], v[62:63]
	v_pk_mov_b32 v[202:203], v[206:207], v[202:203] op_sel:[1,0]
	v_pk_mov_b32 v[30:31], v[208:209], v[30:31] op_sel:[1,0]
	v_add_f32_e32 v14, 0, v15
	v_pk_add_f32 v[30:31], v[202:203], v[30:31]
	v_pk_add_f32 v[202:203], v[46:47], v[62:63]
	v_pk_mul_f32 v[206:207], v[46:47], v[62:63]
	v_fmac_f32_e32 v14, 0x3fd744fd, v205
	v_mov_b32_e32 v203, v207
	v_pk_add_f32 v[30:31], v[202:203], v[30:31]
	v_mul_f32_e32 v15, v14, v14
	v_pk_add_f32 v[30:31], v[30:31], v[14:15]
	s_nop 1
	v_mov_b32_dpp v202, v30 quad_perm:[1,0,3,2] row_mask:0xf bank_mask:0xf bound_ctrl:1
	v_mov_b32_dpp v203, v31 quad_perm:[1,0,3,2] row_mask:0xf bank_mask:0xf bound_ctrl:1
	v_pk_add_f32 v[30:31], v[30:31], v[202:203]
	s_nop 1
	v_mov_b32_dpp v202, v30 quad_perm:[2,3,0,1] row_mask:0xf bank_mask:0xf bound_ctrl:1
	v_mov_b32_dpp v203, v31 quad_perm:[2,3,0,1] row_mask:0xf bank_mask:0xf bound_ctrl:1
	v_pk_add_f32 v[30:31], v[30:31], v[202:203]
	s_nop 1
	v_mov_b32_dpp v202, v30 row_half_mirror row_mask:0xf bank_mask:0xf bound_ctrl:1
	v_mov_b32_dpp v203, v31 row_half_mirror row_mask:0xf bank_mask:0xf bound_ctrl:1
	v_pk_add_f32 v[30:31], v[30:31], v[202:203]
	s_nop 1
	v_mov_b32_dpp v202, v30 row_mirror row_mask:0xf bank_mask:0xf bound_ctrl:1
	v_mov_b32_dpp v203, v31 row_mirror row_mask:0xf bank_mask:0xf bound_ctrl:1
	s_and_saveexec_b64 s[6:7], vcc
	v_pk_add_f32 v[30:31], v[30:31], v[202:203]
	ds_write_b64 v181, v[30:31] offset:456
	s_or_b64 exec, exec, s[6:7]
	ds_read2_b32 v[202:203], v79 offset1:32
	ds_read2_b32 v[206:207], v79 offset0:64 offset1:96
	v_mov_b32_e32 v204, v64
	v_mov_b32_e32 v205, v32
	v_pk_add_f32 v[208:209], v[204:205], 0 op_sel_hi:[1,0]
	v_mov_b32_e32 v204, v48
	v_pk_add_f32 v[204:205], v[204:205], 0 op_sel_hi:[1,0]
	s_waitcnt lgkmcnt(1)
; DI void ag_st64(u64_t* p, u64_t v) { __hip_atomic_store(p, v, __ATOMIC_RELAXED, __HIP_MEMORY_SCOPE_AGENT); }
;   DI void operator()(f32x16 (&acc)[2][4], int grow0, int gcol0, int lane, int w, char* lds) {
;     ...
;         for (int e = 0; e < 4; ++e) {
;           const int i = 4 * (2 * (ps & 1) + qq) + e;
;           const float* xr = (const float*)(xs + (8 * qq + 4 * hh + e) * 512) + l31;
;           float s1 = 0.f, s2 = 0.f;
; #pragma unroll
;           for (int nt = 0; nt < 4; ++nt) {
;             float v = (acc[mt][nt][i] + bia[nt]) * csc[nt];
;             float z = ALPHA * xr[nt * 32] + hs * v;
;             acc[mt][nt][i] = z; s1 += z; s2 += z * z;
;           }
;           s1 = row16_sum(s1); s2 = row16_sum(s2);
;           if ((lane & 15) == 0) { f32x2 sv = {s1, s2}; *(f32x2*)(redw + (mt * 32 + (i & 3) + 8 * (i >> 2)) * 2) = sv; }
;         }
;     }
;     __syncthreads();
;     u64_t* myslots = xstat + ((size_t)pm * 256) * 4;
;     if (tid < 256) {
;       float s1 = (red[tid * 2] + red[(256 + tid) * 2]) + (red[(512 + tid) * 2] + red[(768 + tid) * 2]);
;       float s2 = (red[tid * 2 + 1] + red[(256 + tid) * 2 + 1]) + (red[(512 + tid) * 2 + 1] + red[(768 + tid) * 2 + 1]);
;       ag_st64(myslots + tid * 4 + pn, ((u64_t)__float_as_uint(s2) << 32) | (u64_t)__float_as_uint(s1));
	v_mov_b32_e32 v212, v202
	s_waitcnt lgkmcnt(0)
	v_mov_b32_e32 v213, v206
	s_mov_b32 s2, s67
	v_mov_b32_e32 v226, v203
	v_mov_b32_e32 v227, v206
	v_pk_fma_f32 v[202:203], v[212:213], s[2:3], v[208:209] op_sel_hi:[1,0,1]
	v_pk_fma_f32 v[204:205], v[226:227], s[2:3], v[204:205] op_sel_hi:[1,0,1]
	v_pk_mul_f32 v[214:215], v[212:213], s[2:3] op_sel_hi:[1,0]
	v_pk_mul_f32 v[212:213], v[202:203], v[202:203]
	v_pk_mul_f32 v[226:227], v[204:205], v[204:205]
	v_pk_mov_b32 v[208:209], v[208:209], v[212:213] op_sel:[1,0]
	v_pk_mov_b32 v[212:213], v[214:215], v[226:227] op_sel:[1,0]
	v_add_f32_e32 v30, 0, v16
	v_pk_add_f32 v[208:209], v[208:209], v[212:213]
	v_pk_add_f32 v[212:213], v[202:203], v[204:205]
	v_pk_mul_f32 v[214:215], v[202:203], v[204:205]
	v_fmac_f32_e32 v30, 0x3fd744fd, v207
	v_mov_b32_e32 v213, v215
	v_pk_add_f32 v[208:209], v[212:213], v[208:209]
	v_mul_f32_e32 v31, v30, v30
	v_pk_add_f32 v[206:207], v[208:209], v[30:31]
	s_nop 1
	v_mov_b32_dpp v208, v206 quad_perm:[1,0,3,2] row_mask:0xf bank_mask:0xf bound_ctrl:1
	v_mov_b32_dpp v209, v207 quad_perm:[1,0,3,2] row_mask:0xf bank_mask:0xf bound_ctrl:1
	v_pk_add_f32 v[206:207], v[206:207], v[208:209]
	s_nop 1
	v_mov_b32_dpp v208, v206 quad_perm:[2,3,0,1] row_mask:0xf bank_mask:0xf bound_ctrl:1
	v_mov_b32_dpp v209, v207 quad_perm:[2,3,0,1] row_mask:0xf bank_mask:0xf bound_ctrl:1
	v_pk_add_f32 v[206:207], v[206:207], v[208:209]
	s_nop 1
	v_mov_b32_dpp v208, v206 row_half_mirror row_mask:0xf bank_mask:0xf bound_ctrl:1
	v_mov_b32_dpp v209, v207 row_half_mirror row_mask:0xf bank_mask:0xf bound_ctrl:1
	v_pk_add_f32 v[206:207], v[206:207], v[208:209]
	s_nop 1
	v_mov_b32_dpp v208, v206 row_mirror row_mask:0xf bank_mask:0xf bound_ctrl:1
	v_mov_b32_dpp v209, v207 row_mirror row_mask:0xf bank_mask:0xf bound_ctrl:1
	s_and_saveexec_b64 s[6:7], vcc
	v_pk_add_f32 v[206:207], v[206:207], v[208:209]
	ds_write_b64 v181, v[206:207] offset:464
	s_or_b64 exec, exec, s[6:7]
	ds_read2_b32 v[206:207], v93 offset1:32
	ds_read2_b32 v[208:209], v93 offset0:64 offset1:96
	v_mov_b32_e32 v32, v65
	v_pk_add_f32 v[64:65], v[32:33], 0 op_sel_hi:[1,0]
	v_mov_b32_e32 v32, v49
	v_pk_add_f32 v[48:49], v[32:33], 0 op_sel_hi:[1,0]
	s_waitcnt lgkmcnt(1)
	v_mov_b32_e32 v32, v206
	s_waitcnt lgkmcnt(0)
	v_mov_b32_e32 v33, v208
	s_mov_b32 s2, s67
	v_mov_b32_e32 v206, v207
	v_mov_b32_e32 v207, v208
	v_pk_mul_f32 v[212:213], v[32:33], s[2:3] op_sel_hi:[1,0]
	v_pk_fma_f32 v[32:33], v[32:33], s[2:3], v[64:65] op_sel_hi:[1,0,1]
	v_pk_fma_f32 v[48:49], v[206:207], s[2:3], v[48:49] op_sel_hi:[1,0,1]
	v_pk_mul_f32 v[214:215], v[32:33], v[32:33]
	v_pk_mul_f32 v[206:207], v[48:49], v[48:49]
	v_pk_mov_b32 v[64:65], v[64:65], v[214:215] op_sel:[1,0]
	v_pk_mov_b32 v[206:207], v[212:213], v[206:207] op_sel:[1,0]
	v_add_f32_e32 v16, 0, v17
	v_pk_add_f32 v[64:65], v[64:65], v[206:207]
	v_pk_add_f32 v[206:207], v[32:33], v[48:49]
	v_pk_mul_f32 v[212:213], v[32:33], v[48:49]
	v_fmac_f32_e32 v16, 0x3fd744fd, v209
	v_mov_b32_e32 v207, v213
	v_pk_add_f32 v[64:65], v[206:207], v[64:65]
	v_mul_f32_e32 v17, v16, v16
	v_pk_add_f32 v[64:65], v[64:65], v[16:17]
	s_nop 1
	v_mov_b32_dpp v206, v64 quad_perm:[1,0,3,2] row_mask:0xf bank_mask:0xf bound_ctrl:1
	v_mov_b32_dpp v207, v65 quad_perm:[1,0,3,2] row_mask:0xf bank_mask:0xf bound_ctrl:1
	v_pk_add_f32 v[64:65], v[64:65], v[206:207]
	s_nop 1
	v_mov_b32_dpp v206, v64 quad_perm:[2,3,0,1] row_mask:0xf bank_mask:0xf bound_ctrl:1
	v_mov_b32_dpp v207, v65 quad_perm:[2,3,0,1] row_mask:0xf bank_mask:0xf bound_ctrl:1
	v_pk_add_f32 v[64:65], v[64:65], v[206:207]
	s_nop 1
	v_mov_b32_dpp v206, v64 row_half_mirror row_mask:0xf bank_mask:0xf bound_ctrl:1
	v_mov_b32_dpp v207, v65 row_half_mirror row_mask:0xf bank_mask:0xf bound_ctrl:1
	v_pk_add_f32 v[64:65], v[64:65], v[206:207]
	s_nop 1
	v_mov_b32_dpp v206, v64 row_mirror row_mask:0xf bank_mask:0xf bound_ctrl:1
	v_mov_b32_dpp v207, v65 row_mirror row_mask:0xf bank_mask:0xf bound_ctrl:1
	s_and_saveexec_b64 s[6:7], vcc
	v_pk_add_f32 v[64:65], v[64:65], v[206:207]
	ds_write_b64 v181, v[64:65] offset:472
	s_or_b64 exec, exec, s[6:7]
	v_ashrrev_i32_e32 v206, 8, v163
	v_ashrrev_i32_e32 v207, 31, v206
	v_lshlrev_b64 v[64:65], 13, v[206:207]
	v_lshl_add_u64 v[64:65], s[8:9], 0, v[64:65]
	v_cmp_gt_i32_e64 s[40:41], s60, v164
	v_ashrrev_i32_e32 v201, 31, v200
	s_waitcnt lgkmcnt(0)
	s_barrier
	s_and_saveexec_b64 s[6:7], s[40:41]
	s_cbranch_execz .LBB0_240
	v_lshl_add_u32 v0, v164, 3, v221
	ds_read2st64_b64 v[212:215], v0 offset1:4
	ds_read2st64_b64 v[226:229], v0 offset0:8 offset1:12
	v_ashrrev_i32_e32 v208, 8, v184
	v_ashrrev_i32_e32 v209, 31, v208
	s_waitcnt lgkmcnt(1)
	v_mov_b32_e32 v230, v212
	s_waitcnt lgkmcnt(0)
	v_mov_b32_e32 v231, v226
	v_mov_b32_e32 v232, v214
	v_mov_b32_e32 v233, v228
	v_mov_b32_e32 v226, v213
	v_mov_b32_e32 v228, v215
	v_pk_add_f32 v[230:231], v[230:231], v[232:233]
	v_pk_add_f32 v[212:213], v[226:227], v[228:229]
	v_pk_add_f32 v[230:231], v[230:231], v[230:231] op_sel:[0,1] op_sel_hi:[1,0]
	v_pk_add_f32 v[212:213], v[212:213], v[212:213] op_sel:[0,1] op_sel_hi:[1,0]
	v_lshl_add_u64 v[214:215], v[200:201], 3, v[64:65]
	v_lshl_add_u64 v[208:209], v[208:209], 3, v[214:215]
	v_mov_b32_e32 v231, v212
	global_store_dwordx2 v[208:209], v[230:231], off sc1

; DI f32x16 zero16() { f32x16 z; for (int i = 0; i < 16; ++i) z[i] = 0.f; return z; }
; DI int launder(int x) { asm volatile("" : "+v"(x)); return x; }
; template <int BK> DI int swz(int row) { constexpr int CPR = BK / 8; return (row / (16 / CPR)) % CPR; }
; DI void wait_vm0() { asm volatile("s_waitcnt vmcnt(0)" ::: "memory"); }
;   DI void pre(int grow0, int gcol0, int lane, int w, char* lds) { xpass(0, grow0, gcol0, lane, w, lds); }
;     ...
;   const int tid = launder(threadIdx.x), lane = tid & 63, w = tid >> 6, wm = w % WM, wn = w / WM;
;   const int l31 = lane & 31, hh = lane >> 5;
;   f32x16 acc[2][NTW];
; #pragma unroll
;   for (int a = 0; a < 2; ++a)
; #pragma unroll
;     for (int b = 0; b < NTW; ++b) acc[a][b] = zero16();
;   const bf16_t* Ag = A + (size_t)row0 * lda; const bf16_t* Bg = Bt + (size_t)col0 * ldb;
;   const int wv = __builtin_amdgcn_readfirstlane(tid >> 6);
;   __syncthreads();
;   if (!pre) { stage_tile<BM, BK>(Ag, lda, lds, tid); stage_tile<BN, BK>(Bg, ldb, lds + ABYTES, tid); }
;   wait_vm0();
;   __syncthreads();
;   const int nk = K / BK;
;   for (int kt = 0; kt < nk; ++kt) {
;     char* cur = lds + (kt & 1) * STG; char* nxt = lds + ((kt + 1) & 1) * STG;
;     const bool more = kt + 1 < nk;
;     const bf16_t* An = Ag + (kt + 1) * BK; const bf16_t* Bn = Bg + (kt + 1) * BK;
;     if (!more) epi.pre(row0 + wm * 64, col0 + wn * (32 * NTW), lane, w, lds);
;     bf16x8 fa[2][2], fb[2][NTW];
; #pragma unroll
;     for (int mt = 0; mt < 2; ++mt) { int row = wm * 64 + mt * 32 + l31; fa[0][mt] = *(const bf16x8*)(cur + row * (BK * 2) + ((hh ^ swz<BK>(row)) << 4)); }
; #pragma unroll
;     for (int nt = 0; nt < NTW; ++nt) { int row = wn * (32 * NTW) + nt * 32 + l31; fb[0][nt] = *(const bf16x8*)(cur + ABYTES + row * (BK * 2) + ((hh ^ swz<BK>(row)) << 4)); }
; #pragma unroll
;     for (int kk = 0; kk < NKK; ++kk) {
;       if (kk + 1 < NKK) {
;         const int ch = (kk + 1) * 2 + hh;
; #pragma unroll
;         for (int mt = 0; mt < 2; ++mt) { int row = wm * 64 + mt * 32 + l31; fa[(kk + 1) & 1][mt] = *(const bf16x8*)(cur + row * (BK * 2) + ((ch ^ swz<BK>(row)) << 4)); }
; #pragma unroll
;         for (int nt = 0; nt < NTW; ++nt) { int row = wn * (32 * NTW) + nt * 32 + l31; fb[(kk + 1) & 1][nt] = *(const bf16x8*)(cur + ABYTES + row * (BK * 2) + ((ch ^ swz<BK>(row)) << 4)); }
.LBB0_283:
	v_lshrrev_b32_e32 v4, 30, v3
	v_add_u32_e32 v4, v3, v4
	v_ashrrev_i32_e32 v4, 2, v4
	v_mul_i32_i24_e32 v5, 4, v4
	v_sub_u32_e32 v3, v3, v5
	v_and_b32_e32 v5, 31, v2
	v_lshlrev_b32_e32 v7, 6, v3
	v_or_b32_e32 v7, v7, v5
	v_bfe_u32 v3, v3, 25, 1
	s_waitcnt vmcnt(0)
	v_lshlrev_b32_e32 v140, 7, v7
	v_add_u32_e32 v8, v7, v3
	v_or_b32_e32 v7, 32, v7
	v_add_u32_e32 v3, v7, v3
	v_lshlrev_b32_e32 v142, 7, v7
	v_ashrrev_i32_e32 v7, 1, v3
	v_ashrrev_i32_e32 v3, 31, v3
	v_ashrrev_i32_e32 v9, 1, v8
	v_ashrrev_i32_e32 v8, 31, v8
	v_lshrrev_b32_e32 v3, 29, v3
	v_lshrrev_b32_e32 v8, 29, v8
	v_add_u32_e32 v3, v7, v3
	v_add_u32_e32 v8, v9, v8
	v_and_b32_e32 v3, -8, v3
	v_lshrrev_b32_e32 v6, 5, v2
	v_and_b32_e32 v8, -8, v8
	v_sub_u32_e32 v3, v7, v3
	v_lshl_or_b32 v5, v4, 7, v5
	v_sub_u32_e32 v8, v9, v8
	v_bitop3_b32 v7, v3, v6, 1 bitop3:0x78
	v_lshrrev_b32_e32 v4, 31, v4
	v_bitop3_b32 v9, v8, v6, 1 bitop3:0x78
	v_lshlrev_b32_e32 v144, 4, v7
	v_add_u32_e32 v7, v5, v4
	v_lshlrev_b32_e32 v141, 4, v9
	v_ashrrev_i32_e32 v9, 1, v7
	v_ashrrev_i32_e32 v7, 31, v7
	v_lshrrev_b32_e32 v7, 29, v7
	v_add_u32_e32 v7, v9, v7
	v_and_b32_e32 v7, -8, v7
	v_sub_u32_e32 v7, v9, v7
	v_bitop3_b32 v9, v7, v6, 1 bitop3:0x78
	v_lshlrev_b32_e32 v151, 4, v9
	v_or_b32_e32 v9, 32, v5
	v_lshlrev_b32_e32 v152, 7, v9
	v_add_u32_e32 v9, v9, v4
	v_ashrrev_i32_e32 v10, 1, v9
	v_ashrrev_i32_e32 v9, 31, v9
	v_lshrrev_b32_e32 v9, 29, v9
	v_add_u32_e32 v9, v10, v9
	v_and_b32_e32 v9, -8, v9
	v_sub_u32_e32 v9, v10, v9
	v_bitop3_b32 v10, v9, v6, 1 bitop3:0x78
	v_lshlrev_b32_e32 v143, 7, v5
	v_lshlrev_b32_e32 v154, 4, v10
	v_or_b32_e32 v10, 64, v5
	v_or_b32_e32 v5, 0x60, v5
	v_lshlrev_b32_e32 v153, 7, v10
	v_add_u32_e32 v10, v10, v4
	v_add_u32_e32 v4, v5, v4
	v_lshlrev_b32_e32 v156, 7, v5
	v_ashrrev_i32_e32 v5, 1, v4
	v_ashrrev_i32_e32 v4, 31, v4
	v_lshrrev_b32_e32 v4, 29, v4
	v_add_u32_e32 v4, v5, v4
	v_and_b32_e32 v4, -8, v4
	v_sub_u32_e32 v4, v5, v4
	v_bfe_u32 v2, v2, 5, 1
	v_ashrrev_i32_e32 v11, 1, v10
	v_ashrrev_i32_e32 v10, 31, v10
	v_bitop3_b32 v5, v4, v6, 1 bitop3:0x78
	v_lshrrev_b32_e32 v10, 29, v10
	v_lshlrev_b32_e32 v164, 4, v5
	v_bitop3_b32 v5, v8, v2, 2 bitop3:0x1e
	v_add_u32_e32 v10, v11, v10
	v_lshlrev_b32_e32 v161, 4, v5
	v_bitop3_b32 v5, v3, v2, 2 bitop3:0x1e
	v_and_b32_e32 v10, -8, v10
	v_lshlrev_b32_e32 v163, 4, v5
	v_bitop3_b32 v5, v7, v2, 2 bitop3:0x1e
	v_sub_u32_e32 v10, v11, v10
	v_lshlrev_b32_e32 v159, 4, v5
	v_bitop3_b32 v5, v9, v2, 2 bitop3:0x1e
	s_lshr_b32 s7, s44, 3
	v_lshlrev_b32_e32 v160, 4, v5
	v_bitop3_b32 v5, v10, v2, 2 bitop3:0x1e
	s_and_b32 s7, s7, 7
	s_lshl_b32 s30, s37, 19
	v_lshlrev_b32_e32 v157, 4, v5
	v_bitop3_b32 v5, v4, v2, 2 bitop3:0x1e
	s_lshl_b32 s7, s7, 19
	s_and_b32 s30, s30, 0x1c00000
	v_lshlrev_b32_e32 v158, 4, v5
	v_bitop3_b32 v5, v8, v2, 4 bitop3:0x1e
	s_or_b32 s7, s30, s7
	s_and_b32 s30, s36, 0xffffff00
	v_lshlrev_b32_e32 v149, 4, v5
	v_bitop3_b32 v5, v3, v2, 4 bitop3:0x1e
	s_ashr_i32 s31, s30, 31
	v_lshlrev_b32_e32 v150, 4, v5
	v_bitop3_b32 v5, v7, v2, 4 bitop3:0x1e
	s_lshl_b64 s[30:31], s[30:31], 11
	s_lshl_b32 s3, s3, 10
	v_lshlrev_b32_e32 v147, 4, v5
	v_bitop3_b32 v5, v9, v2, 4 bitop3:0x1e
	v_bitop3_b32 v3, v3, v2, 6 bitop3:0x1e
	v_lshlrev_b32_e32 v148, 4, v5
	v_bitop3_b32 v5, v10, v2, 4 bitop3:0x1e
	v_lshlrev_b32_e32 v139, 4, v3
	v_bitop3_b32 v3, v7, v2, 6 bitop3:0x1e
	s_add_u32 s34, s12, s7
	v_lshlrev_b32_e32 v145, 4, v5
	v_bitop3_b32 v5, v4, v2, 4 bitop3:0x1e
	v_lshlrev_b32_e32 v136, 4, v3
	v_bitop3_b32 v3, v9, v2, 6 bitop3:0x1e
	s_addc_u32 s35, s13, 0
	s_waitcnt vmcnt(0)
	v_lshlrev_b32_e32 v146, 4, v5
	v_bitop3_b32 v5, v8, v2, 6 bitop3:0x1e
	v_lshlrev_b32_e32 v137, 4, v3
	v_bitop3_b32 v3, v10, v2, 6 bitop3:0x1e
	v_bitop3_b32 v2, v4, v2, 6 bitop3:0x1e
	s_add_u32 s30, s40, s30
	v_bitop3_b32 v11, v10, v6, 1 bitop3:0x78
	v_lshlrev_b32_e32 v135, 4, v2
	s_addc_u32 s31, s41, s31
	v_mov_b32_e32 v2, 0
	v_lshlrev_b32_e32 v155, 4, v11
	v_lshlrev_b32_e32 v138, 4, v5
	v_lshlrev_b32_e32 v134, 4, v3
	v_lshl_add_u64 v[130:131], s[34:35], 0, v[0:1]
	v_lshl_add_u64 v[132:133], s[30:31], 0, v[0:1]
	s_mov_b64 s[30:31], 0
	s_mov_b32 s7, 0x10000
	v_mov_b32_e32 v3, v2
	v_mov_b32_e32 v4, v2
	v_mov_b32_e32 v5, v2
	v_mov_b32_e32 v6, v2
	v_mov_b32_e32 v7, v2
	v_mov_b32_e32 v8, v2
	v_mov_b32_e32 v9, v2
	v_mov_b32_e32 v10, v2
	v_mov_b32_e32 v11, v2
	v_mov_b32_e32 v12, v2
	v_mov_b32_e32 v13, v2
	v_mov_b32_e32 v14, v2
	v_mov_b32_e32 v15, v2
	v_mov_b32_e32 v16, v2
	v_mov_b32_e32 v17, v2
	v_mov_b32_e32 v18, v2
	v_mov_b32_e32 v19, v2
	v_mov_b32_e32 v20, v2
	v_mov_b32_e32 v21, v2
	v_mov_b32_e32 v22, v2
	v_mov_b32_e32 v23, v2
	v_mov_b32_e32 v24, v2
	v_mov_b32_e32 v25, v2
	v_mov_b32_e32 v26, v2
	v_mov_b32_e32 v27, v2
	v_mov_b32_e32 v28, v2
	v_mov_b32_e32 v29, v2
	v_mov_b32_e32 v30, v2
	v_mov_b32_e32 v31, v2
	v_mov_b32_e32 v32, v2
	v_mov_b32_e32 v33, v2
	v_mov_b32_e32 v34, v2
	v_mov_b32_e32 v35, v2
	v_mov_b32_e32 v36, v2
	v_mov_b32_e32 v37, v2
	v_mov_b32_e32 v38, v2
	v_mov_b32_e32 v39, v2
	v_mov_b32_e32 v40, v2
	v_mov_b32_e32 v41, v2
	v_mov_b32_e32 v42, v2
	v_mov_b32_e32 v43, v2
	v_mov_b32_e32 v44, v2
	v_mov_b32_e32 v45, v2
	v_mov_b32_e32 v46, v2
	v_mov_b32_e32 v47, v2
	v_mov_b32_e32 v48, v2
	v_mov_b32_e32 v49, v2
	v_mov_b32_e32 v50, v2
	v_mov_b32_e32 v51, v2
	v_mov_b32_e32 v52, v2
	v_mov_b32_e32 v53, v2
	v_mov_b32_e32 v54, v2
	v_mov_b32_e32 v55, v2
	v_mov_b32_e32 v56, v2
	v_mov_b32_e32 v57, v2
	v_mov_b32_e32 v58, v2
	v_mov_b32_e32 v59, v2
	v_mov_b32_e32 v60, v2
	v_mov_b32_e32 v61, v2
	v_mov_b32_e32 v62, v2
	v_mov_b32_e32 v63, v2
	v_mov_b32_e32 v64, v2
	v_mov_b32_e32 v65, v2
	v_mov_b32_e32 v66, v2
	v_mov_b32_e32 v67, v2
	v_mov_b32_e32 v68, v2
	v_mov_b32_e32 v69, v2
; DI f32x16 mfma(bf16x8 a, bf16x8 b, f32x16 c) { return __builtin_amdgcn_mfma_f32_32x32x16_bf16(a, b, c, 0, 0, 0); }
; template <int BK> DI int swz(int row) { constexpr int CPR = BK / 8; return (row / (16 / CPR)) % CPR; }
;   DI void pre(int grow0, int gcol0, int lane, int w, char* lds) { xpass(0, grow0, gcol0, lane, w, lds); }
;     ...
;   for (int kt = 0; kt < nk; ++kt) {
;     char* cur = lds + (kt & 1) * STG; char* nxt = lds + ((kt + 1) & 1) * STG;
;     const bool more = kt + 1 < nk;
;     const bf16_t* An = Ag + (kt + 1) * BK; const bf16_t* Bn = Bg + (kt + 1) * BK;
;     if (!more) epi.pre(row0 + wm * 64, col0 + wn * (32 * NTW), lane, w, lds);
;     bf16x8 fa[2][2], fb[2][NTW];
; #pragma unroll
;     for (int mt = 0; mt < 2; ++mt) { int row = wm * 64 + mt * 32 + l31; fa[0][mt] = *(const bf16x8*)(cur + row * (BK * 2) + ((hh ^ swz<BK>(row)) << 4)); }
; #pragma unroll
;     for (int nt = 0; nt < NTW; ++nt) { int row = wn * (32 * NTW) + nt * 32 + l31; fb[0][nt] = *(const bf16x8*)(cur + ABYTES + row * (BK * 2) + ((hh ^ swz<BK>(row)) << 4)); }
; #pragma unroll
;     for (int kk = 0; kk < NKK; ++kk) {
;       if (kk + 1 < NKK) {
;         const int ch = (kk + 1) * 2 + hh;
; #pragma unroll
;         for (int mt = 0; mt < 2; ++mt) { int row = wm * 64 + mt * 32 + l31; fa[(kk + 1) & 1][mt] = *(const bf16x8*)(cur + row * (BK * 2) + ((ch ^ swz<BK>(row)) << 4)); }
; #pragma unroll
;         for (int nt = 0; nt < NTW; ++nt) { int row = wn * (32 * NTW) + nt * 32 + l31; fb[(kk + 1) & 1][nt] = *(const bf16x8*)(cur + ABYTES + row * (BK * 2) + ((ch ^ swz<BK>(row)) << 4)); }
;       }
;       if (more) {
; #pragma unroll
;         for (int q = 0; q < PPK; ++q) {
;           const int pi = kk * PPK + q;
;           if (pi < NPA) stage_piece<BM, BK>(An, lda, nxt, tid, pi, wv);
;           else if (pi < NP) stage_piece<BN, BK>(Bn, ldb, nxt + ABYTES, tid, pi - NPA, wv);
;         }
;       }
;       __builtin_amdgcn_s_setprio(1);
; #pragma unroll
;       for (int mt = 0; mt < 2; ++mt)
; #pragma unroll
;         for (int nt = 0; nt < NTW; ++nt) acc[mt][nt] = mfma(fa[kk & 1][mt], fb[kk & 1][nt], acc[mt][nt]);
;       __builtin_amdgcn_s_setprio(0);
;       __builtin_amdgcn_sched_barrier(0);
;     }
	v_mov_b32_e32 v70, v2
	v_mov_b32_e32 v71, v2
	v_mov_b32_e32 v72, v2
	v_mov_b32_e32 v73, v2
	v_mov_b32_e32 v74, v2
	v_mov_b32_e32 v75, v2
	v_mov_b32_e32 v76, v2
	v_mov_b32_e32 v77, v2
	v_mov_b32_e32 v78, v2
	v_mov_b32_e32 v79, v2
	v_mov_b32_e32 v80, v2
	v_mov_b32_e32 v81, v2
	v_mov_b32_e32 v82, v2
	v_mov_b32_e32 v83, v2
	v_mov_b32_e32 v84, v2
	v_mov_b32_e32 v85, v2
	v_mov_b32_e32 v86, v2
	v_mov_b32_e32 v87, v2
	v_mov_b32_e32 v88, v2
	v_mov_b32_e32 v89, v2
	v_mov_b32_e32 v90, v2
	v_mov_b32_e32 v91, v2
	v_mov_b32_e32 v92, v2
	v_mov_b32_e32 v93, v2
	v_mov_b32_e32 v94, v2
	v_mov_b32_e32 v95, v2
	v_mov_b32_e32 v96, v2
	v_mov_b32_e32 v97, v2
	v_mov_b32_e32 v98, v2
	v_mov_b32_e32 v99, v2
	v_mov_b32_e32 v100, v2
	v_mov_b32_e32 v101, v2
	v_mov_b32_e32 v102, v2
	v_mov_b32_e32 v103, v2
	v_mov_b32_e32 v104, v2
	v_mov_b32_e32 v105, v2
	v_mov_b32_e32 v106, v2
	v_mov_b32_e32 v107, v2
	v_mov_b32_e32 v108, v2
	v_mov_b32_e32 v109, v2
	v_mov_b32_e32 v110, v2
	v_mov_b32_e32 v111, v2
	v_mov_b32_e32 v112, v2
	v_mov_b32_e32 v113, v2
	v_mov_b32_e32 v114, v2
	v_mov_b32_e32 v115, v2
	v_mov_b32_e32 v116, v2
	v_mov_b32_e32 v117, v2
	v_mov_b32_e32 v118, v2
	v_mov_b32_e32 v119, v2
	v_mov_b32_e32 v120, v2
	v_mov_b32_e32 v121, v2
	v_mov_b32_e32 v122, v2
	v_mov_b32_e32 v123, v2
	v_mov_b32_e32 v124, v2
	v_mov_b32_e32 v125, v2
	v_mov_b32_e32 v126, v2
	v_mov_b32_e32 v127, v2
	v_mov_b32_e32 v128, v2
	v_mov_b32_e32 v129, v2
	s_waitcnt vmcnt(0) lgkmcnt(0)
	s_barrier
	v_add_u32_e32 v166, v140, v141
	v_add_u32_e32 v170, v142, v144
	ds_read_b128 v[166:169], v166
	v_add_u32_e32 v174, v143, v151
	ds_read_b128 v[170:173], v170
	v_add_u32_e32 v178, v152, v154
	ds_read_b128 v[174:177], v174 offset:32768
	v_add_u32_e32 v182, v153, v155
	ds_read_b128 v[178:181], v178 offset:32768
	v_add_u32_e32 v186, v156, v164
	ds_read_b128 v[182:185], v182 offset:32768
	ds_read_b128 v[186:189], v186 offset:32768
.LBB0_284:
	s_and_b32 s35, s7, 0x10000
	s_xor_b32 s100, s35, 0x10000
	s_add_i32 s34, s35, s3
	v_add3_u32 v190, s100, v140, v161
	v_add3_u32 v194, s100, v142, v163
	ds_read_b128 v[190:193], v190
	v_add3_u32 v198, s100, v143, v159
	ds_read_b128 v[194:197], v194
	v_add3_u32 v202, s100, v152, v160
	ds_read_b128 v[198:201], v198 offset:32768
	v_add3_u32 v206, s100, v153, v157
	ds_read_b128 v[202:205], v202 offset:32768
	v_add3_u32 v210, s100, v156, v158
	ds_read_b128 v[206:209], v206 offset:32768
	ds_read_b128 v[210:213], v210 offset:32768
	v_lshl_add_u64 v[214:215], v[130:131], 0, s[30:31]
	v_lshl_add_u64 v[226:227], v[132:133], 0, s[30:31]
	s_mov_b32 m0, s34
	v_lshl_add_u64 v[228:229], v[214:215], 0, s[28:29]
	s_setprio 1
	s_waitcnt lgkmcnt(6)
	v_mfma_f32_32x32x16_bf16 v[114:129], v[166:169], v[174:177], v[114:129]
	global_load_lds_dwordx4 v[228:229], off
	v_lshl_add_u64 v[228:229], v[214:215], 0, s[24:25]
	s_add_i32 m0, s34, 0x2000
	v_mfma_f32_32x32x16_bf16 v[98:113], v[166:169], v[178:181], v[98:113]
	global_load_lds_dwordx4 v[228:229], off
	v_lshl_add_u64 v[228:229], v[214:215], 0, s[26:27]
	s_add_i32 m0, s34, 0x4000
	v_mfma_f32_32x32x16_bf16 v[82:97], v[166:169], v[182:185], v[82:97]
	global_load_lds_dwordx4 v[228:229], off
	v_lshl_add_u64 v[228:229], v[214:215], 0, s[38:39]
	s_add_i32 m0, s34, 0x6000
	v_mfma_f32_32x32x16_bf16 v[66:81], v[166:169], v[186:189], v[66:81]
	global_load_lds_dwordx4 v[228:229], off
	v_lshl_add_u64 v[228:229], v[226:227], 0, s[28:29]
	s_add_i32 m0, s34, 0x8000
	v_mfma_f32_32x32x16_bf16 v[50:65], v[170:173], v[174:177], v[50:65]
	global_load_lds_dwordx4 v[228:229], off
	v_lshl_add_u64 v[228:229], v[226:227], 0, s[24:25]
	s_add_i32 m0, s34, 0xa000
	v_mfma_f32_32x32x16_bf16 v[34:49], v[170:173], v[178:181], v[34:49]
	global_load_lds_dwordx4 v[228:229], off
	v_lshl_add_u64 v[228:229], v[226:227], 0, s[26:27]
	s_add_i32 m0, s34, 0xc000
	v_mfma_f32_32x32x16_bf16 v[18:33], v[170:173], v[182:185], v[18:33]
	global_load_lds_dwordx4 v[228:229], off
	v_lshl_add_u64 v[228:229], v[226:227], 0, s[38:39]
	s_add_i32 m0, s34, 0xe000
	v_mfma_f32_32x32x16_bf16 v[2:17], v[170:173], v[186:189], v[2:17]
	global_load_lds_dwordx4 v[228:229], off
	s_setprio 0
	v_add3_u32 v166, s100, v140, v149
	v_add3_u32 v170, s100, v142, v150
	ds_read_b128 v[166:169], v166
	v_add3_u32 v174, s100, v143, v147
	ds_read_b128 v[170:173], v170
	v_add3_u32 v178, s100, v152, v148
	ds_read_b128 v[174:177], v174 offset:32768
	v_add3_u32 v182, s100, v153, v145
	ds_read_b128 v[178:181], v178 offset:32768
	v_add3_u32 v186, s100, v156, v146
	ds_read_b128 v[182:185], v182 offset:32768
	ds_read_b128 v[186:189], v186 offset:32768
	s_setprio 1
	s_waitcnt lgkmcnt(6)
	v_mfma_f32_32x32x16_bf16 v[114:129], v[190:193], v[198:201], v[114:129]
	v_mfma_f32_32x32x16_bf16 v[98:113], v[190:193], v[202:205], v[98:113]
	v_mfma_f32_32x32x16_bf16 v[82:97], v[190:193], v[206:209], v[82:97]
	v_mfma_f32_32x32x16_bf16 v[66:81], v[190:193], v[210:213], v[66:81]
	v_mfma_f32_32x32x16_bf16 v[50:65], v[194:197], v[198:201], v[50:65]
	v_mfma_f32_32x32x16_bf16 v[34:49], v[194:197], v[202:205], v[34:49]
	v_mfma_f32_32x32x16_bf16 v[18:33], v[194:197], v[206:209], v[18:33]
	v_mfma_f32_32x32x16_bf16 v[2:17], v[194:197], v[210:213], v[2:17]
	s_setprio 0
	v_add3_u32 v190, s100, v140, v138
	v_add3_u32 v194, s100, v142, v139
	ds_read_b128 v[190:193], v190
	v_add3_u32 v198, s100, v143, v136
	ds_read_b128 v[194:197], v194
	v_add3_u32 v202, s100, v152, v137
	ds_read_b128 v[198:201], v198 offset:32768
	v_add3_u32 v206, s100, v153, v134
	ds_read_b128 v[202:205], v202 offset:32768
	v_add3_u32 v210, s100, v156, v135
	ds_read_b128 v[206:209], v206 offset:32768
	ds_read_b128 v[210:213], v210 offset:32768
	s_setprio 1
	s_waitcnt lgkmcnt(6)
	v_mfma_f32_32x32x16_bf16 v[114:129], v[166:169], v[174:177], v[114:129]
	v_mfma_f32_32x32x16_bf16 v[98:113], v[166:169], v[178:181], v[98:113]
	v_mfma_f32_32x32x16_bf16 v[82:97], v[166:169], v[182:185], v[82:97]
	v_mfma_f32_32x32x16_bf16 v[66:81], v[166:169], v[186:189], v[66:81]
	v_mfma_f32_32x32x16_bf16 v[50:65], v[170:173], v[174:177], v[50:65]
	v_mfma_f32_32x32x16_bf16 v[34:49], v[170:173], v[178:181], v[34:49]
	v_mfma_f32_32x32x16_bf16 v[18:33], v[170:173], v[182:185], v[18:33]
	v_mfma_f32_32x32x16_bf16 v[2:17], v[170:173], v[186:189], v[2:17]
	s_setprio 0
	s_add_u32 s30, s30, 0x80
	s_addc_u32 s31, s31, 0
	s_add_i32 s7, s7, 0x10000
	s_waitcnt vmcnt(0) lgkmcnt(0)
	s_barrier
; DI f32x16 mfma(bf16x8 a, bf16x8 b, f32x16 c) { return __builtin_amdgcn_mfma_f32_32x32x16_bf16(a, b, c, 0, 0, 0); }
; template <int BK> DI int swz(int row) { constexpr int CPR = BK / 8; return (row / (16 / CPR)) % CPR; }
; DI void wait_vm0() { asm volatile("s_waitcnt vmcnt(0)" ::: "memory"); }
;   DI void pre(int grow0, int gcol0, int lane, int w, char* lds) { xpass(0, grow0, gcol0, lane, w, lds); }
;     ...
;   for (int kt = 0; kt < nk; ++kt) {
;     char* cur = lds + (kt & 1) * STG; char* nxt = lds + ((kt + 1) & 1) * STG;
;     const bool more = kt + 1 < nk;
;     const bf16_t* An = Ag + (kt + 1) * BK; const bf16_t* Bn = Bg + (kt + 1) * BK;
;     if (!more) epi.pre(row0 + wm * 64, col0 + wn * (32 * NTW), lane, w, lds);
;     bf16x8 fa[2][2], fb[2][NTW];
; #pragma unroll
;     for (int mt = 0; mt < 2; ++mt) { int row = wm * 64 + mt * 32 + l31; fa[0][mt] = *(const bf16x8*)(cur + row * (BK * 2) + ((hh ^ swz<BK>(row)) << 4)); }
; #pragma unroll
;     for (int nt = 0; nt < NTW; ++nt) { int row = wn * (32 * NTW) + nt * 32 + l31; fb[0][nt] = *(const bf16x8*)(cur + ABYTES + row * (BK * 2) + ((hh ^ swz<BK>(row)) << 4)); }
; #pragma unroll
;     for (int kk = 0; kk < NKK; ++kk) {
;       if (kk + 1 < NKK) {
;         const int ch = (kk + 1) * 2 + hh;
; #pragma unroll
;         for (int mt = 0; mt < 2; ++mt) { int row = wm * 64 + mt * 32 + l31; fa[(kk + 1) & 1][mt] = *(const bf16x8*)(cur + row * (BK * 2) + ((ch ^ swz<BK>(row)) << 4)); }
; #pragma unroll
;         for (int nt = 0; nt < NTW; ++nt) { int row = wn * (32 * NTW) + nt * 32 + l31; fb[(kk + 1) & 1][nt] = *(const bf16x8*)(cur + ABYTES + row * (BK * 2) + ((ch ^ swz<BK>(row)) << 4)); }
;       }
;       if (more) {
; #pragma unroll
;         for (int q = 0; q < PPK; ++q) {
;           const int pi = kk * PPK + q;
;           if (pi < NPA) stage_piece<BM, BK>(An, lda, nxt, tid, pi, wv);
;           else if (pi < NP) stage_piece<BN, BK>(Bn, ldb, nxt + ABYTES, tid, pi - NPA, wv);
;         }
;       }
;       __builtin_amdgcn_s_setprio(1);
; #pragma unroll
;       for (int mt = 0; mt < 2; ++mt)
; #pragma unroll
;         for (int nt = 0; nt < NTW; ++nt) acc[mt][nt] = mfma(fa[kk & 1][mt], fb[kk & 1][nt], acc[mt][nt]);
;       __builtin_amdgcn_s_setprio(0);
;       __builtin_amdgcn_sched_barrier(0);
;     }
;     wait_vm0();
;     __syncthreads();
	v_add3_u32 v166, s35, v140, v141
	v_add3_u32 v170, s35, v142, v144
	ds_read_b128 v[166:169], v166
	v_add3_u32 v174, s35, v143, v151
	ds_read_b128 v[170:173], v170
	v_add3_u32 v178, s35, v152, v154
	ds_read_b128 v[174:177], v174 offset:32768
	v_add3_u32 v182, s35, v153, v155
	ds_read_b128 v[178:181], v178 offset:32768
	v_add3_u32 v186, s35, v156, v164
	ds_read_b128 v[182:185], v182 offset:32768
	ds_read_b128 v[186:189], v186 offset:32768
	s_setprio 1
	v_mfma_f32_32x32x16_bf16 v[114:129], v[190:193], v[198:201], v[114:129]
	v_mfma_f32_32x32x16_bf16 v[98:113], v[190:193], v[202:205], v[98:113]
	v_mfma_f32_32x32x16_bf16 v[82:97], v[190:193], v[206:209], v[82:97]
	v_mfma_f32_32x32x16_bf16 v[66:81], v[190:193], v[210:213], v[66:81]
	v_mfma_f32_32x32x16_bf16 v[50:65], v[194:197], v[198:201], v[50:65]
	v_mfma_f32_32x32x16_bf16 v[34:49], v[194:197], v[202:205], v[34:49]
	v_mfma_f32_32x32x16_bf16 v[18:33], v[194:197], v[206:209], v[18:33]
	v_mfma_f32_32x32x16_bf16 v[2:17], v[194:197], v[210:213], v[2:17]
	s_setprio 0
	s_cmpk_eq_i32 s30, 0x780
	s_cbranch_scc0 .LBB0_284
	s_waitcnt lgkmcnt(0)
	v_add_u32_e32 v0, 0x10000, v140
	v_add_u32_e32 v198, 0x10000, v142
	v_add_u32_e32 v130, v0, v141
	v_add_u32_e32 v140, v198, v144
	v_add_u32_e32 v199, 0x18000, v143
	v_add_u32_e32 v200, 0x18000, v152
	ds_read_b128 v[130:133], v130
	ds_read_b128 v[166:169], v140
	v_add_u32_e32 v140, v199, v151
	v_add_u32_e32 v144, v200, v154
	v_add_u32_e32 v201, 0x18000, v153
	ds_read_b128 v[140:143], v140
	ds_read_b128 v[170:173], v144
	v_add_u32_e32 v144, v201, v155
	v_add_u32_e32 v202, 0x18000, v156
	v_add_u32_e32 v151, v202, v164
	ds_read_b128 v[152:155], v144
	ds_read_b128 v[174:177], v151
	v_add_u32_e32 v144, v0, v161
	v_add_u32_e32 v151, v198, v163
	ds_read_b128 v[178:181], v144
	ds_read_b128 v[182:185], v151
	v_add_u32_e32 v144, v199, v159
	v_add_u32_e32 v151, v200, v160
	ds_read_b128 v[186:189], v144
	ds_read_b128 v[190:193], v151
	v_add_u32_e32 v144, v201, v157
	v_add_u32_e32 v151, v202, v158
	ds_read_b128 v[156:159], v144
	ds_read_b128 v[194:197], v151
	s_add_i32 s44, s44, s94
	s_cmpk_gt_i32 s44, 0xff
	s_cselect_b64 s[30:31], -1, 0
	s_cmpk_lt_i32 s44, 0x100
	s_setprio 1
	s_waitcnt lgkmcnt(9)
	v_mfma_f32_32x32x16_bf16 v[114:129], v[130:133], v[140:143], v[114:129]
	s_waitcnt lgkmcnt(8)
	v_mfma_f32_32x32x16_bf16 v[98:113], v[130:133], v[170:173], v[98:113]
	s_waitcnt lgkmcnt(7)
	v_mfma_f32_32x32x16_bf16 v[82:97], v[130:133], v[152:155], v[82:97]
	s_waitcnt lgkmcnt(6)
	v_mfma_f32_32x32x16_bf16 v[66:81], v[130:133], v[174:177], v[66:81]
	v_mfma_f32_32x32x16_bf16 v[50:65], v[166:169], v[140:143], v[50:65]
	v_mfma_f32_32x32x16_bf16 v[34:49], v[166:169], v[170:173], v[34:49]
	v_mfma_f32_32x32x16_bf16 v[18:33], v[166:169], v[152:155], v[18:33]
	v_mfma_f32_32x32x16_bf16 v[2:17], v[166:169], v[174:177], v[2:17]
	s_setprio 0
	v_add_u32_e32 v130, v0, v149
	v_add_u32_e32 v140, v198, v150
	v_add_u32_e32 v144, v199, v147
	ds_read_b128 v[130:133], v130
	ds_read_b128 v[140:143], v140
	v_add_u32_e32 v147, v200, v148
	ds_read_b128 v[148:151], v144
	ds_read_b128 v[152:155], v147
	v_add_u32_e32 v144, v201, v145
	v_add_u32_e32 v160, v202, v146
	ds_read_b128 v[144:147], v144
	ds_read_b128 v[166:169], v160
	s_setprio 1
	s_waitcnt lgkmcnt(9)
	v_mfma_f32_32x32x16_bf16 v[114:129], v[178:181], v[186:189], v[114:129]
	s_waitcnt lgkmcnt(8)
	v_mfma_f32_32x32x16_bf16 v[98:113], v[178:181], v[190:193], v[98:113]
	s_waitcnt lgkmcnt(7)
	v_mfma_f32_32x32x16_bf16 v[82:97], v[178:181], v[156:159], v[82:97]
	s_waitcnt lgkmcnt(6)
	v_mfma_f32_32x32x16_bf16 v[66:81], v[178:181], v[194:197], v[66:81]
	v_mfma_f32_32x32x16_bf16 v[50:65], v[182:185], v[186:189], v[50:65]
	v_mfma_f32_32x32x16_bf16 v[34:49], v[182:185], v[190:193], v[34:49]
	v_mfma_f32_32x32x16_bf16 v[18:33], v[182:185], v[156:159], v[18:33]
	v_mfma_f32_32x32x16_bf16 v[2:17], v[182:185], v[194:197], v[2:17]
	s_setprio 0
	v_add_u32_e32 v0, v0, v138
	v_add_u32_e32 v138, v198, v139
	ds_read_b128 v[156:159], v0
	ds_read_b128 v[170:173], v138
	v_add_u32_e32 v0, v199, v136
	v_add_u32_e32 v160, v200, v137
	ds_read_b128 v[136:139], v0
	ds_read_b128 v[174:177], v160
	v_add_u32_e32 v0, v201, v134
	v_add_u32_e32 v134, v202, v135
	ds_read_b128 v[178:181], v0
	ds_read_b128 v[182:185], v134
	s_setprio 1
	s_waitcnt lgkmcnt(9)
	v_mfma_f32_32x32x16_bf16 v[114:129], v[130:133], v[148:151], v[114:129]
	s_waitcnt lgkmcnt(8)
	v_mfma_f32_32x32x16_bf16 v[98:113], v[130:133], v[152:155], v[98:113]
	s_waitcnt lgkmcnt(7)
	v_mfma_f32_32x32x16_bf16 v[82:97], v[130:133], v[144:147], v[82:97]
	s_waitcnt lgkmcnt(6)
	v_mfma_f32_32x32x16_bf16 v[66:81], v[130:133], v[166:169], v[66:81]
	v_mfma_f32_32x32x16_bf16 v[50:65], v[140:143], v[148:151], v[50:65]
	v_mfma_f32_32x32x16_bf16 v[34:49], v[140:143], v[152:155], v[34:49]
	v_mfma_f32_32x32x16_bf16 v[18:33], v[140:143], v[144:147], v[18:33]
	v_mfma_f32_32x32x16_bf16 v[2:17], v[140:143], v[166:169], v[2:17]
	s_setprio 0
	s_setprio 1
	s_waitcnt lgkmcnt(3)
	v_mfma_f32_32x32x16_bf16 v[114:129], v[156:159], v[136:139], v[114:129]
	s_waitcnt lgkmcnt(2)
	v_mfma_f32_32x32x16_bf16 v[98:113], v[156:159], v[174:177], v[98:113]
	s_waitcnt lgkmcnt(1)
	v_mfma_f32_32x32x16_bf16 v[82:97], v[156:159], v[178:181], v[82:97]
	s_waitcnt lgkmcnt(0)
	v_mfma_f32_32x32x16_bf16 v[66:81], v[156:159], v[182:185], v[66:81]
	v_mfma_f32_32x32x16_bf16 v[50:65], v[170:173], v[136:139], v[50:65]
	v_mfma_f32_32x32x16_bf16 v[34:49], v[170:173], v[174:177], v[34:49]
	v_mfma_f32_32x32x16_bf16 v[18:33], v[170:173], v[178:181], v[18:33]
	v_mfma_f32_32x32x16_bf16 v[2:17], v[170:173], v[182:185], v[2:17]
	s_setprio 0
	s_waitcnt vmcnt(0)
	s_barrier
; DI int launder(int x) { asm volatile("" : "+v"(x)); return x; }
;   DI void pre(int grow0, int gcol0, int lane, int w, char* lds) { xpass(0, grow0, gcol0, lane, w, lds); }
;     ...
;   if (has_next) { const int tid3 = launder(threadIdx.x); stage_tile<BM, BK>(A + (size_t)row0n * lda, lda, lds, tid3); stage_tile<BN, BK>(Bt + (size_t)col0n * ldb, ldb, lds + ABYTES, tid3); }
; template <class Epi>
; DI void gemm_phase256(const bf16_t* A, int lda, const bf16_t* Bt, int K, int nN, char* lds, Epi& epi, int vb) {
;     ...
;   for (int t = vb; t < ntiles; t += gridDim.x) {
;     const int x = t & 7, L = t >> 3; const int pm = 8 * x + (L & 7), pn = L >> 3;
;     const int t2 = t + gridDim.x; const bool hn = t2 < ntiles;
;     const int x2 = t2 & 7, L2 = t2 >> 3; const int pm2 = 8 * x2 + (L2 & 7), pn2 = L2 >> 3;
;     gemm_tile<4, 64>(A, lda, Bt, K, K, pm * 256, pn * 256, lds, epi, pre, hn, pm2 * 256, pn2 * 256);
;     pre = hn;
	s_cbranch_scc0 .LBB0_280
	v_mov_b32_e32 v132, v216
	s_lshl_b32 s3, s44, 3
	v_ashrrev_i32_e32 v0, 31, v132
	v_lshrrev_b32_e32 v130, 29, v0
	v_lshrrev_b32_e32 v0, 28, v0
	v_add_u32_e32 v0, v132, v0
	v_ashrrev_i32_e32 v0, 4, v0
	s_and_b32 s3, s3, 56
	s_bfe_u32 s7, s44, 0x30003
	v_lshrrev_b32_e32 v133, 29, v0
	s_or_b32 s3, s3, s7
	s_lshl_b32 s7, s44, 2
	v_add_u32_e32 v130, v132, v130
	v_add_u32_e32 v133, v0, v133
	s_and_b32 s34, s7, 0xffffff00
	s_lshl_b32 s3, s3, 19
	v_and_b32_e32 v131, 0xffffff8, v130
	v_and_b32_e32 v133, 0xffffff8, v133
	s_add_u32 s46, s12, s3
	v_sub_u32_e32 v131, v132, v131
	v_sub_u32_e32 v0, v0, v133
	v_lshlrev_b32_e32 v130, 8, v130
	v_readfirstlane_b32 s3, v132
	s_addc_u32 s47, s13, 0
	v_xor_b32_e32 v0, v0, v131
	v_and_b32_e32 v130, 0xfffff800, v130
	s_lshl_b32 s3, s3, 4
	v_lshl_add_u32 v0, v0, 4, v130
	s_and_b32 s3, s3, 0xfffffc00
	v_lshl_add_u64 v[130:131], s[46:47], 0, v[0:1]
	s_mov_b32 m0, s3
	v_lshl_add_u64 v[132:133], v[130:131], 0, s[58:59]
	global_load_lds_dwordx4 v0, s[46:47]
	s_add_i32 m0, s3, 0x2000
	s_ashr_i32 s35, s34, 31
	global_load_lds_dwordx4 v[132:133], off
	v_lshl_add_u64 v[132:133], v[130:131], 0, s[48:49]
	s_add_i32 m0, s3, 0x4000
	s_lshl_b64 s[34:35], s[34:35], 11
	global_load_lds_dwordx4 v[132:133], off
	s_add_i32 m0, s3, 0x6000
	s_add_u32 s34, s40, s34
	v_lshl_add_u64 v[130:131], v[130:131], 0, s[50:51]
	s_addc_u32 s35, s41, s35
	global_load_lds_dwordx4 v[130:131], off
	v_lshl_add_u64 v[130:131], s[34:35], 0, v[0:1]
	s_add_i32 m0, s3, 0x8000
	v_lshl_add_u64 v[132:133], v[130:131], 0, s[58:59]
	global_load_lds_dwordx4 v0, s[34:35]
	s_add_i32 m0, s3, 0xa000
	s_nop 0
	global_load_lds_dwordx4 v[132:133], off
	v_lshl_add_u64 v[132:133], v[130:131], 0, s[48:49]
	s_add_i32 m0, s3, 0xc000
	v_lshl_add_u64 v[130:131], v[130:131], 0, s[50:51]
	global_load_lds_dwordx4 v[132:133], off
	s_add_i32 m0, s3, 0xe000
	s_nop 0
	global_load_lds_dwordx4 v[130:131], off
	s_branch .LBB0_280

; DI f32x16 zero16() { f32x16 z; for (int i = 0; i < 16; ++i) z[i] = 0.f; return z; }
;     ...
;   const int tid = launder(threadIdx.x), lane = tid & 63, w = tid >> 6, wm = w % WM, wn = w / WM;
;   const int l31 = lane & 31, hh = lane >> 5;
;   f32x16 acc[2][NTW];
; #pragma unroll
;   for (int a = 0; a < 2; ++a)
; #pragma unroll
;     for (int b = 0; b < NTW; ++b) acc[a][b] = zero16();
;   const bf16_t* Ag = A + (size_t)row0 * lda; const bf16_t* Bg = Bt + (size_t)col0 * ldb;
;   const int wv = __builtin_amdgcn_readfirstlane(tid >> 6);
;   __syncthreads();
;   if (!pre) { stage_tile<BM, BK>(Ag, lda, lds, tid); stage_tile<BN, BK>(Bg, ldb, lds + ABYTES, tid); }
;   wait_vm0();
;   __syncthreads();
;   const int nk = K / BK;
;   for (int kt = 0; kt < nk; ++kt) {
;     char* cur = lds + (kt & 1) * STG; char* nxt = lds + ((kt + 1) & 1) * STG;
;     const bool more = kt + 1 < nk;
;     const bf16_t* An = Ag + (kt + 1) * BK; const bf16_t* Bn = Bg + (kt + 1) * BK;
;     if (!more) epi.pre(row0 + wm * 64, col0 + wn * (32 * NTW), lane, w, lds);
;     bf16x8 fa[2][2], fb[2][NTW];
; #pragma unroll
;     for (int mt = 0; mt < 2; ++mt) { int row = wm * 64 + mt * 32 + l31; fa[0][mt] = *(const bf16x8*)(cur + row * (BK * 2) + ((hh ^ swz<BK>(row)) << 4)); }
; #pragma unroll
;     for (int nt = 0; nt < NTW; ++nt) { int row = wn * (32 * NTW) + nt * 32 + l31; fb[0][nt] = *(const bf16x8*)(cur + ABYTES + row * (BK * 2) + ((hh ^ swz<BK>(row)) << 4)); }
; #pragma unroll
;     for (int kk = 0; kk < NKK; ++kk) {
;       if (kk + 1 < NKK) {
;         const int ch = (kk + 1) * 2 + hh;
; #pragma unroll
;         for (int mt = 0; mt < 2; ++mt) { int row = wm * 64 + mt * 32 + l31; fa[(kk + 1) & 1][mt] = *(const bf16x8*)(cur + row * (BK * 2) + ((ch ^ swz<BK>(row)) << 4)); }
; #pragma unroll
;         for (int nt = 0; nt < NTW; ++nt) { int row = wn * (32 * NTW) + nt * 32 + l31; fb[(kk + 1) & 1][nt] = *(const bf16x8*)(cur + ABYTES + row * (BK * 2) + ((ch ^ swz<BK>(row)) << 4)); }
; template <class Epi>
; DI void gemm_phaseLNX(const bf16_t* A, int K, const bf16_t* Bt, char* lds, Epi& epi, int vb, bool blockdiag = false) {
;   const int t = vb; const int x = t & 7, L = t >> 3; const int pm = 8 * x + (L & 7), pn = L >> 3;
;   if (blockdiag) gemm_tile<4, 64>(A + pn * 256, K, Bt + pn * 256, K, 256, pm * 256, pn * 256, lds, epi);
;   else gemm_tile<4, 64>(A, K, Bt, K, K, pm * 256, pn * 256, lds, epi);
.LBB0_290:
	s_cmp_lg_u32 s71, 0
	s_cbranch_scc0 .LBB0_369
	v_readlane_b32 s2, v255, 39
	v_readlane_b32 s3, v255, 40
	v_mov_b32_e32 v8, v216
	s_load_dwordx2 s[2:3], s[2:3], 0x140
	v_readlane_b32 s30, v253, 27
	v_ashrrev_i32_e32 v2, 31, v8
	v_lshrrev_b32_e32 v3, 29, v2
	v_lshrrev_b32_e32 v2, 28, v2
	v_add_u32_e32 v2, v8, v2
	v_ashrrev_i32_e32 v2, 4, v2
	v_lshrrev_b32_e32 v5, 29, v2
	v_add_u32_e32 v3, v8, v3
	v_add_u32_e32 v5, v2, v5
	v_lshrrev_b32_e32 v4, 3, v3
	v_and_b32_e32 v3, 0xffffff8, v3
	v_and_b32_e32 v5, 0xffffff8, v5
	s_mul_i32 s6, s30, 0x1600
	v_sub_u32_e32 v3, v8, v3
	v_sub_u32_e32 v2, v2, v5
	s_movk_i32 s7, 0x1600
	s_waitcnt lgkmcnt(0)
	s_add_u32 s2, s2, s6
	s_mul_hi_i32 s6, s30, 0x1600
	v_xor_b32_e32 v2, v2, v3
	v_mul_lo_u32 v3, v4, s7
	v_readfirstlane_b32 s7, v8
	v_readlane_b32 s31, v253, 28
	s_addc_u32 s3, s3, s6
	s_lshl_b32 s7, s7, 4
	v_readlane_b32 s30, v253, 37
	s_and_b32 s7, s7, 0xfffffc00
	v_lshl_add_u32 v2, v2, 4, v3
	v_mov_b32_e32 v3, v1
	v_readlane_b32 s31, v253, 38
	s_mov_b32 m0, s7
	s_waitcnt vmcnt(0)
	s_barrier
	v_lshl_add_u64 v[4:5], s[30:31], 0, v[2:3]
	s_nop 0
	global_load_lds_dwordx4 v2, s[30:31]
	s_mov_b64 s[30:31], 0x58000
	v_lshl_add_u64 v[6:7], v[4:5], 0, s[30:31]
	s_add_i32 m0, s7, 0x2000
	s_mov_b64 s[34:35], 0xb0000
	global_load_lds_dwordx4 v[6:7], off
	v_lshl_add_u64 v[6:7], v[4:5], 0, s[34:35]
	s_add_i32 m0, s7, 0x4000
	s_mov_b64 s[36:37], 0x108000
	global_load_lds_dwordx4 v[6:7], off
	v_lshl_add_u64 v[4:5], v[4:5], 0, s[36:37]
	s_add_i32 m0, s7, 0x6000
	v_lshl_add_u64 v[130:131], s[2:3], 0, v[2:3]
	global_load_lds_dwordx4 v[4:5], off
	s_add_i32 m0, s7, 0x8000
	v_lshl_add_u64 v[4:5], v[130:131], 0, s[30:31]
	global_load_lds_dwordx4 v2, s[2:3]
	s_add_i32 m0, s7, 0xa000
	v_ashrrev_i32_e32 v134, 6, v8
	global_load_lds_dwordx4 v[4:5], off
	v_lshl_add_u64 v[4:5], v[130:131], 0, s[34:35]
	s_add_i32 m0, s7, 0xc000
	v_and_b32_e32 v6, 31, v8
	global_load_lds_dwordx4 v[4:5], off
	v_lshl_add_u64 v[4:5], v[130:131], 0, s[36:37]
	s_add_i32 m0, s7, 0xe000
	v_and_b32_e32 v0, 63, v8
	global_load_lds_dwordx4 v[4:5], off
	v_lshrrev_b32_e32 v4, 30, v134
	v_add_u32_e32 v4, v134, v4
	v_ashrrev_i32_e32 v5, 2, v4
	v_mul_i32_i24_e32 v7, 4, v5
	v_sub_u32_e32 v7, v134, v7
	v_lshlrev_b32_e32 v169, 6, v7
	v_lshlrev_b32_e32 v168, 7, v5
	v_or_b32_e32 v5, v169, v6
	v_bfe_u32 v7, v7, 25, 1
	v_bfe_u32 v135, v8, 5, 1
	v_lshlrev_b32_e32 v136, 7, v5
	v_add_u32_e32 v8, v5, v7
	v_or_b32_e32 v5, 32, v5
	v_lshlrev_b32_e32 v144, 7, v5
	v_add_u32_e32 v5, v5, v7
	v_ashrrev_i32_e32 v7, 1, v5
	v_ashrrev_i32_e32 v5, 31, v5
	v_ashrrev_i32_e32 v9, 1, v8
	v_ashrrev_i32_e32 v8, 31, v8
	v_lshrrev_b32_e32 v5, 29, v5
	v_lshrrev_b32_e32 v8, 29, v8
	v_add_u32_e32 v5, v7, v5
	v_add_u32_e32 v8, v9, v8
	v_and_b32_e32 v5, -8, v5
	v_and_b32_e32 v8, -8, v8
	v_sub_u32_e32 v5, v7, v5
	v_or_b32_e32 v6, v168, v6
	v_sub_u32_e32 v8, v9, v8
	v_xor_b32_e32 v7, v5, v135
	v_lshrrev_b32_e32 v4, 31, v4
	v_xor_b32_e32 v9, v8, v135
	v_lshlrev_b32_e32 v146, 4, v7
	v_add_u32_e32 v7, v6, v4
	v_lshlrev_b32_e32 v143, 4, v9
	v_ashrrev_i32_e32 v9, 1, v7
	v_ashrrev_i32_e32 v7, 31, v7
	v_lshrrev_b32_e32 v7, 29, v7
	v_add_u32_e32 v7, v9, v7
	v_and_b32_e32 v7, -8, v7
	v_sub_u32_e32 v7, v9, v7
	v_xor_b32_e32 v9, v7, v135
	v_lshlrev_b32_e32 v151, 4, v9
	v_or_b32_e32 v9, 32, v6
	v_lshlrev_b32_e32 v152, 7, v9
	v_add_u32_e32 v9, v9, v4
	v_ashrrev_i32_e32 v10, 1, v9
	v_ashrrev_i32_e32 v9, 31, v9
	v_lshrrev_b32_e32 v9, 29, v9
	v_add_u32_e32 v9, v10, v9
	v_and_b32_e32 v9, -8, v9
	v_sub_u32_e32 v9, v10, v9
	v_xor_b32_e32 v10, v9, v135
	v_lshlrev_b32_e32 v145, 7, v6
	v_lshlrev_b32_e32 v156, 4, v10
	v_or_b32_e32 v10, 64, v6
	v_or_b32_e32 v6, 0x60, v6
	v_lshlrev_b32_e32 v155, 7, v10
	v_add_u32_e32 v10, v10, v4
	v_add_u32_e32 v4, v6, v4
	v_lshlrev_b32_e32 v158, 7, v6
	v_ashrrev_i32_e32 v6, 1, v4
	v_ashrrev_i32_e32 v4, 31, v4
	v_lshrrev_b32_e32 v4, 29, v4
	v_add_u32_e32 v4, v6, v4
	v_and_b32_e32 v4, -8, v4
	v_sub_u32_e32 v4, v6, v4
	v_ashrrev_i32_e32 v11, 1, v10
	v_ashrrev_i32_e32 v10, 31, v10
	v_xor_b32_e32 v6, v4, v135
	v_lshrrev_b32_e32 v10, 29, v10
	v_lshlrev_b32_e32 v167, 4, v6
	v_bitop3_b32 v6, v8, v135, 2 bitop3:0x1e
	v_add_u32_e32 v10, v11, v10
	v_lshlrev_b32_e32 v164, 4, v6
	v_bitop3_b32 v6, v5, v135, 2 bitop3:0x1e
	v_and_b32_e32 v10, -8, v10
	v_lshlrev_b32_e32 v166, 4, v6
	v_bitop3_b32 v6, v7, v135, 2 bitop3:0x1e
	v_sub_u32_e32 v10, v11, v10
	v_lshlrev_b32_e32 v161, 4, v6
	v_bitop3_b32 v6, v9, v135, 2 bitop3:0x1e
	v_lshlrev_b32_e32 v163, 4, v6
	v_bitop3_b32 v6, v10, v135, 2 bitop3:0x1e
	v_lshlrev_b32_e32 v159, 4, v6
	v_bitop3_b32 v6, v4, v135, 2 bitop3:0x1e
	v_lshlrev_b32_e32 v160, 4, v6
	v_bitop3_b32 v6, v8, v135, 4 bitop3:0x1e
	v_lshlrev_b32_e32 v153, 4, v6
	v_bitop3_b32 v6, v5, v135, 4 bitop3:0x1e
	v_lshlrev_b32_e32 v154, 4, v6
	v_bitop3_b32 v6, v7, v135, 4 bitop3:0x1e
	v_readfirstlane_b32 s6, v134
	v_lshlrev_b32_e32 v149, 4, v6
	v_bitop3_b32 v6, v9, v135, 4 bitop3:0x1e
	v_bitop3_b32 v5, v5, v135, 6 bitop3:0x1e
	s_lshl_b32 s2, s6, 10
	v_lshlrev_b32_e32 v150, 4, v6
	v_bitop3_b32 v6, v10, v135, 4 bitop3:0x1e
	v_lshlrev_b32_e32 v142, 4, v5
	v_bitop3_b32 v5, v7, v135, 6 bitop3:0x1e
	v_readlane_b32 s6, v254, 36
	s_waitcnt vmcnt(0)
;     ...
; #pragma unroll
;   for (int a = 0; a < 2; ++a)
; #pragma unroll
;     for (int b = 0; b < NTW; ++b) acc[a][b] = zero16();
;   const bf16_t* Ag = A + (size_t)row0 * lda; const bf16_t* Bg = Bt + (size_t)col0 * ldb;
;   const int wv = __builtin_amdgcn_readfirstlane(tid >> 6);
;   __syncthreads();
;   if (!pre) { stage_tile<BM, BK>(Ag, lda, lds, tid); stage_tile<BN, BK>(Bg, ldb, lds + ABYTES, tid); }
;   wait_vm0();
;   __syncthreads();
;   const int nk = K / BK;
;   for (int kt = 0; kt < nk; ++kt) {
;     char* cur = lds + (kt & 1) * STG; char* nxt = lds + ((kt + 1) & 1) * STG;
;     const bool more = kt + 1 < nk;
;     const bf16_t* An = Ag + (kt + 1) * BK; const bf16_t* Bn = Bg + (kt + 1) * BK;
;     if (!more) epi.pre(row0 + wm * 64, col0 + wn * (32 * NTW), lane, w, lds);
;     bf16x8 fa[2][2], fb[2][NTW];
; #pragma unroll
;     for (int mt = 0; mt < 2; ++mt) { int row = wm * 64 + mt * 32 + l31; fa[0][mt] = *(const bf16x8*)(cur + row * (BK * 2) + ((hh ^ swz<BK>(row)) << 4)); }
; #pragma unroll
;     for (int nt = 0; nt < NTW; ++nt) { int row = wn * (32 * NTW) + nt * 32 + l31; fb[0][nt] = *(const bf16x8*)(cur + ABYTES + row * (BK * 2) + ((hh ^ swz<BK>(row)) << 4)); }
; #pragma unroll
;     for (int kk = 0; kk < NKK; ++kk) {
;       if (kk + 1 < NKK) {
;         const int ch = (kk + 1) * 2 + hh;
; #pragma unroll
;         for (int mt = 0; mt < 2; ++mt) { int row = wm * 64 + mt * 32 + l31; fa[(kk + 1) & 1][mt] = *(const bf16x8*)(cur + row * (BK * 2) + ((ch ^ swz<BK>(row)) << 4)); }
; #pragma unroll
;         for (int nt = 0; nt < NTW; ++nt) { int row = wn * (32 * NTW) + nt * 32 + l31; fb[(kk + 1) & 1][nt] = *(const bf16x8*)(cur + ABYTES + row * (BK * 2) + ((ch ^ swz<BK>(row)) << 4)); }
;       }
;       if (more) {
; #pragma unroll
;         for (int q = 0; q < PPK; ++q) {
;           const int pi = kk * PPK + q;
;           if (pi < NPA) stage_piece<BM, BK>(An, lda, nxt, tid, pi, wv);
;           else if (pi < NP) stage_piece<BN, BK>(Bn, ldb, nxt + ABYTES, tid, pi - NPA, wv);
;         }
;       }
;       __builtin_amdgcn_s_setprio(1);
; #pragma unroll
;       for (int mt = 0; mt < 2; ++mt)
; #pragma unroll
;         for (int nt = 0; nt < NTW; ++nt) acc[mt][nt] = mfma(fa[kk & 1][mt], fb[kk & 1][nt], acc[mt][nt]);
;       __builtin_amdgcn_s_setprio(0);
;       __builtin_amdgcn_sched_barrier(0);
;     }
	v_lshlrev_b32_e32 v147, 4, v6
	v_bitop3_b32 v6, v4, v135, 4 bitop3:0x1e
	v_lshlrev_b32_e32 v139, 4, v5
	v_bitop3_b32 v5, v9, v135, 6 bitop3:0x1e
	v_readlane_b32 s7, v254, 37
	v_xor_b32_e32 v11, v10, v135
	v_lshlrev_b32_e32 v148, 4, v6
	v_bitop3_b32 v6, v8, v135, 6 bitop3:0x1e
	v_lshlrev_b32_e32 v140, 4, v5
	v_bitop3_b32 v5, v10, v135, 6 bitop3:0x1e
	v_bitop3_b32 v4, v4, v135, 6 bitop3:0x1e
	v_lshl_add_u64 v[132:133], s[6:7], 0, v[2:3]
	v_mov_b32_e32 v2, 0
	v_lshlrev_b32_e32 v157, 4, v11
	v_lshlrev_b32_e32 v141, 4, v6
	v_lshlrev_b32_e32 v137, 4, v5
	v_lshlrev_b32_e32 v138, 4, v4
	s_mov_b64 s[6:7], 0
	s_mov_b32 s3, 0x10000
	v_mov_b32_e32 v3, v2
	v_mov_b32_e32 v4, v2
	v_mov_b32_e32 v5, v2
	v_mov_b32_e32 v6, v2
	v_mov_b32_e32 v7, v2
	v_mov_b32_e32 v8, v2
	v_mov_b32_e32 v9, v2
	v_mov_b32_e32 v10, v2
	v_mov_b32_e32 v11, v2
	v_mov_b32_e32 v12, v2
	v_mov_b32_e32 v13, v2
	v_mov_b32_e32 v14, v2
	v_mov_b32_e32 v15, v2
	v_mov_b32_e32 v16, v2
	v_mov_b32_e32 v17, v2
	v_mov_b32_e32 v18, v2
	v_mov_b32_e32 v19, v2
	v_mov_b32_e32 v20, v2
	v_mov_b32_e32 v21, v2
	v_mov_b32_e32 v22, v2
	v_mov_b32_e32 v23, v2
	v_mov_b32_e32 v24, v2
	v_mov_b32_e32 v25, v2
	v_mov_b32_e32 v26, v2
	v_mov_b32_e32 v27, v2
	v_mov_b32_e32 v28, v2
	v_mov_b32_e32 v29, v2
	v_mov_b32_e32 v30, v2
	v_mov_b32_e32 v31, v2
	v_mov_b32_e32 v32, v2
	v_mov_b32_e32 v33, v2
	v_mov_b32_e32 v34, v2
	v_mov_b32_e32 v35, v2
	v_mov_b32_e32 v36, v2
	v_mov_b32_e32 v37, v2
	v_mov_b32_e32 v38, v2
	v_mov_b32_e32 v39, v2
	v_mov_b32_e32 v40, v2
	v_mov_b32_e32 v41, v2
	v_mov_b32_e32 v42, v2
	v_mov_b32_e32 v43, v2
	v_mov_b32_e32 v44, v2
	v_mov_b32_e32 v45, v2
	v_mov_b32_e32 v46, v2
	v_mov_b32_e32 v47, v2
	v_mov_b32_e32 v48, v2
	v_mov_b32_e32 v49, v2
	v_mov_b32_e32 v50, v2
	v_mov_b32_e32 v51, v2
	v_mov_b32_e32 v52, v2
	v_mov_b32_e32 v53, v2
	v_mov_b32_e32 v54, v2
	v_mov_b32_e32 v55, v2
	v_mov_b32_e32 v56, v2
	v_mov_b32_e32 v57, v2
	v_mov_b32_e32 v58, v2
	v_mov_b32_e32 v59, v2
	v_mov_b32_e32 v60, v2
	v_mov_b32_e32 v61, v2
	v_mov_b32_e32 v62, v2
	v_mov_b32_e32 v63, v2
	v_mov_b32_e32 v64, v2
	v_mov_b32_e32 v65, v2
	v_mov_b32_e32 v66, v2
	v_mov_b32_e32 v67, v2
	v_mov_b32_e32 v68, v2
	v_mov_b32_e32 v69, v2
	v_mov_b32_e32 v70, v2
	v_mov_b32_e32 v71, v2
	v_mov_b32_e32 v72, v2
	v_mov_b32_e32 v73, v2
	v_mov_b32_e32 v74, v2
	v_mov_b32_e32 v75, v2
	v_mov_b32_e32 v76, v2
	v_mov_b32_e32 v77, v2
	v_mov_b32_e32 v78, v2
	v_mov_b32_e32 v79, v2
	v_mov_b32_e32 v80, v2
	v_mov_b32_e32 v81, v2
	v_mov_b32_e32 v82, v2
	v_mov_b32_e32 v83, v2
	v_mov_b32_e32 v84, v2
	v_mov_b32_e32 v85, v2
	v_mov_b32_e32 v86, v2
	v_mov_b32_e32 v87, v2
	v_mov_b32_e32 v88, v2
	v_mov_b32_e32 v89, v2
	v_mov_b32_e32 v90, v2
	v_mov_b32_e32 v91, v2
	v_mov_b32_e32 v92, v2
	v_mov_b32_e32 v93, v2
	v_mov_b32_e32 v94, v2
	v_mov_b32_e32 v95, v2
	v_mov_b32_e32 v96, v2
	v_mov_b32_e32 v97, v2
	v_mov_b32_e32 v98, v2
	v_mov_b32_e32 v99, v2
	v_mov_b32_e32 v100, v2
	v_mov_b32_e32 v101, v2
	v_mov_b32_e32 v102, v2
	v_mov_b32_e32 v103, v2
	v_mov_b32_e32 v104, v2
	v_mov_b32_e32 v105, v2
	v_mov_b32_e32 v106, v2
	v_mov_b32_e32 v107, v2
	v_mov_b32_e32 v108, v2
	v_mov_b32_e32 v109, v2
	v_mov_b32_e32 v110, v2
	v_mov_b32_e32 v111, v2
	v_mov_b32_e32 v112, v2
	v_mov_b32_e32 v113, v2
	v_mov_b32_e32 v114, v2
	v_mov_b32_e32 v115, v2
	v_mov_b32_e32 v116, v2
	v_mov_b32_e32 v117, v2
	v_mov_b32_e32 v118, v2
	v_mov_b32_e32 v119, v2
	v_mov_b32_e32 v120, v2
	v_mov_b32_e32 v121, v2
	v_mov_b32_e32 v122, v2
	v_mov_b32_e32 v123, v2
	v_mov_b32_e32 v124, v2
	v_mov_b32_e32 v125, v2
	v_mov_b32_e32 v126, v2
	v_mov_b32_e32 v127, v2
	v_mov_b32_e32 v128, v2
	v_mov_b32_e32 v129, v2
	s_mov_b64 s[36:37], 0x58080
	s_mov_b64 s[40:41], 0xb0080
	s_mov_b64 s[42:43], 0x108080
	s_waitcnt vmcnt(0) lgkmcnt(0)
	s_barrier
	v_add_u32_e32 v170, v136, v143
	v_add_u32_e32 v174, v144, v146
	ds_read_b128 v[170:173], v170
	v_add_u32_e32 v178, v145, v151
	ds_read_b128 v[174:177], v174
	v_add_u32_e32 v182, v152, v156
	ds_read_b128 v[178:181], v178 offset:32768
	v_add_u32_e32 v186, v155, v157
	ds_read_b128 v[182:185], v182 offset:32768
	v_add_u32_e32 v190, v158, v167
	ds_read_b128 v[186:189], v186 offset:32768
	ds_read_b128 v[190:193], v190 offset:32768
.LBB0_292:
	s_and_b32 s30, s3, 0x10000
	s_xor_b32 s100, s30, 0x10000
	s_add_i32 s31, s30, s2
	v_add3_u32 v194, s100, v136, v164
	v_add3_u32 v198, s100, v144, v166
	ds_read_b128 v[194:197], v194
	v_add3_u32 v202, s100, v145, v161
	ds_read_b128 v[198:201], v198
	v_add3_u32 v206, s100, v152, v163
	ds_read_b128 v[202:205], v202 offset:32768
	v_add3_u32 v210, s100, v155, v159
	ds_read_b128 v[206:209], v206 offset:32768
	v_add3_u32 v226, s100, v158, v160
	ds_read_b128 v[210:213], v210 offset:32768
	ds_read_b128 v[226:229], v226 offset:32768
	v_lshl_add_u64 v[214:215], v[132:133], 0, s[6:7]
	v_lshl_add_u64 v[230:231], v[130:131], 0, s[6:7]
	s_mov_b32 m0, s31
	v_lshl_add_u64 v[232:233], v[214:215], 0, s[28:29]
	s_setprio 1
	s_waitcnt lgkmcnt(6)
; DI f32x16 mfma(bf16x8 a, bf16x8 b, f32x16 c) { return __builtin_amdgcn_mfma_f32_32x32x16_bf16(a, b, c, 0, 0, 0); }
; template <int BK> DI int swz(int row) { constexpr int CPR = BK / 8; return (row / (16 / CPR)) % CPR; }
; DI void wait_vm0() { asm volatile("s_waitcnt vmcnt(0)" ::: "memory"); }
;   DI void pre(int grow0, int gcol0, int lane, int w, char* lds) { xpass(0, grow0, gcol0, lane, w, lds); }
;     ...
;   for (int kt = 0; kt < nk; ++kt) {
;     char* cur = lds + (kt & 1) * STG; char* nxt = lds + ((kt + 1) & 1) * STG;
;     const bool more = kt + 1 < nk;
;     const bf16_t* An = Ag + (kt + 1) * BK; const bf16_t* Bn = Bg + (kt + 1) * BK;
;     if (!more) epi.pre(row0 + wm * 64, col0 + wn * (32 * NTW), lane, w, lds);
;     bf16x8 fa[2][2], fb[2][NTW];
; #pragma unroll
;     for (int mt = 0; mt < 2; ++mt) { int row = wm * 64 + mt * 32 + l31; fa[0][mt] = *(const bf16x8*)(cur + row * (BK * 2) + ((hh ^ swz<BK>(row)) << 4)); }
; #pragma unroll
;     for (int nt = 0; nt < NTW; ++nt) { int row = wn * (32 * NTW) + nt * 32 + l31; fb[0][nt] = *(const bf16x8*)(cur + ABYTES + row * (BK * 2) + ((hh ^ swz<BK>(row)) << 4)); }
; #pragma unroll
;     for (int kk = 0; kk < NKK; ++kk) {
;       if (kk + 1 < NKK) {
;         const int ch = (kk + 1) * 2 + hh;
; #pragma unroll
;         for (int mt = 0; mt < 2; ++mt) { int row = wm * 64 + mt * 32 + l31; fa[(kk + 1) & 1][mt] = *(const bf16x8*)(cur + row * (BK * 2) + ((ch ^ swz<BK>(row)) << 4)); }
; #pragma unroll
;         for (int nt = 0; nt < NTW; ++nt) { int row = wn * (32 * NTW) + nt * 32 + l31; fb[(kk + 1) & 1][nt] = *(const bf16x8*)(cur + ABYTES + row * (BK * 2) + ((ch ^ swz<BK>(row)) << 4)); }
;       }
;       if (more) {
; #pragma unroll
;         for (int q = 0; q < PPK; ++q) {
;           const int pi = kk * PPK + q;
;           if (pi < NPA) stage_piece<BM, BK>(An, lda, nxt, tid, pi, wv);
;           else if (pi < NP) stage_piece<BN, BK>(Bn, ldb, nxt + ABYTES, tid, pi - NPA, wv);
;         }
;       }
;       __builtin_amdgcn_s_setprio(1);
; #pragma unroll
;       for (int mt = 0; mt < 2; ++mt)
; #pragma unroll
;         for (int nt = 0; nt < NTW; ++nt) acc[mt][nt] = mfma(fa[kk & 1][mt], fb[kk & 1][nt], acc[mt][nt]);
;       __builtin_amdgcn_s_setprio(0);
;       __builtin_amdgcn_sched_barrier(0);
;     }
;     wait_vm0();
;     __syncthreads();
	v_mfma_f32_32x32x16_bf16 v[114:129], v[170:173], v[178:181], v[114:129]
	global_load_lds_dwordx4 v[232:233], off
	v_lshl_add_u64 v[232:233], v[214:215], 0, s[36:37]
	s_add_i32 m0, s31, 0x2000
	v_mfma_f32_32x32x16_bf16 v[98:113], v[170:173], v[182:185], v[98:113]
	global_load_lds_dwordx4 v[232:233], off
	v_lshl_add_u64 v[232:233], v[214:215], 0, s[40:41]
	s_add_i32 m0, s31, 0x4000
	v_mfma_f32_32x32x16_bf16 v[82:97], v[170:173], v[186:189], v[82:97]
	global_load_lds_dwordx4 v[232:233], off
	v_lshl_add_u64 v[232:233], v[214:215], 0, s[42:43]
	s_add_i32 m0, s31, 0x6000
	v_mfma_f32_32x32x16_bf16 v[66:81], v[170:173], v[190:193], v[66:81]
	global_load_lds_dwordx4 v[232:233], off
	v_lshl_add_u64 v[232:233], v[230:231], 0, s[28:29]
	s_add_i32 m0, s31, 0x8000
	v_mfma_f32_32x32x16_bf16 v[50:65], v[174:177], v[178:181], v[50:65]
	global_load_lds_dwordx4 v[232:233], off
	v_lshl_add_u64 v[232:233], v[230:231], 0, s[36:37]
	s_add_i32 m0, s31, 0xa000
	v_mfma_f32_32x32x16_bf16 v[34:49], v[174:177], v[182:185], v[34:49]
	global_load_lds_dwordx4 v[232:233], off
	v_lshl_add_u64 v[232:233], v[230:231], 0, s[40:41]
	s_add_i32 m0, s31, 0xc000
	v_mfma_f32_32x32x16_bf16 v[18:33], v[174:177], v[186:189], v[18:33]
	global_load_lds_dwordx4 v[232:233], off
	v_lshl_add_u64 v[232:233], v[230:231], 0, s[42:43]
	s_add_i32 m0, s31, 0xe000
	v_mfma_f32_32x32x16_bf16 v[2:17], v[174:177], v[190:193], v[2:17]
	global_load_lds_dwordx4 v[232:233], off
	s_setprio 0
	v_add3_u32 v170, s100, v136, v153
	v_add3_u32 v174, s100, v144, v154
	ds_read_b128 v[170:173], v170
	v_add3_u32 v178, s100, v145, v149
	ds_read_b128 v[174:177], v174
	v_add3_u32 v182, s100, v152, v150
	ds_read_b128 v[178:181], v178 offset:32768
	v_add3_u32 v186, s100, v155, v147
	ds_read_b128 v[182:185], v182 offset:32768
	v_add3_u32 v190, s100, v158, v148
	ds_read_b128 v[186:189], v186 offset:32768
	ds_read_b128 v[190:193], v190 offset:32768
	s_setprio 1
	s_waitcnt lgkmcnt(6)
	v_mfma_f32_32x32x16_bf16 v[114:129], v[194:197], v[202:205], v[114:129]
	v_mfma_f32_32x32x16_bf16 v[98:113], v[194:197], v[206:209], v[98:113]
	v_mfma_f32_32x32x16_bf16 v[82:97], v[194:197], v[210:213], v[82:97]
	v_mfma_f32_32x32x16_bf16 v[66:81], v[194:197], v[226:229], v[66:81]
	v_mfma_f32_32x32x16_bf16 v[50:65], v[198:201], v[202:205], v[50:65]
	v_mfma_f32_32x32x16_bf16 v[34:49], v[198:201], v[206:209], v[34:49]
	v_mfma_f32_32x32x16_bf16 v[18:33], v[198:201], v[210:213], v[18:33]
	v_mfma_f32_32x32x16_bf16 v[2:17], v[198:201], v[226:229], v[2:17]
	s_setprio 0
	v_add3_u32 v194, s100, v136, v141
	v_add3_u32 v198, s100, v144, v142
	ds_read_b128 v[194:197], v194
	v_add3_u32 v202, s100, v145, v139
	ds_read_b128 v[198:201], v198
	v_add3_u32 v206, s100, v152, v140
	ds_read_b128 v[202:205], v202 offset:32768
	v_add3_u32 v210, s100, v155, v137
	ds_read_b128 v[206:209], v206 offset:32768
	v_add3_u32 v226, s100, v158, v138
	ds_read_b128 v[210:213], v210 offset:32768
	ds_read_b128 v[226:229], v226 offset:32768
	s_setprio 1
	s_waitcnt lgkmcnt(6)
	v_mfma_f32_32x32x16_bf16 v[114:129], v[170:173], v[178:181], v[114:129]
	v_mfma_f32_32x32x16_bf16 v[98:113], v[170:173], v[182:185], v[98:113]
	v_mfma_f32_32x32x16_bf16 v[82:97], v[170:173], v[186:189], v[82:97]
	v_mfma_f32_32x32x16_bf16 v[66:81], v[170:173], v[190:193], v[66:81]
	v_mfma_f32_32x32x16_bf16 v[50:65], v[174:177], v[178:181], v[50:65]
	v_mfma_f32_32x32x16_bf16 v[34:49], v[174:177], v[182:185], v[34:49]
	v_mfma_f32_32x32x16_bf16 v[18:33], v[174:177], v[186:189], v[18:33]
	v_mfma_f32_32x32x16_bf16 v[2:17], v[174:177], v[190:193], v[2:17]
	s_setprio 0
	s_add_u32 s6, s6, 0x80
	s_addc_u32 s7, s7, 0
	s_add_i32 s3, s3, 0x10000
	s_waitcnt vmcnt(0) lgkmcnt(0)
	s_barrier
	v_add3_u32 v170, s30, v136, v143
	v_add3_u32 v174, s30, v144, v146
	ds_read_b128 v[170:173], v170
	v_add3_u32 v178, s30, v145, v151
	ds_read_b128 v[174:177], v174
	v_add3_u32 v182, s30, v152, v156
	ds_read_b128 v[178:181], v178 offset:32768
	v_add3_u32 v186, s30, v155, v157
	ds_read_b128 v[182:185], v182 offset:32768
	v_add3_u32 v190, s30, v158, v167
	ds_read_b128 v[186:189], v186 offset:32768
	ds_read_b128 v[190:193], v190 offset:32768
	s_setprio 1
	v_mfma_f32_32x32x16_bf16 v[114:129], v[194:197], v[202:205], v[114:129]
	v_mfma_f32_32x32x16_bf16 v[98:113], v[194:197], v[206:209], v[98:113]
	v_mfma_f32_32x32x16_bf16 v[82:97], v[194:197], v[210:213], v[82:97]
	v_mfma_f32_32x32x16_bf16 v[66:81], v[194:197], v[226:229], v[66:81]
	v_mfma_f32_32x32x16_bf16 v[50:65], v[198:201], v[202:205], v[50:65]
	v_mfma_f32_32x32x16_bf16 v[34:49], v[198:201], v[206:209], v[34:49]
	v_mfma_f32_32x32x16_bf16 v[18:33], v[198:201], v[210:213], v[18:33]
	v_mfma_f32_32x32x16_bf16 v[2:17], v[198:201], v[226:229], v[2:17]
	s_setprio 0
	s_cmpk_lg_i32 s6, 0x1580
	s_cbranch_scc1 .LBB0_292
; DI f32x16 mfma(bf16x8 a, bf16x8 b, f32x16 c) { return __builtin_amdgcn_mfma_f32_32x32x16_bf16(a, b, c, 0, 0, 0); }
;     ...
;   for (int kt = 0; kt < nk; ++kt) {
;     char* cur = lds + (kt & 1) * STG; char* nxt = lds + ((kt + 1) & 1) * STG;
;     const bool more = kt + 1 < nk;
;     const bf16_t* An = Ag + (kt + 1) * BK; const bf16_t* Bn = Bg + (kt + 1) * BK;
;     if (!more) epi.pre(row0 + wm * 64, col0 + wn * (32 * NTW), lane, w, lds);
;     bf16x8 fa[2][2], fb[2][NTW];
; #pragma unroll
;     for (int mt = 0; mt < 2; ++mt) { int row = wm * 64 + mt * 32 + l31; fa[0][mt] = *(const bf16x8*)(cur + row * (BK * 2) + ((hh ^ swz<BK>(row)) << 4)); }
; #pragma unroll
;     for (int nt = 0; nt < NTW; ++nt) { int row = wn * (32 * NTW) + nt * 32 + l31; fb[0][nt] = *(const bf16x8*)(cur + ABYTES + row * (BK * 2) + ((hh ^ swz<BK>(row)) << 4)); }
; #pragma unroll
;     for (int kk = 0; kk < NKK; ++kk) {
;       if (kk + 1 < NKK) {
;         const int ch = (kk + 1) * 2 + hh;
; #pragma unroll
;         for (int mt = 0; mt < 2; ++mt) { int row = wm * 64 + mt * 32 + l31; fa[(kk + 1) & 1][mt] = *(const bf16x8*)(cur + row * (BK * 2) + ((ch ^ swz<BK>(row)) << 4)); }
; #pragma unroll
;         for (int nt = 0; nt < NTW; ++nt) { int row = wn * (32 * NTW) + nt * 32 + l31; fb[(kk + 1) & 1][nt] = *(const bf16x8*)(cur + ABYTES + row * (BK * 2) + ((ch ^ swz<BK>(row)) << 4)); }
;       }
;       if (more) {
; #pragma unroll
;         for (int q = 0; q < PPK; ++q) {
;           const int pi = kk * PPK + q;
;           if (pi < NPA) stage_piece<BM, BK>(An, lda, nxt, tid, pi, wv);
;           else if (pi < NP) stage_piece<BN, BK>(Bn, ldb, nxt + ABYTES, tid, pi - NPA, wv);
;         }
;       }
;       __builtin_amdgcn_s_setprio(1);
; #pragma unroll
;       for (int mt = 0; mt < 2; ++mt)
; #pragma unroll
;         for (int nt = 0; nt < NTW; ++nt) acc[mt][nt] = mfma(fa[kk & 1][mt], fb[kk & 1][nt], acc[mt][nt]);
;       __builtin_amdgcn_s_setprio(0);
;       __builtin_amdgcn_sched_barrier(0);
;     }
;     wait_vm0();
;     __syncthreads();
;   DI void xpass(int ps, int grow0, int gcol0, int lane, int w, char* lds) const {
;     char* xs = lds + (ps & 1) * 65536 + __builtin_amdgcn_readfirstlane(w) * 8192;
;     const float* xsrc = Xin + (size_t)(grow0 + (ps >> 1) * 32 + (ps & 1) * 16 + (lane >> 5)) * D_ + gcol0 + (lane & 31) * 4;
; #pragma unroll
;     for (int pc = 0; pc < 8; ++pc)
	s_waitcnt lgkmcnt(0)
	v_readlane_b32 s3, v253, 9
	v_readlane_b32 s6, v253, 27
	v_readlane_b32 s54, v255, 29
	v_or_b32_e32 v130, s3, v135
	v_add_u32_e32 v130, v130, v169
	v_ashrrev_i32_e32 v131, 31, v130
	v_lshlrev_b64 v[130:131], 12, v[130:131]
	v_add_u32_e32 v132, s6, v168
	v_readlane_b32 s55, v255, 30
	v_ashrrev_i32_e32 v133, 31, v132
	v_readfirstlane_b32 s2, v134
	v_lshl_add_u64 v[130:131], s[54:55], 0, v[130:131]
	v_lshlrev_b32_e32 v0, 4, v0
	s_lshl_b32 s2, s2, 13
	v_lshl_add_u64 v[130:131], v[132:133], 2, v[130:131]
	v_and_b32_e32 v0, 0x1f0, v0
	v_lshl_add_u64 v[130:131], v[130:131], 0, v[0:1]
	s_mov_b32 m0, s2
	s_mov_b64 s[34:35], 0x2000
	global_load_lds_dwordx4 v[130:131], off
	v_lshl_add_u64 v[132:133], v[130:131], 0, s[34:35]
	s_or_b32 m0, s2, 0x400
	s_mov_b64 s[36:37], 0x4000
	global_load_lds_dwordx4 v[132:133], off
	v_lshl_add_u64 v[132:133], v[130:131], 0, s[36:37]
	s_or_b32 m0, s2, 0x800
	s_mov_b64 s[40:41], 0x6000
	global_load_lds_dwordx4 v[132:133], off
	v_lshl_add_u64 v[132:133], v[130:131], 0, s[40:41]
	s_or_b32 m0, s2, 0xc00
	s_mov_b64 s[42:43], 0x8000
	global_load_lds_dwordx4 v[132:133], off
	v_lshl_add_u64 v[132:133], v[130:131], 0, s[42:43]
	s_or_b32 m0, s2, 0x1000
	s_mov_b64 s[44:45], 0xa000
	global_load_lds_dwordx4 v[132:133], off
	v_lshl_add_u64 v[132:133], v[130:131], 0, s[44:45]
	s_or_b32 m0, s2, 0x1400
	s_mov_b64 s[46:47], 0xc000
	global_load_lds_dwordx4 v[132:133], off
	v_lshl_add_u64 v[132:133], v[130:131], 0, s[46:47]
	s_or_b32 m0, s2, 0x1800
	s_mov_b64 s[52:53], 0xe000
	global_load_lds_dwordx4 v[132:133], off
	v_lshl_add_u64 v[130:131], v[130:131], 0, s[52:53]
	s_or_b32 m0, s2, 0x1c00
	v_add_u32_e32 v0, s30, v136
	global_load_lds_dwordx4 v[130:131], off
	v_add_u32_e32 v134, s30, v144
	v_add_u32_e32 v130, v0, v143
	v_add_u32_e32 v135, v134, v146
	s_waitcnt vmcnt(0)
	ds_read_b128 v[130:133], v130
	ds_read_b128 v[168:171], v135
	v_add_u32_e32 v135, s30, v145
	v_add_u32_e32 v136, v135, v151
	v_add_u32_e32 v143, s30, v152
	v_add_u32_e32 v144, v143, v156
	ds_read_b128 v[172:175], v136 offset:32768
	ds_read_b128 v[176:179], v144 offset:32768
	v_add_u32_e32 v136, s30, v155
	v_add_u32_e32 v144, v136, v157
	v_add_u32_e32 v208, s30, v158
	v_add_u32_e32 v145, v208, v167
	ds_read_b128 v[180:183], v144 offset:32768
	ds_read_b128 v[184:187], v145 offset:32768
	v_add_u32_e32 v144, v0, v164
	v_add_u32_e32 v145, v134, v166
	ds_read_b128 v[188:191], v144
	ds_read_b128 v[192:195], v145
	v_add_u32_e32 v144, v135, v161
	v_add_u32_e32 v145, v143, v163
	ds_read_b128 v[196:199], v144 offset:32768
	ds_read_b128 v[200:203], v145 offset:32768
	v_add_u32_e32 v144, v136, v159
	v_add_u32_e32 v145, v208, v160
	ds_read_b128 v[156:159], v144 offset:32768
	ds_read_b128 v[204:207], v145 offset:32768
	v_readlane_b32 s7, v253, 28
	s_setprio 1
	s_waitcnt lgkmcnt(0)
	v_mfma_f32_32x32x16_bf16 v[114:129], v[130:133], v[172:175], v[114:129]
	v_mfma_f32_32x32x16_bf16 v[98:113], v[130:133], v[176:179], v[98:113]
	v_mfma_f32_32x32x16_bf16 v[82:97], v[130:133], v[180:183], v[82:97]
	v_mfma_f32_32x32x16_bf16 v[66:81], v[130:133], v[184:187], v[66:81]
	v_mfma_f32_32x32x16_bf16 v[50:65], v[168:171], v[172:175], v[50:65]
	v_mfma_f32_32x32x16_bf16 v[34:49], v[168:171], v[176:179], v[34:49]
	v_mfma_f32_32x32x16_bf16 v[18:33], v[168:171], v[180:183], v[18:33]
	v_mfma_f32_32x32x16_bf16 v[2:17], v[168:171], v[184:187], v[2:17]
	s_setprio 0
	v_add_u32_e32 v130, v0, v153
	v_add_u32_e32 v144, v134, v154
	ds_read_b128 v[130:133], v130
	ds_read_b128 v[152:155], v144
	v_add_u32_e32 v144, v135, v149
	v_add_u32_e32 v145, v143, v150
	ds_read_b128 v[166:169], v144 offset:32768
	ds_read_b128 v[170:173], v145 offset:32768
	v_add_u32_e32 v144, v136, v147
	v_add_u32_e32 v148, v208, v148
	ds_read_b128 v[144:147], v144 offset:32768
	ds_read_b128 v[148:151], v148 offset:32768
	s_setprio 1
	v_mfma_f32_32x32x16_bf16 v[114:129], v[188:191], v[196:199], v[114:129]
	v_mfma_f32_32x32x16_bf16 v[98:113], v[188:191], v[200:203], v[98:113]
	v_mfma_f32_32x32x16_bf16 v[82:97], v[188:191], v[156:159], v[82:97]
	v_mfma_f32_32x32x16_bf16 v[66:81], v[188:191], v[204:207], v[66:81]
	v_mfma_f32_32x32x16_bf16 v[50:65], v[192:195], v[196:199], v[50:65]
	v_mfma_f32_32x32x16_bf16 v[34:49], v[192:195], v[200:203], v[34:49]
	v_mfma_f32_32x32x16_bf16 v[18:33], v[192:195], v[156:159], v[18:33]
	v_mfma_f32_32x32x16_bf16 v[2:17], v[192:195], v[204:207], v[2:17]
	s_setprio 0
	v_add_u32_e32 v0, v0, v141
	v_add_u32_e32 v134, v134, v142
	ds_read_b128 v[156:159], v0
	ds_read_b128 v[174:177], v134
	v_add_u32_e32 v0, v135, v139
	v_add_u32_e32 v134, v143, v140
	ds_read_b128 v[140:143], v0 offset:32768
	ds_read_b128 v[178:181], v134 offset:32768
	v_add_u32_e32 v0, v136, v137
	v_add_u32_e32 v138, v208, v138
	ds_read_b128 v[134:137], v0 offset:32768
	ds_read_b128 v[182:185], v138 offset:32768
	s_setprio 1
	s_waitcnt lgkmcnt(9)
	v_mfma_f32_32x32x16_bf16 v[114:129], v[130:133], v[166:169], v[114:129]
	s_waitcnt lgkmcnt(8)
	v_mfma_f32_32x32x16_bf16 v[98:113], v[130:133], v[170:173], v[98:113]
	s_waitcnt lgkmcnt(7)
	v_mfma_f32_32x32x16_bf16 v[82:97], v[130:133], v[144:147], v[82:97]
	s_waitcnt lgkmcnt(6)
	v_mfma_f32_32x32x16_bf16 v[66:81], v[130:133], v[148:151], v[66:81]
	v_mfma_f32_32x32x16_bf16 v[50:65], v[152:155], v[166:169], v[50:65]
	v_mfma_f32_32x32x16_bf16 v[34:49], v[152:155], v[170:173], v[34:49]
	v_mfma_f32_32x32x16_bf16 v[18:33], v[152:155], v[144:147], v[18:33]
	v_mfma_f32_32x32x16_bf16 v[2:17], v[152:155], v[148:151], v[2:17]
	s_setprio 0
	s_setprio 1
	s_waitcnt lgkmcnt(3)
	v_mfma_f32_32x32x16_bf16 v[114:129], v[156:159], v[140:143], v[114:129]
	s_waitcnt lgkmcnt(2)
	v_mfma_f32_32x32x16_bf16 v[98:113], v[156:159], v[178:181], v[98:113]
	s_waitcnt lgkmcnt(1)
	v_mfma_f32_32x32x16_bf16 v[82:97], v[156:159], v[134:137], v[82:97]
	s_waitcnt lgkmcnt(0)
	v_mfma_f32_32x32x16_bf16 v[66:81], v[156:159], v[182:185], v[66:81]
	v_mfma_f32_32x32x16_bf16 v[50:65], v[174:177], v[140:143], v[50:65]
	v_mfma_f32_32x32x16_bf16 v[34:49], v[174:177], v[178:181], v[34:49]
	v_mfma_f32_32x32x16_bf16 v[18:33], v[174:177], v[134:137], v[18:33]
	v_mfma_f32_32x32x16_bf16 v[2:17], v[174:177], v[182:185], v[2:17]
	s_setprio 0
	v_mov_b32_e32 v210, v216
	s_waitcnt vmcnt(0)
	s_barrier
;   DI void xpass(int ps, int grow0, int gcol0, int lane, int w, char* lds) const {
;     char* xs = lds + (ps & 1) * 65536 + __builtin_amdgcn_readfirstlane(w) * 8192;
;     const float* xsrc = Xin + (size_t)(grow0 + (ps >> 1) * 32 + (ps & 1) * 16 + (lane >> 5)) * D_ + gcol0 + (lane & 31) * 4;
; #pragma unroll
;     for (int pc = 0; pc < 8; ++pc)
;       __builtin_amdgcn_global_load_lds((const unsigned*)(xsrc + (size_t)(2 * pc) * D_), (__attribute__((address_space(3))) unsigned*)(xs + pc * 1024), 16, 0, 0);
;   }
;   DI void pre(int grow0, int gcol0, int lane, int w, char* lds) { xpass(0, grow0, gcol0, lane, w, lds); }
;   DI void operator()(f32x16 (&acc)[2][4], int grow0, int gcol0, int lane, int w, char* lds) {
;     float* red = (float*)(lds + 131072); float* stat = (float*)lds;
;     const int l31 = lane & 31, hh = lane >> 5, tid = w * 64 + lane;
;     const int pm = grow0 >> 8, pn = gcol0 >> 8, wn = (gcol0 >> 7) & 1, lrow0 = grow0 & 255;
;     float bia[4], csc[4];
; #pragma unroll
;     for (int nt = 0; nt < 4; ++nt) { int c = gcol0 + nt * 32 + l31; bia[nt] = bias ? bias[c] : 0.f; csc[nt] = cscale ? cscale[c] : 1.f; }
;     float* redw = red + ((wn * 2 + ((lane >> 4) & 1)) * 256 + lrow0 + 4 * hh) * 2;
; #pragma unroll
;     for (int ps = 0; ps < 4; ++ps) {
;       const int mt = ps >> 1;
;       if (ps + 1 < 4) {
;         if (ps >= 1) asm volatile("s_waitcnt lgkmcnt(0)" ::: "memory");
;         xpass(ps + 1, grow0, gcol0, lane, w, lds);
;         if (ps >= 1) asm volatile("s_waitcnt vmcnt(8)" ::: "memory");
;       } else asm volatile("s_waitcnt vmcnt(0)" ::: "memory");
;       const char* xs = lds + (ps & 1) * 65536 + w * 8192;
; #pragma unroll
;       for (int qq = 0; qq < 2; ++qq)
; #pragma unroll
;         for (int e = 0; e < 4; ++e) {
;           const int i = 4 * (2 * (ps & 1) + qq) + e;
;           const float* xr = (const float*)(xs + (8 * qq + 4 * hh + e) * 512) + l31;
;           float s1 = 0.f, s2 = 0.f;
; #pragma unroll
;           for (int nt = 0; nt < 4; ++nt) {
;             float v = (acc[mt][nt][i] + bia[nt]) * csc[nt];
;             float z = ALPHA * xr[nt * 32] + hs * v;
;             acc[mt][nt][i] = z; s1 += z; s2 += z * z;
;           }
;           s1 = row16_sum(s1); s2 = row16_sum(s2);
;           if ((lane & 15) == 0) { f32x2 sv = {s1, s2}; *(f32x2*)(redw + (mt * 32 + (i & 3) + 8 * (i >> 2)) * 2) = sv; }
;         }
	v_add_f32_e32 v114, 0, v114
	v_ashrrev_i32_e32 v169, 6, v210
	v_lshrrev_b32_e32 v0, 30, v169
	v_add_u32_e32 v0, v169, v0
	v_ashrrev_i32_e32 v134, 2, v0
	v_mul_i32_i24_e32 v0, 4, v134
	v_sub_u32_e32 v0, v169, v0
	v_lshlrev_b32_e32 v135, 6, v0
	v_add_u32_e32 v164, s3, v135
	v_bfe_u32 v0, v210, 5, 1
	v_or_b32_e32 v176, v164, v0
	v_or_b32_e32 v130, 16, v176
	v_ashrrev_i32_e32 v131, 31, v130
	v_lshl_add_u32 v154, v134, 7, s6
	v_lshlrev_b32_e32 v168, 2, v210
	v_lshlrev_b64 v[130:131], 12, v[130:131]
	v_ashrrev_i32_e32 v155, 31, v154
	v_and_b32_e32 v0, 0x7c, v168
	v_readfirstlane_b32 s2, v169
	v_lshl_add_u64 v[130:131], s[54:55], 0, v[130:131]
	s_lshl_b32 s2, s2, 13
	v_lshl_add_u64 v[130:131], v[154:155], 2, v[130:131]
	v_lshlrev_b32_e32 v0, 2, v0
	s_add_i32 m0, s2, 0x10000
	v_lshl_add_u64 v[130:131], v[130:131], 0, v[0:1]
	global_load_lds_dwordx4 v[130:131], off
	v_lshl_add_u64 v[132:133], v[130:131], 0, s[34:35]
	s_add_i32 m0, s2, 0x10400
	v_and_b32_e32 v211, 0xc0, v135
	global_load_lds_dwordx4 v[132:133], off
	v_lshl_add_u64 v[132:133], v[130:131], 0, s[36:37]
	s_add_i32 m0, s2, 0x10800
	v_mov_b32_e32 v144, v98
	global_load_lds_dwordx4 v[132:133], off
	v_lshl_add_u64 v[132:133], v[130:131], 0, s[40:41]
	s_add_i32 m0, s2, 0x10c00
	v_mov_b32_e32 v145, v82
	global_load_lds_dwordx4 v[132:133], off
	v_lshl_add_u64 v[132:133], v[130:131], 0, s[42:43]
	s_add_i32 m0, s2, 0x11000
	v_mul_f32_e32 v141, 0.5, v114
	global_load_lds_dwordx4 v[132:133], off
	v_lshl_add_u64 v[132:133], v[130:131], 0, s[44:45]
	s_add_i32 m0, s2, 0x11400
	v_pk_add_f32 v[144:145], v[144:145], 0 op_sel_hi:[1,0]
	global_load_lds_dwordx4 v[132:133], off
	v_lshl_add_u64 v[132:133], v[130:131], 0, s[46:47]
	s_add_i32 m0, s2, 0x11800
	v_lshl_add_u64 v[130:131], v[130:131], 0, s[52:53]
	global_load_lds_dwordx4 v[132:133], off
	s_add_i32 m0, s2, 0x11c00
	v_bfe_u32 v132, v210, 4, 1
	global_load_lds_dwordx4 v[130:131], off
	v_and_b32_e32 v130, 31, v210
	v_lshlrev_b32_e32 v131, 1, v134
	v_bfe_u32 v134, v210, 3, 3
	v_and_or_b32 v131, v131, 2, v132
	v_and_b32_e32 v132, 4, v134
	v_lshlrev_b32_e32 v130, 2, v130
	v_or_b32_e32 v133, v211, v132
	v_lshl_or_b32 v138, v169, 13, v130
	v_lshlrev_b32_e32 v172, 9, v132
	v_lshlrev_b32_e32 v135, 3, v133
	v_or_b32_e32 v132, v138, v172
	v_and_b32_e32 v133, 15, v210
	v_lshl_or_b32 v139, v131, 11, v221
	s_waitcnt vmcnt(8)
	ds_read2_b32 v[130:131], v132 offset1:32
	v_cmp_eq_u32_e32 vcc, 0, v133
	ds_read2_b32 v[132:133], v132 offset0:64 offset1:96
	v_mov_b32_e32 v140, v82
	v_mov_b32_e32 v136, v1
	s_waitcnt lgkmcnt(0)
	v_mul_f32_e32 v137, 0x3fd744fd, v130
	v_mov_b32_e32 v130, v131
	v_mov_b32_e32 v131, v132
	s_mov_b32 s2, s67
	v_pk_add_f32 v[160:161], v[140:141], v[136:137]
	v_pk_mul_f32 v[130:131], v[130:131], s[2:3] op_sel_hi:[1,0]
	v_pk_mul_f32 v[136:137], v[144:145], 0.5 op_sel_hi:[1,0]
	v_pk_fma_f32 v[158:159], v[144:145], 0.5, v[130:131] op_sel_hi:[1,0,1]
	v_mov_b32_e32 v136, v161
	v_mov_b32_e32 v144, v1
	v_mov_b32_e32 v145, v131
	v_add_f32_e32 v142, 0, v66
	v_mov_b32_e32 v143, v133
	v_pk_mul_f32 v[140:141], v[158:159], v[158:159]
	v_pk_add_f32 v[136:137], v[136:137], v[144:145]
	v_mul_f32_e32 v66, 0x3fd744fd, v133
	v_mov_b32_e32 v163, v161
	v_pk_mov_b32 v[130:131], v[130:131], v[140:141] op_sel:[1,0]
	v_pk_add_f32 v[140:141], v[158:159], v[136:137]
	v_pk_mul_f32 v[136:137], v[158:159], v[136:137]
	v_pk_fma_f32 v[166:167], v[142:143], s[66:67], v[66:67] op_sel_hi:[1,1,0]
	v_pk_fma_f32 v[130:131], v[160:161], v[162:163], v[130:131]
	v_mov_b32_e32 v141, v137
	v_pk_mul_f32 v[132:133], v[166:167], v[166:167]
	v_pk_add_f32 v[130:131], v[140:141], v[130:131]
	v_mov_b32_e32 v167, v132
	v_pk_add_f32 v[130:131], v[130:131], v[166:167]
	v_add_u32_e32 v160, v139, v135
	s_nop 0
	v_mov_b32_dpp v132, v130 quad_perm:[1,0,3,2] row_mask:0xf bank_mask:0xf bound_ctrl:1
	v_mov_b32_dpp v133, v131 quad_perm:[1,0,3,2] row_mask:0xf bank_mask:0xf bound_ctrl:1
	v_pk_add_f32 v[130:131], v[130:131], v[132:133]
	s_nop 1
	v_mov_b32_dpp v132, v130 quad_perm:[2,3,0,1] row_mask:0xf bank_mask:0xf bound_ctrl:1
	v_mov_b32_dpp v133, v131 quad_perm:[2,3,0,1] row_mask:0xf bank_mask:0xf bound_ctrl:1
	v_pk_add_f32 v[130:131], v[130:131], v[132:133]
	s_nop 1
	v_mov_b32_dpp v132, v130 row_half_mirror row_mask:0xf bank_mask:0xf bound_ctrl:1
	v_mov_b32_dpp v133, v131 row_half_mirror row_mask:0xf bank_mask:0xf bound_ctrl:1
	v_pk_add_f32 v[130:131], v[130:131], v[132:133]
	s_nop 1
	v_mov_b32_dpp v132, v130 row_mirror row_mask:0xf bank_mask:0xf bound_ctrl:1
	v_mov_b32_dpp v133, v131 row_mirror row_mask:0xf bank_mask:0xf bound_ctrl:1
	s_and_saveexec_b64 s[6:7], vcc
	v_pk_add_f32 v[130:131], v[130:131], v[132:133]
	ds_write_b64 v160, v[130:131]
	s_or_b64 exec, exec, s[6:7]
	v_add_u32_e32 v167, v138, v172
	ds_read2_b32 v[130:131], v167 offset0:128 offset1:160
	ds_read2_b32 v[132:133], v167 offset0:192 offset1:224
	v_add_f32_e32 v82, 0, v115
	v_mul_f32_e32 v115, 0.5, v82
	v_mov_b32_e32 v82, v99
	s_waitcnt lgkmcnt(1)
	v_mul_f32_e32 v137, 0x3fd744fd, v130
	v_pk_add_f32 v[98:99], v[82:83], 0 op_sel_hi:[1,0]
	v_mov_b32_e32 v114, v83
	v_mov_b32_e32 v136, v1
	v_mov_b32_e32 v82, v131
	s_waitcnt lgkmcnt(0)
;   DI void operator()(f32x16 (&acc)[2][4], int grow0, int gcol0, int lane, int w, char* lds) {
;     ...
; #pragma unroll
;       for (int qq = 0; qq < 2; ++qq)
; #pragma unroll
;         for (int e = 0; e < 4; ++e) {
;           const int i = 4 * (2 * (ps & 1) + qq) + e;
;           const float* xr = (const float*)(xs + (8 * qq + 4 * hh + e) * 512) + l31;
;           float s1 = 0.f, s2 = 0.f;
; #pragma unroll
;           for (int nt = 0; nt < 4; ++nt) {
;             float v = (acc[mt][nt][i] + bia[nt]) * csc[nt];
;             float z = ALPHA * xr[nt * 32] + hs * v;
;             acc[mt][nt][i] = z; s1 += z; s2 += z * z;
;           }
;           s1 = row16_sum(s1); s2 = row16_sum(s2);
;           if ((lane & 15) == 0) { f32x2 sv = {s1, s2}; *(f32x2*)(redw + (mt * 32 + (i & 3) + 8 * (i >> 2)) * 2) = sv; }
;         }
	v_mov_b32_e32 v83, v132
	s_mov_b32 s2, s67
	v_pk_add_f32 v[170:171], v[114:115], v[136:137]
	v_pk_mul_f32 v[82:83], v[82:83], s[2:3] op_sel_hi:[1,0]
	v_pk_mul_f32 v[114:115], v[98:99], 0.5 op_sel_hi:[1,0]
	v_pk_fma_f32 v[148:149], v[98:99], 0.5, v[82:83] op_sel_hi:[1,0,1]
	v_mov_b32_e32 v114, v171
	v_mov_b32_e32 v130, v1
	v_mov_b32_e32 v131, v83
	v_pk_mul_f32 v[98:99], v[148:149], v[148:149]
	v_pk_add_f32 v[114:115], v[114:115], v[130:131]
	v_mov_b32_e32 v163, v171
	v_pk_mov_b32 v[82:83], v[82:83], v[98:99] op_sel:[1,0]
	v_pk_add_f32 v[98:99], v[148:149], v[114:115]
	v_pk_mul_f32 v[114:115], v[148:149], v[114:115]
	v_pk_fma_f32 v[82:83], v[170:171], v[162:163], v[82:83]
	v_mov_b32_e32 v99, v115
	v_add_f32_e32 v66, 0, v67
	v_mov_b32_e32 v67, v133
	v_pk_add_f32 v[82:83], v[98:99], v[82:83]
	v_mul_f32_e32 v98, 0x3fd744fd, v133
	v_pk_fma_f32 v[142:143], v[66:67], s[66:67], v[98:99] op_sel_hi:[1,1,0]
	s_nop 0
	v_pk_mul_f32 v[66:67], v[142:143], v[142:143]
	s_nop 0
	v_mov_b32_e32 v143, v66
	v_pk_add_f32 v[66:67], v[82:83], v[142:143]
	s_nop 1
	v_mov_b32_dpp v82, v66 quad_perm:[1,0,3,2] row_mask:0xf bank_mask:0xf bound_ctrl:1
	v_mov_b32_dpp v83, v67 quad_perm:[1,0,3,2] row_mask:0xf bank_mask:0xf bound_ctrl:1
	v_pk_add_f32 v[66:67], v[66:67], v[82:83]
	s_nop 1
	v_mov_b32_dpp v82, v66 quad_perm:[2,3,0,1] row_mask:0xf bank_mask:0xf bound_ctrl:1
	v_mov_b32_dpp v83, v67 quad_perm:[2,3,0,1] row_mask:0xf bank_mask:0xf bound_ctrl:1
	v_pk_add_f32 v[66:67], v[66:67], v[82:83]
	s_nop 1
	v_mov_b32_dpp v82, v66 row_half_mirror row_mask:0xf bank_mask:0xf bound_ctrl:1
	v_mov_b32_dpp v83, v67 row_half_mirror row_mask:0xf bank_mask:0xf bound_ctrl:1
	v_pk_add_f32 v[66:67], v[66:67], v[82:83]
	s_nop 1
	v_mov_b32_dpp v82, v66 row_mirror row_mask:0xf bank_mask:0xf bound_ctrl:1
	v_mov_b32_dpp v83, v67 row_mirror row_mask:0xf bank_mask:0xf bound_ctrl:1
	s_and_saveexec_b64 s[6:7], vcc
	v_pk_add_f32 v[66:67], v[66:67], v[82:83]
	ds_write_b64 v160, v[66:67] offset:8
	s_or_b64 exec, exec, s[6:7]
	v_add_u32_e32 v143, 0x400, v167
	ds_read2_b32 v[66:67], v143 offset1:32
	ds_read2_b32 v[82:83], v143 offset0:64 offset1:96
	v_add_f32_e32 v99, 0, v116
	v_mov_b32_e32 v132, v100
	v_mov_b32_e32 v133, v84
	v_mul_f32_e32 v115, 0.5, v99
	s_waitcnt lgkmcnt(1)
	v_mul_f32_e32 v131, 0x3fd744fd, v66
	v_pk_add_f32 v[132:133], v[132:133], 0 op_sel_hi:[1,0]
	v_mov_b32_e32 v114, v84
	v_mov_b32_e32 v130, v1
	v_mov_b32_e32 v66, v67
	s_waitcnt lgkmcnt(0)
	v_mov_b32_e32 v67, v82
	s_mov_b32 s2, s67
	v_pk_add_f32 v[144:145], v[114:115], v[130:131]
	v_pk_mul_f32 v[114:115], v[66:67], s[2:3] op_sel_hi:[1,0]
	v_pk_mul_f32 v[130:131], v[132:133], 0.5 op_sel_hi:[1,0]
	v_pk_fma_f32 v[66:67], v[132:133], 0.5, v[114:115] op_sel_hi:[1,0,1]
	v_mov_b32_e32 v130, v145
	v_mov_b32_e32 v136, v1
	v_mov_b32_e32 v137, v115
	v_add_f32_e32 v98, 0, v68
	v_mov_b32_e32 v99, v83
	v_pk_mul_f32 v[132:133], v[66:67], v[66:67]
	v_pk_add_f32 v[130:131], v[130:131], v[136:137]
	v_mul_f32_e32 v68, 0x3fd744fd, v83
	v_mov_b32_e32 v163, v145
	v_pk_mov_b32 v[114:115], v[114:115], v[132:133] op_sel:[1,0]
	v_pk_add_f32 v[132:133], v[66:67], v[130:131]
	v_pk_mul_f32 v[130:131], v[66:67], v[130:131]
	v_pk_fma_f32 v[82:83], v[98:99], s[66:67], v[68:69] op_sel_hi:[1,1,0]
	v_pk_fma_f32 v[114:115], v[144:145], v[162:163], v[114:115]
	v_mov_b32_e32 v133, v131
	v_pk_mul_f32 v[98:99], v[82:83], v[82:83]
	v_pk_add_f32 v[114:115], v[132:133], v[114:115]
	v_mov_b32_e32 v83, v98
	v_pk_add_f32 v[98:99], v[114:115], v[82:83]
	s_nop 1
	v_mov_b32_dpp v114, v98 quad_perm:[1,0,3,2] row_mask:0xf bank_mask:0xf bound_ctrl:1
	v_mov_b32_dpp v115, v99 quad_perm:[1,0,3,2] row_mask:0xf bank_mask:0xf bound_ctrl:1
	v_pk_add_f32 v[98:99], v[98:99], v[114:115]
	s_nop 1
	v_mov_b32_dpp v114, v98 quad_perm:[2,3,0,1] row_mask:0xf bank_mask:0xf bound_ctrl:1
	v_mov_b32_dpp v115, v99 quad_perm:[2,3,0,1] row_mask:0xf bank_mask:0xf bound_ctrl:1
	v_pk_add_f32 v[98:99], v[98:99], v[114:115]
	s_nop 1
	v_mov_b32_dpp v114, v98 row_half_mirror row_mask:0xf bank_mask:0xf bound_ctrl:1
	v_mov_b32_dpp v115, v99 row_half_mirror row_mask:0xf bank_mask:0xf bound_ctrl:1
	v_pk_add_f32 v[98:99], v[98:99], v[114:115]
	s_nop 1
	v_mov_b32_dpp v114, v98 row_mirror row_mask:0xf bank_mask:0xf bound_ctrl:1
	v_mov_b32_dpp v115, v99 row_mirror row_mask:0xf bank_mask:0xf bound_ctrl:1
	s_and_saveexec_b64 s[6:7], vcc
	v_pk_add_f32 v[98:99], v[98:99], v[114:115]
	ds_write_b64 v160, v[98:99] offset:16
	s_or_b64 exec, exec, s[6:7]
	v_lshlrev_b32_e32 v139, 9, v134
	v_or_b32_e32 v152, 0x600, v139
	v_add_u32_e32 v144, v138, v152
	ds_read2_b32 v[114:115], v144 offset1:32
	ds_read2_b32 v[130:131], v144 offset0:64 offset1:96
	v_add_f32_e32 v68, 0, v117
	v_add_f32_e32 v116, 0, v69
	v_mul_f32_e32 v69, 0.5, v68
	s_waitcnt lgkmcnt(1)
	v_mul_f32_e32 v99, 0x3fd744fd, v114
	v_mov_b32_e32 v84, v101
	v_mov_b32_e32 v68, v85
	v_mov_b32_e32 v98, v1
	v_pk_add_f32 v[100:101], v[84:85], 0 op_sel_hi:[1,0]
	v_pk_add_f32 v[98:99], v[68:69], v[98:99]
	v_mov_b32_e32 v68, v115
	s_waitcnt lgkmcnt(0)
;   DI void operator()(f32x16 (&acc)[2][4], int grow0, int gcol0, int lane, int w, char* lds) {
;     ...
; #pragma unroll
;       for (int qq = 0; qq < 2; ++qq)
; #pragma unroll
;         for (int e = 0; e < 4; ++e) {
;           const int i = 4 * (2 * (ps & 1) + qq) + e;
;           const float* xr = (const float*)(xs + (8 * qq + 4 * hh + e) * 512) + l31;
;           float s1 = 0.f, s2 = 0.f;
; #pragma unroll
;           for (int nt = 0; nt < 4; ++nt) {
;             float v = (acc[mt][nt][i] + bia[nt]) * csc[nt];
;             float z = ALPHA * xr[nt * 32] + hs * v;
;             acc[mt][nt][i] = z; s1 += z; s2 += z * z;
;           }
;           s1 = row16_sum(s1); s2 = row16_sum(s2);
;           if ((lane & 15) == 0) { f32x2 sv = {s1, s2}; *(f32x2*)(redw + (mt * 32 + (i & 3) + 8 * (i >> 2)) * 2) = sv; }
;         }
	v_mov_b32_e32 v69, v130
	s_mov_b32 s2, s67
	v_pk_mul_f32 v[84:85], v[68:69], s[2:3] op_sel_hi:[1,0]
	v_pk_mul_f32 v[114:115], v[100:101], 0.5 op_sel_hi:[1,0]
	v_pk_fma_f32 v[68:69], v[100:101], 0.5, v[84:85] op_sel_hi:[1,0,1]
	v_mov_b32_e32 v114, v99
	v_mov_b32_e32 v132, v1
	v_mov_b32_e32 v133, v85
	v_pk_mul_f32 v[100:101], v[68:69], v[68:69]
	v_pk_add_f32 v[114:115], v[114:115], v[132:133]
	v_mov_b32_e32 v163, v99
	v_pk_mov_b32 v[84:85], v[84:85], v[100:101] op_sel:[1,0]
	v_pk_add_f32 v[100:101], v[68:69], v[114:115]
	v_pk_mul_f32 v[114:115], v[68:69], v[114:115]
	v_pk_fma_f32 v[84:85], v[98:99], v[162:163], v[84:85]
	v_mov_b32_e32 v101, v115
	v_mov_b32_e32 v117, v131
	v_pk_add_f32 v[100:101], v[100:101], v[84:85]
	v_mul_f32_e32 v84, 0x3fd744fd, v131
	v_pk_fma_f32 v[84:85], v[116:117], s[66:67], v[84:85] op_sel_hi:[1,1,0]
	s_nop 0
	v_pk_mul_f32 v[114:115], v[84:85], v[84:85]
	s_nop 0
	v_mov_b32_e32 v85, v114
	v_pk_add_f32 v[100:101], v[100:101], v[84:85]
	s_nop 1
	v_mov_b32_dpp v114, v100 quad_perm:[1,0,3,2] row_mask:0xf bank_mask:0xf bound_ctrl:1
	v_mov_b32_dpp v115, v101 quad_perm:[1,0,3,2] row_mask:0xf bank_mask:0xf bound_ctrl:1
	v_pk_add_f32 v[100:101], v[100:101], v[114:115]
	s_nop 1
	v_mov_b32_dpp v114, v100 quad_perm:[2,3,0,1] row_mask:0xf bank_mask:0xf bound_ctrl:1
	v_mov_b32_dpp v115, v101 quad_perm:[2,3,0,1] row_mask:0xf bank_mask:0xf bound_ctrl:1
	v_pk_add_f32 v[100:101], v[100:101], v[114:115]
	s_nop 1
	v_mov_b32_dpp v114, v100 row_half_mirror row_mask:0xf bank_mask:0xf bound_ctrl:1
	v_mov_b32_dpp v115, v101 row_half_mirror row_mask:0xf bank_mask:0xf bound_ctrl:1
	v_pk_add_f32 v[100:101], v[100:101], v[114:115]
	s_nop 1
	v_mov_b32_dpp v114, v100 row_mirror row_mask:0xf bank_mask:0xf bound_ctrl:1
	v_mov_b32_dpp v115, v101 row_mirror row_mask:0xf bank_mask:0xf bound_ctrl:1
	s_and_saveexec_b64 s[6:7], vcc
	v_pk_add_f32 v[100:101], v[100:101], v[114:115]
	ds_write_b64 v160, v[100:101] offset:24
	s_or_b64 exec, exec, s[6:7]
	v_add_u32_e32 v83, 0x1000, v167
	ds_read2_b32 v[100:101], v83 offset1:32
	ds_read2_b32 v[114:115], v83 offset0:64 offset1:96
	v_add_f32_e32 v85, 0, v118
	v_mov_b32_e32 v134, v102
	v_mov_b32_e32 v135, v86
	v_mul_f32_e32 v117, 0.5, v85
	s_waitcnt lgkmcnt(1)
	v_mul_f32_e32 v133, 0x3fd744fd, v100
	v_pk_add_f32 v[134:135], v[134:135], 0 op_sel_hi:[1,0]
	v_mov_b32_e32 v116, v86
	v_mov_b32_e32 v132, v1
	v_mov_b32_e32 v100, v101
	s_waitcnt lgkmcnt(0)
	v_mov_b32_e32 v101, v114
	s_mov_b32 s2, s67
	v_pk_add_f32 v[116:117], v[116:117], v[132:133]
	v_pk_mul_f32 v[132:133], v[100:101], s[2:3] op_sel_hi:[1,0]
	v_pk_mul_f32 v[136:137], v[134:135], 0.5 op_sel_hi:[1,0]
	v_pk_fma_f32 v[100:101], v[134:135], 0.5, v[132:133] op_sel_hi:[1,0,1]
	v_mov_b32_e32 v136, v117
	v_mov_b32_e32 v140, v1
	v_mov_b32_e32 v141, v133
	v_add_f32_e32 v130, 0, v70
	v_mov_b32_e32 v131, v115
	v_pk_mul_f32 v[134:135], v[100:101], v[100:101]
	v_pk_add_f32 v[136:137], v[136:137], v[140:141]
	v_mul_f32_e32 v70, 0x3fd744fd, v115
	v_mov_b32_e32 v163, v117
	v_pk_mov_b32 v[132:133], v[132:133], v[134:135] op_sel:[1,0]
	v_pk_add_f32 v[134:135], v[100:101], v[136:137]
	v_pk_mul_f32 v[136:137], v[100:101], v[136:137]
	v_pk_fma_f32 v[114:115], v[130:131], s[66:67], v[70:71] op_sel_hi:[1,1,0]
	v_pk_fma_f32 v[132:133], v[116:117], v[162:163], v[132:133]
	v_mov_b32_e32 v135, v137
	v_pk_mul_f32 v[130:131], v[114:115], v[114:115]
	v_pk_add_f32 v[132:133], v[134:135], v[132:133]
	v_mov_b32_e32 v115, v130
	v_pk_add_f32 v[130:131], v[132:133], v[114:115]
	s_nop 1
	v_mov_b32_dpp v132, v130 quad_perm:[1,0,3,2] row_mask:0xf bank_mask:0xf bound_ctrl:1
	v_mov_b32_dpp v133, v131 quad_perm:[1,0,3,2] row_mask:0xf bank_mask:0xf bound_ctrl:1
	v_pk_add_f32 v[130:131], v[130:131], v[132:133]
	s_nop 1
	v_mov_b32_dpp v132, v130 quad_perm:[2,3,0,1] row_mask:0xf bank_mask:0xf bound_ctrl:1
	v_mov_b32_dpp v133, v131 quad_perm:[2,3,0,1] row_mask:0xf bank_mask:0xf bound_ctrl:1
	v_pk_add_f32 v[130:131], v[130:131], v[132:133]
	s_nop 1
	v_mov_b32_dpp v132, v130 row_half_mirror row_mask:0xf bank_mask:0xf bound_ctrl:1
	v_mov_b32_dpp v133, v131 row_half_mirror row_mask:0xf bank_mask:0xf bound_ctrl:1
	v_pk_add_f32 v[130:131], v[130:131], v[132:133]
	s_nop 1
	v_mov_b32_dpp v132, v130 row_mirror row_mask:0xf bank_mask:0xf bound_ctrl:1
	v_mov_b32_dpp v133, v131 row_mirror row_mask:0xf bank_mask:0xf bound_ctrl:1
	s_and_saveexec_b64 s[6:7], vcc
	v_pk_add_f32 v[130:131], v[130:131], v[132:133]
	ds_write_b64 v160, v[130:131] offset:64
	s_or_b64 exec, exec, s[6:7]
	ds_read2_b32 v[130:131], v83 offset0:128 offset1:160
	ds_read2_b32 v[132:133], v83 offset0:192 offset1:224
	v_add_f32_e32 v70, 0, v119
	v_add_f32_e32 v118, 0, v71
	v_mul_f32_e32 v71, 0.5, v70
	s_waitcnt lgkmcnt(1)
	v_mul_f32_e32 v135, 0x3fd744fd, v130
	v_mov_b32_e32 v86, v103
	v_mov_b32_e32 v70, v87
	v_mov_b32_e32 v134, v1
	v_pk_add_f32 v[136:137], v[86:87], 0 op_sel_hi:[1,0]
	v_pk_add_f32 v[102:103], v[70:71], v[134:135]
	v_mov_b32_e32 v70, v131
	s_waitcnt lgkmcnt(0)
;   DI void operator()(f32x16 (&acc)[2][4], int grow0, int gcol0, int lane, int w, char* lds) {
;     ...
; #pragma unroll
;       for (int qq = 0; qq < 2; ++qq)
; #pragma unroll
;         for (int e = 0; e < 4; ++e) {
;           const int i = 4 * (2 * (ps & 1) + qq) + e;
;           const float* xr = (const float*)(xs + (8 * qq + 4 * hh + e) * 512) + l31;
;           float s1 = 0.f, s2 = 0.f;
; #pragma unroll
;           for (int nt = 0; nt < 4; ++nt) {
;             float v = (acc[mt][nt][i] + bia[nt]) * csc[nt];
;             float z = ALPHA * xr[nt * 32] + hs * v;
;             acc[mt][nt][i] = z; s1 += z; s2 += z * z;
;           }
;           s1 = row16_sum(s1); s2 = row16_sum(s2);
;           if ((lane & 15) == 0) { f32x2 sv = {s1, s2}; *(f32x2*)(redw + (mt * 32 + (i & 3) + 8 * (i >> 2)) * 2) = sv; }
;         }
	v_mov_b32_e32 v71, v132
	s_mov_b32 s2, s67
	v_pk_mul_f32 v[86:87], v[70:71], s[2:3] op_sel_hi:[1,0]
	v_pk_mul_f32 v[130:131], v[136:137], 0.5 op_sel_hi:[1,0]
	v_pk_fma_f32 v[70:71], v[136:137], 0.5, v[86:87] op_sel_hi:[1,0,1]
	v_mov_b32_e32 v130, v103
	v_mov_b32_e32 v136, v1
	v_mov_b32_e32 v137, v87
	v_pk_mul_f32 v[134:135], v[70:71], v[70:71]
	v_pk_add_f32 v[130:131], v[130:131], v[136:137]
	v_mov_b32_e32 v163, v103
	v_pk_mov_b32 v[86:87], v[86:87], v[134:135] op_sel:[1,0]
	v_pk_add_f32 v[134:135], v[70:71], v[130:131]
	v_pk_mul_f32 v[130:131], v[70:71], v[130:131]
	v_pk_fma_f32 v[86:87], v[102:103], v[162:163], v[86:87]
	v_mov_b32_e32 v135, v131
	v_mov_b32_e32 v119, v133
	v_pk_add_f32 v[130:131], v[134:135], v[86:87]
	v_mul_f32_e32 v86, 0x3fd744fd, v133
	v_pk_fma_f32 v[86:87], v[118:119], s[66:67], v[86:87] op_sel_hi:[1,1,0]
	s_nop 0
	v_pk_mul_f32 v[118:119], v[86:87], v[86:87]
	s_nop 0
	v_mov_b32_e32 v87, v118
	v_pk_add_f32 v[118:119], v[130:131], v[86:87]
	s_nop 1
	v_mov_b32_dpp v130, v118 quad_perm:[1,0,3,2] row_mask:0xf bank_mask:0xf bound_ctrl:1
	v_mov_b32_dpp v131, v119 quad_perm:[1,0,3,2] row_mask:0xf bank_mask:0xf bound_ctrl:1
	v_pk_add_f32 v[118:119], v[118:119], v[130:131]
	s_nop 1
	v_mov_b32_dpp v130, v118 quad_perm:[2,3,0,1] row_mask:0xf bank_mask:0xf bound_ctrl:1
	v_mov_b32_dpp v131, v119 quad_perm:[2,3,0,1] row_mask:0xf bank_mask:0xf bound_ctrl:1
	v_pk_add_f32 v[118:119], v[118:119], v[130:131]
	s_nop 1
	v_mov_b32_dpp v130, v118 row_half_mirror row_mask:0xf bank_mask:0xf bound_ctrl:1
	v_mov_b32_dpp v131, v119 row_half_mirror row_mask:0xf bank_mask:0xf bound_ctrl:1
	v_pk_add_f32 v[118:119], v[118:119], v[130:131]
	s_nop 1
	v_mov_b32_dpp v130, v118 row_mirror row_mask:0xf bank_mask:0xf bound_ctrl:1
	v_mov_b32_dpp v131, v119 row_mirror row_mask:0xf bank_mask:0xf bound_ctrl:1
	s_and_saveexec_b64 s[6:7], vcc
	v_pk_add_f32 v[118:119], v[118:119], v[130:131]
	ds_write_b64 v160, v[118:119] offset:72
	s_or_b64 exec, exec, s[6:7]
	v_add_u32_e32 v85, 0x1400, v167
	ds_read2_b32 v[118:119], v85 offset1:32
	ds_read2_b32 v[130:131], v85 offset0:64 offset1:96
	v_add_f32_e32 v87, 0, v120
	v_mov_b32_e32 v140, v104
	v_mov_b32_e32 v141, v88
	v_mul_f32_e32 v133, 0.5, v87
	s_waitcnt lgkmcnt(1)
	v_mul_f32_e32 v137, 0x3fd744fd, v118
	v_pk_add_f32 v[140:141], v[140:141], 0 op_sel_hi:[1,0]
	v_mov_b32_e32 v132, v88
	v_mov_b32_e32 v136, v1
	v_mov_b32_e32 v118, v119
	s_waitcnt lgkmcnt(0)
	v_mov_b32_e32 v119, v130
	s_mov_b32 s2, s67
	v_pk_add_f32 v[132:133], v[132:133], v[136:137]
	v_pk_mul_f32 v[136:137], v[118:119], s[2:3] op_sel_hi:[1,0]
	v_pk_mul_f32 v[146:147], v[140:141], 0.5 op_sel_hi:[1,0]
	v_pk_fma_f32 v[118:119], v[140:141], 0.5, v[136:137] op_sel_hi:[1,0,1]
	v_mov_b32_e32 v146, v133
	v_mov_b32_e32 v150, v1
	v_mov_b32_e32 v151, v137
	v_add_f32_e32 v134, 0, v72
	v_mov_b32_e32 v135, v131
	v_pk_mul_f32 v[140:141], v[118:119], v[118:119]
	v_pk_add_f32 v[146:147], v[146:147], v[150:151]
	v_mul_f32_e32 v72, 0x3fd744fd, v131
	v_mov_b32_e32 v163, v133
	v_pk_mov_b32 v[136:137], v[136:137], v[140:141] op_sel:[1,0]
	v_pk_add_f32 v[140:141], v[118:119], v[146:147]
	v_pk_mul_f32 v[146:147], v[118:119], v[146:147]
	v_pk_fma_f32 v[130:131], v[134:135], s[66:67], v[72:73] op_sel_hi:[1,1,0]
	v_pk_fma_f32 v[136:137], v[132:133], v[162:163], v[136:137]
	v_mov_b32_e32 v141, v147
	v_pk_mul_f32 v[134:135], v[130:131], v[130:131]
	v_pk_add_f32 v[136:137], v[140:141], v[136:137]
	v_mov_b32_e32 v131, v134
	v_pk_add_f32 v[134:135], v[136:137], v[130:131]
	s_nop 1
	v_mov_b32_dpp v136, v134 quad_perm:[1,0,3,2] row_mask:0xf bank_mask:0xf bound_ctrl:1
	v_mov_b32_dpp v137, v135 quad_perm:[1,0,3,2] row_mask:0xf bank_mask:0xf bound_ctrl:1
	v_pk_add_f32 v[134:135], v[134:135], v[136:137]
	s_nop 1
	v_mov_b32_dpp v136, v134 quad_perm:[2,3,0,1] row_mask:0xf bank_mask:0xf bound_ctrl:1
	v_mov_b32_dpp v137, v135 quad_perm:[2,3,0,1] row_mask:0xf bank_mask:0xf bound_ctrl:1
	v_pk_add_f32 v[134:135], v[134:135], v[136:137]
	s_nop 1
	v_mov_b32_dpp v136, v134 row_half_mirror row_mask:0xf bank_mask:0xf bound_ctrl:1
	v_mov_b32_dpp v137, v135 row_half_mirror row_mask:0xf bank_mask:0xf bound_ctrl:1
	v_pk_add_f32 v[134:135], v[134:135], v[136:137]
	s_nop 1
	v_mov_b32_dpp v136, v134 row_mirror row_mask:0xf bank_mask:0xf bound_ctrl:1
	v_mov_b32_dpp v137, v135 row_mirror row_mask:0xf bank_mask:0xf bound_ctrl:1
	s_and_saveexec_b64 s[6:7], vcc
	v_pk_add_f32 v[134:135], v[134:135], v[136:137]
	ds_write_b64 v160, v[134:135] offset:80
	s_or_b64 exec, exec, s[6:7]
	v_or_b32_e32 v115, 0x1600, v139
	v_add_u32_e32 v87, v138, v115
	ds_read2_b32 v[134:135], v87 offset1:32
	ds_read2_b32 v[136:137], v87 offset0:64 offset1:96
	v_add_f32_e32 v72, 0, v121
	v_add_f32_e32 v120, 0, v73
	v_mul_f32_e32 v73, 0.5, v72
	s_waitcnt lgkmcnt(1)
	v_mul_f32_e32 v141, 0x3fd744fd, v134
	v_mov_b32_e32 v88, v105
	v_mov_b32_e32 v72, v89
	v_mov_b32_e32 v140, v1
	v_pk_add_f32 v[146:147], v[88:89], 0 op_sel_hi:[1,0]
	v_pk_add_f32 v[104:105], v[72:73], v[140:141]
	v_mov_b32_e32 v72, v135
	s_waitcnt lgkmcnt(0)
;   DI void xpass(int ps, int grow0, int gcol0, int lane, int w, char* lds) const {
;     char* xs = lds + (ps & 1) * 65536 + __builtin_amdgcn_readfirstlane(w) * 8192;
;     const float* xsrc = Xin + (size_t)(grow0 + (ps >> 1) * 32 + (ps & 1) * 16 + (lane >> 5)) * D_ + gcol0 + (lane & 31) * 4;
; #pragma unroll
;     for (int pc = 0; pc < 8; ++pc)
;       __builtin_amdgcn_global_load_lds((const unsigned*)(xsrc + (size_t)(2 * pc) * D_), (__attribute__((address_space(3))) unsigned*)(xs + pc * 1024), 16, 0, 0);
;   }
;   DI void pre(int grow0, int gcol0, int lane, int w, char* lds) { xpass(0, grow0, gcol0, lane, w, lds); }
;   DI void operator()(f32x16 (&acc)[2][4], int grow0, int gcol0, int lane, int w, char* lds) {
;     float* red = (float*)(lds + 131072); float* stat = (float*)lds;
;     const int l31 = lane & 31, hh = lane >> 5, tid = w * 64 + lane;
;     const int pm = grow0 >> 8, pn = gcol0 >> 8, wn = (gcol0 >> 7) & 1, lrow0 = grow0 & 255;
;     float bia[4], csc[4];
; #pragma unroll
;     for (int nt = 0; nt < 4; ++nt) { int c = gcol0 + nt * 32 + l31; bia[nt] = bias ? bias[c] : 0.f; csc[nt] = cscale ? cscale[c] : 1.f; }
;     float* redw = red + ((wn * 2 + ((lane >> 4) & 1)) * 256 + lrow0 + 4 * hh) * 2;
; #pragma unroll
;     for (int ps = 0; ps < 4; ++ps) {
;       const int mt = ps >> 1;
;       if (ps + 1 < 4) {
;         if (ps >= 1) asm volatile("s_waitcnt lgkmcnt(0)" ::: "memory");
;         xpass(ps + 1, grow0, gcol0, lane, w, lds);
;         if (ps >= 1) asm volatile("s_waitcnt vmcnt(8)" ::: "memory");
;       } else asm volatile("s_waitcnt vmcnt(0)" ::: "memory");
;       const char* xs = lds + (ps & 1) * 65536 + w * 8192;
; #pragma unroll
;       for (int qq = 0; qq < 2; ++qq)
; #pragma unroll
;         for (int e = 0; e < 4; ++e) {
;           const int i = 4 * (2 * (ps & 1) + qq) + e;
;           const float* xr = (const float*)(xs + (8 * qq + 4 * hh + e) * 512) + l31;
;           float s1 = 0.f, s2 = 0.f;
; #pragma unroll
;           for (int nt = 0; nt < 4; ++nt) {
;             float v = (acc[mt][nt][i] + bia[nt]) * csc[nt];
;             float z = ALPHA * xr[nt * 32] + hs * v;
;             acc[mt][nt][i] = z; s1 += z; s2 += z * z;
;           }
;           s1 = row16_sum(s1); s2 = row16_sum(s2);
;           if ((lane & 15) == 0) { f32x2 sv = {s1, s2}; *(f32x2*)(redw + (mt * 32 + (i & 3) + 8 * (i >> 2)) * 2) = sv; }
;         }
	v_mov_b32_e32 v73, v136
	s_mov_b32 s2, s67
	v_pk_mul_f32 v[88:89], v[72:73], s[2:3] op_sel_hi:[1,0]
	v_pk_mul_f32 v[134:135], v[146:147], 0.5 op_sel_hi:[1,0]
	v_pk_fma_f32 v[72:73], v[146:147], 0.5, v[88:89] op_sel_hi:[1,0,1]
	v_mov_b32_e32 v134, v105
	v_mov_b32_e32 v146, v1
	v_mov_b32_e32 v147, v89
	v_pk_mul_f32 v[140:141], v[72:73], v[72:73]
	v_pk_add_f32 v[134:135], v[134:135], v[146:147]
	v_mov_b32_e32 v163, v105
	v_pk_mov_b32 v[88:89], v[88:89], v[140:141] op_sel:[1,0]
	v_pk_add_f32 v[140:141], v[72:73], v[134:135]
	v_pk_mul_f32 v[134:135], v[72:73], v[134:135]
	v_pk_fma_f32 v[88:89], v[104:105], v[162:163], v[88:89]
	v_mov_b32_e32 v141, v135
	v_mov_b32_e32 v121, v137
	v_pk_add_f32 v[134:135], v[140:141], v[88:89]
	v_mul_f32_e32 v88, 0x3fd744fd, v137
	v_pk_fma_f32 v[88:89], v[120:121], s[66:67], v[88:89] op_sel_hi:[1,1,0]
	s_nop 0
	v_pk_mul_f32 v[120:121], v[88:89], v[88:89]
	s_nop 0
	v_mov_b32_e32 v89, v120
	v_pk_add_f32 v[120:121], v[134:135], v[88:89]
	s_nop 1
	v_mov_b32_dpp v134, v120 quad_perm:[1,0,3,2] row_mask:0xf bank_mask:0xf bound_ctrl:1
	v_mov_b32_dpp v135, v121 quad_perm:[1,0,3,2] row_mask:0xf bank_mask:0xf bound_ctrl:1
	v_pk_add_f32 v[120:121], v[120:121], v[134:135]
	s_nop 1
	v_mov_b32_dpp v134, v120 quad_perm:[2,3,0,1] row_mask:0xf bank_mask:0xf bound_ctrl:1
	v_mov_b32_dpp v135, v121 quad_perm:[2,3,0,1] row_mask:0xf bank_mask:0xf bound_ctrl:1
	v_pk_add_f32 v[120:121], v[120:121], v[134:135]
	s_nop 1
	v_mov_b32_dpp v134, v120 row_half_mirror row_mask:0xf bank_mask:0xf bound_ctrl:1
	v_mov_b32_dpp v135, v121 row_half_mirror row_mask:0xf bank_mask:0xf bound_ctrl:1
	v_pk_add_f32 v[120:121], v[120:121], v[134:135]
	s_nop 1
	v_mov_b32_dpp v134, v120 row_mirror row_mask:0xf bank_mask:0xf bound_ctrl:1
	v_mov_b32_dpp v135, v121 row_mirror row_mask:0xf bank_mask:0xf bound_ctrl:1
	s_and_saveexec_b64 s[6:7], vcc
	v_pk_add_f32 v[120:121], v[120:121], v[134:135]
	ds_write_b64 v160, v[120:121] offset:88
	s_or_b64 exec, exec, s[6:7]
	v_or_b32_e32 v120, 32, v176
	v_ashrrev_i32_e32 v121, 31, v120
	v_readlane_b32 s6, v255, 29
	v_lshlrev_b64 v[120:121], 12, v[120:121]
	v_readlane_b32 s7, v255, 30
	v_readfirstlane_b32 s2, v169
	s_lshl_b32 s2, s2, 13
	v_lshl_add_u64 v[120:121], s[6:7], 0, v[120:121]
	v_lshl_add_u64 v[120:121], v[154:155], 2, v[120:121]
	s_waitcnt lgkmcnt(0)
	v_lshl_add_u64 v[120:121], v[120:121], 0, v[0:1]
	s_mov_b32 m0, s2
	s_mov_b64 s[6:7], 0x2000
	global_load_lds_dwordx4 v[120:121], off
	v_lshl_add_u64 v[134:135], v[120:121], 0, s[6:7]
	s_or_b32 m0, s2, 0x400
	s_mov_b64 s[6:7], 0x4000
	global_load_lds_dwordx4 v[134:135], off
	v_lshl_add_u64 v[134:135], v[120:121], 0, s[6:7]
	s_or_b32 m0, s2, 0x800
	s_mov_b64 s[6:7], 0x6000
	global_load_lds_dwordx4 v[134:135], off
	v_lshl_add_u64 v[134:135], v[120:121], 0, s[6:7]
	s_or_b32 m0, s2, 0xc00
	s_mov_b64 s[6:7], 0x8000
	global_load_lds_dwordx4 v[134:135], off
	v_lshl_add_u64 v[134:135], v[120:121], 0, s[6:7]
	s_or_b32 m0, s2, 0x1000
	s_mov_b64 s[6:7], 0xa000
	global_load_lds_dwordx4 v[134:135], off
	v_lshl_add_u64 v[134:135], v[120:121], 0, s[6:7]
	s_or_b32 m0, s2, 0x1400
	s_mov_b64 s[6:7], 0xc000
	global_load_lds_dwordx4 v[134:135], off
	v_lshl_add_u64 v[134:135], v[120:121], 0, s[6:7]
	s_or_b32 m0, s2, 0x1800
	s_mov_b64 s[6:7], 0xe000
	global_load_lds_dwordx4 v[134:135], off
	v_lshl_add_u64 v[120:121], v[120:121], 0, s[6:7]
	s_or_b32 m0, s2, 0x1c00
	v_add_u32_e32 v116, 0x10000, v138
	global_load_lds_dwordx4 v[120:121], off
	s_waitcnt vmcnt(8)
	v_add_u32_e32 v89, v116, v172
	ds_read2_b32 v[120:121], v89 offset1:32
	ds_read2_b32 v[134:135], v89 offset0:64 offset1:96
	v_add_f32_e32 v98, 0, v122
	v_mov_b32_e32 v146, v106
	v_mov_b32_e32 v147, v90
	s_waitcnt lgkmcnt(0)
	v_mul_f32_e32 v137, 0x3fd744fd, v120
	v_mul_f32_e32 v139, 0.5, v98
	v_pk_add_f32 v[146:147], v[146:147], 0 op_sel_hi:[1,0]
	v_mov_b32_e32 v138, v90
	v_mov_b32_e32 v136, v1
	v_mov_b32_e32 v120, v121
	v_mov_b32_e32 v121, v134
	s_mov_b32 s2, s67
	v_pk_add_f32 v[136:137], v[138:139], v[136:137]
	v_pk_mul_f32 v[138:139], v[120:121], s[2:3] op_sel_hi:[1,0]
	v_pk_mul_f32 v[150:151], v[146:147], 0.5 op_sel_hi:[1,0]
	v_pk_fma_f32 v[120:121], v[146:147], 0.5, v[138:139] op_sel_hi:[1,0,1]
	v_mov_b32_e32 v150, v137
	v_mov_b32_e32 v156, v1
	v_mov_b32_e32 v157, v139
	v_add_f32_e32 v140, 0, v74
	v_mov_b32_e32 v141, v135
	v_pk_mul_f32 v[146:147], v[120:121], v[120:121]
	v_pk_add_f32 v[150:151], v[150:151], v[156:157]
	v_mul_f32_e32 v74, 0x3fd744fd, v135
	v_mov_b32_e32 v163, v137
	v_pk_mov_b32 v[138:139], v[138:139], v[146:147] op_sel:[1,0]
	v_pk_add_f32 v[146:147], v[120:121], v[150:151]
	v_pk_mul_f32 v[150:151], v[120:121], v[150:151]
	v_pk_fma_f32 v[134:135], v[140:141], s[66:67], v[74:75] op_sel_hi:[1,1,0]
	v_pk_fma_f32 v[138:139], v[136:137], v[162:163], v[138:139]
	v_mov_b32_e32 v147, v151
	v_pk_mul_f32 v[140:141], v[134:135], v[134:135]
	v_pk_add_f32 v[138:139], v[146:147], v[138:139]
	v_mov_b32_e32 v135, v140
	v_pk_add_f32 v[138:139], v[138:139], v[134:135]
	s_nop 1
	v_mov_b32_dpp v140, v138 quad_perm:[1,0,3,2] row_mask:0xf bank_mask:0xf bound_ctrl:1
	v_mov_b32_dpp v141, v139 quad_perm:[1,0,3,2] row_mask:0xf bank_mask:0xf bound_ctrl:1
	v_pk_add_f32 v[138:139], v[138:139], v[140:141]
	s_nop 1
	v_mov_b32_dpp v140, v138 quad_perm:[2,3,0,1] row_mask:0xf bank_mask:0xf bound_ctrl:1
	v_mov_b32_dpp v141, v139 quad_perm:[2,3,0,1] row_mask:0xf bank_mask:0xf bound_ctrl:1
	v_pk_add_f32 v[138:139], v[138:139], v[140:141]
	s_nop 1
	v_mov_b32_dpp v140, v138 row_half_mirror row_mask:0xf bank_mask:0xf bound_ctrl:1
	v_mov_b32_dpp v141, v139 row_half_mirror row_mask:0xf bank_mask:0xf bound_ctrl:1
	v_pk_add_f32 v[138:139], v[138:139], v[140:141]
	s_nop 1
	v_mov_b32_dpp v140, v138 row_mirror row_mask:0xf bank_mask:0xf bound_ctrl:1
	v_mov_b32_dpp v141, v139 row_mirror row_mask:0xf bank_mask:0xf bound_ctrl:1
	s_and_saveexec_b64 s[6:7], vcc
	v_pk_add_f32 v[138:139], v[138:139], v[140:141]
	ds_write_b64 v160, v[138:139] offset:128
	s_or_b64 exec, exec, s[6:7]
	v_or_b32_e32 v74, 0x200, v172
	v_add_u32_e32 v98, v116, v74
	ds_read2_b32 v[138:139], v98 offset1:32
	ds_read2_b32 v[140:141], v98 offset0:64 offset1:96
	v_add_f32_e32 v74, 0, v123
	v_add_f32_e32 v122, 0, v75
	v_mul_f32_e32 v75, 0.5, v74
	s_waitcnt lgkmcnt(1)
;   DI void operator()(f32x16 (&acc)[2][4], int grow0, int gcol0, int lane, int w, char* lds) {
;     ...
; #pragma unroll
;       for (int qq = 0; qq < 2; ++qq)
; #pragma unroll
;         for (int e = 0; e < 4; ++e) {
;           const int i = 4 * (2 * (ps & 1) + qq) + e;
;           const float* xr = (const float*)(xs + (8 * qq + 4 * hh + e) * 512) + l31;
;           float s1 = 0.f, s2 = 0.f;
; #pragma unroll
;           for (int nt = 0; nt < 4; ++nt) {
;             float v = (acc[mt][nt][i] + bia[nt]) * csc[nt];
;             float z = ALPHA * xr[nt * 32] + hs * v;
;             acc[mt][nt][i] = z; s1 += z; s2 += z * z;
;           }
;           s1 = row16_sum(s1); s2 = row16_sum(s2);
;           if ((lane & 15) == 0) { f32x2 sv = {s1, s2}; *(f32x2*)(redw + (mt * 32 + (i & 3) + 8 * (i >> 2)) * 2) = sv; }
;         }
	v_mul_f32_e32 v147, 0x3fd744fd, v138
	v_mov_b32_e32 v90, v107
	v_mov_b32_e32 v74, v91
	v_mov_b32_e32 v146, v1
	v_pk_add_f32 v[150:151], v[90:91], 0 op_sel_hi:[1,0]
	v_pk_add_f32 v[106:107], v[74:75], v[146:147]
	v_mov_b32_e32 v74, v139
	s_waitcnt lgkmcnt(0)
	v_mov_b32_e32 v75, v140
	s_mov_b32 s2, s67
	v_pk_mul_f32 v[90:91], v[74:75], s[2:3] op_sel_hi:[1,0]
	v_pk_mul_f32 v[138:139], v[150:151], 0.5 op_sel_hi:[1,0]
	v_pk_fma_f32 v[74:75], v[150:151], 0.5, v[90:91] op_sel_hi:[1,0,1]
	v_mov_b32_e32 v138, v107
	v_mov_b32_e32 v150, v1
	v_mov_b32_e32 v151, v91
	v_pk_mul_f32 v[146:147], v[74:75], v[74:75]
	v_pk_add_f32 v[138:139], v[138:139], v[150:151]
	v_mov_b32_e32 v163, v107
	v_pk_mov_b32 v[90:91], v[90:91], v[146:147] op_sel:[1,0]
	v_pk_add_f32 v[146:147], v[74:75], v[138:139]
	v_pk_mul_f32 v[138:139], v[74:75], v[138:139]
	v_pk_fma_f32 v[90:91], v[106:107], v[162:163], v[90:91]
	v_mov_b32_e32 v147, v139
	v_mov_b32_e32 v123, v141
	v_pk_add_f32 v[138:139], v[146:147], v[90:91]
	v_mul_f32_e32 v90, 0x3fd744fd, v141
	v_pk_fma_f32 v[90:91], v[122:123], s[66:67], v[90:91] op_sel_hi:[1,1,0]
	s_nop 0
	v_pk_mul_f32 v[122:123], v[90:91], v[90:91]
	s_nop 0
	v_mov_b32_e32 v91, v122
	v_pk_add_f32 v[122:123], v[138:139], v[90:91]
	s_nop 1
	v_mov_b32_dpp v138, v122 quad_perm:[1,0,3,2] row_mask:0xf bank_mask:0xf bound_ctrl:1
	v_mov_b32_dpp v139, v123 quad_perm:[1,0,3,2] row_mask:0xf bank_mask:0xf bound_ctrl:1
	v_pk_add_f32 v[122:123], v[122:123], v[138:139]
	s_nop 1
	v_mov_b32_dpp v138, v122 quad_perm:[2,3,0,1] row_mask:0xf bank_mask:0xf bound_ctrl:1
	v_mov_b32_dpp v139, v123 quad_perm:[2,3,0,1] row_mask:0xf bank_mask:0xf bound_ctrl:1
	v_pk_add_f32 v[122:123], v[122:123], v[138:139]
	s_nop 1
	v_mov_b32_dpp v138, v122 row_half_mirror row_mask:0xf bank_mask:0xf bound_ctrl:1
	v_mov_b32_dpp v139, v123 row_half_mirror row_mask:0xf bank_mask:0xf bound_ctrl:1
	v_pk_add_f32 v[122:123], v[122:123], v[138:139]
	s_nop 1
	v_mov_b32_dpp v138, v122 row_mirror row_mask:0xf bank_mask:0xf bound_ctrl:1
	v_mov_b32_dpp v139, v123 row_mirror row_mask:0xf bank_mask:0xf bound_ctrl:1
	s_and_saveexec_b64 s[6:7], vcc
	v_pk_add_f32 v[122:123], v[122:123], v[138:139]
	ds_write_b64 v160, v[122:123] offset:136
	s_or_b64 exec, exec, s[6:7]
	v_or_b32_e32 v91, 0x400, v172
	v_add_u32_e32 v102, v116, v91
	ds_read2_b32 v[122:123], v102 offset1:32
	ds_read2_b32 v[138:139], v102 offset0:64 offset1:96
	v_add_f32_e32 v91, 0, v124
	v_mov_b32_e32 v156, v108
	v_mov_b32_e32 v157, v92
	v_mul_f32_e32 v141, 0.5, v91
	s_waitcnt lgkmcnt(1)
	v_mul_f32_e32 v151, 0x3fd744fd, v122
	v_pk_add_f32 v[156:157], v[156:157], 0 op_sel_hi:[1,0]
	v_mov_b32_e32 v140, v92
	v_mov_b32_e32 v150, v1
	v_mov_b32_e32 v122, v123
	s_waitcnt lgkmcnt(0)
	v_mov_b32_e32 v123, v138
	s_mov_b32 s2, s67
	v_pk_add_f32 v[140:141], v[140:141], v[150:151]
	v_pk_mul_f32 v[150:151], v[122:123], s[2:3] op_sel_hi:[1,0]
	v_pk_mul_f32 v[174:175], v[156:157], 0.5 op_sel_hi:[1,0]
	v_pk_fma_f32 v[122:123], v[156:157], 0.5, v[150:151] op_sel_hi:[1,0,1]
	v_mov_b32_e32 v174, v141
	v_mov_b32_e32 v178, v1
	v_mov_b32_e32 v179, v151
	v_add_f32_e32 v146, 0, v76
	v_mov_b32_e32 v147, v139
	v_pk_mul_f32 v[156:157], v[122:123], v[122:123]
	v_pk_add_f32 v[174:175], v[174:175], v[178:179]
	v_mul_f32_e32 v76, 0x3fd744fd, v139
	v_mov_b32_e32 v163, v141
	v_pk_mov_b32 v[150:151], v[150:151], v[156:157] op_sel:[1,0]
	v_pk_add_f32 v[156:157], v[122:123], v[174:175]
	v_pk_mul_f32 v[174:175], v[122:123], v[174:175]
	v_pk_fma_f32 v[138:139], v[146:147], s[66:67], v[76:77] op_sel_hi:[1,1,0]
	v_pk_fma_f32 v[150:151], v[140:141], v[162:163], v[150:151]
	v_mov_b32_e32 v157, v175
	v_pk_mul_f32 v[146:147], v[138:139], v[138:139]
	v_pk_add_f32 v[150:151], v[156:157], v[150:151]
	v_mov_b32_e32 v139, v146
	v_pk_add_f32 v[146:147], v[150:151], v[138:139]
	s_nop 1
	v_mov_b32_dpp v150, v146 quad_perm:[1,0,3,2] row_mask:0xf bank_mask:0xf bound_ctrl:1
	v_mov_b32_dpp v151, v147 quad_perm:[1,0,3,2] row_mask:0xf bank_mask:0xf bound_ctrl:1
	v_pk_add_f32 v[146:147], v[146:147], v[150:151]
	s_nop 1
	v_mov_b32_dpp v150, v146 quad_perm:[2,3,0,1] row_mask:0xf bank_mask:0xf bound_ctrl:1
	v_mov_b32_dpp v151, v147 quad_perm:[2,3,0,1] row_mask:0xf bank_mask:0xf bound_ctrl:1
	v_pk_add_f32 v[146:147], v[146:147], v[150:151]
	s_nop 1
	v_mov_b32_dpp v150, v146 row_half_mirror row_mask:0xf bank_mask:0xf bound_ctrl:1
	v_mov_b32_dpp v151, v147 row_half_mirror row_mask:0xf bank_mask:0xf bound_ctrl:1
	v_pk_add_f32 v[146:147], v[146:147], v[150:151]
	s_nop 1
	v_mov_b32_dpp v150, v146 row_mirror row_mask:0xf bank_mask:0xf bound_ctrl:1
	v_mov_b32_dpp v151, v147 row_mirror row_mask:0xf bank_mask:0xf bound_ctrl:1
	s_and_saveexec_b64 s[6:7], vcc
	v_pk_add_f32 v[146:147], v[146:147], v[150:151]
	ds_write_b64 v160, v[146:147] offset:144
	s_or_b64 exec, exec, s[6:7]
	v_add_u32_e32 v104, v116, v152
	ds_read2_b32 v[146:147], v104 offset1:32
	ds_read2_b32 v[150:151], v104 offset0:64 offset1:96
	v_add_f32_e32 v76, 0, v125
	v_add_f32_e32 v124, 0, v77
	v_mul_f32_e32 v77, 0.5, v76
	s_waitcnt lgkmcnt(1)
	v_mul_f32_e32 v153, 0x3fd744fd, v146
	v_mov_b32_e32 v92, v109
	v_mov_b32_e32 v76, v93
	v_mov_b32_e32 v152, v1
	v_pk_add_f32 v[156:157], v[92:93], 0 op_sel_hi:[1,0]
	v_pk_add_f32 v[108:109], v[76:77], v[152:153]
	v_mov_b32_e32 v76, v147
	s_waitcnt lgkmcnt(0)
;   DI void operator()(f32x16 (&acc)[2][4], int grow0, int gcol0, int lane, int w, char* lds) {
;     ...
; #pragma unroll
;       for (int qq = 0; qq < 2; ++qq)
; #pragma unroll
;         for (int e = 0; e < 4; ++e) {
;           const int i = 4 * (2 * (ps & 1) + qq) + e;
;           const float* xr = (const float*)(xs + (8 * qq + 4 * hh + e) * 512) + l31;
;           float s1 = 0.f, s2 = 0.f;
; #pragma unroll
;           for (int nt = 0; nt < 4; ++nt) {
;             float v = (acc[mt][nt][i] + bia[nt]) * csc[nt];
;             float z = ALPHA * xr[nt * 32] + hs * v;
;             acc[mt][nt][i] = z; s1 += z; s2 += z * z;
;           }
;           s1 = row16_sum(s1); s2 = row16_sum(s2);
;           if ((lane & 15) == 0) { f32x2 sv = {s1, s2}; *(f32x2*)(redw + (mt * 32 + (i & 3) + 8 * (i >> 2)) * 2) = sv; }
;         }
	v_mov_b32_e32 v77, v150
	s_mov_b32 s2, s67
	v_pk_mul_f32 v[92:93], v[76:77], s[2:3] op_sel_hi:[1,0]
	v_pk_mul_f32 v[146:147], v[156:157], 0.5 op_sel_hi:[1,0]
	v_pk_fma_f32 v[76:77], v[156:157], 0.5, v[92:93] op_sel_hi:[1,0,1]
	v_mov_b32_e32 v146, v109
	v_mov_b32_e32 v156, v1
	v_mov_b32_e32 v157, v93
	v_pk_mul_f32 v[152:153], v[76:77], v[76:77]
	v_pk_add_f32 v[146:147], v[146:147], v[156:157]
	v_mov_b32_e32 v163, v109
	v_pk_mov_b32 v[92:93], v[92:93], v[152:153] op_sel:[1,0]
	v_pk_add_f32 v[152:153], v[76:77], v[146:147]
	v_pk_mul_f32 v[146:147], v[76:77], v[146:147]
	v_pk_fma_f32 v[92:93], v[108:109], v[162:163], v[92:93]
	v_mov_b32_e32 v153, v147
	v_mov_b32_e32 v125, v151
	v_pk_add_f32 v[146:147], v[152:153], v[92:93]
	v_mul_f32_e32 v92, 0x3fd744fd, v151
	v_pk_fma_f32 v[92:93], v[124:125], s[66:67], v[92:93] op_sel_hi:[1,1,0]
	s_nop 0
	v_pk_mul_f32 v[124:125], v[92:93], v[92:93]
	s_nop 0
	v_mov_b32_e32 v93, v124
	v_pk_add_f32 v[124:125], v[146:147], v[92:93]
	s_nop 1
	v_mov_b32_dpp v146, v124 quad_perm:[1,0,3,2] row_mask:0xf bank_mask:0xf bound_ctrl:1
	v_mov_b32_dpp v147, v125 quad_perm:[1,0,3,2] row_mask:0xf bank_mask:0xf bound_ctrl:1
	v_pk_add_f32 v[124:125], v[124:125], v[146:147]
	s_nop 1
	v_mov_b32_dpp v146, v124 quad_perm:[2,3,0,1] row_mask:0xf bank_mask:0xf bound_ctrl:1
	v_mov_b32_dpp v147, v125 quad_perm:[2,3,0,1] row_mask:0xf bank_mask:0xf bound_ctrl:1
	v_pk_add_f32 v[124:125], v[124:125], v[146:147]
	s_nop 1
	v_mov_b32_dpp v146, v124 row_half_mirror row_mask:0xf bank_mask:0xf bound_ctrl:1
	v_mov_b32_dpp v147, v125 row_half_mirror row_mask:0xf bank_mask:0xf bound_ctrl:1
	v_pk_add_f32 v[124:125], v[124:125], v[146:147]
	s_nop 1
	v_mov_b32_dpp v146, v124 row_mirror row_mask:0xf bank_mask:0xf bound_ctrl:1
	v_mov_b32_dpp v147, v125 row_mirror row_mask:0xf bank_mask:0xf bound_ctrl:1
	s_and_saveexec_b64 s[6:7], vcc
	v_pk_add_f32 v[124:125], v[124:125], v[146:147]
	ds_write_b64 v160, v[124:125] offset:152
	s_or_b64 exec, exec, s[6:7]
	v_or_b32_e32 v91, 0x1000, v172
	v_add_u32_e32 v93, v116, v91
	ds_read2_b32 v[124:125], v93 offset1:32
	ds_read2_b32 v[146:147], v93 offset0:64 offset1:96
	v_add_f32_e32 v91, 0, v126
	v_mov_b32_e32 v174, v110
	v_mov_b32_e32 v175, v94
	v_mul_f32_e32 v151, 0.5, v91
	s_waitcnt lgkmcnt(1)
	v_mul_f32_e32 v157, 0x3fd744fd, v124
	v_pk_add_f32 v[174:175], v[174:175], 0 op_sel_hi:[1,0]
	v_mov_b32_e32 v150, v94
	v_mov_b32_e32 v156, v1
	v_mov_b32_e32 v124, v125
	s_waitcnt lgkmcnt(0)
	v_mov_b32_e32 v125, v146
	s_mov_b32 s2, s67
	v_pk_add_f32 v[150:151], v[150:151], v[156:157]
	v_pk_mul_f32 v[156:157], v[124:125], s[2:3] op_sel_hi:[1,0]
	v_pk_mul_f32 v[178:179], v[174:175], 0.5 op_sel_hi:[1,0]
	v_pk_fma_f32 v[124:125], v[174:175], 0.5, v[156:157] op_sel_hi:[1,0,1]
	v_mov_b32_e32 v178, v151
	v_mov_b32_e32 v180, v1
	v_mov_b32_e32 v181, v157
	v_add_f32_e32 v152, 0, v78
	v_mov_b32_e32 v153, v147
	v_pk_mul_f32 v[174:175], v[124:125], v[124:125]
	v_pk_add_f32 v[178:179], v[178:179], v[180:181]
	v_mul_f32_e32 v78, 0x3fd744fd, v147
	v_mov_b32_e32 v163, v151
	v_pk_mov_b32 v[156:157], v[156:157], v[174:175] op_sel:[1,0]
	v_pk_add_f32 v[174:175], v[124:125], v[178:179]
	v_pk_mul_f32 v[178:179], v[124:125], v[178:179]
	v_pk_fma_f32 v[146:147], v[152:153], s[66:67], v[78:79] op_sel_hi:[1,1,0]
	v_pk_fma_f32 v[156:157], v[150:151], v[162:163], v[156:157]
	v_mov_b32_e32 v175, v179
	v_pk_mul_f32 v[152:153], v[146:147], v[146:147]
	v_pk_add_f32 v[156:157], v[174:175], v[156:157]
	v_mov_b32_e32 v147, v152
	v_pk_add_f32 v[152:153], v[156:157], v[146:147]
	s_nop 1
	v_mov_b32_dpp v156, v152 quad_perm:[1,0,3,2] row_mask:0xf bank_mask:0xf bound_ctrl:1
	v_mov_b32_dpp v157, v153 quad_perm:[1,0,3,2] row_mask:0xf bank_mask:0xf bound_ctrl:1
	v_pk_add_f32 v[152:153], v[152:153], v[156:157]
	s_nop 1
	v_mov_b32_dpp v156, v152 quad_perm:[2,3,0,1] row_mask:0xf bank_mask:0xf bound_ctrl:1
	v_mov_b32_dpp v157, v153 quad_perm:[2,3,0,1] row_mask:0xf bank_mask:0xf bound_ctrl:1
	v_pk_add_f32 v[152:153], v[152:153], v[156:157]
	s_nop 1
	v_mov_b32_dpp v156, v152 row_half_mirror row_mask:0xf bank_mask:0xf bound_ctrl:1
	v_mov_b32_dpp v157, v153 row_half_mirror row_mask:0xf bank_mask:0xf bound_ctrl:1
	v_pk_add_f32 v[152:153], v[152:153], v[156:157]
	s_nop 1
	v_mov_b32_dpp v156, v152 row_mirror row_mask:0xf bank_mask:0xf bound_ctrl:1
	v_mov_b32_dpp v157, v153 row_mirror row_mask:0xf bank_mask:0xf bound_ctrl:1
	s_and_saveexec_b64 s[6:7], vcc
	v_pk_add_f32 v[152:153], v[152:153], v[156:157]
	ds_write_b64 v160, v[152:153] offset:192
	s_or_b64 exec, exec, s[6:7]
	v_or_b32_e32 v78, 0x1200, v172
	v_add_u32_e32 v106, v116, v78
	ds_read2_b32 v[152:153], v106 offset1:32
	ds_read2_b32 v[156:157], v106 offset0:64 offset1:96
	v_add_f32_e32 v78, 0, v127
	v_add_f32_e32 v126, 0, v79
	v_mul_f32_e32 v79, 0.5, v78
	s_waitcnt lgkmcnt(1)
	v_mul_f32_e32 v175, 0x3fd744fd, v152
	v_mov_b32_e32 v94, v111
	v_mov_b32_e32 v78, v95
	v_mov_b32_e32 v174, v1
	v_pk_add_f32 v[178:179], v[94:95], 0 op_sel_hi:[1,0]
	v_pk_add_f32 v[110:111], v[78:79], v[174:175]
	v_mov_b32_e32 v78, v153
	s_waitcnt lgkmcnt(0)
;   DI void operator()(f32x16 (&acc)[2][4], int grow0, int gcol0, int lane, int w, char* lds) {
;     ...
; #pragma unroll
;       for (int qq = 0; qq < 2; ++qq)
; #pragma unroll
;         for (int e = 0; e < 4; ++e) {
;           const int i = 4 * (2 * (ps & 1) + qq) + e;
;           const float* xr = (const float*)(xs + (8 * qq + 4 * hh + e) * 512) + l31;
;           float s1 = 0.f, s2 = 0.f;
; #pragma unroll
;           for (int nt = 0; nt < 4; ++nt) {
;             float v = (acc[mt][nt][i] + bia[nt]) * csc[nt];
;             float z = ALPHA * xr[nt * 32] + hs * v;
;             acc[mt][nt][i] = z; s1 += z; s2 += z * z;
;           }
;           s1 = row16_sum(s1); s2 = row16_sum(s2);
;           if ((lane & 15) == 0) { f32x2 sv = {s1, s2}; *(f32x2*)(redw + (mt * 32 + (i & 3) + 8 * (i >> 2)) * 2) = sv; }
;         }
	v_mov_b32_e32 v79, v156
	s_mov_b32 s2, s67
	v_pk_mul_f32 v[94:95], v[78:79], s[2:3] op_sel_hi:[1,0]
	v_pk_mul_f32 v[152:153], v[178:179], 0.5 op_sel_hi:[1,0]
	v_pk_fma_f32 v[78:79], v[178:179], 0.5, v[94:95] op_sel_hi:[1,0,1]
	v_mov_b32_e32 v152, v111
	v_mov_b32_e32 v178, v1
	v_mov_b32_e32 v179, v95
	v_pk_mul_f32 v[174:175], v[78:79], v[78:79]
	v_pk_add_f32 v[152:153], v[152:153], v[178:179]
	v_mov_b32_e32 v163, v111
	v_pk_mov_b32 v[94:95], v[94:95], v[174:175] op_sel:[1,0]
	v_pk_add_f32 v[174:175], v[78:79], v[152:153]
	v_pk_mul_f32 v[152:153], v[78:79], v[152:153]
	v_pk_fma_f32 v[94:95], v[110:111], v[162:163], v[94:95]
	v_mov_b32_e32 v175, v153
	v_mov_b32_e32 v127, v157
	v_pk_add_f32 v[152:153], v[174:175], v[94:95]
	v_mul_f32_e32 v94, 0x3fd744fd, v157
	v_pk_fma_f32 v[94:95], v[126:127], s[66:67], v[94:95] op_sel_hi:[1,1,0]
	s_nop 0
	v_pk_mul_f32 v[126:127], v[94:95], v[94:95]
	s_nop 0
	v_mov_b32_e32 v95, v126
	v_pk_add_f32 v[126:127], v[152:153], v[94:95]
	s_nop 1
	v_mov_b32_dpp v152, v126 quad_perm:[1,0,3,2] row_mask:0xf bank_mask:0xf bound_ctrl:1
	v_mov_b32_dpp v153, v127 quad_perm:[1,0,3,2] row_mask:0xf bank_mask:0xf bound_ctrl:1
	v_pk_add_f32 v[126:127], v[126:127], v[152:153]
	s_nop 1
	v_mov_b32_dpp v152, v126 quad_perm:[2,3,0,1] row_mask:0xf bank_mask:0xf bound_ctrl:1
	v_mov_b32_dpp v153, v127 quad_perm:[2,3,0,1] row_mask:0xf bank_mask:0xf bound_ctrl:1
	v_pk_add_f32 v[126:127], v[126:127], v[152:153]
	s_nop 1
	v_mov_b32_dpp v152, v126 row_half_mirror row_mask:0xf bank_mask:0xf bound_ctrl:1
	v_mov_b32_dpp v153, v127 row_half_mirror row_mask:0xf bank_mask:0xf bound_ctrl:1
	v_pk_add_f32 v[126:127], v[126:127], v[152:153]
	s_nop 1
	v_mov_b32_dpp v152, v126 row_mirror row_mask:0xf bank_mask:0xf bound_ctrl:1
	v_mov_b32_dpp v153, v127 row_mirror row_mask:0xf bank_mask:0xf bound_ctrl:1
	s_and_saveexec_b64 s[6:7], vcc
	v_pk_add_f32 v[126:127], v[126:127], v[152:153]
	ds_write_b64 v160, v[126:127] offset:200
	s_or_b64 exec, exec, s[6:7]
	v_or_b32_e32 v91, 0x1400, v172
	v_add_u32_e32 v95, v116, v91
	ds_read2_b32 v[126:127], v95 offset1:32
	ds_read2_b32 v[152:153], v95 offset0:64 offset1:96
	v_add_f32_e32 v91, 0, v128
	v_mov_b32_e32 v178, v112
	v_mov_b32_e32 v179, v96
	v_mul_f32_e32 v157, 0.5, v91
	s_waitcnt lgkmcnt(1)
	v_mul_f32_e32 v175, 0x3fd744fd, v126
	v_pk_add_f32 v[178:179], v[178:179], 0 op_sel_hi:[1,0]
	v_mov_b32_e32 v156, v96
	v_mov_b32_e32 v174, v1
	v_mov_b32_e32 v126, v127
	s_waitcnt lgkmcnt(0)
	v_mov_b32_e32 v127, v152
	s_mov_b32 s2, s67
	v_pk_add_f32 v[156:157], v[156:157], v[174:175]
	v_pk_mul_f32 v[174:175], v[126:127], s[2:3] op_sel_hi:[1,0]
	v_pk_mul_f32 v[180:181], v[178:179], 0.5 op_sel_hi:[1,0]
	v_pk_fma_f32 v[126:127], v[178:179], 0.5, v[174:175] op_sel_hi:[1,0,1]
	v_mov_b32_e32 v180, v157
	v_mov_b32_e32 v182, v1
	v_mov_b32_e32 v183, v175
	v_add_f32_e32 v172, 0, v80
	v_mov_b32_e32 v173, v153
	v_pk_mul_f32 v[178:179], v[126:127], v[126:127]
	v_pk_add_f32 v[180:181], v[180:181], v[182:183]
	v_mul_f32_e32 v80, 0x3fd744fd, v153
	v_mov_b32_e32 v163, v157
	v_pk_mov_b32 v[174:175], v[174:175], v[178:179] op_sel:[1,0]
	v_pk_add_f32 v[178:179], v[126:127], v[180:181]
	v_pk_mul_f32 v[180:181], v[126:127], v[180:181]
	v_pk_fma_f32 v[152:153], v[172:173], s[66:67], v[80:81] op_sel_hi:[1,1,0]
	v_pk_fma_f32 v[174:175], v[156:157], v[162:163], v[174:175]
	v_mov_b32_e32 v179, v181
	v_pk_mul_f32 v[172:173], v[152:153], v[152:153]
	v_pk_add_f32 v[174:175], v[178:179], v[174:175]
	v_mov_b32_e32 v153, v172
	v_pk_add_f32 v[172:173], v[174:175], v[152:153]
	s_nop 1
	v_mov_b32_dpp v174, v172 quad_perm:[1,0,3,2] row_mask:0xf bank_mask:0xf bound_ctrl:1
	v_mov_b32_dpp v175, v173 quad_perm:[1,0,3,2] row_mask:0xf bank_mask:0xf bound_ctrl:1
	v_pk_add_f32 v[172:173], v[172:173], v[174:175]
	s_nop 1
	v_mov_b32_dpp v174, v172 quad_perm:[2,3,0,1] row_mask:0xf bank_mask:0xf bound_ctrl:1
	v_mov_b32_dpp v175, v173 quad_perm:[2,3,0,1] row_mask:0xf bank_mask:0xf bound_ctrl:1
	v_pk_add_f32 v[172:173], v[172:173], v[174:175]
	s_nop 1
	v_mov_b32_dpp v174, v172 row_half_mirror row_mask:0xf bank_mask:0xf bound_ctrl:1
	v_mov_b32_dpp v175, v173 row_half_mirror row_mask:0xf bank_mask:0xf bound_ctrl:1
	v_pk_add_f32 v[172:173], v[172:173], v[174:175]
	s_nop 1
	v_mov_b32_dpp v174, v172 row_mirror row_mask:0xf bank_mask:0xf bound_ctrl:1
	v_mov_b32_dpp v175, v173 row_mirror row_mask:0xf bank_mask:0xf bound_ctrl:1
	s_and_saveexec_b64 s[6:7], vcc
	v_pk_add_f32 v[172:173], v[172:173], v[174:175]
	ds_write_b64 v160, v[172:173] offset:208
	s_or_b64 exec, exec, s[6:7]
	v_add_u32_e32 v91, v116, v115
	v_add_f32_e32 v80, 0, v129
	ds_read2_b32 v[128:129], v91 offset1:32
	ds_read2_b32 v[178:179], v91 offset0:64 offset1:96
	v_mov_b32_e32 v96, v113
	v_mul_f32_e32 v175, 0.5, v80
	v_add_f32_e32 v180, 0, v81
	s_waitcnt lgkmcnt(1)
	v_mul_f32_e32 v173, 0x3fd744fd, v128
	v_pk_add_f32 v[80:81], v[96:97], 0 op_sel_hi:[1,0]
	v_mov_b32_e32 v174, v97
	v_mov_b32_e32 v172, v1
	v_mov_b32_e32 v96, v129
	s_waitcnt lgkmcnt(0)
;   DI void xpass(int ps, int grow0, int gcol0, int lane, int w, char* lds) const {
;     char* xs = lds + (ps & 1) * 65536 + __builtin_amdgcn_readfirstlane(w) * 8192;
;     const float* xsrc = Xin + (size_t)(grow0 + (ps >> 1) * 32 + (ps & 1) * 16 + (lane >> 5)) * D_ + gcol0 + (lane & 31) * 4;
; #pragma unroll
;     for (int pc = 0; pc < 8; ++pc)
;       __builtin_amdgcn_global_load_lds((const unsigned*)(xsrc + (size_t)(2 * pc) * D_), (__attribute__((address_space(3))) unsigned*)(xs + pc * 1024), 16, 0, 0);
;   }
;   DI void pre(int grow0, int gcol0, int lane, int w, char* lds) { xpass(0, grow0, gcol0, lane, w, lds); }
;   DI void operator()(f32x16 (&acc)[2][4], int grow0, int gcol0, int lane, int w, char* lds) {
;     float* red = (float*)(lds + 131072); float* stat = (float*)lds;
;     const int l31 = lane & 31, hh = lane >> 5, tid = w * 64 + lane;
;     const int pm = grow0 >> 8, pn = gcol0 >> 8, wn = (gcol0 >> 7) & 1, lrow0 = grow0 & 255;
;     float bia[4], csc[4];
; #pragma unroll
;     for (int nt = 0; nt < 4; ++nt) { int c = gcol0 + nt * 32 + l31; bia[nt] = bias ? bias[c] : 0.f; csc[nt] = cscale ? cscale[c] : 1.f; }
;     float* redw = red + ((wn * 2 + ((lane >> 4) & 1)) * 256 + lrow0 + 4 * hh) * 2;
; #pragma unroll
;     for (int ps = 0; ps < 4; ++ps) {
;       const int mt = ps >> 1;
;       if (ps + 1 < 4) {
;         if (ps >= 1) asm volatile("s_waitcnt lgkmcnt(0)" ::: "memory");
;         xpass(ps + 1, grow0, gcol0, lane, w, lds);
;         if (ps >= 1) asm volatile("s_waitcnt vmcnt(8)" ::: "memory");
;       } else asm volatile("s_waitcnt vmcnt(0)" ::: "memory");
;       const char* xs = lds + (ps & 1) * 65536 + w * 8192;
; #pragma unroll
;       for (int qq = 0; qq < 2; ++qq)
; #pragma unroll
;         for (int e = 0; e < 4; ++e) {
;           const int i = 4 * (2 * (ps & 1) + qq) + e;
;           const float* xr = (const float*)(xs + (8 * qq + 4 * hh + e) * 512) + l31;
;           float s1 = 0.f, s2 = 0.f;
; #pragma unroll
;           for (int nt = 0; nt < 4; ++nt) {
;             float v = (acc[mt][nt][i] + bia[nt]) * csc[nt];
;             float z = ALPHA * xr[nt * 32] + hs * v;
;             acc[mt][nt][i] = z; s1 += z; s2 += z * z;
;           }
;           s1 = row16_sum(s1); s2 = row16_sum(s2);
;           if ((lane & 15) == 0) { f32x2 sv = {s1, s2}; *(f32x2*)(redw + (mt * 32 + (i & 3) + 8 * (i >> 2)) * 2) = sv; }
;         }
	v_mov_b32_e32 v97, v178
	s_mov_b32 s2, s67
	v_pk_add_f32 v[112:113], v[174:175], v[172:173]
	v_pk_mul_f32 v[96:97], v[96:97], s[2:3] op_sel_hi:[1,0]
	v_pk_mul_f32 v[128:129], v[80:81], 0.5 op_sel_hi:[1,0]
	v_pk_fma_f32 v[80:81], v[80:81], 0.5, v[96:97] op_sel_hi:[1,0,1]
	v_mov_b32_e32 v128, v113
	v_mov_b32_e32 v174, v1
	v_mov_b32_e32 v175, v97
	v_pk_mul_f32 v[172:173], v[80:81], v[80:81]
	v_pk_add_f32 v[128:129], v[128:129], v[174:175]
	v_mov_b32_e32 v163, v113
	v_pk_mov_b32 v[96:97], v[96:97], v[172:173] op_sel:[1,0]
	v_pk_add_f32 v[172:173], v[80:81], v[128:129]
	v_pk_mul_f32 v[128:129], v[80:81], v[128:129]
	v_pk_fma_f32 v[96:97], v[112:113], v[162:163], v[96:97]
	v_mov_b32_e32 v173, v129
	v_mov_b32_e32 v181, v179
	v_pk_add_f32 v[128:129], v[172:173], v[96:97]
	v_mul_f32_e32 v96, 0x3fd744fd, v179
	v_pk_fma_f32 v[96:97], v[180:181], s[66:67], v[96:97] op_sel_hi:[1,1,0]
	s_nop 0
	v_pk_mul_f32 v[172:173], v[96:97], v[96:97]
	s_nop 0
	v_mov_b32_e32 v97, v172
	v_pk_add_f32 v[128:129], v[128:129], v[96:97]
	s_nop 1
	v_mov_b32_dpp v172, v128 quad_perm:[1,0,3,2] row_mask:0xf bank_mask:0xf bound_ctrl:1
	v_mov_b32_dpp v173, v129 quad_perm:[1,0,3,2] row_mask:0xf bank_mask:0xf bound_ctrl:1
	v_pk_add_f32 v[128:129], v[128:129], v[172:173]
	s_nop 1
	v_mov_b32_dpp v172, v128 quad_perm:[2,3,0,1] row_mask:0xf bank_mask:0xf bound_ctrl:1
	v_mov_b32_dpp v173, v129 quad_perm:[2,3,0,1] row_mask:0xf bank_mask:0xf bound_ctrl:1
	v_pk_add_f32 v[128:129], v[128:129], v[172:173]
	s_nop 1
	v_mov_b32_dpp v172, v128 row_half_mirror row_mask:0xf bank_mask:0xf bound_ctrl:1
	v_mov_b32_dpp v173, v129 row_half_mirror row_mask:0xf bank_mask:0xf bound_ctrl:1
	v_pk_add_f32 v[128:129], v[128:129], v[172:173]
	s_nop 1
	v_mov_b32_dpp v172, v128 row_mirror row_mask:0xf bank_mask:0xf bound_ctrl:1
	v_mov_b32_dpp v173, v129 row_mirror row_mask:0xf bank_mask:0xf bound_ctrl:1
	s_and_saveexec_b64 s[6:7], vcc
	v_pk_add_f32 v[128:129], v[128:129], v[172:173]
	ds_write_b64 v160, v[128:129] offset:216
	s_or_b64 exec, exec, s[6:7]
	v_or_b32_e32 v128, 48, v176
	v_ashrrev_i32_e32 v129, 31, v128
	v_readlane_b32 s6, v255, 29
	v_lshlrev_b64 v[128:129], 12, v[128:129]
	v_readlane_b32 s7, v255, 30
	v_readfirstlane_b32 s2, v169
	s_lshl_b32 s2, s2, 13
	v_lshl_add_u64 v[128:129], s[6:7], 0, v[128:129]
	v_lshl_add_u64 v[128:129], v[154:155], 2, v[128:129]
	s_waitcnt lgkmcnt(0)
	s_add_i32 m0, s2, 0x10000
	v_lshl_add_u64 v[128:129], v[128:129], 0, v[0:1]
	s_mov_b64 s[6:7], 0x2000
	global_load_lds_dwordx4 v[128:129], off
	v_lshl_add_u64 v[172:173], v[128:129], 0, s[6:7]
	s_add_i32 m0, s2, 0x10400
	s_mov_b64 s[6:7], 0x4000
	global_load_lds_dwordx4 v[172:173], off
	v_lshl_add_u64 v[172:173], v[128:129], 0, s[6:7]
	s_add_i32 m0, s2, 0x10800
	s_mov_b64 s[6:7], 0x6000
	global_load_lds_dwordx4 v[172:173], off
	v_lshl_add_u64 v[172:173], v[128:129], 0, s[6:7]
	s_add_i32 m0, s2, 0x10c00
	s_mov_b64 s[6:7], 0x8000
	global_load_lds_dwordx4 v[172:173], off
	v_lshl_add_u64 v[172:173], v[128:129], 0, s[6:7]
	s_add_i32 m0, s2, 0x11000
	s_mov_b64 s[6:7], 0xa000
	global_load_lds_dwordx4 v[172:173], off
	v_lshl_add_u64 v[172:173], v[128:129], 0, s[6:7]
	s_add_i32 m0, s2, 0x11400
	s_mov_b64 s[6:7], 0xc000
	global_load_lds_dwordx4 v[172:173], off
	v_lshl_add_u64 v[172:173], v[128:129], 0, s[6:7]
	s_add_i32 m0, s2, 0x11800
	s_mov_b64 s[6:7], 0xe000
	global_load_lds_dwordx4 v[172:173], off
	v_lshl_add_u64 v[128:129], v[128:129], 0, s[6:7]
	s_add_i32 m0, s2, 0x11c00
	v_add_f32_e32 v0, 0, v50
	global_load_lds_dwordx4 v[128:129], off
	s_waitcnt vmcnt(8)
	ds_read2_b32 v[128:129], v167 offset1:32
	ds_read2_b32 v[172:173], v167 offset0:64 offset1:96
	v_mov_b32_e32 v180, v34
	v_mov_b32_e32 v181, v18
	v_mul_f32_e32 v177, 0.5, v0
	s_waitcnt lgkmcnt(0)
	v_mul_f32_e32 v175, 0x3fd744fd, v128
	v_pk_add_f32 v[180:181], v[180:181], 0 op_sel_hi:[1,0]
	v_mov_b32_e32 v176, v18
	v_mov_b32_e32 v174, v1
	v_mov_b32_e32 v128, v129
	v_mov_b32_e32 v129, v172
	s_mov_b32 s2, s67
	v_pk_add_f32 v[174:175], v[176:177], v[174:175]
	v_pk_mul_f32 v[176:177], v[128:129], s[2:3] op_sel_hi:[1,0]
	v_pk_mul_f32 v[182:183], v[180:181], 0.5 op_sel_hi:[1,0]
	v_pk_fma_f32 v[128:129], v[180:181], 0.5, v[176:177] op_sel_hi:[1,0,1]
	v_mov_b32_e32 v182, v175
	v_mov_b32_e32 v184, v1
	v_mov_b32_e32 v185, v177
	v_add_f32_e32 v178, 0, v2
	v_mov_b32_e32 v179, v173
	v_pk_mul_f32 v[180:181], v[128:129], v[128:129]
	v_pk_add_f32 v[182:183], v[182:183], v[184:185]
	v_mul_f32_e32 v0, 0x3fd744fd, v173
	v_mov_b32_e32 v163, v175
	v_pk_mov_b32 v[176:177], v[176:177], v[180:181] op_sel:[1,0]
	v_pk_add_f32 v[180:181], v[128:129], v[182:183]
	v_pk_mul_f32 v[182:183], v[128:129], v[182:183]
	v_pk_fma_f32 v[172:173], v[178:179], s[66:67], v[0:1] op_sel_hi:[1,1,0]
	v_pk_fma_f32 v[176:177], v[174:175], v[162:163], v[176:177]
	v_mov_b32_e32 v181, v183
	v_pk_mul_f32 v[178:179], v[172:173], v[172:173]
	v_pk_add_f32 v[176:177], v[180:181], v[176:177]
	v_mov_b32_e32 v173, v178
	v_pk_add_f32 v[176:177], v[176:177], v[172:173]
	s_nop 1
	v_mov_b32_dpp v178, v176 quad_perm:[1,0,3,2] row_mask:0xf bank_mask:0xf bound_ctrl:1
	v_mov_b32_dpp v179, v177 quad_perm:[1,0,3,2] row_mask:0xf bank_mask:0xf bound_ctrl:1
	v_pk_add_f32 v[176:177], v[176:177], v[178:179]
	s_nop 1
	v_mov_b32_dpp v178, v176 quad_perm:[2,3,0,1] row_mask:0xf bank_mask:0xf bound_ctrl:1
	v_mov_b32_dpp v179, v177 quad_perm:[2,3,0,1] row_mask:0xf bank_mask:0xf bound_ctrl:1
	v_pk_add_f32 v[176:177], v[176:177], v[178:179]
	s_nop 1
	v_mov_b32_dpp v178, v176 row_half_mirror row_mask:0xf bank_mask:0xf bound_ctrl:1
	v_mov_b32_dpp v179, v177 row_half_mirror row_mask:0xf bank_mask:0xf bound_ctrl:1
	v_pk_add_f32 v[176:177], v[176:177], v[178:179]
	s_nop 1
	v_mov_b32_dpp v178, v176 row_mirror row_mask:0xf bank_mask:0xf bound_ctrl:1
	v_mov_b32_dpp v179, v177 row_mirror row_mask:0xf bank_mask:0xf bound_ctrl:1
	s_and_saveexec_b64 s[6:7], vcc
	v_pk_add_f32 v[176:177], v[176:177], v[178:179]
	ds_write_b64 v160, v[176:177] offset:256
	s_or_b64 exec, exec, s[6:7]
	ds_read2_b32 v[176:177], v167 offset0:128 offset1:160
	ds_read2_b32 v[178:179], v167 offset0:192 offset1:224
	v_add_f32_e32 v0, 0, v51
	v_add_f32_e32 v50, 0, v3
	v_mul_f32_e32 v3, 0.5, v0
	s_waitcnt lgkmcnt(1)
;   DI void operator()(f32x16 (&acc)[2][4], int grow0, int gcol0, int lane, int w, char* lds) {
;     ...
; #pragma unroll
;       for (int qq = 0; qq < 2; ++qq)
; #pragma unroll
;         for (int e = 0; e < 4; ++e) {
;           const int i = 4 * (2 * (ps & 1) + qq) + e;
;           const float* xr = (const float*)(xs + (8 * qq + 4 * hh + e) * 512) + l31;
;           float s1 = 0.f, s2 = 0.f;
; #pragma unroll
;           for (int nt = 0; nt < 4; ++nt) {
;             float v = (acc[mt][nt][i] + bia[nt]) * csc[nt];
;             float z = ALPHA * xr[nt * 32] + hs * v;
;             acc[mt][nt][i] = z; s1 += z; s2 += z * z;
;           }
;           s1 = row16_sum(s1); s2 = row16_sum(s2);
;           if ((lane & 15) == 0) { f32x2 sv = {s1, s2}; *(f32x2*)(redw + (mt * 32 + (i & 3) + 8 * (i >> 2)) * 2) = sv; }
;         }
	v_mul_f32_e32 v181, 0x3fd744fd, v176
	v_mov_b32_e32 v18, v35
	v_mov_b32_e32 v2, v19
	v_mov_b32_e32 v180, v1
	v_pk_add_f32 v[182:183], v[18:19], 0 op_sel_hi:[1,0]
	v_pk_add_f32 v[34:35], v[2:3], v[180:181]
	v_mov_b32_e32 v2, v177
	s_waitcnt lgkmcnt(0)
	v_mov_b32_e32 v3, v178
	s_mov_b32 s2, s67
	v_pk_mul_f32 v[18:19], v[2:3], s[2:3] op_sel_hi:[1,0]
	v_pk_mul_f32 v[176:177], v[182:183], 0.5 op_sel_hi:[1,0]
	v_pk_fma_f32 v[2:3], v[182:183], 0.5, v[18:19] op_sel_hi:[1,0,1]
	v_mov_b32_e32 v176, v35
	v_mov_b32_e32 v182, v1
	v_mov_b32_e32 v183, v19
	v_pk_mul_f32 v[180:181], v[2:3], v[2:3]
	v_pk_add_f32 v[176:177], v[176:177], v[182:183]
	v_mov_b32_e32 v163, v35
	v_pk_mov_b32 v[18:19], v[18:19], v[180:181] op_sel:[1,0]
	v_pk_add_f32 v[180:181], v[2:3], v[176:177]
	v_pk_mul_f32 v[176:177], v[2:3], v[176:177]
	v_mov_b32_e32 v51, v179
	v_pk_fma_f32 v[18:19], v[34:35], v[162:163], v[18:19]
	v_mov_b32_e32 v181, v177
	v_mul_f32_e32 v0, 0x3fd744fd, v179
	v_pk_add_f32 v[176:177], v[180:181], v[18:19]
	v_pk_fma_f32 v[18:19], v[50:51], s[66:67], v[0:1] op_sel_hi:[1,1,0]
	s_nop 0
	v_pk_mul_f32 v[50:51], v[18:19], v[18:19]
	s_nop 0
	v_mov_b32_e32 v19, v50
	v_pk_add_f32 v[50:51], v[176:177], v[18:19]
	s_nop 1
	v_mov_b32_dpp v176, v50 quad_perm:[1,0,3,2] row_mask:0xf bank_mask:0xf bound_ctrl:1
	v_mov_b32_dpp v177, v51 quad_perm:[1,0,3,2] row_mask:0xf bank_mask:0xf bound_ctrl:1
	v_pk_add_f32 v[50:51], v[50:51], v[176:177]
	s_nop 1
	v_mov_b32_dpp v176, v50 quad_perm:[2,3,0,1] row_mask:0xf bank_mask:0xf bound_ctrl:1
	v_mov_b32_dpp v177, v51 quad_perm:[2,3,0,1] row_mask:0xf bank_mask:0xf bound_ctrl:1
	v_pk_add_f32 v[50:51], v[50:51], v[176:177]
	s_nop 1
	v_mov_b32_dpp v176, v50 row_half_mirror row_mask:0xf bank_mask:0xf bound_ctrl:1
	v_mov_b32_dpp v177, v51 row_half_mirror row_mask:0xf bank_mask:0xf bound_ctrl:1
	v_pk_add_f32 v[50:51], v[50:51], v[176:177]
	s_nop 1
	v_mov_b32_dpp v176, v50 row_mirror row_mask:0xf bank_mask:0xf bound_ctrl:1
	v_mov_b32_dpp v177, v51 row_mirror row_mask:0xf bank_mask:0xf bound_ctrl:1
	s_and_saveexec_b64 s[6:7], vcc
	v_pk_add_f32 v[50:51], v[50:51], v[176:177]
	ds_write_b64 v160, v[50:51] offset:264
	s_or_b64 exec, exec, s[6:7]
	ds_read2_b32 v[50:51], v143 offset1:32
	ds_read2_b32 v[176:177], v143 offset0:64 offset1:96
	v_add_f32_e32 v0, 0, v52
	v_mov_b32_e32 v184, v36
	v_mov_b32_e32 v185, v20
	v_mul_f32_e32 v179, 0.5, v0
	s_waitcnt lgkmcnt(1)
	v_mul_f32_e32 v183, 0x3fd744fd, v50
	v_pk_add_f32 v[184:185], v[184:185], 0 op_sel_hi:[1,0]
	v_mov_b32_e32 v178, v20
	v_mov_b32_e32 v182, v1
	v_mov_b32_e32 v50, v51
	s_waitcnt lgkmcnt(0)
	v_mov_b32_e32 v51, v176
	s_mov_b32 s2, s67
	v_pk_add_f32 v[178:179], v[178:179], v[182:183]
	v_pk_mul_f32 v[182:183], v[50:51], s[2:3] op_sel_hi:[1,0]
	v_pk_mul_f32 v[186:187], v[184:185], 0.5 op_sel_hi:[1,0]
	v_pk_fma_f32 v[50:51], v[184:185], 0.5, v[182:183] op_sel_hi:[1,0,1]
	v_mov_b32_e32 v186, v179
	v_mov_b32_e32 v188, v1
	v_mov_b32_e32 v189, v183
	v_add_f32_e32 v180, 0, v4
	v_mov_b32_e32 v181, v177
	v_pk_mul_f32 v[184:185], v[50:51], v[50:51]
	v_pk_add_f32 v[186:187], v[186:187], v[188:189]
	v_mul_f32_e32 v0, 0x3fd744fd, v177
	v_mov_b32_e32 v163, v179
	v_pk_mov_b32 v[182:183], v[182:183], v[184:185] op_sel:[1,0]
	v_pk_add_f32 v[184:185], v[50:51], v[186:187]
	v_pk_mul_f32 v[186:187], v[50:51], v[186:187]
	v_pk_fma_f32 v[176:177], v[180:181], s[66:67], v[0:1] op_sel_hi:[1,1,0]
	v_pk_fma_f32 v[182:183], v[178:179], v[162:163], v[182:183]
	v_mov_b32_e32 v185, v187
	v_pk_mul_f32 v[180:181], v[176:177], v[176:177]
	v_pk_add_f32 v[182:183], v[184:185], v[182:183]
	v_mov_b32_e32 v177, v180
	v_pk_add_f32 v[180:181], v[182:183], v[176:177]
	s_nop 1
	v_mov_b32_dpp v182, v180 quad_perm:[1,0,3,2] row_mask:0xf bank_mask:0xf bound_ctrl:1
	v_mov_b32_dpp v183, v181 quad_perm:[1,0,3,2] row_mask:0xf bank_mask:0xf bound_ctrl:1
	v_pk_add_f32 v[180:181], v[180:181], v[182:183]
	s_nop 1
	v_mov_b32_dpp v182, v180 quad_perm:[2,3,0,1] row_mask:0xf bank_mask:0xf bound_ctrl:1
	v_mov_b32_dpp v183, v181 quad_perm:[2,3,0,1] row_mask:0xf bank_mask:0xf bound_ctrl:1
	v_pk_add_f32 v[180:181], v[180:181], v[182:183]
	s_nop 1
	v_mov_b32_dpp v182, v180 row_half_mirror row_mask:0xf bank_mask:0xf bound_ctrl:1
	v_mov_b32_dpp v183, v181 row_half_mirror row_mask:0xf bank_mask:0xf bound_ctrl:1
	v_pk_add_f32 v[180:181], v[180:181], v[182:183]
	s_nop 1
	v_mov_b32_dpp v182, v180 row_mirror row_mask:0xf bank_mask:0xf bound_ctrl:1
	v_mov_b32_dpp v183, v181 row_mirror row_mask:0xf bank_mask:0xf bound_ctrl:1
	s_and_saveexec_b64 s[6:7], vcc
	v_pk_add_f32 v[180:181], v[180:181], v[182:183]
	ds_write_b64 v160, v[180:181] offset:272
	s_or_b64 exec, exec, s[6:7]
	ds_read2_b32 v[180:181], v144 offset1:32
	ds_read2_b32 v[182:183], v144 offset0:64 offset1:96
	v_add_f32_e32 v0, 0, v53
	v_add_f32_e32 v52, 0, v5
	v_mul_f32_e32 v5, 0.5, v0
	s_waitcnt lgkmcnt(1)
	v_mul_f32_e32 v185, 0x3fd744fd, v180
	v_mov_b32_e32 v20, v37
	v_mov_b32_e32 v4, v21
	v_mov_b32_e32 v184, v1
	v_pk_add_f32 v[186:187], v[20:21], 0 op_sel_hi:[1,0]
	v_pk_add_f32 v[36:37], v[4:5], v[184:185]
	v_mov_b32_e32 v4, v181
	s_waitcnt lgkmcnt(0)
; template <int CTRL> DI float dpp_f(float v) { return __int_as_float(__builtin_amdgcn_update_dpp(0, __float_as_int(v), CTRL, 0xF, 0xF, true)); }
; DI float row16_sum(float v) {
;   v += dpp_f<0xB1>(v);
;   v += dpp_f<0x4E>(v);
;   v += dpp_f<0x141>(v);
;   v += dpp_f<0x140>(v);
;   return v;
; }
;   DI void operator()(f32x16 (&acc)[2][4], int grow0, int gcol0, int lane, int w, char* lds) {
;     ...
;         for (int e = 0; e < 4; ++e) {
;           const int i = 4 * (2 * (ps & 1) + qq) + e;
;           const float* xr = (const float*)(xs + (8 * qq + 4 * hh + e) * 512) + l31;
;           float s1 = 0.f, s2 = 0.f;
; #pragma unroll
;           for (int nt = 0; nt < 4; ++nt) {
;             float v = (acc[mt][nt][i] + bia[nt]) * csc[nt];
;             float z = ALPHA * xr[nt * 32] + hs * v;
;             acc[mt][nt][i] = z; s1 += z; s2 += z * z;
;           }
;           s1 = row16_sum(s1); s2 = row16_sum(s2);
;           if ((lane & 15) == 0) { f32x2 sv = {s1, s2}; *(f32x2*)(redw + (mt * 32 + (i & 3) + 8 * (i >> 2)) * 2) = sv; }
	v_mov_b32_e32 v5, v182
	s_mov_b32 s2, s67
	v_pk_mul_f32 v[20:21], v[4:5], s[2:3] op_sel_hi:[1,0]
	v_pk_mul_f32 v[180:181], v[186:187], 0.5 op_sel_hi:[1,0]
	v_pk_fma_f32 v[4:5], v[186:187], 0.5, v[20:21] op_sel_hi:[1,0,1]
	v_mov_b32_e32 v180, v37
	v_mov_b32_e32 v186, v1
	v_mov_b32_e32 v187, v21
	v_pk_mul_f32 v[184:185], v[4:5], v[4:5]
	v_pk_add_f32 v[180:181], v[180:181], v[186:187]
	v_mov_b32_e32 v163, v37
	v_pk_mov_b32 v[20:21], v[20:21], v[184:185] op_sel:[1,0]
	v_pk_add_f32 v[184:185], v[4:5], v[180:181]
	v_pk_mul_f32 v[180:181], v[4:5], v[180:181]
	v_mov_b32_e32 v53, v183
	v_pk_fma_f32 v[20:21], v[36:37], v[162:163], v[20:21]
	v_mov_b32_e32 v185, v181
	v_mul_f32_e32 v0, 0x3fd744fd, v183
	v_pk_add_f32 v[180:181], v[184:185], v[20:21]
	v_pk_fma_f32 v[20:21], v[52:53], s[66:67], v[0:1] op_sel_hi:[1,1,0]
	s_nop 0
	v_pk_mul_f32 v[52:53], v[20:21], v[20:21]
	s_nop 0
	v_mov_b32_e32 v21, v52
	v_pk_add_f32 v[52:53], v[180:181], v[20:21]
	s_nop 1
	v_mov_b32_dpp v180, v52 quad_perm:[1,0,3,2] row_mask:0xf bank_mask:0xf bound_ctrl:1
	v_mov_b32_dpp v181, v53 quad_perm:[1,0,3,2] row_mask:0xf bank_mask:0xf bound_ctrl:1
	v_pk_add_f32 v[52:53], v[52:53], v[180:181]
	s_nop 1
	v_mov_b32_dpp v180, v52 quad_perm:[2,3,0,1] row_mask:0xf bank_mask:0xf bound_ctrl:1
	v_mov_b32_dpp v181, v53 quad_perm:[2,3,0,1] row_mask:0xf bank_mask:0xf bound_ctrl:1
	v_pk_add_f32 v[52:53], v[52:53], v[180:181]
	s_nop 1
	v_mov_b32_dpp v180, v52 row_half_mirror row_mask:0xf bank_mask:0xf bound_ctrl:1
	v_mov_b32_dpp v181, v53 row_half_mirror row_mask:0xf bank_mask:0xf bound_ctrl:1
	v_pk_add_f32 v[52:53], v[52:53], v[180:181]
	s_nop 1
	v_mov_b32_dpp v180, v52 row_mirror row_mask:0xf bank_mask:0xf bound_ctrl:1
	v_mov_b32_dpp v181, v53 row_mirror row_mask:0xf bank_mask:0xf bound_ctrl:1
	s_and_saveexec_b64 s[6:7], vcc
	v_pk_add_f32 v[52:53], v[52:53], v[180:181]
	ds_write_b64 v160, v[52:53] offset:280
	s_or_b64 exec, exec, s[6:7]
	ds_read2_b32 v[52:53], v83 offset1:32
	ds_read2_b32 v[180:181], v83 offset0:64 offset1:96
	v_add_f32_e32 v0, 0, v54
	v_mov_b32_e32 v188, v38
	v_mov_b32_e32 v189, v22
	v_mul_f32_e32 v183, 0.5, v0
	s_waitcnt lgkmcnt(1)
	v_mul_f32_e32 v187, 0x3fd744fd, v52
	v_pk_add_f32 v[188:189], v[188:189], 0 op_sel_hi:[1,0]
	v_mov_b32_e32 v182, v22
	v_mov_b32_e32 v186, v1
	v_mov_b32_e32 v52, v53
	s_waitcnt lgkmcnt(0)
	v_mov_b32_e32 v53, v180
	s_mov_b32 s2, s67
	v_pk_add_f32 v[182:183], v[182:183], v[186:187]
	v_pk_mul_f32 v[186:187], v[52:53], s[2:3] op_sel_hi:[1,0]
	v_pk_mul_f32 v[190:191], v[188:189], 0.5 op_sel_hi:[1,0]
	v_pk_fma_f32 v[52:53], v[188:189], 0.5, v[186:187] op_sel_hi:[1,0,1]
	v_mov_b32_e32 v190, v183
	v_mov_b32_e32 v192, v1
	v_mov_b32_e32 v193, v187
	v_add_f32_e32 v184, 0, v6
	v_mov_b32_e32 v185, v181
	v_pk_mul_f32 v[188:189], v[52:53], v[52:53]
	v_pk_add_f32 v[190:191], v[190:191], v[192:193]
	v_mul_f32_e32 v0, 0x3fd744fd, v181
	v_mov_b32_e32 v163, v183
	v_pk_mov_b32 v[186:187], v[186:187], v[188:189] op_sel:[1,0]
	v_pk_add_f32 v[188:189], v[52:53], v[190:191]
	v_pk_mul_f32 v[190:191], v[52:53], v[190:191]
	v_pk_fma_f32 v[180:181], v[184:185], s[66:67], v[0:1] op_sel_hi:[1,1,0]
	v_pk_fma_f32 v[186:187], v[182:183], v[162:163], v[186:187]
	v_mov_b32_e32 v189, v191
	v_pk_mul_f32 v[184:185], v[180:181], v[180:181]
	v_pk_add_f32 v[186:187], v[188:189], v[186:187]
	v_mov_b32_e32 v181, v184
	v_pk_add_f32 v[184:185], v[186:187], v[180:181]
	s_nop 1
	v_mov_b32_dpp v186, v184 quad_perm:[1,0,3,2] row_mask:0xf bank_mask:0xf bound_ctrl:1
	v_mov_b32_dpp v187, v185 quad_perm:[1,0,3,2] row_mask:0xf bank_mask:0xf bound_ctrl:1
	v_pk_add_f32 v[184:185], v[184:185], v[186:187]
	s_nop 1
	v_mov_b32_dpp v186, v184 quad_perm:[2,3,0,1] row_mask:0xf bank_mask:0xf bound_ctrl:1
	v_mov_b32_dpp v187, v185 quad_perm:[2,3,0,1] row_mask:0xf bank_mask:0xf bound_ctrl:1
	v_pk_add_f32 v[184:185], v[184:185], v[186:187]
	s_nop 1
	v_mov_b32_dpp v186, v184 row_half_mirror row_mask:0xf bank_mask:0xf bound_ctrl:1
	v_mov_b32_dpp v187, v185 row_half_mirror row_mask:0xf bank_mask:0xf bound_ctrl:1
	v_pk_add_f32 v[184:185], v[184:185], v[186:187]
	s_nop 1
	v_mov_b32_dpp v186, v184 row_mirror row_mask:0xf bank_mask:0xf bound_ctrl:1
	v_mov_b32_dpp v187, v185 row_mirror row_mask:0xf bank_mask:0xf bound_ctrl:1
	s_and_saveexec_b64 s[6:7], vcc
	v_pk_add_f32 v[184:185], v[184:185], v[186:187]
	ds_write_b64 v160, v[184:185] offset:320
	s_or_b64 exec, exec, s[6:7]
	ds_read2_b32 v[184:185], v83 offset0:128 offset1:160
	ds_read2_b32 v[186:187], v83 offset0:192 offset1:224
	v_add_f32_e32 v0, 0, v55
	v_add_f32_e32 v54, 0, v7
	v_mul_f32_e32 v7, 0.5, v0
	s_waitcnt lgkmcnt(1)
	v_mul_f32_e32 v189, 0x3fd744fd, v184
	v_mov_b32_e32 v22, v39
	v_mov_b32_e32 v6, v23
	v_mov_b32_e32 v188, v1
	v_pk_add_f32 v[190:191], v[22:23], 0 op_sel_hi:[1,0]
	v_pk_add_f32 v[38:39], v[6:7], v[188:189]
	v_mov_b32_e32 v6, v185
	s_waitcnt lgkmcnt(0)
; template <int CTRL> DI float dpp_f(float v) { return __int_as_float(__builtin_amdgcn_update_dpp(0, __float_as_int(v), CTRL, 0xF, 0xF, true)); }
; DI float row16_sum(float v) {
;   v += dpp_f<0xB1>(v);
;   v += dpp_f<0x4E>(v);
;   v += dpp_f<0x141>(v);
;   v += dpp_f<0x140>(v);
;   return v;
; }
;   DI void operator()(f32x16 (&acc)[2][4], int grow0, int gcol0, int lane, int w, char* lds) {
;     ...
;         for (int e = 0; e < 4; ++e) {
;           const int i = 4 * (2 * (ps & 1) + qq) + e;
;           const float* xr = (const float*)(xs + (8 * qq + 4 * hh + e) * 512) + l31;
;           float s1 = 0.f, s2 = 0.f;
; #pragma unroll
;           for (int nt = 0; nt < 4; ++nt) {
;             float v = (acc[mt][nt][i] + bia[nt]) * csc[nt];
;             float z = ALPHA * xr[nt * 32] + hs * v;
;             acc[mt][nt][i] = z; s1 += z; s2 += z * z;
;           }
;           s1 = row16_sum(s1); s2 = row16_sum(s2);
;           if ((lane & 15) == 0) { f32x2 sv = {s1, s2}; *(f32x2*)(redw + (mt * 32 + (i & 3) + 8 * (i >> 2)) * 2) = sv; }
	v_mov_b32_e32 v7, v186
	s_mov_b32 s2, s67
	v_pk_mul_f32 v[22:23], v[6:7], s[2:3] op_sel_hi:[1,0]
	v_pk_mul_f32 v[184:185], v[190:191], 0.5 op_sel_hi:[1,0]
	v_pk_fma_f32 v[6:7], v[190:191], 0.5, v[22:23] op_sel_hi:[1,0,1]
	v_mov_b32_e32 v184, v39
	v_mov_b32_e32 v190, v1
	v_mov_b32_e32 v191, v23
	v_pk_mul_f32 v[188:189], v[6:7], v[6:7]
	v_pk_add_f32 v[184:185], v[184:185], v[190:191]
	v_mov_b32_e32 v163, v39
	v_pk_mov_b32 v[22:23], v[22:23], v[188:189] op_sel:[1,0]
	v_pk_add_f32 v[188:189], v[6:7], v[184:185]
	v_pk_mul_f32 v[184:185], v[6:7], v[184:185]
	v_mov_b32_e32 v55, v187
	v_pk_fma_f32 v[22:23], v[38:39], v[162:163], v[22:23]
	v_mov_b32_e32 v189, v185
	v_mul_f32_e32 v0, 0x3fd744fd, v187
	v_pk_add_f32 v[184:185], v[188:189], v[22:23]
	v_pk_fma_f32 v[22:23], v[54:55], s[66:67], v[0:1] op_sel_hi:[1,1,0]
	s_nop 0
	v_pk_mul_f32 v[54:55], v[22:23], v[22:23]
	s_nop 0
	v_mov_b32_e32 v23, v54
	v_pk_add_f32 v[54:55], v[184:185], v[22:23]
	s_nop 1
	v_mov_b32_dpp v184, v54 quad_perm:[1,0,3,2] row_mask:0xf bank_mask:0xf bound_ctrl:1
	v_mov_b32_dpp v185, v55 quad_perm:[1,0,3,2] row_mask:0xf bank_mask:0xf bound_ctrl:1
	v_pk_add_f32 v[54:55], v[54:55], v[184:185]
	s_nop 1
	v_mov_b32_dpp v184, v54 quad_perm:[2,3,0,1] row_mask:0xf bank_mask:0xf bound_ctrl:1
	v_mov_b32_dpp v185, v55 quad_perm:[2,3,0,1] row_mask:0xf bank_mask:0xf bound_ctrl:1
	v_pk_add_f32 v[54:55], v[54:55], v[184:185]
	s_nop 1
	v_mov_b32_dpp v184, v54 row_half_mirror row_mask:0xf bank_mask:0xf bound_ctrl:1
	v_mov_b32_dpp v185, v55 row_half_mirror row_mask:0xf bank_mask:0xf bound_ctrl:1
	v_pk_add_f32 v[54:55], v[54:55], v[184:185]
	s_nop 1
	v_mov_b32_dpp v184, v54 row_mirror row_mask:0xf bank_mask:0xf bound_ctrl:1
	v_mov_b32_dpp v185, v55 row_mirror row_mask:0xf bank_mask:0xf bound_ctrl:1
	s_and_saveexec_b64 s[6:7], vcc
	v_pk_add_f32 v[54:55], v[54:55], v[184:185]
	ds_write_b64 v160, v[54:55] offset:328
	s_or_b64 exec, exec, s[6:7]
	ds_read2_b32 v[54:55], v85 offset1:32
	ds_read2_b32 v[184:185], v85 offset0:64 offset1:96
	v_add_f32_e32 v0, 0, v56
	v_mov_b32_e32 v192, v40
	v_mov_b32_e32 v193, v24
	v_mul_f32_e32 v187, 0.5, v0
	s_waitcnt lgkmcnt(1)
	v_mul_f32_e32 v191, 0x3fd744fd, v54
	v_pk_add_f32 v[192:193], v[192:193], 0 op_sel_hi:[1,0]
	v_mov_b32_e32 v186, v24
	v_mov_b32_e32 v190, v1
	v_mov_b32_e32 v54, v55
	s_waitcnt lgkmcnt(0)
	v_mov_b32_e32 v55, v184
	s_mov_b32 s2, s67
	v_pk_add_f32 v[186:187], v[186:187], v[190:191]
	v_pk_mul_f32 v[190:191], v[54:55], s[2:3] op_sel_hi:[1,0]
	v_pk_mul_f32 v[194:195], v[192:193], 0.5 op_sel_hi:[1,0]
	v_pk_fma_f32 v[54:55], v[192:193], 0.5, v[190:191] op_sel_hi:[1,0,1]
	v_mov_b32_e32 v194, v187
	v_mov_b32_e32 v196, v1
	v_mov_b32_e32 v197, v191
	v_add_f32_e32 v188, 0, v8
	v_mov_b32_e32 v189, v185
	v_pk_mul_f32 v[192:193], v[54:55], v[54:55]
	v_pk_add_f32 v[194:195], v[194:195], v[196:197]
	v_mul_f32_e32 v0, 0x3fd744fd, v185
	v_mov_b32_e32 v163, v187
	v_pk_mov_b32 v[190:191], v[190:191], v[192:193] op_sel:[1,0]
	v_pk_add_f32 v[192:193], v[54:55], v[194:195]
	v_pk_mul_f32 v[194:195], v[54:55], v[194:195]
	v_pk_fma_f32 v[184:185], v[188:189], s[66:67], v[0:1] op_sel_hi:[1,1,0]
	v_pk_fma_f32 v[190:191], v[186:187], v[162:163], v[190:191]
	v_mov_b32_e32 v193, v195
	v_pk_mul_f32 v[188:189], v[184:185], v[184:185]
	v_pk_add_f32 v[190:191], v[192:193], v[190:191]
	v_mov_b32_e32 v185, v188
	v_pk_add_f32 v[188:189], v[190:191], v[184:185]
	s_nop 1
	v_mov_b32_dpp v190, v188 quad_perm:[1,0,3,2] row_mask:0xf bank_mask:0xf bound_ctrl:1
	v_mov_b32_dpp v191, v189 quad_perm:[1,0,3,2] row_mask:0xf bank_mask:0xf bound_ctrl:1
	v_pk_add_f32 v[188:189], v[188:189], v[190:191]
	s_nop 1
	v_mov_b32_dpp v190, v188 quad_perm:[2,3,0,1] row_mask:0xf bank_mask:0xf bound_ctrl:1
	v_mov_b32_dpp v191, v189 quad_perm:[2,3,0,1] row_mask:0xf bank_mask:0xf bound_ctrl:1
	v_pk_add_f32 v[188:189], v[188:189], v[190:191]
	s_nop 1
	v_mov_b32_dpp v190, v188 row_half_mirror row_mask:0xf bank_mask:0xf bound_ctrl:1
	v_mov_b32_dpp v191, v189 row_half_mirror row_mask:0xf bank_mask:0xf bound_ctrl:1
	v_pk_add_f32 v[188:189], v[188:189], v[190:191]
	s_nop 1
	v_mov_b32_dpp v190, v188 row_mirror row_mask:0xf bank_mask:0xf bound_ctrl:1
	v_mov_b32_dpp v191, v189 row_mirror row_mask:0xf bank_mask:0xf bound_ctrl:1
	s_and_saveexec_b64 s[6:7], vcc
	v_pk_add_f32 v[188:189], v[188:189], v[190:191]
	ds_write_b64 v160, v[188:189] offset:336
	s_or_b64 exec, exec, s[6:7]
	ds_read2_b32 v[188:189], v87 offset1:32
	ds_read2_b32 v[190:191], v87 offset0:64 offset1:96
	v_add_f32_e32 v0, 0, v57
	v_add_f32_e32 v56, 0, v9
	v_mul_f32_e32 v9, 0.5, v0
	s_waitcnt lgkmcnt(1)
	v_mul_f32_e32 v193, 0x3fd744fd, v188
	v_mov_b32_e32 v24, v41
	v_mov_b32_e32 v8, v25
	v_mov_b32_e32 v192, v1
	v_pk_add_f32 v[194:195], v[24:25], 0 op_sel_hi:[1,0]
	v_pk_add_f32 v[40:41], v[8:9], v[192:193]
	v_mov_b32_e32 v8, v189
	s_waitcnt lgkmcnt(0)
; template <int CTRL> DI float dpp_f(float v) { return __int_as_float(__builtin_amdgcn_update_dpp(0, __float_as_int(v), CTRL, 0xF, 0xF, true)); }
; DI float row16_sum(float v) {
;   v += dpp_f<0xB1>(v);
;   v += dpp_f<0x4E>(v);
;   v += dpp_f<0x141>(v);
;   v += dpp_f<0x140>(v);
;   return v;
; }
;   DI void operator()(f32x16 (&acc)[2][4], int grow0, int gcol0, int lane, int w, char* lds) {
;     ...
;       if (ps + 1 < 4) {
;         if (ps >= 1) asm volatile("s_waitcnt lgkmcnt(0)" ::: "memory");
;         xpass(ps + 1, grow0, gcol0, lane, w, lds);
;         if (ps >= 1) asm volatile("s_waitcnt vmcnt(8)" ::: "memory");
;       } else asm volatile("s_waitcnt vmcnt(0)" ::: "memory");
;       const char* xs = lds + (ps & 1) * 65536 + w * 8192;
; #pragma unroll
;       for (int qq = 0; qq < 2; ++qq)
; #pragma unroll
;         for (int e = 0; e < 4; ++e) {
;           const int i = 4 * (2 * (ps & 1) + qq) + e;
;           const float* xr = (const float*)(xs + (8 * qq + 4 * hh + e) * 512) + l31;
;           float s1 = 0.f, s2 = 0.f;
; #pragma unroll
;           for (int nt = 0; nt < 4; ++nt) {
;             float v = (acc[mt][nt][i] + bia[nt]) * csc[nt];
;             float z = ALPHA * xr[nt * 32] + hs * v;
;             acc[mt][nt][i] = z; s1 += z; s2 += z * z;
;           }
;           s1 = row16_sum(s1); s2 = row16_sum(s2);
;           if ((lane & 15) == 0) { f32x2 sv = {s1, s2}; *(f32x2*)(redw + (mt * 32 + (i & 3) + 8 * (i >> 2)) * 2) = sv; }
	v_mov_b32_e32 v9, v190
	s_mov_b32 s2, s67
	v_pk_mul_f32 v[24:25], v[8:9], s[2:3] op_sel_hi:[1,0]
	v_pk_mul_f32 v[188:189], v[194:195], 0.5 op_sel_hi:[1,0]
	v_pk_fma_f32 v[8:9], v[194:195], 0.5, v[24:25] op_sel_hi:[1,0,1]
	v_mov_b32_e32 v188, v41
	v_mov_b32_e32 v194, v1
	v_mov_b32_e32 v195, v25
	v_pk_mul_f32 v[192:193], v[8:9], v[8:9]
	v_pk_add_f32 v[188:189], v[188:189], v[194:195]
	v_mov_b32_e32 v163, v41
	v_pk_mov_b32 v[24:25], v[24:25], v[192:193] op_sel:[1,0]
	v_pk_add_f32 v[192:193], v[8:9], v[188:189]
	v_pk_mul_f32 v[188:189], v[8:9], v[188:189]
	v_mov_b32_e32 v57, v191
	v_pk_fma_f32 v[24:25], v[40:41], v[162:163], v[24:25]
	v_mov_b32_e32 v193, v189
	v_mul_f32_e32 v0, 0x3fd744fd, v191
	v_pk_add_f32 v[188:189], v[192:193], v[24:25]
	v_pk_fma_f32 v[24:25], v[56:57], s[66:67], v[0:1] op_sel_hi:[1,1,0]
	s_nop 0
	v_pk_mul_f32 v[56:57], v[24:25], v[24:25]
	s_nop 0
	v_mov_b32_e32 v25, v56
	v_pk_add_f32 v[56:57], v[188:189], v[24:25]
	s_nop 1
	v_mov_b32_dpp v188, v56 quad_perm:[1,0,3,2] row_mask:0xf bank_mask:0xf bound_ctrl:1
	v_mov_b32_dpp v189, v57 quad_perm:[1,0,3,2] row_mask:0xf bank_mask:0xf bound_ctrl:1
	v_pk_add_f32 v[56:57], v[56:57], v[188:189]
	s_nop 1
	v_mov_b32_dpp v188, v56 quad_perm:[2,3,0,1] row_mask:0xf bank_mask:0xf bound_ctrl:1
	v_mov_b32_dpp v189, v57 quad_perm:[2,3,0,1] row_mask:0xf bank_mask:0xf bound_ctrl:1
	v_pk_add_f32 v[56:57], v[56:57], v[188:189]
	s_nop 1
	v_mov_b32_dpp v188, v56 row_half_mirror row_mask:0xf bank_mask:0xf bound_ctrl:1
	v_mov_b32_dpp v189, v57 row_half_mirror row_mask:0xf bank_mask:0xf bound_ctrl:1
	v_pk_add_f32 v[56:57], v[56:57], v[188:189]
	s_nop 1
	v_mov_b32_dpp v188, v56 row_mirror row_mask:0xf bank_mask:0xf bound_ctrl:1
	v_mov_b32_dpp v189, v57 row_mirror row_mask:0xf bank_mask:0xf bound_ctrl:1
	s_and_saveexec_b64 s[6:7], vcc
	v_pk_add_f32 v[56:57], v[56:57], v[188:189]
	ds_write_b64 v160, v[56:57] offset:344
	s_or_b64 exec, exec, s[6:7]
	s_waitcnt vmcnt(0)
	ds_read2_b32 v[56:57], v89 offset1:32
	ds_read2_b32 v[190:191], v89 offset0:64 offset1:96
	v_add_f32_e32 v0, 0, v58
	v_mul_f32_e32 v189, 0.5, v0
	v_mov_b32_e32 v188, v26
	s_waitcnt lgkmcnt(1)
	v_mul_f32_e32 v193, 0x3fd744fd, v56
	v_add_f32_e32 v56, 0, v42
	v_mul_f32_e32 v0, 0x3fd744fd, v57
	v_mov_b32_e32 v192, v1
	v_pk_fma_f32 v[56:57], v[56:57], s[66:67], v[0:1] op_sel_hi:[1,1,0]
	v_pk_add_f32 v[192:193], v[188:189], v[192:193]
	s_waitcnt lgkmcnt(0)
	v_mov_b32_e32 v188, v190
	v_mov_b32_e32 v189, v56
	v_mov_b32_e32 v196, v165
	v_mov_b32_e32 v197, v56
	v_mov_b32_e32 v163, v193
	v_pk_mul_f32 v[196:197], v[188:189], v[196:197]
	v_pk_mul_f32 v[198:199], v[192:193], v[162:163]
	v_mov_b32_e32 v200, v1
	v_pk_mov_b32 v[198:199], v[192:193], v[198:199] op_sel:[1,0]
	v_mov_b32_e32 v201, v196
	v_add_f32_e32 v194, 0, v10
	v_mov_b32_e32 v195, v191
	v_pk_fma_f32 v[188:189], v[192:193], v[162:163], v[196:197]
	v_pk_add_f32 v[196:197], v[198:199], v[200:201]
	v_mul_f32_e32 v0, 0x3fd744fd, v191
	v_pk_add_f32 v[198:199], v[56:57], v[196:197]
	v_pk_mul_f32 v[196:197], v[188:189], v[196:197] op_sel_hi:[0,1]
	v_pk_fma_f32 v[190:191], v[194:195], s[66:67], v[0:1] op_sel_hi:[1,1,0]
	v_mov_b32_e32 v199, v197
	v_pk_mul_f32 v[194:195], v[190:191], v[190:191]
	v_pk_add_f32 v[196:197], v[188:189], v[198:199]
	v_mov_b32_e32 v191, v194
	v_pk_add_f32 v[194:195], v[196:197], v[190:191]
	s_nop 1
	v_mov_b32_dpp v196, v194 quad_perm:[1,0,3,2] row_mask:0xf bank_mask:0xf bound_ctrl:1
	v_mov_b32_dpp v197, v195 quad_perm:[1,0,3,2] row_mask:0xf bank_mask:0xf bound_ctrl:1
	v_pk_add_f32 v[194:195], v[194:195], v[196:197]
	s_nop 1
	v_mov_b32_dpp v196, v194 quad_perm:[2,3,0,1] row_mask:0xf bank_mask:0xf bound_ctrl:1
	v_mov_b32_dpp v197, v195 quad_perm:[2,3,0,1] row_mask:0xf bank_mask:0xf bound_ctrl:1
	v_pk_add_f32 v[194:195], v[194:195], v[196:197]
	s_nop 1
	v_mov_b32_dpp v196, v194 row_half_mirror row_mask:0xf bank_mask:0xf bound_ctrl:1
	v_mov_b32_dpp v197, v195 row_half_mirror row_mask:0xf bank_mask:0xf bound_ctrl:1
	v_pk_add_f32 v[194:195], v[194:195], v[196:197]
	s_nop 1
	v_mov_b32_dpp v196, v194 row_mirror row_mask:0xf bank_mask:0xf bound_ctrl:1
	v_mov_b32_dpp v197, v195 row_mirror row_mask:0xf bank_mask:0xf bound_ctrl:1
	s_and_saveexec_b64 s[6:7], vcc
	v_pk_add_f32 v[194:195], v[194:195], v[196:197]
	ds_write_b64 v160, v[194:195] offset:384
	s_or_b64 exec, exec, s[6:7]
	ds_read2_b32 v[194:195], v98 offset1:32
	ds_read2_b32 v[196:197], v98 offset0:64 offset1:96
	v_add_f32_e32 v0, 0, v59
	v_add_f32_e32 v58, 0, v11
	v_mul_f32_e32 v11, 0.5, v0
	s_waitcnt lgkmcnt(1)
	v_mul_f32_e32 v199, 0x3fd744fd, v194
	v_mov_b32_e32 v26, v43
	v_mov_b32_e32 v10, v27
	v_mov_b32_e32 v198, v1
	v_pk_add_f32 v[200:201], v[26:27], 0 op_sel_hi:[1,0]
	v_pk_add_f32 v[42:43], v[10:11], v[198:199]
	v_mov_b32_e32 v10, v195
	s_waitcnt lgkmcnt(0)
; template <int CTRL> DI float dpp_f(float v) { return __int_as_float(__builtin_amdgcn_update_dpp(0, __float_as_int(v), CTRL, 0xF, 0xF, true)); }
; DI float row16_sum(float v) {
;   v += dpp_f<0xB1>(v);
;   v += dpp_f<0x4E>(v);
;   v += dpp_f<0x141>(v);
;   v += dpp_f<0x140>(v);
;   return v;
; }
;   DI void operator()(f32x16 (&acc)[2][4], int grow0, int gcol0, int lane, int w, char* lds) {
;     ...
;         for (int e = 0; e < 4; ++e) {
;           const int i = 4 * (2 * (ps & 1) + qq) + e;
;           const float* xr = (const float*)(xs + (8 * qq + 4 * hh + e) * 512) + l31;
;           float s1 = 0.f, s2 = 0.f;
; #pragma unroll
;           for (int nt = 0; nt < 4; ++nt) {
;             float v = (acc[mt][nt][i] + bia[nt]) * csc[nt];
;             float z = ALPHA * xr[nt * 32] + hs * v;
;             acc[mt][nt][i] = z; s1 += z; s2 += z * z;
;           }
;           s1 = row16_sum(s1); s2 = row16_sum(s2);
;           if ((lane & 15) == 0) { f32x2 sv = {s1, s2}; *(f32x2*)(redw + (mt * 32 + (i & 3) + 8 * (i >> 2)) * 2) = sv; }
	v_mov_b32_e32 v11, v196
	s_mov_b32 s2, s67
	v_pk_mul_f32 v[26:27], v[10:11], s[2:3] op_sel_hi:[1,0]
	v_pk_mul_f32 v[194:195], v[200:201], 0.5 op_sel_hi:[1,0]
	v_pk_fma_f32 v[10:11], v[200:201], 0.5, v[26:27] op_sel_hi:[1,0,1]
	v_mov_b32_e32 v194, v43
	v_mov_b32_e32 v200, v1
	v_mov_b32_e32 v201, v27
	v_pk_mul_f32 v[198:199], v[10:11], v[10:11]
	v_pk_add_f32 v[194:195], v[194:195], v[200:201]
	v_mov_b32_e32 v163, v43
	v_pk_mov_b32 v[26:27], v[26:27], v[198:199] op_sel:[1,0]
	v_pk_add_f32 v[198:199], v[10:11], v[194:195]
	v_pk_mul_f32 v[194:195], v[10:11], v[194:195]
	v_mov_b32_e32 v59, v197
	v_pk_fma_f32 v[26:27], v[42:43], v[162:163], v[26:27]
	v_mov_b32_e32 v199, v195
	v_mul_f32_e32 v0, 0x3fd744fd, v197
	v_pk_add_f32 v[194:195], v[198:199], v[26:27]
	v_pk_fma_f32 v[26:27], v[58:59], s[66:67], v[0:1] op_sel_hi:[1,1,0]
	s_nop 0
	v_pk_mul_f32 v[58:59], v[26:27], v[26:27]
	s_nop 0
	v_mov_b32_e32 v27, v58
	v_pk_add_f32 v[58:59], v[194:195], v[26:27]
	s_nop 1
	v_mov_b32_dpp v194, v58 quad_perm:[1,0,3,2] row_mask:0xf bank_mask:0xf bound_ctrl:1
	v_mov_b32_dpp v195, v59 quad_perm:[1,0,3,2] row_mask:0xf bank_mask:0xf bound_ctrl:1
	v_pk_add_f32 v[58:59], v[58:59], v[194:195]
	s_nop 1
	v_mov_b32_dpp v194, v58 quad_perm:[2,3,0,1] row_mask:0xf bank_mask:0xf bound_ctrl:1
	v_mov_b32_dpp v195, v59 quad_perm:[2,3,0,1] row_mask:0xf bank_mask:0xf bound_ctrl:1
	v_pk_add_f32 v[58:59], v[58:59], v[194:195]
	s_nop 1
	v_mov_b32_dpp v194, v58 row_half_mirror row_mask:0xf bank_mask:0xf bound_ctrl:1
	v_mov_b32_dpp v195, v59 row_half_mirror row_mask:0xf bank_mask:0xf bound_ctrl:1
	v_pk_add_f32 v[58:59], v[58:59], v[194:195]
	s_nop 1
	v_mov_b32_dpp v194, v58 row_mirror row_mask:0xf bank_mask:0xf bound_ctrl:1
	v_mov_b32_dpp v195, v59 row_mirror row_mask:0xf bank_mask:0xf bound_ctrl:1
	s_and_saveexec_b64 s[6:7], vcc
	v_pk_add_f32 v[58:59], v[58:59], v[194:195]
	ds_write_b64 v160, v[58:59] offset:392
	s_or_b64 exec, exec, s[6:7]
	ds_read2_b32 v[58:59], v102 offset1:32
	ds_read2_b32 v[194:195], v102 offset0:64 offset1:96
	v_add_f32_e32 v0, 0, v60
	v_mov_b32_e32 v202, v44
	v_mov_b32_e32 v203, v28
	v_mul_f32_e32 v197, 0.5, v0
	s_waitcnt lgkmcnt(1)
	v_mul_f32_e32 v201, 0x3fd744fd, v58
	v_pk_add_f32 v[202:203], v[202:203], 0 op_sel_hi:[1,0]
	v_mov_b32_e32 v196, v28
	v_mov_b32_e32 v200, v1
	v_mov_b32_e32 v58, v59
	s_waitcnt lgkmcnt(0)
	v_mov_b32_e32 v59, v194
	s_mov_b32 s2, s67
	v_pk_add_f32 v[196:197], v[196:197], v[200:201]
	v_pk_mul_f32 v[200:201], v[58:59], s[2:3] op_sel_hi:[1,0]
	v_pk_mul_f32 v[204:205], v[202:203], 0.5 op_sel_hi:[1,0]
	v_pk_fma_f32 v[58:59], v[202:203], 0.5, v[200:201] op_sel_hi:[1,0,1]
	v_mov_b32_e32 v204, v197
	v_mov_b32_e32 v206, v1
	v_mov_b32_e32 v207, v201
	v_add_f32_e32 v198, 0, v12
	v_mov_b32_e32 v199, v195
	v_pk_mul_f32 v[202:203], v[58:59], v[58:59]
	v_pk_add_f32 v[204:205], v[204:205], v[206:207]
	v_mul_f32_e32 v0, 0x3fd744fd, v195
	v_mov_b32_e32 v163, v197
	v_pk_mov_b32 v[200:201], v[200:201], v[202:203] op_sel:[1,0]
	v_pk_add_f32 v[202:203], v[58:59], v[204:205]
	v_pk_mul_f32 v[204:205], v[58:59], v[204:205]
	v_pk_fma_f32 v[194:195], v[198:199], s[66:67], v[0:1] op_sel_hi:[1,1,0]
	v_pk_fma_f32 v[200:201], v[196:197], v[162:163], v[200:201]
	v_mov_b32_e32 v203, v205
	v_pk_mul_f32 v[198:199], v[194:195], v[194:195]
	v_pk_add_f32 v[200:201], v[202:203], v[200:201]
	v_mov_b32_e32 v195, v198
	v_pk_add_f32 v[198:199], v[200:201], v[194:195]
	s_nop 1
	v_mov_b32_dpp v200, v198 quad_perm:[1,0,3,2] row_mask:0xf bank_mask:0xf bound_ctrl:1
	v_mov_b32_dpp v201, v199 quad_perm:[1,0,3,2] row_mask:0xf bank_mask:0xf bound_ctrl:1
	v_pk_add_f32 v[198:199], v[198:199], v[200:201]
	s_nop 1
	v_mov_b32_dpp v200, v198 quad_perm:[2,3,0,1] row_mask:0xf bank_mask:0xf bound_ctrl:1
	v_mov_b32_dpp v201, v199 quad_perm:[2,3,0,1] row_mask:0xf bank_mask:0xf bound_ctrl:1
	v_pk_add_f32 v[198:199], v[198:199], v[200:201]
	s_nop 1
	v_mov_b32_dpp v200, v198 row_half_mirror row_mask:0xf bank_mask:0xf bound_ctrl:1
	v_mov_b32_dpp v201, v199 row_half_mirror row_mask:0xf bank_mask:0xf bound_ctrl:1
	v_pk_add_f32 v[198:199], v[198:199], v[200:201]
	s_nop 1
	v_mov_b32_dpp v200, v198 row_mirror row_mask:0xf bank_mask:0xf bound_ctrl:1
	v_mov_b32_dpp v201, v199 row_mirror row_mask:0xf bank_mask:0xf bound_ctrl:1
	s_and_saveexec_b64 s[6:7], vcc
	v_pk_add_f32 v[198:199], v[198:199], v[200:201]
	ds_write_b64 v160, v[198:199] offset:400
	s_or_b64 exec, exec, s[6:7]
	ds_read2_b32 v[198:199], v104 offset1:32
	ds_read2_b32 v[200:201], v104 offset0:64 offset1:96
	v_add_f32_e32 v0, 0, v61
	v_add_f32_e32 v60, 0, v13
	v_mul_f32_e32 v13, 0.5, v0
	s_waitcnt lgkmcnt(1)
	v_mul_f32_e32 v203, 0x3fd744fd, v198
	v_mov_b32_e32 v28, v45
	v_mov_b32_e32 v12, v29
	v_mov_b32_e32 v202, v1
	v_pk_add_f32 v[204:205], v[28:29], 0 op_sel_hi:[1,0]
	v_pk_add_f32 v[44:45], v[12:13], v[202:203]
	v_mov_b32_e32 v12, v199
	s_waitcnt lgkmcnt(0)
; template <int CTRL> DI float dpp_f(float v) { return __int_as_float(__builtin_amdgcn_update_dpp(0, __float_as_int(v), CTRL, 0xF, 0xF, true)); }
; DI float row16_sum(float v) {
;   v += dpp_f<0xB1>(v);
;   v += dpp_f<0x4E>(v);
;   v += dpp_f<0x141>(v);
;   v += dpp_f<0x140>(v);
;   return v;
; }
;   DI void operator()(f32x16 (&acc)[2][4], int grow0, int gcol0, int lane, int w, char* lds) {
;     ...
;         for (int e = 0; e < 4; ++e) {
;           const int i = 4 * (2 * (ps & 1) + qq) + e;
;           const float* xr = (const float*)(xs + (8 * qq + 4 * hh + e) * 512) + l31;
;           float s1 = 0.f, s2 = 0.f;
; #pragma unroll
;           for (int nt = 0; nt < 4; ++nt) {
;             float v = (acc[mt][nt][i] + bia[nt]) * csc[nt];
;             float z = ALPHA * xr[nt * 32] + hs * v;
;             acc[mt][nt][i] = z; s1 += z; s2 += z * z;
;           }
;           s1 = row16_sum(s1); s2 = row16_sum(s2);
;           if ((lane & 15) == 0) { f32x2 sv = {s1, s2}; *(f32x2*)(redw + (mt * 32 + (i & 3) + 8 * (i >> 2)) * 2) = sv; }
	v_mov_b32_e32 v13, v200
	s_mov_b32 s2, s67
	v_pk_mul_f32 v[28:29], v[12:13], s[2:3] op_sel_hi:[1,0]
	v_pk_mul_f32 v[198:199], v[204:205], 0.5 op_sel_hi:[1,0]
	v_pk_fma_f32 v[12:13], v[204:205], 0.5, v[28:29] op_sel_hi:[1,0,1]
	v_mov_b32_e32 v198, v45
	v_mov_b32_e32 v204, v1
	v_mov_b32_e32 v205, v29
	v_pk_mul_f32 v[202:203], v[12:13], v[12:13]
	v_pk_add_f32 v[198:199], v[198:199], v[204:205]
	v_mov_b32_e32 v163, v45
	v_pk_mov_b32 v[28:29], v[28:29], v[202:203] op_sel:[1,0]
	v_pk_add_f32 v[202:203], v[12:13], v[198:199]
	v_pk_mul_f32 v[198:199], v[12:13], v[198:199]
	v_mov_b32_e32 v61, v201
	v_pk_fma_f32 v[28:29], v[44:45], v[162:163], v[28:29]
	v_mov_b32_e32 v203, v199
	v_mul_f32_e32 v0, 0x3fd744fd, v201
	v_pk_add_f32 v[198:199], v[202:203], v[28:29]
	v_pk_fma_f32 v[28:29], v[60:61], s[66:67], v[0:1] op_sel_hi:[1,1,0]
	s_nop 0
	v_pk_mul_f32 v[60:61], v[28:29], v[28:29]
	s_nop 0
	v_mov_b32_e32 v29, v60
	v_pk_add_f32 v[60:61], v[198:199], v[28:29]
	s_nop 1
	v_mov_b32_dpp v198, v60 quad_perm:[1,0,3,2] row_mask:0xf bank_mask:0xf bound_ctrl:1
	v_mov_b32_dpp v199, v61 quad_perm:[1,0,3,2] row_mask:0xf bank_mask:0xf bound_ctrl:1
	v_pk_add_f32 v[60:61], v[60:61], v[198:199]
	s_nop 1
	v_mov_b32_dpp v198, v60 quad_perm:[2,3,0,1] row_mask:0xf bank_mask:0xf bound_ctrl:1
	v_mov_b32_dpp v199, v61 quad_perm:[2,3,0,1] row_mask:0xf bank_mask:0xf bound_ctrl:1
	v_pk_add_f32 v[60:61], v[60:61], v[198:199]
	s_nop 1
	v_mov_b32_dpp v198, v60 row_half_mirror row_mask:0xf bank_mask:0xf bound_ctrl:1
	v_mov_b32_dpp v199, v61 row_half_mirror row_mask:0xf bank_mask:0xf bound_ctrl:1
	v_pk_add_f32 v[60:61], v[60:61], v[198:199]
	s_nop 1
	v_mov_b32_dpp v198, v60 row_mirror row_mask:0xf bank_mask:0xf bound_ctrl:1
	v_mov_b32_dpp v199, v61 row_mirror row_mask:0xf bank_mask:0xf bound_ctrl:1
	s_and_saveexec_b64 s[6:7], vcc
	v_pk_add_f32 v[60:61], v[60:61], v[198:199]
	ds_write_b64 v160, v[60:61] offset:408
	s_or_b64 exec, exec, s[6:7]
	ds_read2_b32 v[60:61], v93 offset1:32
	ds_read2_b32 v[198:199], v93 offset0:64 offset1:96
	v_add_f32_e32 v0, 0, v62
	v_mov_b32_e32 v206, v46
	v_mov_b32_e32 v207, v30
	v_mul_f32_e32 v201, 0.5, v0
	s_waitcnt lgkmcnt(1)
	v_mul_f32_e32 v205, 0x3fd744fd, v60
	v_pk_add_f32 v[206:207], v[206:207], 0 op_sel_hi:[1,0]
	v_mov_b32_e32 v200, v30
	v_mov_b32_e32 v204, v1
	v_mov_b32_e32 v60, v61
	s_waitcnt lgkmcnt(0)
	v_mov_b32_e32 v61, v198
	s_mov_b32 s2, s67
	v_pk_add_f32 v[200:201], v[200:201], v[204:205]
	v_pk_mul_f32 v[204:205], v[60:61], s[2:3] op_sel_hi:[1,0]
	v_pk_mul_f32 v[208:209], v[206:207], 0.5 op_sel_hi:[1,0]
	v_pk_fma_f32 v[60:61], v[206:207], 0.5, v[204:205] op_sel_hi:[1,0,1]
	v_mov_b32_e32 v208, v201
	v_mov_b32_e32 v212, v1
	v_mov_b32_e32 v213, v205
	v_add_f32_e32 v202, 0, v14
	v_mov_b32_e32 v203, v199
	v_pk_mul_f32 v[206:207], v[60:61], v[60:61]
	v_pk_add_f32 v[208:209], v[208:209], v[212:213]
	v_mul_f32_e32 v0, 0x3fd744fd, v199
	v_mov_b32_e32 v163, v201
	v_pk_mov_b32 v[204:205], v[204:205], v[206:207] op_sel:[1,0]
	v_pk_add_f32 v[206:207], v[60:61], v[208:209]
	v_pk_mul_f32 v[208:209], v[60:61], v[208:209]
	v_pk_fma_f32 v[198:199], v[202:203], s[66:67], v[0:1] op_sel_hi:[1,1,0]
	v_pk_fma_f32 v[204:205], v[200:201], v[162:163], v[204:205]
	v_mov_b32_e32 v207, v209
	v_pk_mul_f32 v[202:203], v[198:199], v[198:199]
	v_pk_add_f32 v[204:205], v[206:207], v[204:205]
	v_mov_b32_e32 v199, v202
	v_pk_add_f32 v[202:203], v[204:205], v[198:199]
	s_nop 1
	v_mov_b32_dpp v204, v202 quad_perm:[1,0,3,2] row_mask:0xf bank_mask:0xf bound_ctrl:1
	v_mov_b32_dpp v205, v203 quad_perm:[1,0,3,2] row_mask:0xf bank_mask:0xf bound_ctrl:1
	v_pk_add_f32 v[202:203], v[202:203], v[204:205]
	s_nop 1
	v_mov_b32_dpp v204, v202 quad_perm:[2,3,0,1] row_mask:0xf bank_mask:0xf bound_ctrl:1
	v_mov_b32_dpp v205, v203 quad_perm:[2,3,0,1] row_mask:0xf bank_mask:0xf bound_ctrl:1
	v_pk_add_f32 v[202:203], v[202:203], v[204:205]
	s_nop 1
	v_mov_b32_dpp v204, v202 row_half_mirror row_mask:0xf bank_mask:0xf bound_ctrl:1
	v_mov_b32_dpp v205, v203 row_half_mirror row_mask:0xf bank_mask:0xf bound_ctrl:1
	v_pk_add_f32 v[202:203], v[202:203], v[204:205]
	s_nop 1
	v_mov_b32_dpp v204, v202 row_mirror row_mask:0xf bank_mask:0xf bound_ctrl:1
	v_mov_b32_dpp v205, v203 row_mirror row_mask:0xf bank_mask:0xf bound_ctrl:1
	s_and_saveexec_b64 s[6:7], vcc
	v_pk_add_f32 v[202:203], v[202:203], v[204:205]
	ds_write_b64 v160, v[202:203] offset:448
	s_or_b64 exec, exec, s[6:7]
	ds_read2_b32 v[202:203], v106 offset1:32
	ds_read2_b32 v[204:205], v106 offset0:64 offset1:96
	v_add_f32_e32 v0, 0, v63
	v_add_f32_e32 v62, 0, v15
	v_mul_f32_e32 v15, 0.5, v0
	s_waitcnt lgkmcnt(1)
	v_mul_f32_e32 v207, 0x3fd744fd, v202
	v_mov_b32_e32 v30, v47
	v_mov_b32_e32 v14, v31
	v_mov_b32_e32 v206, v1
	v_pk_add_f32 v[208:209], v[30:31], 0 op_sel_hi:[1,0]
	v_pk_add_f32 v[46:47], v[14:15], v[206:207]
	v_mov_b32_e32 v14, v203
	s_waitcnt lgkmcnt(0)
;   DI void operator()(f32x16 (&acc)[2][4], int grow0, int gcol0, int lane, int w, char* lds) {
;     ...
;         for (int e = 0; e < 4; ++e) {
;           const int i = 4 * (2 * (ps & 1) + qq) + e;
;           const float* xr = (const float*)(xs + (8 * qq + 4 * hh + e) * 512) + l31;
;           float s1 = 0.f, s2 = 0.f;
; #pragma unroll
;           for (int nt = 0; nt < 4; ++nt) {
;             float v = (acc[mt][nt][i] + bia[nt]) * csc[nt];
;             float z = ALPHA * xr[nt * 32] + hs * v;
;             acc[mt][nt][i] = z; s1 += z; s2 += z * z;
;           }
;           s1 = row16_sum(s1); s2 = row16_sum(s2);
;           if ((lane & 15) == 0) { f32x2 sv = {s1, s2}; *(f32x2*)(redw + (mt * 32 + (i & 3) + 8 * (i >> 2)) * 2) = sv; }
;         }
;     }
;     __syncthreads();
;     u64_t* myslots = xstat + ((size_t)pm * 256) * 4;
;     if (tid < 256) {
	v_mov_b32_e32 v15, v204
	s_mov_b32 s2, s67
	v_pk_mul_f32 v[30:31], v[14:15], s[2:3] op_sel_hi:[1,0]
	v_pk_mul_f32 v[202:203], v[208:209], 0.5 op_sel_hi:[1,0]
	v_pk_fma_f32 v[14:15], v[208:209], 0.5, v[30:31] op_sel_hi:[1,0,1]
	v_mov_b32_e32 v202, v47
	v_mov_b32_e32 v208, v1
	v_mov_b32_e32 v209, v31
	v_pk_mul_f32 v[206:207], v[14:15], v[14:15]
	v_pk_add_f32 v[202:203], v[202:203], v[208:209]
	v_mov_b32_e32 v163, v47
	v_pk_mov_b32 v[30:31], v[30:31], v[206:207] op_sel:[1,0]
	v_pk_add_f32 v[206:207], v[14:15], v[202:203]
	v_pk_mul_f32 v[202:203], v[14:15], v[202:203]
	v_mov_b32_e32 v63, v205
	v_pk_fma_f32 v[30:31], v[46:47], v[162:163], v[30:31]
	v_mov_b32_e32 v207, v203
	v_mul_f32_e32 v0, 0x3fd744fd, v205
	v_pk_add_f32 v[202:203], v[206:207], v[30:31]
	v_pk_fma_f32 v[30:31], v[62:63], s[66:67], v[0:1] op_sel_hi:[1,1,0]
	s_nop 0
	v_pk_mul_f32 v[62:63], v[30:31], v[30:31]
	s_nop 0
	v_mov_b32_e32 v31, v62
	v_pk_add_f32 v[62:63], v[202:203], v[30:31]
	s_nop 1
	v_mov_b32_dpp v202, v62 quad_perm:[1,0,3,2] row_mask:0xf bank_mask:0xf bound_ctrl:1
	v_mov_b32_dpp v203, v63 quad_perm:[1,0,3,2] row_mask:0xf bank_mask:0xf bound_ctrl:1
	v_pk_add_f32 v[62:63], v[62:63], v[202:203]
	s_nop 1
	v_mov_b32_dpp v202, v62 quad_perm:[2,3,0,1] row_mask:0xf bank_mask:0xf bound_ctrl:1
	v_mov_b32_dpp v203, v63 quad_perm:[2,3,0,1] row_mask:0xf bank_mask:0xf bound_ctrl:1
	v_pk_add_f32 v[62:63], v[62:63], v[202:203]
	s_nop 1
	v_mov_b32_dpp v202, v62 row_half_mirror row_mask:0xf bank_mask:0xf bound_ctrl:1
	v_mov_b32_dpp v203, v63 row_half_mirror row_mask:0xf bank_mask:0xf bound_ctrl:1
	v_pk_add_f32 v[62:63], v[62:63], v[202:203]
	s_nop 1
	v_mov_b32_dpp v202, v62 row_mirror row_mask:0xf bank_mask:0xf bound_ctrl:1
	v_mov_b32_dpp v203, v63 row_mirror row_mask:0xf bank_mask:0xf bound_ctrl:1
	s_and_saveexec_b64 s[6:7], vcc
	v_pk_add_f32 v[62:63], v[62:63], v[202:203]
	ds_write_b64 v160, v[62:63] offset:456
	s_or_b64 exec, exec, s[6:7]
	ds_read2_b32 v[62:63], v95 offset1:32
	ds_read2_b32 v[202:203], v95 offset0:64 offset1:96
	v_add_f32_e32 v0, 0, v64
	v_mov_b32_e32 v212, v48
	v_mov_b32_e32 v213, v32
	v_mul_f32_e32 v205, 0.5, v0
	s_waitcnt lgkmcnt(1)
	v_mul_f32_e32 v209, 0x3fd744fd, v62
	v_pk_add_f32 v[212:213], v[212:213], 0 op_sel_hi:[1,0]
	v_mov_b32_e32 v204, v32
	v_mov_b32_e32 v208, v1
	v_mov_b32_e32 v62, v63
	s_waitcnt lgkmcnt(0)
	v_mov_b32_e32 v63, v202
	s_mov_b32 s2, s67
	v_pk_add_f32 v[204:205], v[204:205], v[208:209]
	v_pk_mul_f32 v[208:209], v[62:63], s[2:3] op_sel_hi:[1,0]
	v_pk_mul_f32 v[214:215], v[212:213], 0.5 op_sel_hi:[1,0]
	v_pk_fma_f32 v[62:63], v[212:213], 0.5, v[208:209] op_sel_hi:[1,0,1]
	v_mov_b32_e32 v214, v205
	v_mov_b32_e32 v226, v1
	v_mov_b32_e32 v227, v209
	v_add_f32_e32 v206, 0, v16
	v_mov_b32_e32 v207, v203
	v_pk_mul_f32 v[212:213], v[62:63], v[62:63]
	v_pk_add_f32 v[214:215], v[214:215], v[226:227]
	v_mul_f32_e32 v0, 0x3fd744fd, v203
	v_mov_b32_e32 v163, v205
	v_pk_mov_b32 v[208:209], v[208:209], v[212:213] op_sel:[1,0]
	v_pk_add_f32 v[212:213], v[62:63], v[214:215]
	v_pk_mul_f32 v[214:215], v[62:63], v[214:215]
	v_pk_fma_f32 v[202:203], v[206:207], s[66:67], v[0:1] op_sel_hi:[1,1,0]
	v_pk_fma_f32 v[208:209], v[204:205], v[162:163], v[208:209]
	v_mov_b32_e32 v213, v215
	v_pk_mul_f32 v[206:207], v[202:203], v[202:203]
	v_pk_add_f32 v[208:209], v[212:213], v[208:209]
	v_mov_b32_e32 v203, v206
	v_pk_add_f32 v[206:207], v[208:209], v[202:203]
	s_nop 1
	v_mov_b32_dpp v208, v206 quad_perm:[1,0,3,2] row_mask:0xf bank_mask:0xf bound_ctrl:1
	v_mov_b32_dpp v209, v207 quad_perm:[1,0,3,2] row_mask:0xf bank_mask:0xf bound_ctrl:1
	v_pk_add_f32 v[206:207], v[206:207], v[208:209]
	s_nop 1
	v_mov_b32_dpp v208, v206 quad_perm:[2,3,0,1] row_mask:0xf bank_mask:0xf bound_ctrl:1
	v_mov_b32_dpp v209, v207 quad_perm:[2,3,0,1] row_mask:0xf bank_mask:0xf bound_ctrl:1
	v_pk_add_f32 v[206:207], v[206:207], v[208:209]
	s_nop 1
	v_mov_b32_dpp v208, v206 row_half_mirror row_mask:0xf bank_mask:0xf bound_ctrl:1
	v_mov_b32_dpp v209, v207 row_half_mirror row_mask:0xf bank_mask:0xf bound_ctrl:1
	v_pk_add_f32 v[206:207], v[206:207], v[208:209]
	s_nop 1
	v_mov_b32_dpp v208, v206 row_mirror row_mask:0xf bank_mask:0xf bound_ctrl:1
	v_mov_b32_dpp v209, v207 row_mirror row_mask:0xf bank_mask:0xf bound_ctrl:1
	s_and_saveexec_b64 s[6:7], vcc
	v_pk_add_f32 v[206:207], v[206:207], v[208:209]
	ds_write_b64 v160, v[206:207] offset:464
	s_or_b64 exec, exec, s[6:7]
	v_add_f32_e32 v0, 0, v65
	ds_read2_b32 v[64:65], v91 offset1:32
	ds_read2_b32 v[212:213], v91 offset0:64 offset1:96
	v_mov_b32_e32 v32, v49
	v_mul_f32_e32 v209, 0.5, v0
	v_add_f32_e32 v214, 0, v17
	s_waitcnt lgkmcnt(1)
	v_mul_f32_e32 v207, 0x3fd744fd, v64
	v_pk_add_f32 v[16:17], v[32:33], 0 op_sel_hi:[1,0]
	v_mov_b32_e32 v208, v33
	v_mov_b32_e32 v206, v1
	v_mov_b32_e32 v32, v65
	s_waitcnt lgkmcnt(0)
	v_mov_b32_e32 v33, v212
	s_mov_b32 s2, s67
	v_pk_add_f32 v[48:49], v[208:209], v[206:207]
	v_pk_mul_f32 v[32:33], v[32:33], s[2:3] op_sel_hi:[1,0]
	v_pk_mul_f32 v[64:65], v[16:17], 0.5 op_sel_hi:[1,0]
	v_pk_fma_f32 v[16:17], v[16:17], 0.5, v[32:33] op_sel_hi:[1,0,1]
	v_mov_b32_e32 v64, v49
	v_mov_b32_e32 v208, v1
	v_mov_b32_e32 v209, v33
	v_pk_mul_f32 v[206:207], v[16:17], v[16:17]
	v_pk_add_f32 v[64:65], v[64:65], v[208:209]
	v_mov_b32_e32 v163, v49
	v_pk_mov_b32 v[32:33], v[32:33], v[206:207] op_sel:[1,0]
	v_pk_add_f32 v[206:207], v[16:17], v[64:65]
	v_pk_mul_f32 v[64:65], v[16:17], v[64:65]
	v_mov_b32_e32 v215, v213
	v_pk_fma_f32 v[32:33], v[48:49], v[162:163], v[32:33]
	v_mov_b32_e32 v207, v65
	v_mul_f32_e32 v0, 0x3fd744fd, v213
	v_pk_add_f32 v[64:65], v[206:207], v[32:33]
	v_pk_fma_f32 v[32:33], v[214:215], s[66:67], v[0:1] op_sel_hi:[1,1,0]
	s_nop 0
	v_pk_mul_f32 v[206:207], v[32:33], v[32:33]
	s_nop 0
	v_mov_b32_e32 v33, v206
	v_pk_add_f32 v[64:65], v[64:65], v[32:33]
	s_nop 1
	v_mov_b32_dpp v206, v64 quad_perm:[1,0,3,2] row_mask:0xf bank_mask:0xf bound_ctrl:1
	v_mov_b32_dpp v207, v65 quad_perm:[1,0,3,2] row_mask:0xf bank_mask:0xf bound_ctrl:1
	v_pk_add_f32 v[64:65], v[64:65], v[206:207]
	s_nop 1
	v_mov_b32_dpp v206, v64 quad_perm:[2,3,0,1] row_mask:0xf bank_mask:0xf bound_ctrl:1
	v_mov_b32_dpp v207, v65 quad_perm:[2,3,0,1] row_mask:0xf bank_mask:0xf bound_ctrl:1
	v_pk_add_f32 v[64:65], v[64:65], v[206:207]
	s_nop 1
	v_mov_b32_dpp v206, v64 row_half_mirror row_mask:0xf bank_mask:0xf bound_ctrl:1
	v_mov_b32_dpp v207, v65 row_half_mirror row_mask:0xf bank_mask:0xf bound_ctrl:1
	v_pk_add_f32 v[64:65], v[64:65], v[206:207]
	s_nop 1
	v_mov_b32_dpp v206, v64 row_mirror row_mask:0xf bank_mask:0xf bound_ctrl:1
	v_mov_b32_dpp v207, v65 row_mirror row_mask:0xf bank_mask:0xf bound_ctrl:1
	s_and_saveexec_b64 s[6:7], vcc
	v_pk_add_f32 v[64:65], v[64:65], v[206:207]
	ds_write_b64 v160, v[64:65] offset:472
	s_or_b64 exec, exec, s[6:7]
	v_ashrrev_i32_e32 v206, 8, v164
	v_ashrrev_i32_e32 v207, 31, v206
	v_lshlrev_b64 v[64:65], 13, v[206:207]
	v_lshl_add_u64 v[64:65], s[8:9], 0, v[64:65]
	v_cmp_gt_i32_e64 s[40:41], s60, v210
	v_ashrrev_i32_e32 v169, 31, v168
	s_waitcnt lgkmcnt(0)
	s_barrier
; DI void ag_st64(u64_t* p, u64_t v) { __hip_atomic_store(p, v, __ATOMIC_RELAXED, __HIP_MEMORY_SCOPE_AGENT); }
;   DI void operator()(f32x16 (&acc)[2][4], int grow0, int gcol0, int lane, int w, char* lds) {
;     ...
;     __syncthreads();
;     u64_t* myslots = xstat + ((size_t)pm * 256) * 4;
;     if (tid < 256) {
;       float s1 = (red[tid * 2] + red[(256 + tid) * 2]) + (red[(512 + tid) * 2] + red[(768 + tid) * 2]);
;       float s2 = (red[tid * 2 + 1] + red[(256 + tid) * 2 + 1]) + (red[(512 + tid) * 2 + 1] + red[(768 + tid) * 2 + 1]);
;       ag_st64(myslots + tid * 4 + pn, ((u64_t)__float_as_uint(s2) << 32) | (u64_t)__float_as_uint(s1));
	s_and_saveexec_b64 s[6:7], s[40:41]
	s_cbranch_execz .LBB0_359
	v_lshl_add_u32 v0, v210, 3, v221
	ds_read2st64_b64 v[212:215], v0 offset1:4
	ds_read2st64_b64 v[226:229], v0 offset0:8 offset1:12
	v_ashrrev_i32_e32 v208, 8, v154
	v_ashrrev_i32_e32 v209, 31, v208
	s_waitcnt lgkmcnt(1)
	v_mov_b32_e32 v230, v212
	s_waitcnt lgkmcnt(0)
	v_mov_b32_e32 v231, v226
	v_mov_b32_e32 v232, v214
	v_mov_b32_e32 v233, v228
	v_mov_b32_e32 v226, v213
	v_mov_b32_e32 v228, v215
	v_pk_add_f32 v[230:231], v[230:231], v[232:233]
	v_pk_add_f32 v[212:213], v[226:227], v[228:229]
	v_pk_add_f32 v[230:231], v[230:231], v[230:231] op_sel:[0,1] op_sel_hi:[1,0]
	v_pk_add_f32 v[212:213], v[212:213], v[212:213] op_sel:[0,1] op_sel_hi:[1,0]
	v_lshl_add_u64 v[214:215], v[168:169], 3, v[64:65]
	v_lshl_add_u64 v[208:209], v[208:209], 3, v[214:215]
	v_mov_b32_e32 v231, v212
	global_store_dwordx2 v[208:209], v[230:231], off sc1

; DI unsigned pack2(float lo, float hi) { f32x2 v = {lo, hi}; bf2_t r = __builtin_convertvector(v, bf2_t); return __builtin_bit_cast(unsigned, r); }
; DI f32x16 mfma(bf16x8 a, bf16x8 b, f32x16 c) { return __builtin_amdgcn_mfma_f32_32x32x16_bf16(a, b, c, 0, 0, 0); }
; DI void phase_ret(const Params& p, char* lds) {
;     ...
;       {
;         bf16_t* orow = p.Or + (tokb + s0 + myi) * 2048 + h * 512 + sl * 64 + et * 32;
; #pragma unroll
;         for (int q4 = 0; q4 < 4; ++q4) {
;           u32x2 pk; pk.x = pack2(o[4 * q4], o[4 * q4 + 1]); pk.y = pack2(o[4 * q4 + 2], o[4 * q4 + 3]);
;           *(u32x2*)(orow + 8 * q4 + 4 * hhk) = pk;
;         }
;       }
;       asm volatile("" ::: "memory");
;       if (ck < 15) {
;         const bf16_t* kdr = p.Vt + ((size_t)bh * 256 + w * 32 + l31k) * S_ + s0;
;         bf16x8 ka[8];
; #pragma unroll
;         for (int kk = 0; kk < 8; ++kk) ka[kk] = *(const bf16x8*)(kdr + kk * 16 + 8 * hhk);
; #pragma unroll
;         for (int nt = 0; nt < 2; ++nt) {
; #pragma unroll
;           for (int i = 0; i < 16; ++i) R[nt][i] *= cd;
; #pragma unroll
;           for (int kk = 0; kk < 8; ++kk) {
;             const char* rp = v_l + (nt * 32 + l31k) * 264 + (kk * 16 + 8 * hhk) * 2;
;             s16x4 lo = *(const s16x4*)rp, hi = *(const s16x4*)(rp + 8);
;             bf16x8 bfrag = __builtin_shufflevector(lo, hi, 0, 1, 2, 3, 4, 5, 6, 7);
;             R[nt] = mfma(ka[kk], bfrag, R[nt]);
;           }
;         }
;         __syncthreads();
; #pragma unroll
;         for (int nt = 0; nt < 2; ++nt) {
;           const int e = nt * 32 + l31k;
; #pragma unroll
;           for (int q4 = 0; q4 < 4; ++q4) {
;             int d = w * 32 + 8 * q4 + 4 * hhk;
;             u32x2 pk; pk.x = pack2(R[nt][4 * q4], R[nt][4 * q4 + 1]); pk.y = pack2(R[nt][4 * q4 + 2], R[nt][4 * q4 + 3]);
;             *(u32x2*)(r_l + e * 512 + (((d >> 3) ^ (e & 15)) << 4) + (d & 7) * 2) = pk;
;           }
;         }
.LBB0_427:
	s_or_b64 exec, exec, s[34:35]
	v_lshlrev_b64 v[2:3], 12, v[192:193]
	v_lshl_add_u64 v[2:3], v[170:171], 0, v[2:3]
	v_ashrrev_i32_e32 v11, 31, v10
	v_lshl_add_u64 v[2:3], v[10:11], 1, v[2:3]
	v_cvt_pk_bf16_f32 v4, v48, v49
	v_cvt_pk_bf16_f32 v5, v50, v51
	global_store_dwordx2 v[2:3], v[4:5], off
	v_cvt_pk_bf16_f32 v4, v52, v53
	v_cvt_pk_bf16_f32 v5, v54, v55
	global_store_dwordx2 v[2:3], v[4:5], off offset:16
	v_cvt_pk_bf16_f32 v4, v56, v57
	v_cvt_pk_bf16_f32 v5, v58, v59
	global_store_dwordx2 v[2:3], v[4:5], off offset:32
	v_cvt_pk_bf16_f32 v4, v60, v61
	v_cvt_pk_bf16_f32 v5, v62, v63
	global_store_dwordx2 v[2:3], v[4:5], off offset:48
	s_cmp_lg_u32 s2, 15
	s_cbranch_scc0 .LBB0_418
	v_ashrrev_i32_e32 v189, 31, v188
	v_lshl_add_u64 v[2:3], v[160:161], 0, v[188:189]
	v_lshlrev_b64 v[2:3], 12, v[2:3]
	v_lshl_add_u64 v[2:3], s[82:83], 0, v[2:3]
	v_lshl_add_u64 v[2:3], s[92:93], 1, v[2:3]
	v_lshl_add_u64 v[2:3], v[190:191], 1, v[2:3]
	global_load_dwordx4 v[80:83], v[2:3], off
	global_load_dwordx4 v[84:87], v[2:3], off offset:32
	global_load_dwordx4 v[88:91], v[2:3], off offset:64
	global_load_dwordx4 v[92:95], v[2:3], off offset:96
	global_load_dwordx4 v[96:99], v[2:3], off offset:128
	global_load_dwordx4 v[100:103], v[2:3], off offset:160
	global_load_dwordx4 v[104:107], v[2:3], off offset:192
	global_load_dwordx4 v[108:111], v[2:3], off offset:224
	v_lshlrev_b32_e32 v8, 4, v155
	s_mov_b32 s3, 0x10000
	v_add3_u32 v0, v8, v0, s3
	v_mov_b32_e32 v157, v156
	v_pk_mul_f32 v[16:17], v[186:187], v[16:17]
	v_pk_mul_f32 v[30:31], v[156:157], v[30:31]
	v_pk_mul_f32 v[28:29], v[156:157], v[28:29]
	v_pk_mul_f32 v[26:27], v[156:157], v[26:27]
	v_pk_mul_f32 v[24:25], v[156:157], v[24:25]
	v_pk_mul_f32 v[22:23], v[156:157], v[22:23]
	v_pk_mul_f32 v[20:21], v[156:157], v[20:21]
	v_pk_mul_f32 v[18:19], v[156:157], v[18:19]
	v_add_u32_e32 v8, 0x2100, v0
	ds_read2_b64 v[112:115], v0 offset1:1
	ds_read2_b64 v[116:119], v8 offset1:1
	ds_read2_b64 v[120:123], v0 offset0:4 offset1:5
	ds_read2_b64 v[124:127], v8 offset0:4 offset1:5
	ds_read2_b64 v[128:131], v0 offset0:8 offset1:9
	ds_read2_b64 v[132:135], v8 offset0:8 offset1:9
	ds_read2_b64 v[136:139], v0 offset0:12 offset1:13
	ds_read2_b64 v[140:143], v8 offset0:12 offset1:13
	v_pk_mul_f32 v[32:33], v[186:187], v[32:33]
	v_pk_mul_f32 v[46:47], v[156:157], v[46:47]
	v_pk_mul_f32 v[44:45], v[156:157], v[44:45]
	v_pk_mul_f32 v[42:43], v[156:157], v[42:43]
	v_pk_mul_f32 v[40:41], v[156:157], v[40:41]
	v_pk_mul_f32 v[38:39], v[156:157], v[38:39]
	v_pk_mul_f32 v[36:37], v[156:157], v[36:37]
	v_pk_mul_f32 v[34:35], v[156:157], v[34:35]
	v_add_u32_e32 v10, v10, v146
	v_and_b32_e32 v11, 8, v190
	v_lshl_or_b32 v11, v188, 9, v11
	v_lshrrev_b32_e32 v10, 3, v10
	v_add_u32_e32 v11, 0x14200, v11
	v_bitop3_b32 v52, v10, v188, 15 bitop3:0x78
	s_waitcnt vmcnt(7) lgkmcnt(7)
	v_mfma_f32_32x32x16_bf16 v[16:31], v[80:83], v[112:115], v[16:31]
	ds_read2_b64 v[112:115], v0 offset0:16 offset1:17
	s_waitcnt lgkmcnt(7)
	v_mfma_f32_32x32x16_bf16 v[32:47], v[80:83], v[116:119], v[32:47]
	ds_read2_b64 v[116:119], v8 offset0:16 offset1:17
	s_waitcnt vmcnt(6) lgkmcnt(7)
	v_mfma_f32_32x32x16_bf16 v[16:31], v[84:87], v[120:123], v[16:31]
	ds_read2_b64 v[120:123], v0 offset0:20 offset1:21
	s_waitcnt lgkmcnt(7)
	v_mfma_f32_32x32x16_bf16 v[32:47], v[84:87], v[124:127], v[32:47]
	ds_read2_b64 v[124:127], v8 offset0:20 offset1:21
	s_waitcnt vmcnt(5) lgkmcnt(7)
	v_mfma_f32_32x32x16_bf16 v[16:31], v[88:91], v[128:131], v[16:31]
	ds_read2_b64 v[128:131], v0 offset0:24 offset1:25
	s_waitcnt lgkmcnt(7)
	v_mfma_f32_32x32x16_bf16 v[32:47], v[88:91], v[132:135], v[32:47]
	ds_read2_b64 v[132:135], v8 offset0:24 offset1:25
	s_waitcnt vmcnt(4) lgkmcnt(7)
	v_mfma_f32_32x32x16_bf16 v[16:31], v[92:95], v[136:139], v[16:31]
	ds_read2_b64 v[136:139], v0 offset0:28 offset1:29
	s_waitcnt lgkmcnt(7)
	v_mfma_f32_32x32x16_bf16 v[32:47], v[92:95], v[140:143], v[32:47]
	ds_read2_b64 v[140:143], v8 offset0:28 offset1:29
	s_waitcnt vmcnt(3) lgkmcnt(7)
	v_mfma_f32_32x32x16_bf16 v[16:31], v[96:99], v[112:115], v[16:31]
	s_waitcnt lgkmcnt(6)
	v_mfma_f32_32x32x16_bf16 v[32:47], v[96:99], v[116:119], v[32:47]
	s_waitcnt vmcnt(2) lgkmcnt(5)
	v_mfma_f32_32x32x16_bf16 v[16:31], v[100:103], v[120:123], v[16:31]
	s_waitcnt lgkmcnt(4)
	v_mfma_f32_32x32x16_bf16 v[32:47], v[100:103], v[124:127], v[32:47]
	s_waitcnt vmcnt(1) lgkmcnt(3)
	v_mfma_f32_32x32x16_bf16 v[16:31], v[104:107], v[128:131], v[16:31]
	s_waitcnt lgkmcnt(2)
	v_mfma_f32_32x32x16_bf16 v[32:47], v[104:107], v[132:135], v[32:47]
	v_add_u32_e32 v12, 1, v10
	v_add_u32_e32 v13, 2, v10
	v_add_u32_e32 v10, 3, v10
	v_lshl_add_u32 v0, v52, 4, v11
	v_bitop3_b32 v12, v12, v188, 15 bitop3:0x78
	v_bitop3_b32 v13, v13, v188, 15 bitop3:0x78
	v_bitop3_b32 v10, v10, v188, 15 bitop3:0x78
	v_lshl_add_u32 v50, v12, 4, v11
	v_lshl_add_u32 v51, v13, 4, v11
	v_lshl_add_u32 v52, v10, 4, v11
	s_waitcnt vmcnt(0) lgkmcnt(1)
	v_mfma_f32_32x32x16_bf16 v[16:31], v[108:111], v[136:139], v[16:31]
	s_waitcnt lgkmcnt(0)
	s_barrier
	v_mfma_f32_32x32x16_bf16 v[32:47], v[108:111], v[140:143], v[32:47]
	s_nop 4
	s_nop 3
	v_cvt_pk_bf16_f32 v2, v16, v17
	v_cvt_pk_bf16_f32 v3, v18, v19
	v_cvt_pk_bf16_f32 v4, v20, v21
	v_cvt_pk_bf16_f32 v5, v22, v23
	v_cvt_pk_bf16_f32 v6, v24, v25
	v_cvt_pk_bf16_f32 v7, v26, v27
	v_cvt_pk_bf16_f32 v8, v28, v29
	v_cvt_pk_bf16_f32 v9, v30, v31
	v_cvt_pk_bf16_f32 v10, v32, v33
	v_cvt_pk_bf16_f32 v11, v34, v35
	v_cvt_pk_bf16_f32 v12, v36, v37
	v_cvt_pk_bf16_f32 v13, v38, v39
	v_cvt_pk_bf16_f32 v14, v40, v41
	v_cvt_pk_bf16_f32 v15, v42, v43
	v_cvt_pk_bf16_f32 v48, v44, v45
	v_cvt_pk_bf16_f32 v49, v46, v47
	ds_write_b64 v0, v[2:3]
	ds_write_b64 v50, v[4:5]
	ds_write_b64 v51, v[6:7]
	ds_write_b64 v52, v[8:9]
	ds_write_b64 v0, v[10:11] offset:16384
	ds_write_b64 v50, v[12:13] offset:16384
	ds_write_b64 v51, v[14:15] offset:16384
	ds_write_b64 v52, v[48:49] offset:16384
	s_branch .LBB0_418

; DI f32x16 zero16() { f32x16 z; for (int i = 0; i < 16; ++i) z[i] = 0.f; return z; }
; DI int launder(int x) { asm volatile("" : "+v"(x)); return x; }
; template <int BK> DI int swz(int row) { constexpr int CPR = BK / 8; return (row / (16 / CPR)) % CPR; }
; DI void wait_vm0() { asm volatile("s_waitcnt vmcnt(0)" ::: "memory"); }
;   DI void pre(int grow0, int gcol0, int lane, int w, char* lds) { xpass(0, grow0, gcol0, lane, w, lds); }
;     ...
;   const int tid = launder(threadIdx.x), lane = tid & 63, w = tid >> 6, wm = w % WM, wn = w / WM;
;   const int l31 = lane & 31, hh = lane >> 5;
;   f32x16 acc[2][NTW];
; #pragma unroll
;   for (int a = 0; a < 2; ++a)
; #pragma unroll
;     for (int b = 0; b < NTW; ++b) acc[a][b] = zero16();
;   const bf16_t* Ag = A + (size_t)row0 * lda; const bf16_t* Bg = Bt + (size_t)col0 * ldb;
;   const int wv = __builtin_amdgcn_readfirstlane(tid >> 6);
;   __syncthreads();
;   if (!pre) { stage_tile<BM, BK>(Ag, lda, lds, tid); stage_tile<BN, BK>(Bg, ldb, lds + ABYTES, tid); }
;   wait_vm0();
;   __syncthreads();
;   const int nk = K / BK;
;   for (int kt = 0; kt < nk; ++kt) {
;     char* cur = lds + (kt & 1) * STG; char* nxt = lds + ((kt + 1) & 1) * STG;
;     const bool more = kt + 1 < nk;
;     const bf16_t* An = Ag + (kt + 1) * BK; const bf16_t* Bn = Bg + (kt + 1) * BK;
;     if (!more) epi.pre(row0 + wm * 64, col0 + wn * (32 * NTW), lane, w, lds);
;     bf16x8 fa[2][2], fb[2][NTW];
; #pragma unroll
;     for (int mt = 0; mt < 2; ++mt) { int row = wm * 64 + mt * 32 + l31; fa[0][mt] = *(const bf16x8*)(cur + row * (BK * 2) + ((hh ^ swz<BK>(row)) << 4)); }
; #pragma unroll
;     for (int nt = 0; nt < NTW; ++nt) { int row = wn * (32 * NTW) + nt * 32 + l31; fb[0][nt] = *(const bf16x8*)(cur + ABYTES + row * (BK * 2) + ((hh ^ swz<BK>(row)) << 4)); }
.LBB0_438:
	v_lshrrev_b32_e32 v4, 30, v3
	v_add_u32_e32 v4, v3, v4
	v_ashrrev_i32_e32 v4, 2, v4
	v_mul_i32_i24_e32 v5, 4, v4
	v_sub_u32_e32 v3, v3, v5
	v_and_b32_e32 v5, 31, v2
	v_lshlrev_b32_e32 v7, 6, v3
	v_or_b32_e32 v7, v7, v5
	v_bfe_u32 v3, v3, 25, 1
	v_lshlrev_b32_e32 v140, 7, v7
	v_add_u32_e32 v8, v7, v3
	v_or_b32_e32 v7, 32, v7
	v_add_u32_e32 v3, v7, v3
	v_lshlrev_b32_e32 v142, 7, v7
	v_ashrrev_i32_e32 v7, 1, v3
	v_ashrrev_i32_e32 v3, 31, v3
	v_ashrrev_i32_e32 v9, 1, v8
	v_ashrrev_i32_e32 v8, 31, v8
	v_lshrrev_b32_e32 v3, 29, v3
	v_lshrrev_b32_e32 v8, 29, v8
	v_add_u32_e32 v3, v7, v3
	v_add_u32_e32 v8, v9, v8
	v_and_b32_e32 v3, -8, v3
	v_lshrrev_b32_e32 v6, 5, v2
	v_and_b32_e32 v8, -8, v8
	v_sub_u32_e32 v3, v7, v3
	v_lshl_or_b32 v5, v4, 7, v5
	v_sub_u32_e32 v8, v9, v8
	v_bitop3_b32 v7, v3, v6, 1 bitop3:0x78
	v_lshrrev_b32_e32 v4, 31, v4
	v_bitop3_b32 v9, v8, v6, 1 bitop3:0x78
	v_lshlrev_b32_e32 v144, 4, v7
	v_add_u32_e32 v7, v5, v4
	v_lshlrev_b32_e32 v141, 4, v9
	v_ashrrev_i32_e32 v9, 1, v7
	v_ashrrev_i32_e32 v7, 31, v7
	v_lshrrev_b32_e32 v7, 29, v7
	v_add_u32_e32 v7, v9, v7
	v_and_b32_e32 v7, -8, v7
	v_sub_u32_e32 v7, v9, v7
	v_bitop3_b32 v9, v7, v6, 1 bitop3:0x78
	v_lshlrev_b32_e32 v151, 4, v9
	v_or_b32_e32 v9, 32, v5
	v_lshlrev_b32_e32 v152, 7, v9
	v_add_u32_e32 v9, v9, v4
	v_ashrrev_i32_e32 v10, 1, v9
	v_ashrrev_i32_e32 v9, 31, v9
	v_lshrrev_b32_e32 v9, 29, v9
	v_add_u32_e32 v9, v10, v9
	v_and_b32_e32 v9, -8, v9
	v_sub_u32_e32 v9, v10, v9
	v_bitop3_b32 v10, v9, v6, 1 bitop3:0x78
	v_lshlrev_b32_e32 v143, 7, v5
	v_lshlrev_b32_e32 v154, 4, v10
	v_or_b32_e32 v10, 64, v5
	v_or_b32_e32 v5, 0x60, v5
	v_lshlrev_b32_e32 v153, 7, v10
	v_add_u32_e32 v10, v10, v4
	v_add_u32_e32 v4, v5, v4
	v_lshlrev_b32_e32 v156, 7, v5
	v_ashrrev_i32_e32 v5, 1, v4
	v_ashrrev_i32_e32 v4, 31, v4
	v_lshrrev_b32_e32 v4, 29, v4
	v_add_u32_e32 v4, v5, v4
	v_and_b32_e32 v4, -8, v4
	v_sub_u32_e32 v4, v5, v4
	s_lshr_b32 s7, s36, 3
	v_bfe_u32 v2, v2, 5, 1
	v_ashrrev_i32_e32 v11, 1, v10
	v_ashrrev_i32_e32 v10, 31, v10
	v_bitop3_b32 v5, v4, v6, 1 bitop3:0x78
	s_and_b32 s7, s7, 7
	s_lshl_b32 s30, s35, 19
	v_lshrrev_b32_e32 v10, 29, v10
	v_lshlrev_b32_e32 v164, 4, v5
	v_bitop3_b32 v5, v8, v2, 2 bitop3:0x1e
	s_lshl_b32 s7, s7, 19
	s_and_b32 s30, s30, 0x1c00000
	v_add_u32_e32 v10, v11, v10
	v_lshlrev_b32_e32 v161, 4, v5
	v_bitop3_b32 v5, v3, v2, 2 bitop3:0x1e
	s_or_b32 s7, s30, s7
	s_and_b32 s30, s34, 0xffffff00
	v_and_b32_e32 v10, -8, v10
	v_lshlrev_b32_e32 v163, 4, v5
	v_bitop3_b32 v5, v7, v2, 2 bitop3:0x1e
	s_ashr_i32 s31, s30, 31
	v_sub_u32_e32 v10, v11, v10
	v_lshlrev_b32_e32 v159, 4, v5
	v_bitop3_b32 v5, v9, v2, 2 bitop3:0x1e
	s_lshl_b64 s[30:31], s[30:31], 11
	s_lshl_b32 s3, s3, 10
	v_lshlrev_b32_e32 v160, 4, v5
	v_bitop3_b32 v5, v10, v2, 2 bitop3:0x1e
	v_lshlrev_b32_e32 v157, 4, v5
	v_bitop3_b32 v5, v4, v2, 2 bitop3:0x1e
	s_add_u32 s40, s12, s7
	v_lshlrev_b32_e32 v158, 4, v5
	v_bitop3_b32 v5, v8, v2, 4 bitop3:0x1e
	s_addc_u32 s41, s13, 0
	s_waitcnt vmcnt(0)
	s_waitcnt vmcnt(0) lgkmcnt(0)
	s_barrier
	v_lshlrev_b32_e32 v149, 4, v5
	v_bitop3_b32 v5, v3, v2, 4 bitop3:0x1e
	v_lshl_add_u64 v[130:131], s[40:41], 0, v[0:1]
	s_load_dwordx4 s[40:43], s[0:1], 0x1a0
	v_lshlrev_b32_e32 v150, 4, v5
	v_bitop3_b32 v5, v7, v2, 4 bitop3:0x1e
	v_lshlrev_b32_e32 v147, 4, v5
	v_bitop3_b32 v5, v9, v2, 4 bitop3:0x1e
	v_bitop3_b32 v3, v3, v2, 6 bitop3:0x1e
	v_lshlrev_b32_e32 v148, 4, v5
	v_bitop3_b32 v5, v10, v2, 4 bitop3:0x1e
	v_lshlrev_b32_e32 v139, 4, v3
	v_bitop3_b32 v3, v7, v2, 6 bitop3:0x1e
	v_lshlrev_b32_e32 v145, 4, v5
	v_bitop3_b32 v5, v4, v2, 4 bitop3:0x1e
	v_lshlrev_b32_e32 v136, 4, v3
	v_bitop3_b32 v3, v9, v2, 6 bitop3:0x1e
	v_lshlrev_b32_e32 v146, 4, v5
	v_bitop3_b32 v5, v8, v2, 6 bitop3:0x1e
	v_lshlrev_b32_e32 v137, 4, v3
	v_bitop3_b32 v3, v10, v2, 6 bitop3:0x1e
	v_bitop3_b32 v2, v4, v2, 6 bitop3:0x1e
	s_waitcnt lgkmcnt(0)
	s_add_u32 s30, s42, s30
	v_bitop3_b32 v11, v10, v6, 1 bitop3:0x78
	v_lshlrev_b32_e32 v135, 4, v2
	s_addc_u32 s31, s43, s31
	v_mov_b32_e32 v2, 0
	v_lshlrev_b32_e32 v155, 4, v11
	v_lshlrev_b32_e32 v138, 4, v5
	v_lshlrev_b32_e32 v134, 4, v3
	v_lshl_add_u64 v[132:133], s[30:31], 0, v[0:1]
	s_mov_b64 s[30:31], 0
	s_mov_b32 s7, 0x10000
	v_mov_b32_e32 v3, v2
	v_mov_b32_e32 v4, v2
	v_mov_b32_e32 v5, v2
	v_mov_b32_e32 v6, v2
	v_mov_b32_e32 v7, v2
	v_mov_b32_e32 v8, v2
	v_mov_b32_e32 v9, v2
	v_mov_b32_e32 v10, v2
	v_mov_b32_e32 v11, v2
	v_mov_b32_e32 v12, v2
	v_mov_b32_e32 v13, v2
	v_mov_b32_e32 v14, v2
	v_mov_b32_e32 v15, v2
	v_mov_b32_e32 v16, v2
	v_mov_b32_e32 v17, v2
	v_mov_b32_e32 v18, v2
	v_mov_b32_e32 v19, v2
	v_mov_b32_e32 v20, v2
	v_mov_b32_e32 v21, v2
	v_mov_b32_e32 v22, v2
	v_mov_b32_e32 v23, v2
	v_mov_b32_e32 v24, v2
	v_mov_b32_e32 v25, v2
	v_mov_b32_e32 v26, v2
	v_mov_b32_e32 v27, v2
	v_mov_b32_e32 v28, v2
	v_mov_b32_e32 v29, v2
	v_mov_b32_e32 v30, v2
	v_mov_b32_e32 v31, v2
	v_mov_b32_e32 v32, v2
	v_mov_b32_e32 v33, v2
	v_mov_b32_e32 v66, v2
	v_mov_b32_e32 v67, v2
	v_mov_b32_e32 v68, v2
	v_mov_b32_e32 v69, v2
	v_mov_b32_e32 v70, v2
	v_mov_b32_e32 v71, v2
	v_mov_b32_e32 v72, v2
	v_mov_b32_e32 v73, v2
	v_mov_b32_e32 v74, v2
	v_mov_b32_e32 v75, v2
	v_mov_b32_e32 v76, v2
	v_mov_b32_e32 v77, v2
	v_mov_b32_e32 v78, v2
	v_mov_b32_e32 v79, v2
	v_mov_b32_e32 v80, v2
	v_mov_b32_e32 v81, v2
	v_mov_b32_e32 v82, v2
	v_mov_b32_e32 v83, v2
	v_mov_b32_e32 v84, v2
	v_mov_b32_e32 v85, v2
	v_mov_b32_e32 v86, v2
	v_mov_b32_e32 v87, v2
	v_mov_b32_e32 v88, v2
	v_mov_b32_e32 v89, v2
	v_mov_b32_e32 v90, v2
	v_mov_b32_e32 v91, v2
	v_mov_b32_e32 v92, v2
	v_mov_b32_e32 v93, v2
	v_mov_b32_e32 v94, v2
	v_mov_b32_e32 v95, v2
	v_mov_b32_e32 v96, v2
	v_mov_b32_e32 v97, v2
;     ...
;   f32x16 acc[2][NTW];
; #pragma unroll
;   for (int a = 0; a < 2; ++a)
; #pragma unroll
;     for (int b = 0; b < NTW; ++b) acc[a][b] = zero16();
;   const bf16_t* Ag = A + (size_t)row0 * lda; const bf16_t* Bg = Bt + (size_t)col0 * ldb;
;   const int wv = __builtin_amdgcn_readfirstlane(tid >> 6);
;   __syncthreads();
;   if (!pre) { stage_tile<BM, BK>(Ag, lda, lds, tid); stage_tile<BN, BK>(Bg, ldb, lds + ABYTES, tid); }
;   wait_vm0();
;   __syncthreads();
;   const int nk = K / BK;
;   for (int kt = 0; kt < nk; ++kt) {
;     char* cur = lds + (kt & 1) * STG; char* nxt = lds + ((kt + 1) & 1) * STG;
;     const bool more = kt + 1 < nk;
;     const bf16_t* An = Ag + (kt + 1) * BK; const bf16_t* Bn = Bg + (kt + 1) * BK;
;     if (!more) epi.pre(row0 + wm * 64, col0 + wn * (32 * NTW), lane, w, lds);
;     bf16x8 fa[2][2], fb[2][NTW];
; #pragma unroll
;     for (int mt = 0; mt < 2; ++mt) { int row = wm * 64 + mt * 32 + l31; fa[0][mt] = *(const bf16x8*)(cur + row * (BK * 2) + ((hh ^ swz<BK>(row)) << 4)); }
; #pragma unroll
;     for (int nt = 0; nt < NTW; ++nt) { int row = wn * (32 * NTW) + nt * 32 + l31; fb[0][nt] = *(const bf16x8*)(cur + ABYTES + row * (BK * 2) + ((hh ^ swz<BK>(row)) << 4)); }
; #pragma unroll
;     for (int kk = 0; kk < NKK; ++kk) {
;       if (kk + 1 < NKK) {
;         const int ch = (kk + 1) * 2 + hh;
; #pragma unroll
;         for (int mt = 0; mt < 2; ++mt) { int row = wm * 64 + mt * 32 + l31; fa[(kk + 1) & 1][mt] = *(const bf16x8*)(cur + row * (BK * 2) + ((ch ^ swz<BK>(row)) << 4)); }
; #pragma unroll
;         for (int nt = 0; nt < NTW; ++nt) { int row = wn * (32 * NTW) + nt * 32 + l31; fb[(kk + 1) & 1][nt] = *(const bf16x8*)(cur + ABYTES + row * (BK * 2) + ((ch ^ swz<BK>(row)) << 4)); }
;       }
;       if (more) {
; #pragma unroll
;         for (int q = 0; q < PPK; ++q) {
;           const int pi = kk * PPK + q;
;           if (pi < NPA) stage_piece<BM, BK>(An, lda, nxt, tid, pi, wv);
;           else if (pi < NP) stage_piece<BN, BK>(Bn, ldb, nxt + ABYTES, tid, pi - NPA, wv);
;         }
;       }
;       __builtin_amdgcn_s_setprio(1);
; #pragma unroll
;       for (int mt = 0; mt < 2; ++mt)
; #pragma unroll
;         for (int nt = 0; nt < NTW; ++nt) acc[mt][nt] = mfma(fa[kk & 1][mt], fb[kk & 1][nt], acc[mt][nt]);
;       __builtin_amdgcn_s_setprio(0);
;       __builtin_amdgcn_sched_barrier(0);
;     }
	v_mov_b32_e32 v34, v2
	v_mov_b32_e32 v35, v2
	v_mov_b32_e32 v36, v2
	v_mov_b32_e32 v37, v2
	v_mov_b32_e32 v38, v2
	v_mov_b32_e32 v39, v2
	v_mov_b32_e32 v40, v2
	v_mov_b32_e32 v41, v2
	v_mov_b32_e32 v42, v2
	v_mov_b32_e32 v43, v2
	v_mov_b32_e32 v44, v2
	v_mov_b32_e32 v45, v2
	v_mov_b32_e32 v46, v2
	v_mov_b32_e32 v47, v2
	v_mov_b32_e32 v48, v2
	v_mov_b32_e32 v49, v2
	v_mov_b32_e32 v50, v2
	v_mov_b32_e32 v51, v2
	v_mov_b32_e32 v52, v2
	v_mov_b32_e32 v53, v2
	v_mov_b32_e32 v54, v2
	v_mov_b32_e32 v55, v2
	v_mov_b32_e32 v56, v2
	v_mov_b32_e32 v57, v2
	v_mov_b32_e32 v58, v2
	v_mov_b32_e32 v59, v2
	v_mov_b32_e32 v60, v2
	v_mov_b32_e32 v61, v2
	v_mov_b32_e32 v62, v2
	v_mov_b32_e32 v63, v2
	v_mov_b32_e32 v64, v2
	v_mov_b32_e32 v65, v2
	v_mov_b32_e32 v98, v2
	v_mov_b32_e32 v99, v2
	v_mov_b32_e32 v100, v2
	v_mov_b32_e32 v101, v2
	v_mov_b32_e32 v102, v2
	v_mov_b32_e32 v103, v2
	v_mov_b32_e32 v104, v2
	v_mov_b32_e32 v105, v2
	v_mov_b32_e32 v106, v2
	v_mov_b32_e32 v107, v2
	v_mov_b32_e32 v108, v2
	v_mov_b32_e32 v109, v2
	v_mov_b32_e32 v110, v2
	v_mov_b32_e32 v111, v2
	v_mov_b32_e32 v112, v2
	v_mov_b32_e32 v113, v2
	v_mov_b32_e32 v114, v2
	v_mov_b32_e32 v115, v2
	v_mov_b32_e32 v116, v2
	v_mov_b32_e32 v117, v2
	v_mov_b32_e32 v118, v2
	v_mov_b32_e32 v119, v2
	v_mov_b32_e32 v120, v2
	v_mov_b32_e32 v121, v2
	v_mov_b32_e32 v122, v2
	v_mov_b32_e32 v123, v2
	v_mov_b32_e32 v124, v2
	v_mov_b32_e32 v125, v2
	v_mov_b32_e32 v126, v2
	v_mov_b32_e32 v127, v2
	v_mov_b32_e32 v128, v2
	v_mov_b32_e32 v129, v2
	v_add_u32_e32 v166, v140, v141
	v_add_u32_e32 v170, v142, v144
	ds_read_b128 v[166:169], v166
	v_add_u32_e32 v174, v143, v151
	ds_read_b128 v[170:173], v170
	v_add_u32_e32 v178, v152, v154
	ds_read_b128 v[174:177], v174 offset:32768
	v_add_u32_e32 v182, v153, v155
	ds_read_b128 v[178:181], v178 offset:32768
	v_add_u32_e32 v186, v156, v164
	ds_read_b128 v[182:185], v182 offset:32768
	ds_read_b128 v[186:189], v186 offset:32768
.LBB0_439:
	s_and_b32 s40, s7, 0x10000
	s_xor_b32 s100, s40, 0x10000
	s_add_i32 s37, s40, s3
	v_add3_u32 v190, s100, v140, v161
	v_add3_u32 v194, s100, v142, v163
	ds_read_b128 v[190:193], v190
	v_add3_u32 v198, s100, v143, v159
	ds_read_b128 v[194:197], v194
	v_add3_u32 v202, s100, v152, v160
	ds_read_b128 v[198:201], v198 offset:32768
	v_add3_u32 v206, s100, v153, v157
	ds_read_b128 v[202:205], v202 offset:32768
	v_add3_u32 v210, s100, v156, v158
	ds_read_b128 v[206:209], v206 offset:32768
	ds_read_b128 v[210:213], v210 offset:32768
	v_lshl_add_u64 v[214:215], v[130:131], 0, s[30:31]
	v_lshl_add_u64 v[226:227], v[132:133], 0, s[30:31]
	s_mov_b32 m0, s37
	v_lshl_add_u64 v[228:229], v[214:215], 0, s[28:29]
	s_setprio 1
	s_waitcnt lgkmcnt(6)
	v_mfma_f32_32x32x16_bf16 v[114:129], v[166:169], v[174:177], v[114:129]
	global_load_lds_dwordx4 v[228:229], off
	v_lshl_add_u64 v[228:229], v[214:215], 0, s[24:25]
	s_add_i32 m0, s37, 0x2000
	v_mfma_f32_32x32x16_bf16 v[98:113], v[166:169], v[178:181], v[98:113]
	global_load_lds_dwordx4 v[228:229], off
	v_lshl_add_u64 v[228:229], v[214:215], 0, s[26:27]
	s_add_i32 m0, s37, 0x4000
	v_mfma_f32_32x32x16_bf16 v[50:65], v[166:169], v[182:185], v[50:65]
	global_load_lds_dwordx4 v[228:229], off
	v_lshl_add_u64 v[228:229], v[214:215], 0, s[38:39]
	s_add_i32 m0, s37, 0x6000
	v_mfma_f32_32x32x16_bf16 v[34:49], v[166:169], v[186:189], v[34:49]
	global_load_lds_dwordx4 v[228:229], off
	v_lshl_add_u64 v[228:229], v[226:227], 0, s[28:29]
	s_add_i32 m0, s37, 0x8000
	v_mfma_f32_32x32x16_bf16 v[82:97], v[170:173], v[174:177], v[82:97]
	global_load_lds_dwordx4 v[228:229], off
	v_lshl_add_u64 v[228:229], v[226:227], 0, s[24:25]
	s_add_i32 m0, s37, 0xa000
	v_mfma_f32_32x32x16_bf16 v[66:81], v[170:173], v[178:181], v[66:81]
	global_load_lds_dwordx4 v[228:229], off
	v_lshl_add_u64 v[228:229], v[226:227], 0, s[26:27]
	s_add_i32 m0, s37, 0xc000
	v_mfma_f32_32x32x16_bf16 v[18:33], v[170:173], v[182:185], v[18:33]
	global_load_lds_dwordx4 v[228:229], off
	v_lshl_add_u64 v[228:229], v[226:227], 0, s[38:39]
	s_add_i32 m0, s37, 0xe000
	v_mfma_f32_32x32x16_bf16 v[2:17], v[170:173], v[186:189], v[2:17]
	global_load_lds_dwordx4 v[228:229], off
	s_setprio 0
	v_add3_u32 v166, s100, v140, v149
	v_add3_u32 v170, s100, v142, v150
	ds_read_b128 v[166:169], v166
	v_add3_u32 v174, s100, v143, v147
	ds_read_b128 v[170:173], v170
	v_add3_u32 v178, s100, v152, v148
	ds_read_b128 v[174:177], v174 offset:32768
	v_add3_u32 v182, s100, v153, v145
	ds_read_b128 v[178:181], v178 offset:32768
	v_add3_u32 v186, s100, v156, v146
	ds_read_b128 v[182:185], v182 offset:32768
	ds_read_b128 v[186:189], v186 offset:32768
	s_setprio 1
	s_waitcnt lgkmcnt(6)
	v_mfma_f32_32x32x16_bf16 v[114:129], v[190:193], v[198:201], v[114:129]
	v_mfma_f32_32x32x16_bf16 v[98:113], v[190:193], v[202:205], v[98:113]
	v_mfma_f32_32x32x16_bf16 v[50:65], v[190:193], v[206:209], v[50:65]
	v_mfma_f32_32x32x16_bf16 v[34:49], v[190:193], v[210:213], v[34:49]
	v_mfma_f32_32x32x16_bf16 v[82:97], v[194:197], v[198:201], v[82:97]
	v_mfma_f32_32x32x16_bf16 v[66:81], v[194:197], v[202:205], v[66:81]
	v_mfma_f32_32x32x16_bf16 v[18:33], v[194:197], v[206:209], v[18:33]
	v_mfma_f32_32x32x16_bf16 v[2:17], v[194:197], v[210:213], v[2:17]
	s_setprio 0
	v_add3_u32 v190, s100, v140, v138
	v_add3_u32 v194, s100, v142, v139
	ds_read_b128 v[190:193], v190
	v_add3_u32 v198, s100, v143, v136
	ds_read_b128 v[194:197], v194
	v_add3_u32 v202, s100, v152, v137
	ds_read_b128 v[198:201], v198 offset:32768
	v_add3_u32 v206, s100, v153, v134
	ds_read_b128 v[202:205], v202 offset:32768
	v_add3_u32 v210, s100, v156, v135
	ds_read_b128 v[206:209], v206 offset:32768
	ds_read_b128 v[210:213], v210 offset:32768
	s_setprio 1
	s_waitcnt lgkmcnt(6)
	v_mfma_f32_32x32x16_bf16 v[114:129], v[166:169], v[174:177], v[114:129]
	v_mfma_f32_32x32x16_bf16 v[98:113], v[166:169], v[178:181], v[98:113]
	v_mfma_f32_32x32x16_bf16 v[50:65], v[166:169], v[182:185], v[50:65]
	v_mfma_f32_32x32x16_bf16 v[34:49], v[166:169], v[186:189], v[34:49]
	v_mfma_f32_32x32x16_bf16 v[82:97], v[170:173], v[174:177], v[82:97]
	v_mfma_f32_32x32x16_bf16 v[66:81], v[170:173], v[178:181], v[66:81]
	v_mfma_f32_32x32x16_bf16 v[18:33], v[170:173], v[182:185], v[18:33]
	v_mfma_f32_32x32x16_bf16 v[2:17], v[170:173], v[186:189], v[2:17]
	s_setprio 0
	s_add_u32 s30, s30, 0x80
	s_addc_u32 s31, s31, 0
	s_add_i32 s7, s7, 0x10000
	s_waitcnt vmcnt(0) lgkmcnt(0)
	s_barrier
; DI f32x16 mfma(bf16x8 a, bf16x8 b, f32x16 c) { return __builtin_amdgcn_mfma_f32_32x32x16_bf16(a, b, c, 0, 0, 0); }
; template <int BK> DI int swz(int row) { constexpr int CPR = BK / 8; return (row / (16 / CPR)) % CPR; }
; DI void wait_vm0() { asm volatile("s_waitcnt vmcnt(0)" ::: "memory"); }
;   DI void pre(int grow0, int gcol0, int lane, int w, char* lds) { xpass(0, grow0, gcol0, lane, w, lds); }
;     ...
;   for (int kt = 0; kt < nk; ++kt) {
;     char* cur = lds + (kt & 1) * STG; char* nxt = lds + ((kt + 1) & 1) * STG;
;     const bool more = kt + 1 < nk;
;     const bf16_t* An = Ag + (kt + 1) * BK; const bf16_t* Bn = Bg + (kt + 1) * BK;
;     if (!more) epi.pre(row0 + wm * 64, col0 + wn * (32 * NTW), lane, w, lds);
;     bf16x8 fa[2][2], fb[2][NTW];
; #pragma unroll
;     for (int mt = 0; mt < 2; ++mt) { int row = wm * 64 + mt * 32 + l31; fa[0][mt] = *(const bf16x8*)(cur + row * (BK * 2) + ((hh ^ swz<BK>(row)) << 4)); }
; #pragma unroll
;     for (int nt = 0; nt < NTW; ++nt) { int row = wn * (32 * NTW) + nt * 32 + l31; fb[0][nt] = *(const bf16x8*)(cur + ABYTES + row * (BK * 2) + ((hh ^ swz<BK>(row)) << 4)); }
; #pragma unroll
;     for (int kk = 0; kk < NKK; ++kk) {
;       if (kk + 1 < NKK) {
;         const int ch = (kk + 1) * 2 + hh;
; #pragma unroll
;         for (int mt = 0; mt < 2; ++mt) { int row = wm * 64 + mt * 32 + l31; fa[(kk + 1) & 1][mt] = *(const bf16x8*)(cur + row * (BK * 2) + ((ch ^ swz<BK>(row)) << 4)); }
; #pragma unroll
;         for (int nt = 0; nt < NTW; ++nt) { int row = wn * (32 * NTW) + nt * 32 + l31; fb[(kk + 1) & 1][nt] = *(const bf16x8*)(cur + ABYTES + row * (BK * 2) + ((ch ^ swz<BK>(row)) << 4)); }
;       }
;       if (more) {
; #pragma unroll
;         for (int q = 0; q < PPK; ++q) {
;           const int pi = kk * PPK + q;
;           if (pi < NPA) stage_piece<BM, BK>(An, lda, nxt, tid, pi, wv);
;           else if (pi < NP) stage_piece<BN, BK>(Bn, ldb, nxt + ABYTES, tid, pi - NPA, wv);
;         }
;       }
;       __builtin_amdgcn_s_setprio(1);
; #pragma unroll
;       for (int mt = 0; mt < 2; ++mt)
; #pragma unroll
;         for (int nt = 0; nt < NTW; ++nt) acc[mt][nt] = mfma(fa[kk & 1][mt], fb[kk & 1][nt], acc[mt][nt]);
;       __builtin_amdgcn_s_setprio(0);
;       __builtin_amdgcn_sched_barrier(0);
;     }
;     wait_vm0();
;     __syncthreads();
;   }
	v_add3_u32 v166, s40, v140, v141
	v_add3_u32 v170, s40, v142, v144
	ds_read_b128 v[166:169], v166
	v_add3_u32 v174, s40, v143, v151
	ds_read_b128 v[170:173], v170
	v_add3_u32 v178, s40, v152, v154
	ds_read_b128 v[174:177], v174 offset:32768
	v_add3_u32 v182, s40, v153, v155
	ds_read_b128 v[178:181], v178 offset:32768
	v_add3_u32 v186, s40, v156, v164
	ds_read_b128 v[182:185], v182 offset:32768
	ds_read_b128 v[186:189], v186 offset:32768
	s_setprio 1
	v_mfma_f32_32x32x16_bf16 v[114:129], v[190:193], v[198:201], v[114:129]
	v_mfma_f32_32x32x16_bf16 v[98:113], v[190:193], v[202:205], v[98:113]
	v_mfma_f32_32x32x16_bf16 v[50:65], v[190:193], v[206:209], v[50:65]
	v_mfma_f32_32x32x16_bf16 v[34:49], v[190:193], v[210:213], v[34:49]
	v_mfma_f32_32x32x16_bf16 v[82:97], v[194:197], v[198:201], v[82:97]
	v_mfma_f32_32x32x16_bf16 v[66:81], v[194:197], v[202:205], v[66:81]
	v_mfma_f32_32x32x16_bf16 v[18:33], v[194:197], v[206:209], v[18:33]
	v_mfma_f32_32x32x16_bf16 v[2:17], v[194:197], v[210:213], v[2:17]
	s_setprio 0
	s_cmpk_eq_i32 s30, 0x780
	s_cbranch_scc0 .LBB0_439
	s_waitcnt lgkmcnt(0)
	v_add_u32_e32 v0, 0x10000, v140
	v_add_u32_e32 v198, 0x10000, v142
	v_add_u32_e32 v130, v0, v141
	v_add_u32_e32 v140, v198, v144
	v_add_u32_e32 v199, 0x18000, v143
	v_add_u32_e32 v200, 0x18000, v152
	ds_read_b128 v[130:133], v130
	ds_read_b128 v[166:169], v140
	v_add_u32_e32 v140, v199, v151
	v_add_u32_e32 v144, v200, v154
	v_add_u32_e32 v201, 0x18000, v153
	ds_read_b128 v[140:143], v140
	ds_read_b128 v[170:173], v144
	v_add_u32_e32 v144, v201, v155
	v_add_u32_e32 v202, 0x18000, v156
	v_add_u32_e32 v151, v202, v164
	ds_read_b128 v[152:155], v144
	ds_read_b128 v[174:177], v151
	v_add_u32_e32 v144, v0, v161
	v_add_u32_e32 v151, v198, v163
	ds_read_b128 v[178:181], v144
	ds_read_b128 v[182:185], v151
	v_add_u32_e32 v144, v199, v159
	v_add_u32_e32 v151, v200, v160
	ds_read_b128 v[186:189], v144
	ds_read_b128 v[190:193], v151
	v_add_u32_e32 v144, v201, v157
	v_add_u32_e32 v151, v202, v158
	ds_read_b128 v[156:159], v144
	ds_read_b128 v[194:197], v151
	s_add_i32 s36, s36, s94
	s_cmpk_gt_i32 s36, 0x5ff
	s_cselect_b64 s[42:43], -1, 0
	s_cmpk_lt_i32 s36, 0x600
	s_setprio 1
	s_waitcnt lgkmcnt(9)
	v_mfma_f32_32x32x16_bf16 v[114:129], v[130:133], v[140:143], v[114:129]
	s_waitcnt lgkmcnt(8)
	v_mfma_f32_32x32x16_bf16 v[98:113], v[130:133], v[170:173], v[98:113]
	s_waitcnt lgkmcnt(7)
	v_mfma_f32_32x32x16_bf16 v[50:65], v[130:133], v[152:155], v[50:65]
	s_waitcnt lgkmcnt(6)
	v_mfma_f32_32x32x16_bf16 v[34:49], v[130:133], v[174:177], v[34:49]
	v_mfma_f32_32x32x16_bf16 v[82:97], v[166:169], v[140:143], v[82:97]
	v_mfma_f32_32x32x16_bf16 v[66:81], v[166:169], v[170:173], v[66:81]
	v_mfma_f32_32x32x16_bf16 v[18:33], v[166:169], v[152:155], v[18:33]
	v_mfma_f32_32x32x16_bf16 v[2:17], v[166:169], v[174:177], v[2:17]
	s_setprio 0
	v_add_u32_e32 v130, v0, v149
	v_add_u32_e32 v140, v198, v150
	v_add_u32_e32 v144, v199, v147
	ds_read_b128 v[130:133], v130
	ds_read_b128 v[140:143], v140
	v_add_u32_e32 v147, v200, v148
	ds_read_b128 v[148:151], v144
	ds_read_b128 v[152:155], v147
	v_add_u32_e32 v144, v201, v145
	v_add_u32_e32 v160, v202, v146
	ds_read_b128 v[144:147], v144
	ds_read_b128 v[166:169], v160
	s_setprio 1
	s_waitcnt lgkmcnt(9)
	v_mfma_f32_32x32x16_bf16 v[114:129], v[178:181], v[186:189], v[114:129]
	s_waitcnt lgkmcnt(8)
	v_mfma_f32_32x32x16_bf16 v[98:113], v[178:181], v[190:193], v[98:113]
	s_waitcnt lgkmcnt(7)
	v_mfma_f32_32x32x16_bf16 v[50:65], v[178:181], v[156:159], v[50:65]
	s_waitcnt lgkmcnt(6)
	v_mfma_f32_32x32x16_bf16 v[34:49], v[178:181], v[194:197], v[34:49]
	v_mfma_f32_32x32x16_bf16 v[82:97], v[182:185], v[186:189], v[82:97]
	v_mfma_f32_32x32x16_bf16 v[66:81], v[182:185], v[190:193], v[66:81]
	v_mfma_f32_32x32x16_bf16 v[18:33], v[182:185], v[156:159], v[18:33]
	v_mfma_f32_32x32x16_bf16 v[2:17], v[182:185], v[194:197], v[2:17]
	s_setprio 0
	v_add_u32_e32 v0, v0, v138
	v_add_u32_e32 v138, v198, v139
	ds_read_b128 v[156:159], v0
	ds_read_b128 v[170:173], v138
	v_add_u32_e32 v0, v199, v136
	v_add_u32_e32 v160, v200, v137
	ds_read_b128 v[136:139], v0
	ds_read_b128 v[174:177], v160
	v_add_u32_e32 v0, v201, v134
	v_add_u32_e32 v134, v202, v135
	ds_read_b128 v[178:181], v0
	ds_read_b128 v[182:185], v134
	s_setprio 1
	s_waitcnt lgkmcnt(9)
	v_mfma_f32_32x32x16_bf16 v[114:129], v[130:133], v[148:151], v[114:129]
	s_waitcnt lgkmcnt(8)
	v_mfma_f32_32x32x16_bf16 v[98:113], v[130:133], v[152:155], v[98:113]
	s_waitcnt lgkmcnt(7)
	v_mfma_f32_32x32x16_bf16 v[50:65], v[130:133], v[144:147], v[50:65]
	s_waitcnt lgkmcnt(6)
	v_mfma_f32_32x32x16_bf16 v[34:49], v[130:133], v[166:169], v[34:49]
	v_mfma_f32_32x32x16_bf16 v[82:97], v[140:143], v[148:151], v[82:97]
	v_mfma_f32_32x32x16_bf16 v[66:81], v[140:143], v[152:155], v[66:81]
	v_mfma_f32_32x32x16_bf16 v[18:33], v[140:143], v[144:147], v[18:33]
	v_mfma_f32_32x32x16_bf16 v[2:17], v[140:143], v[166:169], v[2:17]
	s_setprio 0
	s_setprio 1
	s_waitcnt lgkmcnt(3)
	v_mfma_f32_32x32x16_bf16 v[114:129], v[156:159], v[136:139], v[114:129]
	s_waitcnt lgkmcnt(2)
	v_mfma_f32_32x32x16_bf16 v[98:113], v[156:159], v[174:177], v[98:113]
	s_waitcnt lgkmcnt(1)
	v_mfma_f32_32x32x16_bf16 v[50:65], v[156:159], v[178:181], v[50:65]
	s_waitcnt lgkmcnt(0)
	v_mfma_f32_32x32x16_bf16 v[34:49], v[156:159], v[182:185], v[34:49]
	v_mfma_f32_32x32x16_bf16 v[82:97], v[170:173], v[136:139], v[82:97]
	v_mfma_f32_32x32x16_bf16 v[66:81], v[170:173], v[174:177], v[66:81]
	v_mfma_f32_32x32x16_bf16 v[18:33], v[170:173], v[178:181], v[18:33]
	v_mfma_f32_32x32x16_bf16 v[2:17], v[170:173], v[182:185], v[2:17]
	s_setprio 0
	s_waitcnt vmcnt(0)
	s_barrier
; DI int launder(int x) { asm volatile("" : "+v"(x)); return x; }
;   DI void pre(int grow0, int gcol0, int lane, int w, char* lds) { xpass(0, grow0, gcol0, lane, w, lds); }
;     ...
;   if (has_next) { const int tid3 = launder(threadIdx.x); stage_tile<BM, BK>(A + (size_t)row0n * lda, lda, lds, tid3); stage_tile<BN, BK>(Bt + (size_t)col0n * ldb, ldb, lds + ABYTES, tid3); }
; template <class Epi>
; DI void gemm_phase256(const bf16_t* A, int lda, const bf16_t* Bt, int K, int nN, char* lds, Epi& epi, int vb) {
;     ...
;   for (int t = vb; t < ntiles; t += gridDim.x) {
;     const int x = t & 7, L = t >> 3; const int pm = 8 * x + (L & 7), pn = L >> 3;
;     const int t2 = t + gridDim.x; const bool hn = t2 < ntiles;
;     const int x2 = t2 & 7, L2 = t2 >> 3; const int pm2 = 8 * x2 + (L2 & 7), pn2 = L2 >> 3;
;     gemm_tile<4, 64>(A, lda, Bt, K, K, pm * 256, pn * 256, lds, epi, pre, hn, pm2 * 256, pn2 * 256);
	s_cbranch_scc0 .LBB0_442
	v_mov_b32_e32 v132, v216
	s_lshl_b32 s3, s36, 3
	v_ashrrev_i32_e32 v0, 31, v132
	v_lshrrev_b32_e32 v130, 29, v0
	v_lshrrev_b32_e32 v0, 28, v0
	v_add_u32_e32 v0, v132, v0
	v_ashrrev_i32_e32 v0, 4, v0
	s_and_b32 s3, s3, 56
	s_bfe_u32 s7, s36, 0x30003
	v_lshrrev_b32_e32 v133, 29, v0
	s_or_b32 s3, s3, s7
	s_lshl_b32 s7, s36, 2
	v_add_u32_e32 v130, v132, v130
	v_add_u32_e32 v133, v0, v133
	s_and_b32 s30, s7, 0xffffff00
	s_lshl_b32 s3, s3, 19
	v_and_b32_e32 v131, 0xffffff8, v130
	v_and_b32_e32 v133, 0xffffff8, v133
	s_add_u32 s40, s12, s3
	v_sub_u32_e32 v131, v132, v131
	v_sub_u32_e32 v0, v0, v133
	v_lshlrev_b32_e32 v130, 8, v130
	v_readfirstlane_b32 s3, v132
	s_addc_u32 s41, s13, 0
	v_xor_b32_e32 v0, v0, v131
	v_and_b32_e32 v130, 0xfffff800, v130
	s_lshl_b32 s3, s3, 4
	v_lshl_add_u32 v0, v0, 4, v130
	s_and_b32 s3, s3, 0xfffffc00
	s_load_dwordx4 s[44:47], s[0:1], 0x1a0
	v_lshl_add_u64 v[130:131], s[40:41], 0, v[0:1]
	s_mov_b32 m0, s3
	v_lshl_add_u64 v[132:133], v[130:131], 0, s[58:59]
	global_load_lds_dwordx4 v0, s[40:41]
	s_add_i32 m0, s3, 0x2000
	s_ashr_i32 s31, s30, 31
	global_load_lds_dwordx4 v[132:133], off
	v_lshl_add_u64 v[132:133], v[130:131], 0, s[48:49]
	s_add_i32 m0, s3, 0x4000
	s_lshl_b64 s[30:31], s[30:31], 11
	global_load_lds_dwordx4 v[132:133], off
	s_add_i32 m0, s3, 0x6000
	s_waitcnt lgkmcnt(0)
	s_add_u32 s30, s46, s30
	v_lshl_add_u64 v[130:131], v[130:131], 0, s[50:51]
	s_addc_u32 s31, s47, s31
	global_load_lds_dwordx4 v[130:131], off
	v_lshl_add_u64 v[130:131], s[30:31], 0, v[0:1]
	s_add_i32 m0, s3, 0x8000
	v_lshl_add_u64 v[132:133], v[130:131], 0, s[58:59]
	global_load_lds_dwordx4 v0, s[30:31]
	s_add_i32 m0, s3, 0xa000
	s_nop 0
	global_load_lds_dwordx4 v[132:133], off
	v_lshl_add_u64 v[132:133], v[130:131], 0, s[48:49]
	s_add_i32 m0, s3, 0xc000
	v_lshl_add_u64 v[130:131], v[130:131], 0, s[50:51]
	global_load_lds_dwordx4 v[132:133], off
	s_add_i32 m0, s3, 0xe000
	s_nop 0
	global_load_lds_dwordx4 v[130:131], off

; DI f32x16 zero16() { f32x16 z; for (int i = 0; i < 16; ++i) z[i] = 0.f; return z; }
; DI int launder(int x) { asm volatile("" : "+v"(x)); return x; }
; template <int BK> DI int swz(int row) { constexpr int CPR = BK / 8; return (row / (16 / CPR)) % CPR; }
; DI void wait_vm0() { asm volatile("s_waitcnt vmcnt(0)" ::: "memory"); }
;   DI void pre(int grow0, int gcol0, int lane, int w, char* lds) { xpass(0, grow0, gcol0, lane, w, lds); }
;     ...
;   const int tid = launder(threadIdx.x), lane = tid & 63, w = tid >> 6, wm = w % WM, wn = w / WM;
;   const int l31 = lane & 31, hh = lane >> 5;
;   f32x16 acc[2][NTW];
; #pragma unroll
;   for (int a = 0; a < 2; ++a)
; #pragma unroll
;     for (int b = 0; b < NTW; ++b) acc[a][b] = zero16();
;   const bf16_t* Ag = A + (size_t)row0 * lda; const bf16_t* Bg = Bt + (size_t)col0 * ldb;
;   const int wv = __builtin_amdgcn_readfirstlane(tid >> 6);
;   __syncthreads();
;   if (!pre) { stage_tile<BM, BK>(Ag, lda, lds, tid); stage_tile<BN, BK>(Bg, ldb, lds + ABYTES, tid); }
;   wait_vm0();
;   __syncthreads();
;   const int nk = K / BK;
;   for (int kt = 0; kt < nk; ++kt) {
;     char* cur = lds + (kt & 1) * STG; char* nxt = lds + ((kt + 1) & 1) * STG;
;     const bool more = kt + 1 < nk;
;     const bf16_t* An = Ag + (kt + 1) * BK; const bf16_t* Bn = Bg + (kt + 1) * BK;
;     if (!more) epi.pre(row0 + wm * 64, col0 + wn * (32 * NTW), lane, w, lds);
;     bf16x8 fa[2][2], fb[2][NTW];
; #pragma unroll
;     for (int mt = 0; mt < 2; ++mt) { int row = wm * 64 + mt * 32 + l31; fa[0][mt] = *(const bf16x8*)(cur + row * (BK * 2) + ((hh ^ swz<BK>(row)) << 4)); }
; #pragma unroll
;     for (int nt = 0; nt < NTW; ++nt) { int row = wn * (32 * NTW) + nt * 32 + l31; fb[0][nt] = *(const bf16x8*)(cur + ABYTES + row * (BK * 2) + ((hh ^ swz<BK>(row)) << 4)); }
.LBB0_516:
	v_mov_b32_e32 v2, v216
	s_lshl_b32 s2, s36, 3
	v_ashrrev_i32_e32 v0, 31, v2
	v_lshrrev_b32_e32 v4, 29, v0
	v_lshrrev_b32_e32 v0, 28, v0
	v_add_u32_e32 v0, v2, v0
	v_ashrrev_i32_e32 v0, 4, v0
	s_waitcnt lgkmcnt(0)
	v_lshrrev_b32_e32 v6, 29, v0
	v_add_u32_e32 v4, v2, v4
	v_add_u32_e32 v6, v0, v6
	v_and_b32_e32 v5, 0xffffff8, v4
	v_and_b32_e32 v6, 0xffffff8, v6
	s_and_b32 s2, s2, 56
	s_bfe_u32 s3, s36, 0x30003
	v_sub_u32_e32 v5, v2, v5
	v_sub_u32_e32 v0, v0, v6
	v_lshlrev_b32_e32 v4, 8, v4
	s_or_b32 s2, s2, s3
	s_lshl_b32 s3, s36, 2
	v_ashrrev_i32_e32 v3, 6, v2
	v_xor_b32_e32 v0, v0, v5
	v_and_b32_e32 v4, 0xfffff800, v4
	s_and_b32 s6, s3, 0xffffff00
	v_readfirstlane_b32 s3, v3
	v_lshl_add_u32 v0, v0, 4, v4
	s_and_b64 vcc, exec, s[30:31]
	s_waitcnt vmcnt(0)
	s_barrier
	s_cbranch_vccnz .LBB0_518
	s_lshl_b32 s7, s2, 19
	s_add_u32 s30, s12, s7
	s_addc_u32 s31, s13, 0
	s_ashr_i32 s7, s6, 31
	s_lshl_b64 s[42:43], s[6:7], 11
	s_add_u32 s42, s40, s42
	v_readfirstlane_b32 s7, v2
	s_addc_u32 s43, s41, s43
	s_lshl_b32 s7, s7, 4
	s_and_b32 s7, s7, 0xfffffc00
	v_lshl_add_u64 v[4:5], s[30:31], 0, v[0:1]
	s_mov_b32 m0, s7
	v_lshl_add_u64 v[6:7], v[4:5], 0, s[58:59]
	global_load_lds_dwordx4 v[4:5], off
	s_add_i32 m0, s7, 0x2000
	s_nop 0
	global_load_lds_dwordx4 v[6:7], off
	v_lshl_add_u64 v[6:7], v[4:5], 0, s[48:49]
	s_add_i32 m0, s7, 0x4000
	v_lshl_add_u64 v[4:5], v[4:5], 0, s[50:51]
	global_load_lds_dwordx4 v[6:7], off
	s_add_i32 m0, s7, 0x6000
	s_nop 0
	global_load_lds_dwordx4 v[4:5], off
	v_lshl_add_u64 v[4:5], s[42:43], 0, v[0:1]
	s_add_i32 m0, s7, 0x8000
	v_lshl_add_u64 v[6:7], v[4:5], 0, s[58:59]
	global_load_lds_dwordx4 v[4:5], off
	s_add_i32 m0, s7, 0xa000
	s_nop 0
	global_load_lds_dwordx4 v[6:7], off
	v_lshl_add_u64 v[6:7], v[4:5], 0, s[48:49]
	s_add_i32 m0, s7, 0xc000
	v_lshl_add_u64 v[4:5], v[4:5], 0, s[50:51]
	global_load_lds_dwordx4 v[6:7], off
	s_add_i32 m0, s7, 0xe000
	s_nop 0
	global_load_lds_dwordx4 v[4:5], off
.LBB0_518:
	v_lshrrev_b32_e32 v4, 30, v3
	v_add_u32_e32 v4, v3, v4
	v_ashrrev_i32_e32 v4, 2, v4
	v_mul_i32_i24_e32 v5, 4, v4
	v_sub_u32_e32 v3, v3, v5
	v_and_b32_e32 v5, 31, v2
	v_lshlrev_b32_e32 v7, 6, v3
	v_or_b32_e32 v7, v7, v5
	v_bfe_u32 v3, v3, 25, 1
	v_lshlrev_b32_e32 v140, 7, v7
	v_add_u32_e32 v8, v7, v3
	v_or_b32_e32 v7, 32, v7
	v_add_u32_e32 v3, v7, v3
	v_lshlrev_b32_e32 v142, 7, v7
	v_ashrrev_i32_e32 v7, 1, v3
	v_ashrrev_i32_e32 v3, 31, v3
	v_ashrrev_i32_e32 v9, 1, v8
	v_ashrrev_i32_e32 v8, 31, v8
	v_lshrrev_b32_e32 v3, 29, v3
	v_lshrrev_b32_e32 v8, 29, v8
	v_add_u32_e32 v3, v7, v3
	v_add_u32_e32 v8, v9, v8
	v_and_b32_e32 v3, -8, v3
	v_lshrrev_b32_e32 v6, 5, v2
	v_and_b32_e32 v8, -8, v8
	v_sub_u32_e32 v3, v7, v3
	v_lshl_or_b32 v5, v4, 7, v5
	v_sub_u32_e32 v8, v9, v8
	v_bitop3_b32 v7, v3, v6, 1 bitop3:0x78
	v_lshrrev_b32_e32 v4, 31, v4
	v_bitop3_b32 v9, v8, v6, 1 bitop3:0x78
	v_lshlrev_b32_e32 v144, 4, v7
	v_add_u32_e32 v7, v5, v4
	v_lshlrev_b32_e32 v141, 4, v9
	v_ashrrev_i32_e32 v9, 1, v7
	v_ashrrev_i32_e32 v7, 31, v7
	v_lshrrev_b32_e32 v7, 29, v7
	v_add_u32_e32 v7, v9, v7
	v_and_b32_e32 v7, -8, v7
	v_sub_u32_e32 v7, v9, v7
	v_bitop3_b32 v9, v7, v6, 1 bitop3:0x78
	v_lshlrev_b32_e32 v151, 4, v9
	v_or_b32_e32 v9, 32, v5
	v_lshlrev_b32_e32 v152, 7, v9
	v_add_u32_e32 v9, v9, v4
	v_ashrrev_i32_e32 v10, 1, v9
	v_ashrrev_i32_e32 v9, 31, v9
	v_lshrrev_b32_e32 v9, 29, v9
	v_add_u32_e32 v9, v10, v9
	v_and_b32_e32 v9, -8, v9
	v_sub_u32_e32 v9, v10, v9
	v_bitop3_b32 v10, v9, v6, 1 bitop3:0x78
	v_lshlrev_b32_e32 v143, 7, v5
	v_lshlrev_b32_e32 v154, 4, v10
	v_or_b32_e32 v10, 64, v5
	v_or_b32_e32 v5, 0x60, v5
	v_lshlrev_b32_e32 v153, 7, v10
	v_add_u32_e32 v10, v10, v4
	v_add_u32_e32 v4, v5, v4
	v_lshlrev_b32_e32 v156, 7, v5
	v_ashrrev_i32_e32 v5, 1, v4
	v_ashrrev_i32_e32 v4, 31, v4
	v_lshrrev_b32_e32 v4, 29, v4
	v_add_u32_e32 v4, v5, v4
	v_and_b32_e32 v4, -8, v4
	v_sub_u32_e32 v4, v5, v4
	v_bfe_u32 v2, v2, 5, 1
	v_ashrrev_i32_e32 v11, 1, v10
	v_ashrrev_i32_e32 v10, 31, v10
	v_bitop3_b32 v5, v4, v6, 1 bitop3:0x78
	v_lshrrev_b32_e32 v10, 29, v10
	v_lshlrev_b32_e32 v164, 4, v5
	v_bitop3_b32 v5, v8, v2, 2 bitop3:0x1e
	v_add_u32_e32 v10, v11, v10
	v_lshlrev_b32_e32 v161, 4, v5
	v_bitop3_b32 v5, v3, v2, 2 bitop3:0x1e
	v_and_b32_e32 v10, -8, v10
	v_lshlrev_b32_e32 v163, 4, v5
	v_bitop3_b32 v5, v7, v2, 2 bitop3:0x1e
	v_sub_u32_e32 v10, v11, v10
	v_lshlrev_b32_e32 v159, 4, v5
	v_bitop3_b32 v5, v9, v2, 2 bitop3:0x1e
	s_lshr_b32 s7, s36, 3
	v_lshlrev_b32_e32 v160, 4, v5
	v_bitop3_b32 v5, v10, v2, 2 bitop3:0x1e
	s_and_b32 s7, s7, 7
	s_lshl_b32 s30, s35, 19
	v_lshlrev_b32_e32 v157, 4, v5
	v_bitop3_b32 v5, v4, v2, 2 bitop3:0x1e
	s_lshl_b32 s7, s7, 19
	s_and_b32 s30, s30, 0x1c00000
	v_lshlrev_b32_e32 v158, 4, v5
	v_bitop3_b32 v5, v8, v2, 4 bitop3:0x1e
	s_or_b32 s7, s30, s7
	s_and_b32 s30, s34, 0xffffff00
	v_lshlrev_b32_e32 v149, 4, v5
	v_bitop3_b32 v5, v3, v2, 4 bitop3:0x1e
	s_ashr_i32 s31, s30, 31
	v_lshlrev_b32_e32 v150, 4, v5
	v_bitop3_b32 v5, v7, v2, 4 bitop3:0x1e
	s_lshl_b64 s[30:31], s[30:31], 11
	s_lshl_b32 s3, s3, 10
	v_lshlrev_b32_e32 v147, 4, v5
	v_bitop3_b32 v5, v9, v2, 4 bitop3:0x1e
	v_bitop3_b32 v3, v3, v2, 6 bitop3:0x1e
	v_lshlrev_b32_e32 v148, 4, v5
	v_bitop3_b32 v5, v10, v2, 4 bitop3:0x1e
	v_lshlrev_b32_e32 v139, 4, v3
	v_bitop3_b32 v3, v7, v2, 6 bitop3:0x1e
	s_add_u32 s42, s12, s7
	v_lshlrev_b32_e32 v145, 4, v5
	v_bitop3_b32 v5, v4, v2, 4 bitop3:0x1e
	v_lshlrev_b32_e32 v136, 4, v3
	v_bitop3_b32 v3, v9, v2, 6 bitop3:0x1e
	s_addc_u32 s43, s13, 0
	s_waitcnt vmcnt(0)
;     ...
;   f32x16 acc[2][NTW];
; #pragma unroll
;   for (int a = 0; a < 2; ++a)
; #pragma unroll
;     for (int b = 0; b < NTW; ++b) acc[a][b] = zero16();
;   const bf16_t* Ag = A + (size_t)row0 * lda; const bf16_t* Bg = Bt + (size_t)col0 * ldb;
;   const int wv = __builtin_amdgcn_readfirstlane(tid >> 6);
;   __syncthreads();
;   if (!pre) { stage_tile<BM, BK>(Ag, lda, lds, tid); stage_tile<BN, BK>(Bg, ldb, lds + ABYTES, tid); }
;   wait_vm0();
;   __syncthreads();
;   const int nk = K / BK;
;   for (int kt = 0; kt < nk; ++kt) {
;     char* cur = lds + (kt & 1) * STG; char* nxt = lds + ((kt + 1) & 1) * STG;
;     const bool more = kt + 1 < nk;
;     const bf16_t* An = Ag + (kt + 1) * BK; const bf16_t* Bn = Bg + (kt + 1) * BK;
;     if (!more) epi.pre(row0 + wm * 64, col0 + wn * (32 * NTW), lane, w, lds);
;     bf16x8 fa[2][2], fb[2][NTW];
; #pragma unroll
;     for (int mt = 0; mt < 2; ++mt) { int row = wm * 64 + mt * 32 + l31; fa[0][mt] = *(const bf16x8*)(cur + row * (BK * 2) + ((hh ^ swz<BK>(row)) << 4)); }
; #pragma unroll
;     for (int nt = 0; nt < NTW; ++nt) { int row = wn * (32 * NTW) + nt * 32 + l31; fb[0][nt] = *(const bf16x8*)(cur + ABYTES + row * (BK * 2) + ((hh ^ swz<BK>(row)) << 4)); }
; #pragma unroll
;     for (int kk = 0; kk < NKK; ++kk) {
;       if (kk + 1 < NKK) {
;         const int ch = (kk + 1) * 2 + hh;
; #pragma unroll
;         for (int mt = 0; mt < 2; ++mt) { int row = wm * 64 + mt * 32 + l31; fa[(kk + 1) & 1][mt] = *(const bf16x8*)(cur + row * (BK * 2) + ((ch ^ swz<BK>(row)) << 4)); }
; #pragma unroll
;         for (int nt = 0; nt < NTW; ++nt) { int row = wn * (32 * NTW) + nt * 32 + l31; fb[(kk + 1) & 1][nt] = *(const bf16x8*)(cur + ABYTES + row * (BK * 2) + ((ch ^ swz<BK>(row)) << 4)); }
;       }
;       if (more) {
; #pragma unroll
;         for (int q = 0; q < PPK; ++q) {
;           const int pi = kk * PPK + q;
;           if (pi < NPA) stage_piece<BM, BK>(An, lda, nxt, tid, pi, wv);
;           else if (pi < NP) stage_piece<BN, BK>(Bn, ldb, nxt + ABYTES, tid, pi - NPA, wv);
;         }
;       }
;       __builtin_amdgcn_s_setprio(1);
; #pragma unroll
;       for (int mt = 0; mt < 2; ++mt)
; #pragma unroll
;         for (int nt = 0; nt < NTW; ++nt) acc[mt][nt] = mfma(fa[kk & 1][mt], fb[kk & 1][nt], acc[mt][nt]);
;       __builtin_amdgcn_s_setprio(0);
;       __builtin_amdgcn_sched_barrier(0);
;     }
	v_lshlrev_b32_e32 v146, 4, v5
	v_bitop3_b32 v5, v8, v2, 6 bitop3:0x1e
	v_lshlrev_b32_e32 v137, 4, v3
	v_bitop3_b32 v3, v10, v2, 6 bitop3:0x1e
	v_bitop3_b32 v2, v4, v2, 6 bitop3:0x1e
	s_add_u32 s30, s40, s30
	v_bitop3_b32 v11, v10, v6, 1 bitop3:0x78
	v_lshlrev_b32_e32 v135, 4, v2
	s_addc_u32 s31, s41, s31
	v_mov_b32_e32 v2, 0
	v_lshlrev_b32_e32 v155, 4, v11
	v_lshlrev_b32_e32 v138, 4, v5
	v_lshlrev_b32_e32 v134, 4, v3
	v_lshl_add_u64 v[130:131], s[42:43], 0, v[0:1]
	v_lshl_add_u64 v[132:133], s[30:31], 0, v[0:1]
	s_mov_b64 s[30:31], 0
	s_mov_b32 s7, 0x10000
	v_mov_b32_e32 v3, v2
	v_mov_b32_e32 v4, v2
	v_mov_b32_e32 v5, v2
	v_mov_b32_e32 v6, v2
	v_mov_b32_e32 v7, v2
	v_mov_b32_e32 v8, v2
	v_mov_b32_e32 v9, v2
	v_mov_b32_e32 v10, v2
	v_mov_b32_e32 v11, v2
	v_mov_b32_e32 v12, v2
	v_mov_b32_e32 v13, v2
	v_mov_b32_e32 v14, v2
	v_mov_b32_e32 v15, v2
	v_mov_b32_e32 v16, v2
	v_mov_b32_e32 v17, v2
	v_mov_b32_e32 v18, v2
	v_mov_b32_e32 v19, v2
	v_mov_b32_e32 v20, v2
	v_mov_b32_e32 v21, v2
	v_mov_b32_e32 v22, v2
	v_mov_b32_e32 v23, v2
	v_mov_b32_e32 v24, v2
	v_mov_b32_e32 v25, v2
	v_mov_b32_e32 v26, v2
	v_mov_b32_e32 v27, v2
	v_mov_b32_e32 v28, v2
	v_mov_b32_e32 v29, v2
	v_mov_b32_e32 v30, v2
	v_mov_b32_e32 v31, v2
	v_mov_b32_e32 v32, v2
	v_mov_b32_e32 v33, v2
	v_mov_b32_e32 v34, v2
	v_mov_b32_e32 v35, v2
	v_mov_b32_e32 v36, v2
	v_mov_b32_e32 v37, v2
	v_mov_b32_e32 v38, v2
	v_mov_b32_e32 v39, v2
	v_mov_b32_e32 v40, v2
	v_mov_b32_e32 v41, v2
	v_mov_b32_e32 v42, v2
	v_mov_b32_e32 v43, v2
	v_mov_b32_e32 v44, v2
	v_mov_b32_e32 v45, v2
	v_mov_b32_e32 v46, v2
	v_mov_b32_e32 v47, v2
	v_mov_b32_e32 v48, v2
	v_mov_b32_e32 v49, v2
	v_mov_b32_e32 v50, v2
	v_mov_b32_e32 v51, v2
	v_mov_b32_e32 v52, v2
	v_mov_b32_e32 v53, v2
	v_mov_b32_e32 v54, v2
	v_mov_b32_e32 v55, v2
	v_mov_b32_e32 v56, v2
	v_mov_b32_e32 v57, v2
	v_mov_b32_e32 v58, v2
	v_mov_b32_e32 v59, v2
	v_mov_b32_e32 v60, v2
	v_mov_b32_e32 v61, v2
	v_mov_b32_e32 v62, v2
	v_mov_b32_e32 v63, v2
	v_mov_b32_e32 v64, v2
	v_mov_b32_e32 v65, v2
	v_mov_b32_e32 v66, v2
	v_mov_b32_e32 v67, v2
	v_mov_b32_e32 v68, v2
	v_mov_b32_e32 v69, v2
	v_mov_b32_e32 v70, v2
	v_mov_b32_e32 v71, v2
	v_mov_b32_e32 v72, v2
	v_mov_b32_e32 v73, v2
	v_mov_b32_e32 v74, v2
	v_mov_b32_e32 v75, v2
	v_mov_b32_e32 v76, v2
	v_mov_b32_e32 v77, v2
	v_mov_b32_e32 v78, v2
	v_mov_b32_e32 v79, v2
	v_mov_b32_e32 v80, v2
	v_mov_b32_e32 v81, v2
	v_mov_b32_e32 v82, v2
	v_mov_b32_e32 v83, v2
	v_mov_b32_e32 v84, v2
	v_mov_b32_e32 v85, v2
	v_mov_b32_e32 v86, v2
	v_mov_b32_e32 v87, v2
	v_mov_b32_e32 v88, v2
	v_mov_b32_e32 v89, v2
	v_mov_b32_e32 v90, v2
	v_mov_b32_e32 v91, v2
	v_mov_b32_e32 v92, v2
	v_mov_b32_e32 v93, v2
	v_mov_b32_e32 v94, v2
	v_mov_b32_e32 v95, v2
	v_mov_b32_e32 v96, v2
	v_mov_b32_e32 v97, v2
	v_mov_b32_e32 v98, v2
	v_mov_b32_e32 v99, v2
	v_mov_b32_e32 v100, v2
	v_mov_b32_e32 v101, v2
	v_mov_b32_e32 v102, v2
	v_mov_b32_e32 v103, v2
	v_mov_b32_e32 v104, v2
	v_mov_b32_e32 v105, v2
	v_mov_b32_e32 v106, v2
	v_mov_b32_e32 v107, v2
	v_mov_b32_e32 v108, v2
	v_mov_b32_e32 v109, v2
	v_mov_b32_e32 v110, v2
	v_mov_b32_e32 v111, v2
	v_mov_b32_e32 v112, v2
	v_mov_b32_e32 v113, v2
	v_mov_b32_e32 v114, v2
	v_mov_b32_e32 v115, v2
	v_mov_b32_e32 v116, v2
	v_mov_b32_e32 v117, v2
	v_mov_b32_e32 v118, v2
	v_mov_b32_e32 v119, v2
	v_mov_b32_e32 v120, v2
	v_mov_b32_e32 v121, v2
	v_mov_b32_e32 v122, v2
	v_mov_b32_e32 v123, v2
	v_mov_b32_e32 v124, v2
	v_mov_b32_e32 v125, v2
	v_mov_b32_e32 v126, v2
	v_mov_b32_e32 v127, v2
	v_mov_b32_e32 v128, v2
	v_mov_b32_e32 v129, v2
	s_waitcnt vmcnt(0) lgkmcnt(0)
	s_barrier
	v_add_u32_e32 v166, v140, v141
	v_add_u32_e32 v170, v142, v144
	ds_read_b128 v[166:169], v166
	v_add_u32_e32 v174, v143, v151
	ds_read_b128 v[170:173], v170
	v_add_u32_e32 v178, v152, v154
	ds_read_b128 v[174:177], v174 offset:32768
	v_add_u32_e32 v182, v153, v155
	ds_read_b128 v[178:181], v178 offset:32768
	v_add_u32_e32 v186, v156, v164
	ds_read_b128 v[182:185], v182 offset:32768
	ds_read_b128 v[186:189], v186 offset:32768
.LBB0_519:
	s_and_b32 s42, s7, 0x10000
	s_xor_b32 s100, s42, 0x10000
	s_add_i32 s37, s42, s3
	v_add3_u32 v190, s100, v140, v161
	v_add3_u32 v194, s100, v142, v163
	ds_read_b128 v[190:193], v190
	v_add3_u32 v198, s100, v143, v159
	ds_read_b128 v[194:197], v194
	v_add3_u32 v202, s100, v152, v160
	ds_read_b128 v[198:201], v198 offset:32768
	v_add3_u32 v206, s100, v153, v157
	ds_read_b128 v[202:205], v202 offset:32768
	v_add3_u32 v210, s100, v156, v158
	ds_read_b128 v[206:209], v206 offset:32768
	ds_read_b128 v[210:213], v210 offset:32768
	v_lshl_add_u64 v[214:215], v[130:131], 0, s[30:31]
	v_lshl_add_u64 v[226:227], v[132:133], 0, s[30:31]
	s_mov_b32 m0, s37
	v_lshl_add_u64 v[228:229], v[214:215], 0, s[28:29]
	s_setprio 1
	s_waitcnt lgkmcnt(6)
; DI f32x16 mfma(bf16x8 a, bf16x8 b, f32x16 c) { return __builtin_amdgcn_mfma_f32_32x32x16_bf16(a, b, c, 0, 0, 0); }
; template <int BK> DI int swz(int row) { constexpr int CPR = BK / 8; return (row / (16 / CPR)) % CPR; }
;   DI void pre(int grow0, int gcol0, int lane, int w, char* lds) { xpass(0, grow0, gcol0, lane, w, lds); }
;     ...
;   for (int kt = 0; kt < nk; ++kt) {
;     char* cur = lds + (kt & 1) * STG; char* nxt = lds + ((kt + 1) & 1) * STG;
;     const bool more = kt + 1 < nk;
;     const bf16_t* An = Ag + (kt + 1) * BK; const bf16_t* Bn = Bg + (kt + 1) * BK;
;     if (!more) epi.pre(row0 + wm * 64, col0 + wn * (32 * NTW), lane, w, lds);
;     bf16x8 fa[2][2], fb[2][NTW];
; #pragma unroll
;     for (int mt = 0; mt < 2; ++mt) { int row = wm * 64 + mt * 32 + l31; fa[0][mt] = *(const bf16x8*)(cur + row * (BK * 2) + ((hh ^ swz<BK>(row)) << 4)); }
; #pragma unroll
;     for (int nt = 0; nt < NTW; ++nt) { int row = wn * (32 * NTW) + nt * 32 + l31; fb[0][nt] = *(const bf16x8*)(cur + ABYTES + row * (BK * 2) + ((hh ^ swz<BK>(row)) << 4)); }
; #pragma unroll
;     for (int kk = 0; kk < NKK; ++kk) {
;       if (kk + 1 < NKK) {
;         const int ch = (kk + 1) * 2 + hh;
; #pragma unroll
;         for (int mt = 0; mt < 2; ++mt) { int row = wm * 64 + mt * 32 + l31; fa[(kk + 1) & 1][mt] = *(const bf16x8*)(cur + row * (BK * 2) + ((ch ^ swz<BK>(row)) << 4)); }
; #pragma unroll
;         for (int nt = 0; nt < NTW; ++nt) { int row = wn * (32 * NTW) + nt * 32 + l31; fb[(kk + 1) & 1][nt] = *(const bf16x8*)(cur + ABYTES + row * (BK * 2) + ((ch ^ swz<BK>(row)) << 4)); }
;       }
;       if (more) {
; #pragma unroll
;         for (int q = 0; q < PPK; ++q) {
;           const int pi = kk * PPK + q;
;           if (pi < NPA) stage_piece<BM, BK>(An, lda, nxt, tid, pi, wv);
;           else if (pi < NP) stage_piece<BN, BK>(Bn, ldb, nxt + ABYTES, tid, pi - NPA, wv);
;         }
;       }
;       __builtin_amdgcn_s_setprio(1);
; #pragma unroll
;       for (int mt = 0; mt < 2; ++mt)
; #pragma unroll
;         for (int nt = 0; nt < NTW; ++nt) acc[mt][nt] = mfma(fa[kk & 1][mt], fb[kk & 1][nt], acc[mt][nt]);
;       __builtin_amdgcn_s_setprio(0);
;       __builtin_amdgcn_sched_barrier(0);
;     }
	v_mfma_f32_32x32x16_bf16 v[114:129], v[166:169], v[174:177], v[114:129]
	global_load_lds_dwordx4 v[228:229], off
	v_lshl_add_u64 v[228:229], v[214:215], 0, s[24:25]
	s_add_i32 m0, s37, 0x2000
	v_mfma_f32_32x32x16_bf16 v[98:113], v[166:169], v[178:181], v[98:113]
	global_load_lds_dwordx4 v[228:229], off
	v_lshl_add_u64 v[228:229], v[214:215], 0, s[26:27]
	s_add_i32 m0, s37, 0x4000
	v_mfma_f32_32x32x16_bf16 v[82:97], v[166:169], v[182:185], v[82:97]
	global_load_lds_dwordx4 v[228:229], off
	v_lshl_add_u64 v[228:229], v[214:215], 0, s[38:39]
	s_add_i32 m0, s37, 0x6000
	v_mfma_f32_32x32x16_bf16 v[66:81], v[166:169], v[186:189], v[66:81]
	global_load_lds_dwordx4 v[228:229], off
	v_lshl_add_u64 v[228:229], v[226:227], 0, s[28:29]
	s_add_i32 m0, s37, 0x8000
	v_mfma_f32_32x32x16_bf16 v[50:65], v[170:173], v[174:177], v[50:65]
	global_load_lds_dwordx4 v[228:229], off
	v_lshl_add_u64 v[228:229], v[226:227], 0, s[24:25]
	s_add_i32 m0, s37, 0xa000
	v_mfma_f32_32x32x16_bf16 v[34:49], v[170:173], v[178:181], v[34:49]
	global_load_lds_dwordx4 v[228:229], off
	v_lshl_add_u64 v[228:229], v[226:227], 0, s[26:27]
	s_add_i32 m0, s37, 0xc000
	v_mfma_f32_32x32x16_bf16 v[18:33], v[170:173], v[182:185], v[18:33]
	global_load_lds_dwordx4 v[228:229], off
	v_lshl_add_u64 v[228:229], v[226:227], 0, s[38:39]
	s_add_i32 m0, s37, 0xe000
	v_mfma_f32_32x32x16_bf16 v[2:17], v[170:173], v[186:189], v[2:17]
	global_load_lds_dwordx4 v[228:229], off
	s_setprio 0
	v_add3_u32 v166, s100, v140, v149
	v_add3_u32 v170, s100, v142, v150
	ds_read_b128 v[166:169], v166
	v_add3_u32 v174, s100, v143, v147
	ds_read_b128 v[170:173], v170
	v_add3_u32 v178, s100, v152, v148
	ds_read_b128 v[174:177], v174 offset:32768
	v_add3_u32 v182, s100, v153, v145
	ds_read_b128 v[178:181], v178 offset:32768
	v_add3_u32 v186, s100, v156, v146
	ds_read_b128 v[182:185], v182 offset:32768
	ds_read_b128 v[186:189], v186 offset:32768
	s_setprio 1
	s_waitcnt lgkmcnt(6)
	v_mfma_f32_32x32x16_bf16 v[114:129], v[190:193], v[198:201], v[114:129]
	v_mfma_f32_32x32x16_bf16 v[98:113], v[190:193], v[202:205], v[98:113]
	v_mfma_f32_32x32x16_bf16 v[82:97], v[190:193], v[206:209], v[82:97]
	v_mfma_f32_32x32x16_bf16 v[66:81], v[190:193], v[210:213], v[66:81]
	v_mfma_f32_32x32x16_bf16 v[50:65], v[194:197], v[198:201], v[50:65]
	v_mfma_f32_32x32x16_bf16 v[34:49], v[194:197], v[202:205], v[34:49]
	v_mfma_f32_32x32x16_bf16 v[18:33], v[194:197], v[206:209], v[18:33]
	v_mfma_f32_32x32x16_bf16 v[2:17], v[194:197], v[210:213], v[2:17]
	s_setprio 0
	v_add3_u32 v190, s100, v140, v138
	v_add3_u32 v194, s100, v142, v139
	ds_read_b128 v[190:193], v190
	v_add3_u32 v198, s100, v143, v136
	ds_read_b128 v[194:197], v194
	v_add3_u32 v202, s100, v152, v137
	ds_read_b128 v[198:201], v198 offset:32768
	v_add3_u32 v206, s100, v153, v134
	ds_read_b128 v[202:205], v202 offset:32768
	v_add3_u32 v210, s100, v156, v135
	ds_read_b128 v[206:209], v206 offset:32768
	ds_read_b128 v[210:213], v210 offset:32768
	s_setprio 1
	s_waitcnt lgkmcnt(6)
	v_mfma_f32_32x32x16_bf16 v[114:129], v[166:169], v[174:177], v[114:129]
	v_mfma_f32_32x32x16_bf16 v[98:113], v[166:169], v[178:181], v[98:113]
	v_mfma_f32_32x32x16_bf16 v[82:97], v[166:169], v[182:185], v[82:97]
	v_mfma_f32_32x32x16_bf16 v[66:81], v[166:169], v[186:189], v[66:81]
	v_mfma_f32_32x32x16_bf16 v[50:65], v[170:173], v[174:177], v[50:65]
	v_mfma_f32_32x32x16_bf16 v[34:49], v[170:173], v[178:181], v[34:49]
	v_mfma_f32_32x32x16_bf16 v[18:33], v[170:173], v[182:185], v[18:33]
	v_mfma_f32_32x32x16_bf16 v[2:17], v[170:173], v[186:189], v[2:17]
	s_setprio 0
	s_add_u32 s30, s30, 0x80
	s_addc_u32 s31, s31, 0
	s_add_i32 s7, s7, 0x10000
	s_waitcnt vmcnt(0) lgkmcnt(0)
	s_barrier
	v_add3_u32 v166, s42, v140, v141
	v_add3_u32 v170, s42, v142, v144
	ds_read_b128 v[166:169], v166
	v_add3_u32 v174, s42, v143, v151
	ds_read_b128 v[170:173], v170
	v_add3_u32 v178, s42, v152, v154
	ds_read_b128 v[174:177], v174 offset:32768
	v_add3_u32 v182, s42, v153, v155
	ds_read_b128 v[178:181], v178 offset:32768
	v_add3_u32 v186, s42, v156, v164
	ds_read_b128 v[182:185], v182 offset:32768
	ds_read_b128 v[186:189], v186 offset:32768
	s_setprio 1
	v_mfma_f32_32x32x16_bf16 v[114:129], v[190:193], v[198:201], v[114:129]
	v_mfma_f32_32x32x16_bf16 v[98:113], v[190:193], v[202:205], v[98:113]
	v_mfma_f32_32x32x16_bf16 v[82:97], v[190:193], v[206:209], v[82:97]
	v_mfma_f32_32x32x16_bf16 v[66:81], v[190:193], v[210:213], v[66:81]
	v_mfma_f32_32x32x16_bf16 v[50:65], v[194:197], v[198:201], v[50:65]
	v_mfma_f32_32x32x16_bf16 v[34:49], v[194:197], v[202:205], v[34:49]
	v_mfma_f32_32x32x16_bf16 v[18:33], v[194:197], v[206:209], v[18:33]
	v_mfma_f32_32x32x16_bf16 v[2:17], v[194:197], v[210:213], v[2:17]
	s_setprio 0
	s_cmpk_eq_i32 s30, 0x780
	s_cbranch_scc0 .LBB0_519
; DI f32x16 mfma(bf16x8 a, bf16x8 b, f32x16 c) { return __builtin_amdgcn_mfma_f32_32x32x16_bf16(a, b, c, 0, 0, 0); }
; DI int launder(int x) { asm volatile("" : "+v"(x)); return x; }
; DI void wait_vm0() { asm volatile("s_waitcnt vmcnt(0)" ::: "memory"); }
;     ...
;   for (int kt = 0; kt < nk; ++kt) {
;     char* cur = lds + (kt & 1) * STG; char* nxt = lds + ((kt + 1) & 1) * STG;
;     const bool more = kt + 1 < nk;
;     const bf16_t* An = Ag + (kt + 1) * BK; const bf16_t* Bn = Bg + (kt + 1) * BK;
;     if (!more) epi.pre(row0 + wm * 64, col0 + wn * (32 * NTW), lane, w, lds);
;     bf16x8 fa[2][2], fb[2][NTW];
; #pragma unroll
;     for (int mt = 0; mt < 2; ++mt) { int row = wm * 64 + mt * 32 + l31; fa[0][mt] = *(const bf16x8*)(cur + row * (BK * 2) + ((hh ^ swz<BK>(row)) << 4)); }
; #pragma unroll
;     for (int nt = 0; nt < NTW; ++nt) { int row = wn * (32 * NTW) + nt * 32 + l31; fb[0][nt] = *(const bf16x8*)(cur + ABYTES + row * (BK * 2) + ((hh ^ swz<BK>(row)) << 4)); }
; #pragma unroll
;     for (int kk = 0; kk < NKK; ++kk) {
;       if (kk + 1 < NKK) {
;         const int ch = (kk + 1) * 2 + hh;
; #pragma unroll
;         for (int mt = 0; mt < 2; ++mt) { int row = wm * 64 + mt * 32 + l31; fa[(kk + 1) & 1][mt] = *(const bf16x8*)(cur + row * (BK * 2) + ((ch ^ swz<BK>(row)) << 4)); }
; #pragma unroll
;         for (int nt = 0; nt < NTW; ++nt) { int row = wn * (32 * NTW) + nt * 32 + l31; fb[(kk + 1) & 1][nt] = *(const bf16x8*)(cur + ABYTES + row * (BK * 2) + ((ch ^ swz<BK>(row)) << 4)); }
;       }
;       if (more) {
; #pragma unroll
;         for (int q = 0; q < PPK; ++q) {
;           const int pi = kk * PPK + q;
;           if (pi < NPA) stage_piece<BM, BK>(An, lda, nxt, tid, pi, wv);
;           else if (pi < NP) stage_piece<BN, BK>(Bn, ldb, nxt + ABYTES, tid, pi - NPA, wv);
;         }
;       }
;       __builtin_amdgcn_s_setprio(1);
; #pragma unroll
;       for (int mt = 0; mt < 2; ++mt)
; #pragma unroll
;         for (int nt = 0; nt < NTW; ++nt) acc[mt][nt] = mfma(fa[kk & 1][mt], fb[kk & 1][nt], acc[mt][nt]);
;       __builtin_amdgcn_s_setprio(0);
;       __builtin_amdgcn_sched_barrier(0);
;     }
;     wait_vm0();
;     __syncthreads();
;   }
;   if (has_next) { const int tid3 = launder(threadIdx.x); stage_tile<BM, BK>(A + (size_t)row0n * lda, lda, lds, tid3); stage_tile<BN, BK>(Bt + (size_t)col0n * ldb, ldb, lds + ABYTES, tid3); }
	s_waitcnt lgkmcnt(0)
	v_add_u32_e32 v0, 0x10000, v140
	v_add_u32_e32 v198, 0x10000, v142
	v_add_u32_e32 v130, v0, v141
	v_add_u32_e32 v140, v198, v144
	v_add_u32_e32 v199, 0x18000, v143
	v_add_u32_e32 v200, 0x18000, v152
	ds_read_b128 v[130:133], v130
	ds_read_b128 v[166:169], v140
	v_add_u32_e32 v140, v199, v151
	v_add_u32_e32 v144, v200, v154
	v_add_u32_e32 v201, 0x18000, v153
	ds_read_b128 v[140:143], v140
	ds_read_b128 v[170:173], v144
	v_add_u32_e32 v144, v201, v155
	v_add_u32_e32 v202, 0x18000, v156
	v_add_u32_e32 v151, v202, v164
	ds_read_b128 v[152:155], v144
	ds_read_b128 v[174:177], v151
	v_add_u32_e32 v144, v0, v161
	v_add_u32_e32 v151, v198, v163
	ds_read_b128 v[178:181], v144
	ds_read_b128 v[182:185], v151
	v_add_u32_e32 v144, v199, v159
	v_add_u32_e32 v151, v200, v160
	ds_read_b128 v[186:189], v144
	ds_read_b128 v[190:193], v151
	v_add_u32_e32 v144, v201, v157
	v_add_u32_e32 v151, v202, v158
	ds_read_b128 v[156:159], v144
	ds_read_b128 v[194:197], v151
	s_add_i32 s36, s36, s94
	s_cmpk_gt_i32 s36, 0x2ff
	s_cselect_b64 s[42:43], -1, 0
	s_cmpk_lt_i32 s36, 0x300
	s_setprio 1
	s_waitcnt lgkmcnt(9)
	v_mfma_f32_32x32x16_bf16 v[114:129], v[130:133], v[140:143], v[114:129]
	s_waitcnt lgkmcnt(8)
	v_mfma_f32_32x32x16_bf16 v[98:113], v[130:133], v[170:173], v[98:113]
	s_waitcnt lgkmcnt(7)
	v_mfma_f32_32x32x16_bf16 v[82:97], v[130:133], v[152:155], v[82:97]
	s_waitcnt lgkmcnt(6)
	v_mfma_f32_32x32x16_bf16 v[66:81], v[130:133], v[174:177], v[66:81]
	v_mfma_f32_32x32x16_bf16 v[50:65], v[166:169], v[140:143], v[50:65]
	v_mfma_f32_32x32x16_bf16 v[34:49], v[166:169], v[170:173], v[34:49]
	v_mfma_f32_32x32x16_bf16 v[18:33], v[166:169], v[152:155], v[18:33]
	v_mfma_f32_32x32x16_bf16 v[2:17], v[166:169], v[174:177], v[2:17]
	s_setprio 0
	v_add_u32_e32 v130, v0, v149
	v_add_u32_e32 v140, v198, v150
	v_add_u32_e32 v144, v199, v147
	ds_read_b128 v[130:133], v130
	ds_read_b128 v[140:143], v140
	v_add_u32_e32 v147, v200, v148
	ds_read_b128 v[148:151], v144
	ds_read_b128 v[152:155], v147
	v_add_u32_e32 v144, v201, v145
	v_add_u32_e32 v160, v202, v146
	ds_read_b128 v[144:147], v144
	ds_read_b128 v[166:169], v160
	s_setprio 1
	s_waitcnt lgkmcnt(9)
	v_mfma_f32_32x32x16_bf16 v[114:129], v[178:181], v[186:189], v[114:129]
	s_waitcnt lgkmcnt(8)
	v_mfma_f32_32x32x16_bf16 v[98:113], v[178:181], v[190:193], v[98:113]
	s_waitcnt lgkmcnt(7)
	v_mfma_f32_32x32x16_bf16 v[82:97], v[178:181], v[156:159], v[82:97]
	s_waitcnt lgkmcnt(6)
	v_mfma_f32_32x32x16_bf16 v[66:81], v[178:181], v[194:197], v[66:81]
	v_mfma_f32_32x32x16_bf16 v[50:65], v[182:185], v[186:189], v[50:65]
	v_mfma_f32_32x32x16_bf16 v[34:49], v[182:185], v[190:193], v[34:49]
	v_mfma_f32_32x32x16_bf16 v[18:33], v[182:185], v[156:159], v[18:33]
	v_mfma_f32_32x32x16_bf16 v[2:17], v[182:185], v[194:197], v[2:17]
	s_setprio 0
	v_add_u32_e32 v0, v0, v138
	v_add_u32_e32 v138, v198, v139
	ds_read_b128 v[156:159], v0
	ds_read_b128 v[170:173], v138
	v_add_u32_e32 v0, v199, v136
	v_add_u32_e32 v160, v200, v137
	ds_read_b128 v[136:139], v0
	ds_read_b128 v[174:177], v160
	v_add_u32_e32 v0, v201, v134
	v_add_u32_e32 v134, v202, v135
	ds_read_b128 v[178:181], v0
	ds_read_b128 v[182:185], v134
	s_setprio 1
	s_waitcnt lgkmcnt(9)
	v_mfma_f32_32x32x16_bf16 v[114:129], v[130:133], v[148:151], v[114:129]
	s_waitcnt lgkmcnt(8)
	v_mfma_f32_32x32x16_bf16 v[98:113], v[130:133], v[152:155], v[98:113]
	s_waitcnt lgkmcnt(7)
	v_mfma_f32_32x32x16_bf16 v[82:97], v[130:133], v[144:147], v[82:97]
	s_waitcnt lgkmcnt(6)
	v_mfma_f32_32x32x16_bf16 v[66:81], v[130:133], v[166:169], v[66:81]
	v_mfma_f32_32x32x16_bf16 v[50:65], v[140:143], v[148:151], v[50:65]
	v_mfma_f32_32x32x16_bf16 v[34:49], v[140:143], v[152:155], v[34:49]
	v_mfma_f32_32x32x16_bf16 v[18:33], v[140:143], v[144:147], v[18:33]
	v_mfma_f32_32x32x16_bf16 v[2:17], v[140:143], v[166:169], v[2:17]
	s_setprio 0
	s_setprio 1
	s_waitcnt lgkmcnt(3)
	v_mfma_f32_32x32x16_bf16 v[114:129], v[156:159], v[136:139], v[114:129]
	s_waitcnt lgkmcnt(2)
	v_mfma_f32_32x32x16_bf16 v[98:113], v[156:159], v[174:177], v[98:113]
	s_waitcnt lgkmcnt(1)
	v_mfma_f32_32x32x16_bf16 v[82:97], v[156:159], v[178:181], v[82:97]
	s_waitcnt lgkmcnt(0)
	v_mfma_f32_32x32x16_bf16 v[66:81], v[156:159], v[182:185], v[66:81]
	v_mfma_f32_32x32x16_bf16 v[50:65], v[170:173], v[136:139], v[50:65]
	v_mfma_f32_32x32x16_bf16 v[34:49], v[170:173], v[174:177], v[34:49]
	v_mfma_f32_32x32x16_bf16 v[18:33], v[170:173], v[178:181], v[18:33]
	v_mfma_f32_32x32x16_bf16 v[2:17], v[170:173], v[182:185], v[2:17]
	s_setprio 0
	s_waitcnt vmcnt(0)
	s_barrier
	s_cbranch_scc0 .LBB0_522
	v_mov_b32_e32 v132, v216
	s_lshl_b32 s3, s36, 3
	v_ashrrev_i32_e32 v0, 31, v132
	v_lshrrev_b32_e32 v130, 29, v0
	v_lshrrev_b32_e32 v0, 28, v0
	v_add_u32_e32 v0, v132, v0
	v_ashrrev_i32_e32 v0, 4, v0
	s_and_b32 s3, s3, 56
	s_bfe_u32 s7, s36, 0x30003
	v_lshrrev_b32_e32 v133, 29, v0
	s_or_b32 s3, s3, s7
	s_lshl_b32 s7, s36, 2
	v_add_u32_e32 v130, v132, v130
	v_add_u32_e32 v133, v0, v133
	s_and_b32 s30, s7, 0xffffff00
	s_lshl_b32 s3, s3, 19
	v_and_b32_e32 v131, 0xffffff8, v130
	v_and_b32_e32 v133, 0xffffff8, v133
	s_add_u32 s44, s12, s3
	v_sub_u32_e32 v131, v132, v131
	v_sub_u32_e32 v0, v0, v133
	v_lshlrev_b32_e32 v130, 8, v130
	v_readfirstlane_b32 s3, v132
	s_addc_u32 s45, s13, 0
	v_xor_b32_e32 v0, v0, v131
	v_and_b32_e32 v130, 0xfffff800, v130
	s_lshl_b32 s3, s3, 4
	v_lshl_add_u32 v0, v0, 4, v130
	s_and_b32 s3, s3, 0xfffffc00
	v_lshl_add_u64 v[130:131], s[44:45], 0, v[0:1]
	s_mov_b32 m0, s3
	v_lshl_add_u64 v[132:133], v[130:131], 0, s[58:59]
	global_load_lds_dwordx4 v0, s[44:45]
	s_add_i32 m0, s3, 0x2000
	s_ashr_i32 s31, s30, 31
	global_load_lds_dwordx4 v[132:133], off
	v_lshl_add_u64 v[132:133], v[130:131], 0, s[48:49]
	s_add_i32 m0, s3, 0x4000
	s_lshl_b64 s[30:31], s[30:31], 11
	global_load_lds_dwordx4 v[132:133], off
	s_add_i32 m0, s3, 0x6000
	s_add_u32 s30, s40, s30
	v_lshl_add_u64 v[130:131], v[130:131], 0, s[50:51]
	s_addc_u32 s31, s41, s31
	global_load_lds_dwordx4 v[130:131], off
	v_lshl_add_u64 v[130:131], s[30:31], 0, v[0:1]
	s_add_i32 m0, s3, 0x8000
	v_lshl_add_u64 v[132:133], v[130:131], 0, s[58:59]
	global_load_lds_dwordx4 v0, s[30:31]
	s_add_i32 m0, s3, 0xa000
	s_nop 0
	global_load_lds_dwordx4 v[132:133], off
	v_lshl_add_u64 v[132:133], v[130:131], 0, s[48:49]
	s_add_i32 m0, s3, 0xc000
	v_lshl_add_u64 v[130:131], v[130:131], 0, s[50:51]
	global_load_lds_dwordx4 v[132:133], off
	s_add_i32 m0, s3, 0xe000
	s_nop 0
	global_load_lds_dwordx4 v[130:131], off

; DI f32x16 zero16() { f32x16 z; for (int i = 0; i < 16; ++i) z[i] = 0.f; return z; }
; DI int launder(int x) { asm volatile("" : "+v"(x)); return x; }
; template <int BK> DI int swz(int row) { constexpr int CPR = BK / 8; return (row / (16 / CPR)) % CPR; }
; DI void wait_vm0() { asm volatile("s_waitcnt vmcnt(0)" ::: "memory"); }
;   DI void pre(int grow0, int gcol0, int lane, int w, char* lds) { xpass(0, grow0, gcol0, lane, w, lds); }
;     ...
;   const int tid = launder(threadIdx.x), lane = tid & 63, w = tid >> 6, wm = w % WM, wn = w / WM;
;   const int l31 = lane & 31, hh = lane >> 5;
;   f32x16 acc[2][NTW];
; #pragma unroll
;   for (int a = 0; a < 2; ++a)
; #pragma unroll
;     for (int b = 0; b < NTW; ++b) acc[a][b] = zero16();
;   const bf16_t* Ag = A + (size_t)row0 * lda; const bf16_t* Bg = Bt + (size_t)col0 * ldb;
;   const int wv = __builtin_amdgcn_readfirstlane(tid >> 6);
;   __syncthreads();
;   if (!pre) { stage_tile<BM, BK>(Ag, lda, lds, tid); stage_tile<BN, BK>(Bg, ldb, lds + ABYTES, tid); }
;   wait_vm0();
;   __syncthreads();
;   const int nk = K / BK;
;   for (int kt = 0; kt < nk; ++kt) {
;     char* cur = lds + (kt & 1) * STG; char* nxt = lds + ((kt + 1) & 1) * STG;
;     const bool more = kt + 1 < nk;
;     const bf16_t* An = Ag + (kt + 1) * BK; const bf16_t* Bn = Bg + (kt + 1) * BK;
;     if (!more) epi.pre(row0 + wm * 64, col0 + wn * (32 * NTW), lane, w, lds);
;     bf16x8 fa[2][2], fb[2][NTW];
; #pragma unroll
;     for (int mt = 0; mt < 2; ++mt) { int row = wm * 64 + mt * 32 + l31; fa[0][mt] = *(const bf16x8*)(cur + row * (BK * 2) + ((hh ^ swz<BK>(row)) << 4)); }
; #pragma unroll
;     for (int nt = 0; nt < NTW; ++nt) { int row = wn * (32 * NTW) + nt * 32 + l31; fb[0][nt] = *(const bf16x8*)(cur + ABYTES + row * (BK * 2) + ((hh ^ swz<BK>(row)) << 4)); }
; __global__ void __launch_bounds__(NT) fwd_megakernel(Params p) {
;     ...
;         for (int t = blockIdx.x; t < 256; t += gridDim.x) {
;           int layer = t >> 6, pm = t & 7, pn = (t >> 3) & 7;
;           EpiXkv e{p.Kx + (size_t)layer * 2048 * D_, p.Vxt + (size_t)layer * 32 * 256 * 256};
;           gemm_tile<4, 64>(p.memb, D_, p.wxkv[layer], D_, D_, pm * 256, pn * 256, lds, e);
.LBB0_626:
	s_lshl_b32 s2, s37, 11
	s_ashr_i32 s6, s40, 6
	s_and_b32 s41, s2, 0x380000
	s_lshl_b32 s2, s36, 11
	s_ashr_i32 s7, s6, 31
	s_and_b32 s35, s2, 0x380000
	s_lshl_b64 s[2:3], s[6:7], 3
	s_add_u32 s2, s0, s2
	s_addc_u32 s3, s1, s3
	v_mov_b32_e32 v4, v216
	s_load_dwordx2 s[30:31], s[2:3], 0x1d8
	s_lshl_b32 s2, s40, 8
	s_and_b32 s2, s2, 0x700
	v_ashrrev_i32_e32 v0, 6, v4
	s_lshl_b32 s3, s40, 5
	v_lshrrev_b32_e32 v2, 30, v0
	s_and_b32 s3, s3, 0x700
	s_waitcnt lgkmcnt(0)
	v_add_u32_e32 v6, v0, v2
	s_lshl_b32 s34, s2, 11
	v_ashrrev_i32_e32 v7, 2, v6
	s_add_u32 s42, s14, s34
	v_mul_i32_i24_e32 v2, 4, v7
	s_addc_u32 s43, s15, 0
	s_lshl_b32 s34, s3, 11
	v_sub_u32_e32 v9, v0, v2
	s_add_u32 s44, s30, s34
	v_readfirstlane_b32 s34, v0
	v_ashrrev_i32_e32 v0, 31, v4
	v_lshrrev_b32_e32 v2, 29, v0
	v_lshrrev_b32_e32 v0, 28, v0
	v_add_u32_e32 v0, v4, v0
	v_ashrrev_i32_e32 v0, 4, v0
	v_lshrrev_b32_e32 v5, 29, v0
	v_add_u32_e32 v2, v4, v2
	v_add_u32_e32 v5, v0, v5
	v_and_b32_e32 v3, 0xffffff8, v2
	v_and_b32_e32 v5, 0xffffff8, v5
	v_sub_u32_e32 v3, v4, v3
	v_sub_u32_e32 v0, v0, v5
	v_lshlrev_b32_e32 v2, 8, v2
	v_readfirstlane_b32 s46, v4
	s_addc_u32 s45, s31, 0
	v_xor_b32_e32 v0, v0, v3
	v_and_b32_e32 v2, 0xfffff800, v2
	s_lshl_b32 s46, s46, 4
	v_lshl_add_u32 v0, v0, 4, v2
	s_and_b32 s46, s46, 0xfffffc00
	v_lshl_add_u64 v[2:3], s[42:43], 0, v[0:1]
	s_mov_b32 m0, s46
	v_lshrrev_b32_e32 v8, 5, v4
	v_and_b32_e32 v10, 31, v4
	v_bfe_u32 v11, v4, 5, 1
	s_waitcnt vmcnt(0)
	s_barrier
	global_load_lds_dwordx4 v0, s[42:43]
	v_lshl_add_u64 v[4:5], v[2:3], 0, s[58:59]
	s_add_i32 m0, s46, 0x2000
	s_lshl_b32 s34, s34, 10
	global_load_lds_dwordx4 v[4:5], off
	v_lshl_add_u64 v[4:5], v[2:3], 0, s[48:49]
	s_add_i32 m0, s46, 0x4000
	v_lshl_add_u64 v[2:3], v[2:3], 0, s[50:51]
	global_load_lds_dwordx4 v[4:5], off
	s_add_i32 m0, s46, 0x6000
	s_nop 0
	global_load_lds_dwordx4 v[2:3], off
	v_lshl_add_u64 v[2:3], s[44:45], 0, v[0:1]
	s_add_i32 m0, s46, 0x8000
	v_lshl_add_u64 v[4:5], v[2:3], 0, s[58:59]
	global_load_lds_dwordx4 v0, s[44:45]
	s_add_i32 m0, s46, 0xa000
	s_nop 0
	global_load_lds_dwordx4 v[4:5], off
	v_lshl_add_u64 v[4:5], v[2:3], 0, s[48:49]
	s_add_i32 m0, s46, 0xc000
	v_lshl_add_u64 v[2:3], v[2:3], 0, s[50:51]
	global_load_lds_dwordx4 v[4:5], off
	s_add_i32 m0, s46, 0xe000
	v_bfe_u32 v4, v9, 25, 1
	global_load_lds_dwordx4 v[2:3], off
	v_lshlrev_b32_e32 v2, 6, v9
	v_or_b32_e32 v2, v2, v10
	v_lshlrev_b32_e32 v136, 7, v2
	v_add_u32_e32 v5, v2, v4
	v_or_b32_e32 v2, 32, v2
	v_lshlrev_b32_e32 v142, 7, v2
	v_add_u32_e32 v2, v2, v4
	v_ashrrev_i32_e32 v4, 1, v2
	v_ashrrev_i32_e32 v2, 31, v2
	v_lshrrev_b32_e32 v2, 29, v2
	v_lshl_or_b32 v3, v7, 7, v10
	v_ashrrev_i32_e32 v7, 1, v5
	v_ashrrev_i32_e32 v5, 31, v5
	v_add_u32_e32 v2, v4, v2
	v_lshrrev_b32_e32 v5, 29, v5
	v_and_b32_e32 v2, -8, v2
	v_add_u32_e32 v5, v7, v5
	v_sub_u32_e32 v2, v4, v2
	v_and_b32_e32 v5, -8, v5
	v_bitop3_b32 v4, v2, v8, 1 bitop3:0x78
	v_sub_u32_e32 v5, v7, v5
	v_lshlrev_b32_e32 v144, 4, v4
	v_lshrrev_b32_e32 v4, 31, v6
	v_bitop3_b32 v7, v5, v8, 1 bitop3:0x78
	v_add_u32_e32 v6, v3, v4
	v_lshlrev_b32_e32 v141, 4, v7
	v_ashrrev_i32_e32 v7, 1, v6
	v_ashrrev_i32_e32 v6, 31, v6
	v_lshrrev_b32_e32 v6, 29, v6
	v_add_u32_e32 v6, v7, v6
	v_and_b32_e32 v6, -8, v6
	v_sub_u32_e32 v6, v7, v6
	v_bitop3_b32 v7, v6, v8, 1 bitop3:0x78
	v_lshlrev_b32_e32 v151, 4, v7
	v_or_b32_e32 v7, 32, v3
	v_lshlrev_b32_e32 v152, 7, v7
	v_add_u32_e32 v7, v7, v4
	v_ashrrev_i32_e32 v9, 1, v7
	v_ashrrev_i32_e32 v7, 31, v7
	v_lshrrev_b32_e32 v7, 29, v7
	v_add_u32_e32 v7, v9, v7
	v_and_b32_e32 v7, -8, v7
	v_sub_u32_e32 v7, v9, v7
	v_bitop3_b32 v9, v7, v8, 1 bitop3:0x78
	v_lshlrev_b32_e32 v143, 7, v3
	v_lshlrev_b32_e32 v154, 4, v9
	v_or_b32_e32 v9, 64, v3
	v_or_b32_e32 v3, 0x60, v3
	v_lshlrev_b32_e32 v156, 7, v3
	v_add_u32_e32 v3, v3, v4
	v_lshlrev_b32_e32 v153, 7, v9
	v_add_u32_e32 v9, v9, v4
	v_ashrrev_i32_e32 v4, 1, v3
	v_ashrrev_i32_e32 v3, 31, v3
	v_lshrrev_b32_e32 v3, 29, v3
	v_add_u32_e32 v3, v4, v3
	v_and_b32_e32 v3, -8, v3
	v_sub_u32_e32 v3, v4, v3
	v_ashrrev_i32_e32 v10, 1, v9
	v_ashrrev_i32_e32 v9, 31, v9
	v_bitop3_b32 v4, v3, v8, 1 bitop3:0x78
	v_lshrrev_b32_e32 v9, 29, v9
	v_lshlrev_b32_e32 v164, 4, v4
	v_bitop3_b32 v4, v5, v11, 2 bitop3:0x1e
	v_add_u32_e32 v9, v10, v9
	v_lshlrev_b32_e32 v161, 4, v4
	v_bitop3_b32 v4, v2, v11, 2 bitop3:0x1e
	v_and_b32_e32 v9, -8, v9
	v_lshlrev_b32_e32 v163, 4, v4
	v_bitop3_b32 v4, v6, v11, 2 bitop3:0x1e
	v_sub_u32_e32 v9, v10, v9
	v_lshlrev_b32_e32 v159, 4, v4
	v_bitop3_b32 v4, v7, v11, 2 bitop3:0x1e
	v_lshlrev_b32_e32 v160, 4, v4
	v_bitop3_b32 v4, v9, v11, 2 bitop3:0x1e
	v_lshlrev_b32_e32 v157, 4, v4
	v_bitop3_b32 v4, v3, v11, 2 bitop3:0x1e
	v_lshlrev_b32_e32 v158, 4, v4
	v_bitop3_b32 v4, v5, v11, 4 bitop3:0x1e
	v_lshlrev_b32_e32 v149, 4, v4
	v_bitop3_b32 v4, v2, v11, 4 bitop3:0x1e
	v_bitop3_b32 v2, v2, v11, 6 bitop3:0x1e
	v_lshlrev_b32_e32 v150, 4, v4
	v_bitop3_b32 v4, v6, v11, 4 bitop3:0x1e
	v_lshlrev_b32_e32 v140, 4, v2
	v_bitop3_b32 v2, v6, v11, 6 bitop3:0x1e
	v_lshlrev_b32_e32 v147, 4, v4
	v_bitop3_b32 v4, v7, v11, 4 bitop3:0x1e
	v_lshlrev_b32_e32 v137, 4, v2
	v_bitop3_b32 v2, v7, v11, 6 bitop3:0x1e
	s_add_u32 s42, s14, s41
	v_lshlrev_b32_e32 v148, 4, v4
	v_bitop3_b32 v4, v9, v11, 4 bitop3:0x1e
	v_lshlrev_b32_e32 v138, 4, v2
	v_bitop3_b32 v2, v9, v11, 6 bitop3:0x1e
	s_addc_u32 s43, s15, 0
	s_waitcnt vmcnt(0)
;     ...
;   f32x16 acc[2][NTW];
; #pragma unroll
;   for (int a = 0; a < 2; ++a)
; #pragma unroll
;     for (int b = 0; b < NTW; ++b) acc[a][b] = zero16();
;   const bf16_t* Ag = A + (size_t)row0 * lda; const bf16_t* Bg = Bt + (size_t)col0 * ldb;
;   const int wv = __builtin_amdgcn_readfirstlane(tid >> 6);
;   __syncthreads();
;   if (!pre) { stage_tile<BM, BK>(Ag, lda, lds, tid); stage_tile<BN, BK>(Bg, ldb, lds + ABYTES, tid); }
;   wait_vm0();
;   __syncthreads();
;   const int nk = K / BK;
;   for (int kt = 0; kt < nk; ++kt) {
;     char* cur = lds + (kt & 1) * STG; char* nxt = lds + ((kt + 1) & 1) * STG;
;     const bool more = kt + 1 < nk;
;     const bf16_t* An = Ag + (kt + 1) * BK; const bf16_t* Bn = Bg + (kt + 1) * BK;
;     if (!more) epi.pre(row0 + wm * 64, col0 + wn * (32 * NTW), lane, w, lds);
;     bf16x8 fa[2][2], fb[2][NTW];
; #pragma unroll
;     for (int mt = 0; mt < 2; ++mt) { int row = wm * 64 + mt * 32 + l31; fa[0][mt] = *(const bf16x8*)(cur + row * (BK * 2) + ((hh ^ swz<BK>(row)) << 4)); }
; #pragma unroll
;     for (int nt = 0; nt < NTW; ++nt) { int row = wn * (32 * NTW) + nt * 32 + l31; fb[0][nt] = *(const bf16x8*)(cur + ABYTES + row * (BK * 2) + ((hh ^ swz<BK>(row)) << 4)); }
; #pragma unroll
;     for (int kk = 0; kk < NKK; ++kk) {
;       if (kk + 1 < NKK) {
;         const int ch = (kk + 1) * 2 + hh;
; #pragma unroll
;         for (int mt = 0; mt < 2; ++mt) { int row = wm * 64 + mt * 32 + l31; fa[(kk + 1) & 1][mt] = *(const bf16x8*)(cur + row * (BK * 2) + ((ch ^ swz<BK>(row)) << 4)); }
; #pragma unroll
;         for (int nt = 0; nt < NTW; ++nt) { int row = wn * (32 * NTW) + nt * 32 + l31; fb[(kk + 1) & 1][nt] = *(const bf16x8*)(cur + ABYTES + row * (BK * 2) + ((ch ^ swz<BK>(row)) << 4)); }
;       }
;       if (more) {
; #pragma unroll
;         for (int q = 0; q < PPK; ++q) {
;           const int pi = kk * PPK + q;
;           if (pi < NPA) stage_piece<BM, BK>(An, lda, nxt, tid, pi, wv);
;           else if (pi < NP) stage_piece<BN, BK>(Bn, ldb, nxt + ABYTES, tid, pi - NPA, wv);
;         }
;       }
;       __builtin_amdgcn_s_setprio(1);
; #pragma unroll
;       for (int mt = 0; mt < 2; ++mt)
; #pragma unroll
;         for (int nt = 0; nt < NTW; ++nt) acc[mt][nt] = mfma(fa[kk & 1][mt], fb[kk & 1][nt], acc[mt][nt]);
;       __builtin_amdgcn_s_setprio(0);
;       __builtin_amdgcn_sched_barrier(0);
;     }
	v_lshlrev_b32_e32 v145, 4, v4
	v_bitop3_b32 v4, v3, v11, 4 bitop3:0x1e
	v_lshlrev_b32_e32 v134, 4, v2
	v_bitop3_b32 v2, v3, v11, 6 bitop3:0x1e
	s_add_u32 s30, s30, s35
	v_bitop3_b32 v10, v9, v8, 1 bitop3:0x78
	v_lshlrev_b32_e32 v146, 4, v4
	v_bitop3_b32 v4, v5, v11, 6 bitop3:0x1e
	v_lshlrev_b32_e32 v135, 4, v2
	s_addc_u32 s31, s31, 0
	v_mov_b32_e32 v2, 0
	v_lshlrev_b32_e32 v155, 4, v10
	v_lshlrev_b32_e32 v139, 4, v4
	v_lshl_add_u64 v[130:131], s[42:43], 0, v[0:1]
	v_lshl_add_u64 v[132:133], s[30:31], 0, v[0:1]
	s_mov_b64 s[30:31], 0
	s_mov_b32 s35, 0x10000
	v_mov_b32_e32 v3, v2
	v_mov_b32_e32 v4, v2
	v_mov_b32_e32 v5, v2
	v_mov_b32_e32 v6, v2
	v_mov_b32_e32 v7, v2
	v_mov_b32_e32 v8, v2
	v_mov_b32_e32 v9, v2
	v_mov_b32_e32 v10, v2
	v_mov_b32_e32 v11, v2
	v_mov_b32_e32 v12, v2
	v_mov_b32_e32 v13, v2
	v_mov_b32_e32 v14, v2
	v_mov_b32_e32 v15, v2
	v_mov_b32_e32 v16, v2
	v_mov_b32_e32 v17, v2
	v_mov_b32_e32 v18, v2
	v_mov_b32_e32 v19, v2
	v_mov_b32_e32 v20, v2
	v_mov_b32_e32 v21, v2
	v_mov_b32_e32 v22, v2
	v_mov_b32_e32 v23, v2
	v_mov_b32_e32 v24, v2
	v_mov_b32_e32 v25, v2
	v_mov_b32_e32 v26, v2
	v_mov_b32_e32 v27, v2
	v_mov_b32_e32 v28, v2
	v_mov_b32_e32 v29, v2
	v_mov_b32_e32 v30, v2
	v_mov_b32_e32 v31, v2
	v_mov_b32_e32 v32, v2
	v_mov_b32_e32 v33, v2
	v_mov_b32_e32 v34, v2
	v_mov_b32_e32 v35, v2
	v_mov_b32_e32 v36, v2
	v_mov_b32_e32 v37, v2
	v_mov_b32_e32 v38, v2
	v_mov_b32_e32 v39, v2
	v_mov_b32_e32 v40, v2
	v_mov_b32_e32 v41, v2
	v_mov_b32_e32 v42, v2
	v_mov_b32_e32 v43, v2
	v_mov_b32_e32 v44, v2
	v_mov_b32_e32 v45, v2
	v_mov_b32_e32 v46, v2
	v_mov_b32_e32 v47, v2
	v_mov_b32_e32 v48, v2
	v_mov_b32_e32 v49, v2
	v_mov_b32_e32 v50, v2
	v_mov_b32_e32 v51, v2
	v_mov_b32_e32 v52, v2
	v_mov_b32_e32 v53, v2
	v_mov_b32_e32 v54, v2
	v_mov_b32_e32 v55, v2
	v_mov_b32_e32 v56, v2
	v_mov_b32_e32 v57, v2
	v_mov_b32_e32 v58, v2
	v_mov_b32_e32 v59, v2
	v_mov_b32_e32 v60, v2
	v_mov_b32_e32 v61, v2
	v_mov_b32_e32 v62, v2
	v_mov_b32_e32 v63, v2
	v_mov_b32_e32 v64, v2
	v_mov_b32_e32 v65, v2
	v_mov_b32_e32 v66, v2
	v_mov_b32_e32 v67, v2
	v_mov_b32_e32 v68, v2
	v_mov_b32_e32 v69, v2
	v_mov_b32_e32 v70, v2
	v_mov_b32_e32 v71, v2
	v_mov_b32_e32 v72, v2
	v_mov_b32_e32 v73, v2
	v_mov_b32_e32 v74, v2
	v_mov_b32_e32 v75, v2
	v_mov_b32_e32 v76, v2
	v_mov_b32_e32 v77, v2
	v_mov_b32_e32 v78, v2
	v_mov_b32_e32 v79, v2
	v_mov_b32_e32 v80, v2
	v_mov_b32_e32 v81, v2
	v_mov_b32_e32 v82, v2
	v_mov_b32_e32 v83, v2
	v_mov_b32_e32 v84, v2
	v_mov_b32_e32 v85, v2
	v_mov_b32_e32 v86, v2
	v_mov_b32_e32 v87, v2
	v_mov_b32_e32 v88, v2
	v_mov_b32_e32 v89, v2
	v_mov_b32_e32 v90, v2
	v_mov_b32_e32 v91, v2
	v_mov_b32_e32 v92, v2
	v_mov_b32_e32 v93, v2
	v_mov_b32_e32 v94, v2
	v_mov_b32_e32 v95, v2
	v_mov_b32_e32 v96, v2
	v_mov_b32_e32 v97, v2
	v_mov_b32_e32 v98, v2
	v_mov_b32_e32 v99, v2
	v_mov_b32_e32 v100, v2
	v_mov_b32_e32 v101, v2
	v_mov_b32_e32 v102, v2
	v_mov_b32_e32 v103, v2
	v_mov_b32_e32 v104, v2
	v_mov_b32_e32 v105, v2
	v_mov_b32_e32 v106, v2
	v_mov_b32_e32 v107, v2
	v_mov_b32_e32 v108, v2
	v_mov_b32_e32 v109, v2
	v_mov_b32_e32 v110, v2
	v_mov_b32_e32 v111, v2
	v_mov_b32_e32 v112, v2
	v_mov_b32_e32 v113, v2
	v_mov_b32_e32 v114, v2
	v_mov_b32_e32 v115, v2
	v_mov_b32_e32 v116, v2
	v_mov_b32_e32 v117, v2
	v_mov_b32_e32 v118, v2
	v_mov_b32_e32 v119, v2
	v_mov_b32_e32 v120, v2
	v_mov_b32_e32 v121, v2
	v_mov_b32_e32 v122, v2
	v_mov_b32_e32 v123, v2
	v_mov_b32_e32 v124, v2
	v_mov_b32_e32 v125, v2
	v_mov_b32_e32 v126, v2
	v_mov_b32_e32 v127, v2
	v_mov_b32_e32 v128, v2
	v_mov_b32_e32 v129, v2
	s_waitcnt vmcnt(0) lgkmcnt(0)
	s_barrier
	v_add_u32_e32 v166, v136, v141
	v_add_u32_e32 v170, v142, v144
	ds_read_b128 v[166:169], v166
	v_add_u32_e32 v174, v143, v151
	ds_read_b128 v[170:173], v170
	v_add_u32_e32 v178, v152, v154
	ds_read_b128 v[174:177], v174 offset:32768
	v_add_u32_e32 v182, v153, v155
	ds_read_b128 v[178:181], v178 offset:32768
	v_add_u32_e32 v186, v156, v164
	ds_read_b128 v[182:185], v182 offset:32768
	ds_read_b128 v[186:189], v186 offset:32768
.LBB0_627:
	s_and_b32 s42, s35, 0x10000
	s_xor_b32 s100, s42, 0x10000
	s_add_i32 s41, s42, s34
	v_add3_u32 v190, s100, v136, v161
	v_add3_u32 v194, s100, v142, v163
	ds_read_b128 v[190:193], v190
	v_add3_u32 v198, s100, v143, v159
	ds_read_b128 v[194:197], v194
	v_add3_u32 v202, s100, v152, v160
	ds_read_b128 v[198:201], v198 offset:32768
	v_add3_u32 v206, s100, v153, v157
	ds_read_b128 v[202:205], v202 offset:32768
	v_add3_u32 v210, s100, v156, v158
	ds_read_b128 v[206:209], v206 offset:32768
	ds_read_b128 v[210:213], v210 offset:32768
	v_lshl_add_u64 v[214:215], v[130:131], 0, s[30:31]
	v_lshl_add_u64 v[226:227], v[132:133], 0, s[30:31]
	s_mov_b32 m0, s41
	v_lshl_add_u64 v[228:229], v[214:215], 0, s[28:29]
	s_setprio 1
	s_waitcnt lgkmcnt(6)
; DI f32x16 mfma(bf16x8 a, bf16x8 b, f32x16 c) { return __builtin_amdgcn_mfma_f32_32x32x16_bf16(a, b, c, 0, 0, 0); }
; template <int BK> DI int swz(int row) { constexpr int CPR = BK / 8; return (row / (16 / CPR)) % CPR; }
;   DI void pre(int grow0, int gcol0, int lane, int w, char* lds) { xpass(0, grow0, gcol0, lane, w, lds); }
;     ...
;   for (int kt = 0; kt < nk; ++kt) {
;     char* cur = lds + (kt & 1) * STG; char* nxt = lds + ((kt + 1) & 1) * STG;
;     const bool more = kt + 1 < nk;
;     const bf16_t* An = Ag + (kt + 1) * BK; const bf16_t* Bn = Bg + (kt + 1) * BK;
;     if (!more) epi.pre(row0 + wm * 64, col0 + wn * (32 * NTW), lane, w, lds);
;     bf16x8 fa[2][2], fb[2][NTW];
; #pragma unroll
;     for (int mt = 0; mt < 2; ++mt) { int row = wm * 64 + mt * 32 + l31; fa[0][mt] = *(const bf16x8*)(cur + row * (BK * 2) + ((hh ^ swz<BK>(row)) << 4)); }
; #pragma unroll
;     for (int nt = 0; nt < NTW; ++nt) { int row = wn * (32 * NTW) + nt * 32 + l31; fb[0][nt] = *(const bf16x8*)(cur + ABYTES + row * (BK * 2) + ((hh ^ swz<BK>(row)) << 4)); }
; #pragma unroll
;     for (int kk = 0; kk < NKK; ++kk) {
;       if (kk + 1 < NKK) {
;         const int ch = (kk + 1) * 2 + hh;
; #pragma unroll
;         for (int mt = 0; mt < 2; ++mt) { int row = wm * 64 + mt * 32 + l31; fa[(kk + 1) & 1][mt] = *(const bf16x8*)(cur + row * (BK * 2) + ((ch ^ swz<BK>(row)) << 4)); }
; #pragma unroll
;         for (int nt = 0; nt < NTW; ++nt) { int row = wn * (32 * NTW) + nt * 32 + l31; fb[(kk + 1) & 1][nt] = *(const bf16x8*)(cur + ABYTES + row * (BK * 2) + ((ch ^ swz<BK>(row)) << 4)); }
;       }
;       if (more) {
; #pragma unroll
;         for (int q = 0; q < PPK; ++q) {
;           const int pi = kk * PPK + q;
;           if (pi < NPA) stage_piece<BM, BK>(An, lda, nxt, tid, pi, wv);
;           else if (pi < NP) stage_piece<BN, BK>(Bn, ldb, nxt + ABYTES, tid, pi - NPA, wv);
;         }
;       }
;       __builtin_amdgcn_s_setprio(1);
; #pragma unroll
;       for (int mt = 0; mt < 2; ++mt)
; #pragma unroll
;         for (int nt = 0; nt < NTW; ++nt) acc[mt][nt] = mfma(fa[kk & 1][mt], fb[kk & 1][nt], acc[mt][nt]);
;       __builtin_amdgcn_s_setprio(0);
;       __builtin_amdgcn_sched_barrier(0);
;     }
	v_mfma_f32_32x32x16_bf16 v[114:129], v[166:169], v[174:177], v[114:129]
	global_load_lds_dwordx4 v[228:229], off
	v_lshl_add_u64 v[228:229], v[214:215], 0, s[24:25]
	s_add_i32 m0, s41, 0x2000
	v_mfma_f32_32x32x16_bf16 v[98:113], v[166:169], v[178:181], v[98:113]
	global_load_lds_dwordx4 v[228:229], off
	v_lshl_add_u64 v[228:229], v[214:215], 0, s[26:27]
	s_add_i32 m0, s41, 0x4000
	v_mfma_f32_32x32x16_bf16 v[82:97], v[166:169], v[182:185], v[82:97]
	global_load_lds_dwordx4 v[228:229], off
	v_lshl_add_u64 v[228:229], v[214:215], 0, s[38:39]
	s_add_i32 m0, s41, 0x6000
	v_mfma_f32_32x32x16_bf16 v[66:81], v[166:169], v[186:189], v[66:81]
	global_load_lds_dwordx4 v[228:229], off
	v_lshl_add_u64 v[228:229], v[226:227], 0, s[28:29]
	s_add_i32 m0, s41, 0x8000
	v_mfma_f32_32x32x16_bf16 v[50:65], v[170:173], v[174:177], v[50:65]
	global_load_lds_dwordx4 v[228:229], off
	v_lshl_add_u64 v[228:229], v[226:227], 0, s[24:25]
	s_add_i32 m0, s41, 0xa000
	v_mfma_f32_32x32x16_bf16 v[34:49], v[170:173], v[178:181], v[34:49]
	global_load_lds_dwordx4 v[228:229], off
	v_lshl_add_u64 v[228:229], v[226:227], 0, s[26:27]
	s_add_i32 m0, s41, 0xc000
	v_mfma_f32_32x32x16_bf16 v[18:33], v[170:173], v[182:185], v[18:33]
	global_load_lds_dwordx4 v[228:229], off
	v_lshl_add_u64 v[228:229], v[226:227], 0, s[38:39]
	s_add_i32 m0, s41, 0xe000
	v_mfma_f32_32x32x16_bf16 v[2:17], v[170:173], v[186:189], v[2:17]
	global_load_lds_dwordx4 v[228:229], off
	s_setprio 0
	v_add3_u32 v166, s100, v136, v149
	v_add3_u32 v170, s100, v142, v150
	ds_read_b128 v[166:169], v166
	v_add3_u32 v174, s100, v143, v147
	ds_read_b128 v[170:173], v170
	v_add3_u32 v178, s100, v152, v148
	ds_read_b128 v[174:177], v174 offset:32768
	v_add3_u32 v182, s100, v153, v145
	ds_read_b128 v[178:181], v178 offset:32768
	v_add3_u32 v186, s100, v156, v146
	ds_read_b128 v[182:185], v182 offset:32768
	ds_read_b128 v[186:189], v186 offset:32768
	s_setprio 1
	s_waitcnt lgkmcnt(6)
	v_mfma_f32_32x32x16_bf16 v[114:129], v[190:193], v[198:201], v[114:129]
	v_mfma_f32_32x32x16_bf16 v[98:113], v[190:193], v[202:205], v[98:113]
	v_mfma_f32_32x32x16_bf16 v[82:97], v[190:193], v[206:209], v[82:97]
	v_mfma_f32_32x32x16_bf16 v[66:81], v[190:193], v[210:213], v[66:81]
	v_mfma_f32_32x32x16_bf16 v[50:65], v[194:197], v[198:201], v[50:65]
	v_mfma_f32_32x32x16_bf16 v[34:49], v[194:197], v[202:205], v[34:49]
	v_mfma_f32_32x32x16_bf16 v[18:33], v[194:197], v[206:209], v[18:33]
	v_mfma_f32_32x32x16_bf16 v[2:17], v[194:197], v[210:213], v[2:17]
	s_setprio 0
	v_add3_u32 v190, s100, v136, v139
	v_add3_u32 v194, s100, v142, v140
	ds_read_b128 v[190:193], v190
	v_add3_u32 v198, s100, v143, v137
	ds_read_b128 v[194:197], v194
	v_add3_u32 v202, s100, v152, v138
	ds_read_b128 v[198:201], v198 offset:32768
	v_add3_u32 v206, s100, v153, v134
	ds_read_b128 v[202:205], v202 offset:32768
	v_add3_u32 v210, s100, v156, v135
	ds_read_b128 v[206:209], v206 offset:32768
	ds_read_b128 v[210:213], v210 offset:32768
	s_setprio 1
	s_waitcnt lgkmcnt(6)
	v_mfma_f32_32x32x16_bf16 v[114:129], v[166:169], v[174:177], v[114:129]
	v_mfma_f32_32x32x16_bf16 v[98:113], v[166:169], v[178:181], v[98:113]
	v_mfma_f32_32x32x16_bf16 v[82:97], v[166:169], v[182:185], v[82:97]
	v_mfma_f32_32x32x16_bf16 v[66:81], v[166:169], v[186:189], v[66:81]
	v_mfma_f32_32x32x16_bf16 v[50:65], v[170:173], v[174:177], v[50:65]
	v_mfma_f32_32x32x16_bf16 v[34:49], v[170:173], v[178:181], v[34:49]
	v_mfma_f32_32x32x16_bf16 v[18:33], v[170:173], v[182:185], v[18:33]
	v_mfma_f32_32x32x16_bf16 v[2:17], v[170:173], v[186:189], v[2:17]
	s_setprio 0
	s_add_u32 s30, s30, 0x80
	s_addc_u32 s31, s31, 0
	s_add_i32 s35, s35, 0x10000
	s_waitcnt vmcnt(0) lgkmcnt(0)
	s_barrier
	v_add3_u32 v166, s42, v136, v141
	v_add3_u32 v170, s42, v142, v144
	ds_read_b128 v[166:169], v166
	v_add3_u32 v174, s42, v143, v151
	ds_read_b128 v[170:173], v170
	v_add3_u32 v178, s42, v152, v154
	ds_read_b128 v[174:177], v174 offset:32768
	v_add3_u32 v182, s42, v153, v155
	ds_read_b128 v[178:181], v178 offset:32768
	v_add3_u32 v186, s42, v156, v164
	ds_read_b128 v[182:185], v182 offset:32768
	ds_read_b128 v[186:189], v186 offset:32768
	s_setprio 1
	v_mfma_f32_32x32x16_bf16 v[114:129], v[190:193], v[198:201], v[114:129]
	v_mfma_f32_32x32x16_bf16 v[98:113], v[190:193], v[202:205], v[98:113]
	v_mfma_f32_32x32x16_bf16 v[82:97], v[190:193], v[206:209], v[82:97]
	v_mfma_f32_32x32x16_bf16 v[66:81], v[190:193], v[210:213], v[66:81]
	v_mfma_f32_32x32x16_bf16 v[50:65], v[194:197], v[198:201], v[50:65]
	v_mfma_f32_32x32x16_bf16 v[34:49], v[194:197], v[202:205], v[34:49]
	v_mfma_f32_32x32x16_bf16 v[18:33], v[194:197], v[206:209], v[18:33]
	v_mfma_f32_32x32x16_bf16 v[2:17], v[194:197], v[210:213], v[2:17]
	s_setprio 0
	s_cmpk_lg_i32 s30, 0x780
	s_cbranch_scc1 .LBB0_627
;     ...
;   for (int kt = 0; kt < nk; ++kt) {
;     char* cur = lds + (kt & 1) * STG; char* nxt = lds + ((kt + 1) & 1) * STG;
;     const bool more = kt + 1 < nk;
;     const bf16_t* An = Ag + (kt + 1) * BK; const bf16_t* Bn = Bg + (kt + 1) * BK;
;     if (!more) epi.pre(row0 + wm * 64, col0 + wn * (32 * NTW), lane, w, lds);
;     bf16x8 fa[2][2], fb[2][NTW];
; #pragma unroll
;     for (int mt = 0; mt < 2; ++mt) { int row = wm * 64 + mt * 32 + l31; fa[0][mt] = *(const bf16x8*)(cur + row * (BK * 2) + ((hh ^ swz<BK>(row)) << 4)); }
; #pragma unroll
;     for (int nt = 0; nt < NTW; ++nt) { int row = wn * (32 * NTW) + nt * 32 + l31; fb[0][nt] = *(const bf16x8*)(cur + ABYTES + row * (BK * 2) + ((hh ^ swz<BK>(row)) << 4)); }
; #pragma unroll
;     for (int kk = 0; kk < NKK; ++kk) {
;       if (kk + 1 < NKK) {
;         const int ch = (kk + 1) * 2 + hh;
; #pragma unroll
;         for (int mt = 0; mt < 2; ++mt) { int row = wm * 64 + mt * 32 + l31; fa[(kk + 1) & 1][mt] = *(const bf16x8*)(cur + row * (BK * 2) + ((ch ^ swz<BK>(row)) << 4)); }
; #pragma unroll
;         for (int nt = 0; nt < NTW; ++nt) { int row = wn * (32 * NTW) + nt * 32 + l31; fb[(kk + 1) & 1][nt] = *(const bf16x8*)(cur + ABYTES + row * (BK * 2) + ((ch ^ swz<BK>(row)) << 4)); }
;       }
;       if (more) {
; #pragma unroll
;         for (int q = 0; q < PPK; ++q) {
;           const int pi = kk * PPK + q;
;           if (pi < NPA) stage_piece<BM, BK>(An, lda, nxt, tid, pi, wv);
;           else if (pi < NP) stage_piece<BN, BK>(Bn, ldb, nxt + ABYTES, tid, pi - NPA, wv);
;         }
;       }
;       __builtin_amdgcn_s_setprio(1);
; #pragma unroll
;       for (int mt = 0; mt < 2; ++mt)
; #pragma unroll
;         for (int nt = 0; nt < NTW; ++nt) acc[mt][nt] = mfma(fa[kk & 1][mt], fb[kk & 1][nt], acc[mt][nt]);
;       __builtin_amdgcn_s_setprio(0);
;       __builtin_amdgcn_sched_barrier(0);
;     }
;     wait_vm0();
;     __syncthreads();
;   }
;   DI void operator()(f32x16 (&acc)[2][4], int grow0, int gcol0, int lane, int w, char* lds) {
;     const int l31 = lane & 31, hh = lane >> 5;
;     if (gcol0 < 1024) {
; #pragma unroll
;       for (int mt = 0; mt < 2; ++mt)
; #pragma unroll
;         for (int nt = 0; nt < 4; ++nt)
; #pragma unroll
;           for (int i = 0; i < 16; ++i) { int row = grow0 + mt * 32 + crow(i, hh); Kx[(size_t)row * D_ + gcol0 + nt * 32 + l31] = f2bf(acc[mt][nt][i]); }
;     } else {
	s_waitcnt lgkmcnt(0)
	v_add_u32_e32 v0, 0x10000, v136
	v_add_u32_e32 v136, 0x10000, v142
	v_add_u32_e32 v130, v0, v141
	v_add_u32_e32 v141, v136, v144
	ds_read_b128 v[130:133], v130
	ds_read_b128 v[166:169], v141
	v_add_u32_e32 v141, 0x18000, v143
	v_add_u32_e32 v142, v141, v151
	v_add_u32_e32 v202, 0x18000, v152
	v_add_u32_e32 v203, 0x18000, v153
	v_add_u32_e32 v143, v202, v154
	ds_read_b128 v[170:173], v142
	ds_read_b128 v[174:177], v143
	v_add_u32_e32 v142, v203, v155
	v_add_u32_e32 v204, 0x18000, v156
	v_add_u32_e32 v143, v204, v164
	ds_read_b128 v[152:155], v142
	ds_read_b128 v[178:181], v143
	v_add_u32_e32 v142, v0, v161
	v_add_u32_e32 v143, v136, v163
	ds_read_b128 v[182:185], v142
	ds_read_b128 v[186:189], v143
	v_add_u32_e32 v142, v141, v159
	v_add_u32_e32 v143, v202, v160
	ds_read_b128 v[190:193], v142
	ds_read_b128 v[194:197], v143
	v_add_u32_e32 v142, v203, v157
	v_add_u32_e32 v143, v204, v158
	ds_read_b128 v[156:159], v142
	ds_read_b128 v[198:201], v143
	s_lshl_b64 s[30:31], s[6:7], 22
	s_setprio 1
	s_waitcnt lgkmcnt(9)
	v_mfma_f32_32x32x16_bf16 v[114:129], v[130:133], v[170:173], v[114:129]
	s_waitcnt lgkmcnt(8)
	v_mfma_f32_32x32x16_bf16 v[98:113], v[130:133], v[174:177], v[98:113]
	s_waitcnt lgkmcnt(7)
	v_mfma_f32_32x32x16_bf16 v[82:97], v[130:133], v[152:155], v[82:97]
	s_waitcnt lgkmcnt(6)
	v_mfma_f32_32x32x16_bf16 v[66:81], v[130:133], v[178:181], v[66:81]
	v_mfma_f32_32x32x16_bf16 v[50:65], v[166:169], v[170:173], v[50:65]
	v_mfma_f32_32x32x16_bf16 v[34:49], v[166:169], v[174:177], v[34:49]
	v_mfma_f32_32x32x16_bf16 v[18:33], v[166:169], v[152:155], v[18:33]
	v_mfma_f32_32x32x16_bf16 v[2:17], v[166:169], v[178:181], v[2:17]
	s_setprio 0
	v_add_u32_e32 v130, v0, v149
	v_add_u32_e32 v142, v136, v150
	ds_read_b128 v[130:133], v130
	ds_read_b128 v[150:153], v142
	v_add_u32_e32 v142, v141, v147
	v_add_u32_e32 v143, v202, v148
	ds_read_b128 v[166:169], v142
	ds_read_b128 v[170:173], v143
	v_add_u32_e32 v142, v203, v145
	v_add_u32_e32 v146, v204, v146
	ds_read_b128 v[142:145], v142
	ds_read_b128 v[146:149], v146
	s_setprio 1
	s_waitcnt lgkmcnt(9)
	v_mfma_f32_32x32x16_bf16 v[114:129], v[182:185], v[190:193], v[114:129]
	s_waitcnt lgkmcnt(8)
	v_mfma_f32_32x32x16_bf16 v[98:113], v[182:185], v[194:197], v[98:113]
	s_waitcnt lgkmcnt(7)
	v_mfma_f32_32x32x16_bf16 v[82:97], v[182:185], v[156:159], v[82:97]
	s_waitcnt lgkmcnt(6)
	v_mfma_f32_32x32x16_bf16 v[66:81], v[182:185], v[198:201], v[66:81]
	v_mfma_f32_32x32x16_bf16 v[50:65], v[186:189], v[190:193], v[50:65]
	v_mfma_f32_32x32x16_bf16 v[34:49], v[186:189], v[194:197], v[34:49]
	v_mfma_f32_32x32x16_bf16 v[18:33], v[186:189], v[156:159], v[18:33]
	v_mfma_f32_32x32x16_bf16 v[2:17], v[186:189], v[198:201], v[2:17]
	s_setprio 0
	v_add_u32_e32 v0, v0, v139
	v_add_u32_e32 v136, v136, v140
	ds_read_b128 v[154:157], v0
	ds_read_b128 v[158:161], v136
	v_add_u32_e32 v0, v141, v137
	v_add_u32_e32 v140, v202, v138
	ds_read_b128 v[136:139], v0
	ds_read_b128 v[174:177], v140
	v_add_u32_e32 v0, v203, v134
	v_add_u32_e32 v134, v204, v135
	ds_read_b128 v[178:181], v0
	ds_read_b128 v[182:185], v134
	s_setprio 1
	s_waitcnt lgkmcnt(9)
	v_mfma_f32_32x32x16_bf16 v[114:129], v[130:133], v[166:169], v[114:129]
	s_waitcnt lgkmcnt(8)
	v_mfma_f32_32x32x16_bf16 v[98:113], v[130:133], v[170:173], v[98:113]
	s_waitcnt lgkmcnt(7)
	v_mfma_f32_32x32x16_bf16 v[82:97], v[130:133], v[142:145], v[82:97]
	s_waitcnt lgkmcnt(6)
	v_mfma_f32_32x32x16_bf16 v[66:81], v[130:133], v[146:149], v[66:81]
	v_mfma_f32_32x32x16_bf16 v[50:65], v[150:153], v[166:169], v[50:65]
	v_mfma_f32_32x32x16_bf16 v[34:49], v[150:153], v[170:173], v[34:49]
	v_mfma_f32_32x32x16_bf16 v[18:33], v[150:153], v[142:145], v[18:33]
	v_mfma_f32_32x32x16_bf16 v[2:17], v[150:153], v[146:149], v[2:17]
	s_setprio 0
	s_setprio 1
	s_waitcnt lgkmcnt(3)
	v_mfma_f32_32x32x16_bf16 v[114:129], v[154:157], v[136:139], v[114:129]
	s_waitcnt lgkmcnt(2)
	v_mfma_f32_32x32x16_bf16 v[98:113], v[154:157], v[174:177], v[98:113]
	s_waitcnt lgkmcnt(1)
	v_mfma_f32_32x32x16_bf16 v[82:97], v[154:157], v[178:181], v[82:97]
	s_waitcnt lgkmcnt(0)
	v_mfma_f32_32x32x16_bf16 v[66:81], v[154:157], v[182:185], v[66:81]
	v_mfma_f32_32x32x16_bf16 v[50:65], v[158:161], v[136:139], v[50:65]
	v_mfma_f32_32x32x16_bf16 v[34:49], v[158:161], v[174:177], v[34:49]
	v_mfma_f32_32x32x16_bf16 v[18:33], v[158:161], v[178:181], v[18:33]
	v_mfma_f32_32x32x16_bf16 v[2:17], v[158:161], v[182:185], v[2:17]
	s_setprio 0
	v_mov_b32_e32 v135, v216
	s_waitcnt vmcnt(0)
	s_barrier
	s_nop 0
	v_ashrrev_i32_e32 v134, 6, v135
	v_lshrrev_b32_e32 v0, 30, v134
	v_add_u32_e32 v0, v134, v0
	v_ashrrev_i32_e32 v130, 2, v0
	v_mul_i32_i24_e32 v0, 4, v130
	v_sub_u32_e32 v0, v134, v0
	v_lshlrev_b32_e32 v136, 6, v0
	v_lshl_add_u32 v132, v130, 7, s3
	v_add_u32_e32 v0, s2, v136
	v_and_b32_e32 v131, 31, v135
	v_bfe_u32 v133, v135, 5, 1
	v_cmp_lt_i32_e32 vcc, s57, v132
	s_and_saveexec_b64 s[2:3], vcc
	s_xor_b64 s[6:7], exec, s[2:3]
	s_cbranch_execz .LBB0_630
; DI unsigned pack2(float lo, float hi) { f32x2 v = {lo, hi}; bf2_t r = __builtin_convertvector(v, bf2_t); return __builtin_bit_cast(unsigned, r); }
; DI void tr_put(char* stg, int erow, const f32x16& v, int hh, float mul) {
; #pragma unroll
;   for (int qd = 0; qd < 4; ++qd) {
;     u32x2 pk; pk.x = pack2(v[4 * qd] * mul, v[4 * qd + 1] * mul); pk.y = pack2(v[4 * qd + 2] * mul, v[4 * qd + 3] * mul);
;     *(u32x2*)(stg + erow * 64 + (8 * qd + 4 * hh) * 2) = pk;
;   }
; }
; template <int R>
; DI void tr_flush(const char* stg, int row0, bf16_t* g, size_t grs, int lane) {
;   const int r0 = lane >> 2, ch = lane & 3;
; #pragma unroll
;   for (int it = 0; it < R / 16; ++it) {
;     const int r = it * 16 + r0;
;     u32x4 v = *(const u32x4*)(stg + (row0 + r) * 64 + ch * 16);
;     *(u32x4*)((char*)(g + (size_t)r * grs) + ch * 16) = v;
;   }
; }
;   DI void operator()(f32x16 (&acc)[2][4], int grow0, int gcol0, int lane, int w, char* lds) {
;     ...
;       const int cin = gcol0 - 1024, h = cin >> 8, b = grow0 >> 8, m0 = grow0 & 255;
;       char* stg = tr_stage(lds, w);
; #pragma unroll
;       for (int mt = 0; mt < 2; ++mt) {
; #pragma unroll
;         for (int nt = 0; nt < 4; ++nt) tr_put(stg, nt * 32 + l31, acc[mt][nt], hh, 1.f);
;         tr_flush<128>(stg, 0, Vxt + ((size_t)(b * 4 + h) * 256 + (cin & 255)) * 256 + m0 + mt * 32, 256, lane);
;       }
	v_add_u32_e32 v132, 0xfffffc00, v132
	v_lshl_add_u32 v134, v134, 13, v224
	v_lshlrev_b32_e32 v131, 6, v131
	v_lshlrev_b32_e32 v133, 3, v133
	v_ashrrev_i32_e32 v0, 6, v0
	v_lshrrev_b32_e32 v132, 8, v132
	v_or3_b32 v131, v134, v131, v133
	v_and_b32_e32 v0, -4, v0
	v_cvt_pk_bf16_f32 v66, v66, v67
	v_cvt_pk_bf16_f32 v67, v68, v69
	v_add_u32_e32 v132, v132, v0
	ds_write_b64 v131, v[66:67] offset:6144
	v_cvt_pk_bf16_f32 v66, v70, v71
	v_cvt_pk_bf16_f32 v67, v72, v73
	v_and_b32_e32 v135, 63, v135
	s_add_u32 s34, s74, s30
	v_ashrrev_i32_e32 v133, 31, v132
	v_cvt_pk_bf16_f32 v114, v114, v115
	v_cvt_pk_bf16_f32 v115, v116, v117
	ds_write_b64 v131, v[66:67] offset:6160
	v_cvt_pk_bf16_f32 v66, v74, v75
	v_cvt_pk_bf16_f32 v67, v76, v77
	s_addc_u32 s35, s75, s31
	v_lshlrev_b64 v[132:133], 17, v[132:133]
	v_lshlrev_b32_e32 v0, 4, v135
	ds_write_b64 v131, v[114:115]
	v_cvt_pk_bf16_f32 v114, v118, v119
	v_cvt_pk_bf16_f32 v115, v120, v121
	ds_write_b64 v131, v[66:67] offset:6176
	v_cvt_pk_bf16_f32 v66, v78, v79
	v_cvt_pk_bf16_f32 v67, v80, v81
	v_lshlrev_b32_e32 v68, 16, v130
	v_and_b32_e32 v136, 0xc0, v136
	v_lshrrev_b32_e32 v137, 2, v135
	v_and_b32_e32 v0, 48, v0
	ds_write_b64 v131, v[114:115] offset:16
	v_cvt_pk_bf16_f32 v114, v122, v123
	v_cvt_pk_bf16_f32 v115, v124, v125
	ds_write_b64 v131, v[66:67] offset:6192
	v_lshl_add_u64 v[66:67], s[34:35], 0, v[132:133]
	v_and_b32_e32 v68, 0x10000, v68
	v_mov_b32_e32 v69, v1
	v_or_b32_e32 v134, v134, v0
	v_or_b32_e32 v138, 16, v137
	ds_write_b64 v131, v[114:115] offset:32
	v_cvt_pk_bf16_f32 v114, v126, v127
	v_cvt_pk_bf16_f32 v115, v128, v129
	v_lshl_add_u64 v[66:67], v[66:67], 0, v[68:69]
	v_lshlrev_b32_e32 v68, 1, v136
	v_lshl_or_b32 v139, v138, 6, v134
	ds_write_b64 v131, v[114:115] offset:48
	v_lshl_add_u64 v[70:71], v[66:67], 0, v[68:69]
	v_cvt_pk_bf16_f32 v98, v98, v99
	v_cvt_pk_bf16_f32 v99, v100, v101
	v_lshl_add_u64 v[74:75], v[70:71], 0, v[0:1]
	ds_read_b128 v[70:73], v139
	ds_write_b64 v131, v[98:99] offset:2048
	v_cvt_pk_bf16_f32 v98, v102, v103
	v_cvt_pk_bf16_f32 v99, v104, v105
	ds_write_b64 v131, v[98:99] offset:2064
	v_cvt_pk_bf16_f32 v98, v106, v107
	v_cvt_pk_bf16_f32 v99, v108, v109
	v_lshlrev_b32_e32 v0, 9, v137
	v_or_b32_e32 v142, 48, v137
	ds_write_b64 v131, v[98:99] offset:2080
	v_cvt_pk_bf16_f32 v98, v110, v111
	v_cvt_pk_bf16_f32 v99, v112, v113
	v_lshl_add_u64 v[76:77], v[74:75], 0, v[0:1]
	v_lshlrev_b32_e32 v0, 9, v138
	v_lshl_or_b32 v143, v142, 6, v134
	ds_write_b64 v131, v[98:99] offset:2096
	v_lshl_add_u64 v[78:79], v[74:75], 0, v[0:1]
	v_cvt_pk_bf16_f32 v82, v82, v83
	v_cvt_pk_bf16_f32 v83, v84, v85
	s_waitcnt lgkmcnt(4)
	global_store_dwordx4 v[78:79], v[70:73], off
	ds_read_b128 v[70:73], v143
	v_or_b32_e32 v140, 32, v137
	ds_write_b64 v131, v[82:83] offset:4096
	v_cvt_pk_bf16_f32 v82, v86, v87
	v_cvt_pk_bf16_f32 v83, v88, v89
	ds_write_b64 v131, v[82:83] offset:4112
	v_cvt_pk_bf16_f32 v82, v90, v91
	v_cvt_pk_bf16_f32 v83, v92, v93
	v_lshlrev_b32_e32 v0, 9, v140
	v_or_b32_e32 v146, 0x50, v137
	ds_write_b64 v131, v[82:83] offset:4128
	v_cvt_pk_bf16_f32 v82, v94, v95
	v_cvt_pk_bf16_f32 v83, v96, v97
	v_lshl_add_u64 v[80:81], v[74:75], 0, v[0:1]
	v_lshlrev_b32_e32 v0, 9, v142
	v_lshl_or_b32 v135, v137, 6, v134
	v_lshl_or_b32 v147, v146, 6, v134
	ds_write_b64 v131, v[82:83] offset:4144
	v_lshl_add_u64 v[82:83], v[74:75], 0, v[0:1]
	ds_read_b128 v[66:69], v135
	s_waitcnt lgkmcnt(5)
	global_store_dwordx4 v[82:83], v[70:73], off
	ds_read_b128 v[70:73], v147
	v_or_b32_e32 v144, 64, v137
	v_lshlrev_b32_e32 v0, 9, v144
	v_or_b32_e32 v148, 0x60, v137
	v_or_b32_e32 v150, 0x70, v137
	v_lshl_add_u64 v[84:85], v[74:75], 0, v[0:1]
	v_lshlrev_b32_e32 v0, 9, v146
	v_lshl_or_b32 v141, v140, 6, v134
	v_lshl_or_b32 v145, v144, 6, v134
	v_lshl_or_b32 v149, v148, 6, v134
	v_lshl_or_b32 v134, v150, 6, v134
	v_lshl_add_u64 v[86:87], v[74:75], 0, v[0:1]
	s_waitcnt lgkmcnt(0)
	global_store_dwordx4 v[86:87], v[70:73], off
	ds_read_b128 v[70:73], v134
	global_store_dwordx4 v[76:77], v[66:69], off
	ds_read_b128 v[66:69], v141
	v_cvt_pk_bf16_f32 v50, v50, v51
	v_cvt_pk_bf16_f32 v51, v52, v53
	v_cvt_pk_bf16_f32 v34, v34, v35
	v_cvt_pk_bf16_f32 v35, v36, v37
	s_waitcnt lgkmcnt(0)
	global_store_dwordx4 v[80:81], v[66:69], off
	ds_read_b128 v[66:69], v145
	v_cvt_pk_bf16_f32 v18, v18, v19
	v_cvt_pk_bf16_f32 v19, v20, v21
	v_lshlrev_b32_e32 v0, 9, v148
	ds_write_b64 v131, v[50:51]
	s_waitcnt lgkmcnt(1)
	global_store_dwordx4 v[84:85], v[66:69], off
	ds_read_b128 v[66:69], v149
	v_cvt_pk_bf16_f32 v50, v54, v55
	v_cvt_pk_bf16_f32 v51, v56, v57
	ds_write_b64 v131, v[34:35] offset:2048
	v_cvt_pk_bf16_f32 v34, v38, v39
	v_cvt_pk_bf16_f32 v35, v40, v41
	ds_write_b64 v131, v[18:19] offset:4096
	v_cvt_pk_bf16_f32 v18, v22, v23
	v_cvt_pk_bf16_f32 v19, v24, v25
	v_cvt_pk_bf16_f32 v2, v2, v3
	v_cvt_pk_bf16_f32 v3, v4, v5
	v_lshl_add_u64 v[88:89], v[74:75], 0, v[0:1]
	v_lshlrev_b32_e32 v0, 9, v150
	ds_write_b64 v131, v[50:51] offset:16
	v_cvt_pk_bf16_f32 v50, v58, v59
	v_cvt_pk_bf16_f32 v51, v60, v61
	ds_write_b64 v131, v[34:35] offset:2064
	v_cvt_pk_bf16_f32 v34, v42, v43
	v_cvt_pk_bf16_f32 v35, v44, v45
	ds_write_b64 v131, v[18:19] offset:4112
	v_cvt_pk_bf16_f32 v18, v26, v27
	v_cvt_pk_bf16_f32 v19, v28, v29
	ds_write_b64 v131, v[2:3] offset:6144
	v_cvt_pk_bf16_f32 v2, v6, v7
	v_cvt_pk_bf16_f32 v3, v8, v9
	s_waitcnt lgkmcnt(6)
	global_store_dwordx4 v[88:89], v[66:69], off
	ds_write_b64 v131, v[50:51] offset:32
	v_cvt_pk_bf16_f32 v50, v62, v63
	v_lshl_add_u64 v[66:67], v[74:75], 0, v[0:1]
	v_cvt_pk_bf16_f32 v51, v64, v65
	ds_write_b64 v131, v[34:35] offset:2080
	v_cvt_pk_bf16_f32 v34, v46, v47
	v_cvt_pk_bf16_f32 v35, v48, v49
	ds_write_b64 v131, v[18:19] offset:4128
	v_cvt_pk_bf16_f32 v18, v30, v31
	v_cvt_pk_bf16_f32 v19, v32, v33
	ds_write_b64 v131, v[2:3] offset:6160
	v_cvt_pk_bf16_f32 v2, v10, v11
	v_cvt_pk_bf16_f32 v3, v12, v13
	global_store_dwordx4 v[66:67], v[70:73], off
	ds_write_b64 v131, v[50:51] offset:48
	ds_write_b64 v131, v[34:35] offset:2096
	ds_write_b64 v131, v[18:19] offset:4144
	ds_write_b64 v131, v[2:3] offset:6176
	ds_read_b128 v[2:5], v135
	ds_read_b128 v[6:9], v139
	ds_read_b128 v[10:13], v141
	v_cvt_pk_bf16_f32 v14, v14, v15
	v_cvt_pk_bf16_f32 v15, v16, v17
	ds_write_b64 v131, v[14:15] offset:6192
	s_waitcnt lgkmcnt(3)
	global_store_dwordx4 v[76:77], v[2:5], off offset:64
	s_waitcnt lgkmcnt(2)
	global_store_dwordx4 v[78:79], v[6:9], off offset:64
	s_waitcnt lgkmcnt(1)
	global_store_dwordx4 v[80:81], v[10:13], off offset:64
	ds_read_b128 v[2:5], v143
	ds_read_b128 v[6:9], v145
	ds_read_b128 v[10:13], v147
	ds_read_b128 v[14:17], v149
	ds_read_b128 v[18:21], v134
	s_waitcnt lgkmcnt(4)
	global_store_dwordx4 v[82:83], v[2:5], off offset:64
	s_waitcnt lgkmcnt(3)
	global_store_dwordx4 v[84:85], v[6:9], off offset:64
	s_waitcnt lgkmcnt(2)
	global_store_dwordx4 v[86:87], v[10:13], off offset:64
	s_waitcnt lgkmcnt(1)
	global_store_dwordx4 v[88:89], v[14:17], off offset:64
	s_waitcnt lgkmcnt(0)
	global_store_dwordx4 v[66:67], v[18:21], off offset:64
